# K-loops: the s_setprio 0 / s_setprio 1 pair between the two 16-MFMA blocks of each segment removed (priority stays raised through the 32 MFMAs)
# baseline (speedup 1.0000x reference)
.LBB0_175:
	s_ashr_i32 s57, s56, 31
	s_lshl_b64 s[52:53], s[56:57], 20
	v_readlane_b32 s66, v254, 17
	v_readlane_b32 s67, v254, 18
	s_add_u32 s66, s66, s52
	s_addc_u32 s67, s67, s53
	s_and_b64 s[52:53], s[6:7], exec
	s_cselect_b32 s11, s67, s9
	s_cselect_b32 s13, s66, s8
	s_ashr_i32 s61, s60, 31
	s_lshl_b64 s[52:53], s[60:61], 20
	v_readlane_b32 s68, v254, 21
	v_readlane_b32 s69, v254, 22
	s_add_u32 s88, s68, s52
	s_addc_u32 s89, s69, s53
	s_and_b64 s[52:53], s[6:7], exec
	s_cselect_b32 s57, s89, s15
	s_cselect_b32 s61, s88, s14
	s_add_u32 s8, s8, 0x80080
	s_addc_u32 s9, s9, 0
	s_add_u32 s68, s14, 0x100
	s_addc_u32 s69, s15, 0
	s_mov_b32 s90, -2
	s_add_u32 s14, s8, 0xfff80080
	s_addc_u32 s15, s9, -1
	s_add_i32 s91, 0, 0x10000
	s_cmp_eq_u32 s90, 28
	s_cselect_b32 s53, s11, s15
	s_cselect_b32 s52, s13, s14
	v_add_u32_e32 v14, s91, v188
	s_cselect_b32 s15, s57, s69
	s_cselect_b32 s14, s61, s68
	s_add_i32 s96, 0, 0x14000
	ds_read_b128 v[6:9], v14
	ds_read_b128 v[10:13], v14 offset:1024
	ds_read_b128 v[140:143], v14 offset:2048
	ds_read_b128 v[144:147], v14 offset:3072
	v_add_u32_e32 v14, s96, v188
	ds_read_b128 v[148:151], v14
	ds_read_b128 v[152:155], v14 offset:1024
	ds_read_b128 v[180:183], v14 offset:2048
	ds_read_b128 v[208:211], v14 offset:3072
	v_lshl_add_u64 v[14:15], s[8:9], 0, v[176:177]
	s_add_i32 m0, s40, 0xc000
	ds_read_b128 v[212:215], v206
	ds_read_b128 v[216:219], v206 offset:1024
	ds_read_b128 v[220:223], v206 offset:2048
	ds_read_b128 v[224:227], v206 offset:3072
	ds_read_b128 v[238:241], v206 offset:4096
	ds_read_b128 v[242:245], v206 offset:5120
	ds_read_b128 v[246:249], v206 offset:6144
	ds_read_b128 v[250:253], v206 offset:7168
	global_load_lds_dwordx4 v[14:15], off
	s_add_i32 m0, s40, 0xe000
	v_lshl_add_u64 v[14:15], s[8:9], 0, v[178:179]
	global_load_lds_dwordx4 v[14:15], off
	s_waitcnt vmcnt(8) lgkmcnt(0)
	s_setprio 1
	s_barrier
	v_mfma_f32_16x16x32_bf16 v[136:139], v[6:9], v[212:215], 0
	v_mfma_f32_16x16x32_bf16 v[104:107], v[140:143], v[212:215], 0
	v_mfma_f32_16x16x32_bf16 v[132:135], v[6:9], v[220:223], 0
	v_mfma_f32_16x16x32_bf16 v[100:103], v[140:143], v[220:223], 0
	v_mfma_f32_16x16x32_bf16 v[128:131], v[6:9], v[238:241], 0
	v_mfma_f32_16x16x32_bf16 v[96:99], v[140:143], v[238:241], 0
	v_mfma_f32_16x16x32_bf16 v[124:127], v[6:9], v[246:249], 0
	v_mfma_f32_16x16x32_bf16 v[92:95], v[140:143], v[246:249], 0
	v_mfma_f32_16x16x32_bf16 v[136:139], v[10:13], v[216:219], v[136:139]
	v_mfma_f32_16x16x32_bf16 v[104:107], v[144:147], v[216:219], v[104:107]
	v_mfma_f32_16x16x32_bf16 v[132:135], v[10:13], v[224:227], v[132:135]
	v_mfma_f32_16x16x32_bf16 v[100:103], v[144:147], v[224:227], v[100:103]
	v_mfma_f32_16x16x32_bf16 v[128:131], v[10:13], v[242:245], v[128:131]
	v_mfma_f32_16x16x32_bf16 v[96:99], v[144:147], v[242:245], v[96:99]
	v_mfma_f32_16x16x32_bf16 v[124:127], v[10:13], v[250:253], v[124:127]
	v_mfma_f32_16x16x32_bf16 v[92:95], v[144:147], v[250:253], v[92:95]
	v_mfma_f32_16x16x32_bf16 v[72:75], v[148:151], v[212:215], 0
	v_mfma_f32_16x16x32_bf16 v[40:43], v[180:183], v[212:215], 0
	v_mfma_f32_16x16x32_bf16 v[68:71], v[148:151], v[220:223], 0
	v_mfma_f32_16x16x32_bf16 v[36:39], v[180:183], v[220:223], 0
	v_mfma_f32_16x16x32_bf16 v[64:67], v[148:151], v[238:241], 0
	v_mfma_f32_16x16x32_bf16 v[32:35], v[180:183], v[238:241], 0
	v_mfma_f32_16x16x32_bf16 v[60:63], v[148:151], v[246:249], 0
	v_mfma_f32_16x16x32_bf16 v[28:31], v[180:183], v[246:249], 0
	v_mfma_f32_16x16x32_bf16 v[72:75], v[152:155], v[216:219], v[72:75]
	v_mfma_f32_16x16x32_bf16 v[40:43], v[208:211], v[216:219], v[40:43]
	v_mfma_f32_16x16x32_bf16 v[68:71], v[152:155], v[224:227], v[68:71]
	v_mfma_f32_16x16x32_bf16 v[36:39], v[208:211], v[224:227], v[36:39]
	v_mfma_f32_16x16x32_bf16 v[64:67], v[152:155], v[242:245], v[64:67]
	v_mfma_f32_16x16x32_bf16 v[32:35], v[208:211], v[242:245], v[32:35]
	v_mfma_f32_16x16x32_bf16 v[60:63], v[152:155], v[250:253], v[60:63]
	v_mfma_f32_16x16x32_bf16 v[28:31], v[208:211], v[250:253], v[28:31]
	s_barrier
	s_setprio 0
	s_add_i32 s91, s91, s33
	v_lshl_add_u64 v[156:157], s[14:15], 0, v[160:161]
	s_mov_b32 m0, s91
	ds_read_b128 v[212:215], v206 offset:16384
	ds_read_b128 v[216:219], v206 offset:17408
	ds_read_b128 v[220:223], v206 offset:18432
	ds_read_b128 v[224:227], v206 offset:19456
	ds_read_b128 v[238:241], v206 offset:20480
	ds_read_b128 v[242:245], v206 offset:21504
	ds_read_b128 v[246:249], v206 offset:22528
	ds_read_b128 v[250:253], v206 offset:23552
	global_load_lds_dwordx4 v[156:157], off
	s_add_i32 m0, s91, 0x2000
	s_add_u32 vcc_lo, s14, 0x80000
	v_lshl_add_u64 v[184:185], s[14:15], 0, v[164:165]
	s_addc_u32 vcc_hi, s15, 0
	s_add_i32 s91, s96, s33
	global_load_lds_dwordx4 v[184:185], off
	v_lshl_add_u64 v[14:15], vcc, 0, v[160:161]
	s_mov_b32 m0, s91
	v_lshl_add_u64 v[196:197], s[52:53], 0, v[158:159]
	global_load_lds_dwordx4 v[14:15], off
	v_lshl_add_u64 v[14:15], vcc, 0, v[164:165]
	s_add_i32 m0, s91, 0x2000
	v_lshl_add_u64 v[198:199], s[52:53], 0, v[162:163]
	global_load_lds_dwordx4 v[14:15], off
	s_mov_b32 m0, s40
	s_nop 0
	global_load_lds_dwordx4 v[196:197], off
	s_mov_b32 m0, s41
	s_nop 0
	global_load_lds_dwordx4 v[198:199], off
	s_waitcnt vmcnt(8) lgkmcnt(0)
	s_setprio 1
	s_barrier
	v_mfma_f32_16x16x32_bf16 v[120:123], v[6:9], v[212:215], 0
	v_mfma_f32_16x16x32_bf16 v[88:91], v[140:143], v[212:215], 0
	v_mfma_f32_16x16x32_bf16 v[116:119], v[6:9], v[220:223], 0
	v_mfma_f32_16x16x32_bf16 v[84:87], v[140:143], v[220:223], 0
	v_mfma_f32_16x16x32_bf16 v[112:115], v[6:9], v[238:241], 0
	v_mfma_f32_16x16x32_bf16 v[80:83], v[140:143], v[238:241], 0
	v_mfma_f32_16x16x32_bf16 v[6:9], v[6:9], v[246:249], 0
	v_mfma_f32_16x16x32_bf16 v[120:123], v[10:13], v[216:219], v[120:123]
	v_mfma_f32_16x16x32_bf16 v[88:91], v[144:147], v[216:219], v[88:91]
	v_mfma_f32_16x16x32_bf16 v[116:119], v[10:13], v[224:227], v[116:119]
	v_mfma_f32_16x16x32_bf16 v[84:87], v[144:147], v[224:227], v[84:87]
	v_mfma_f32_16x16x32_bf16 v[112:115], v[10:13], v[242:245], v[112:115]
	v_mfma_f32_16x16x32_bf16 v[80:83], v[144:147], v[242:245], v[80:83]
	v_mfma_f32_16x16x32_bf16 v[6:9], v[10:13], v[250:253], v[6:9]
	v_mfma_f32_16x16x32_bf16 v[10:13], v[140:143], v[246:249], 0
	v_mfma_f32_16x16x32_bf16 v[10:13], v[144:147], v[250:253], v[10:13]
	v_mfma_f32_16x16x32_bf16 v[56:59], v[148:151], v[212:215], 0
	v_mfma_f32_16x16x32_bf16 v[24:27], v[180:183], v[212:215], 0
	v_mfma_f32_16x16x32_bf16 v[52:55], v[148:151], v[220:223], 0
	v_mfma_f32_16x16x32_bf16 v[20:23], v[180:183], v[220:223], 0
	v_mfma_f32_16x16x32_bf16 v[48:51], v[148:151], v[238:241], 0
	v_mfma_f32_16x16x32_bf16 v[14:17], v[180:183], v[238:241], 0
	v_mfma_f32_16x16x32_bf16 v[44:47], v[148:151], v[246:249], 0
	v_mfma_f32_16x16x32_bf16 v[2:5], v[180:183], v[246:249], 0
	v_mfma_f32_16x16x32_bf16 v[56:59], v[152:155], v[216:219], v[56:59]
	v_mfma_f32_16x16x32_bf16 v[24:27], v[208:211], v[216:219], v[24:27]
	v_mfma_f32_16x16x32_bf16 v[52:55], v[152:155], v[224:227], v[52:55]
	v_mfma_f32_16x16x32_bf16 v[20:23], v[208:211], v[224:227], v[20:23]
	v_mfma_f32_16x16x32_bf16 v[48:51], v[152:155], v[242:245], v[48:51]
	v_mfma_f32_16x16x32_bf16 v[14:17], v[208:211], v[242:245], v[14:17]
	v_mfma_f32_16x16x32_bf16 v[44:47], v[152:155], v[250:253], v[44:47]
	v_mfma_f32_16x16x32_bf16 v[2:5], v[208:211], v[250:253], v[2:5]
	s_barrier
	s_setprio 0
	s_add_i32 s91, 0, 0x18000
	v_add_u32_e32 v18, s91, v188
	s_add_i32 s96, 0, 0x1c000
	ds_read_b128 v[76:79], v18
	ds_read_b128 v[108:111], v18 offset:1024
	ds_read_b128 v[140:143], v18 offset:2048
	ds_read_b128 v[144:147], v18 offset:3072
	v_add_u32_e32 v18, s96, v188
	ds_read_b128 v[148:151], v18
	ds_read_b128 v[152:155], v18 offset:1024
	ds_read_b128 v[180:183], v18 offset:2048
	ds_read_b128 v[208:211], v18 offset:3072
	s_add_u32 s52, s52, 0x80000
	s_addc_u32 s53, s53, 0
	s_mov_b32 m0, s42
	v_lshl_add_u64 v[18:19], s[52:53], 0, v[158:159]
	ds_read_b128 v[212:215], v206 offset:32768
	ds_read_b128 v[216:219], v206 offset:33792
	ds_read_b128 v[220:223], v206 offset:34816
	ds_read_b128 v[224:227], v206 offset:35840
	ds_read_b128 v[238:241], v206 offset:36864
	ds_read_b128 v[242:245], v206 offset:37888
	ds_read_b128 v[246:249], v206 offset:38912
	ds_read_b128 v[250:253], v206 offset:39936
	global_load_lds_dwordx4 v[18:19], off
	s_mov_b32 m0, s43
	v_lshl_add_u64 v[18:19], s[52:53], 0, v[162:163]
	global_load_lds_dwordx4 v[18:19], off
	s_waitcnt vmcnt(8) lgkmcnt(0)
	s_setprio 1
	s_barrier
	v_mfma_f32_16x16x32_bf16 v[136:139], v[76:79], v[212:215], v[136:139]
	v_mfma_f32_16x16x32_bf16 v[104:107], v[140:143], v[212:215], v[104:107]
	v_mfma_f32_16x16x32_bf16 v[132:135], v[76:79], v[220:223], v[132:135]
	v_mfma_f32_16x16x32_bf16 v[100:103], v[140:143], v[220:223], v[100:103]
	v_mfma_f32_16x16x32_bf16 v[128:131], v[76:79], v[238:241], v[128:131]
	v_mfma_f32_16x16x32_bf16 v[96:99], v[140:143], v[238:241], v[96:99]
	v_mfma_f32_16x16x32_bf16 v[124:127], v[76:79], v[246:249], v[124:127]
	v_mfma_f32_16x16x32_bf16 v[92:95], v[140:143], v[246:249], v[92:95]
	v_mfma_f32_16x16x32_bf16 v[136:139], v[108:111], v[216:219], v[136:139]
	v_mfma_f32_16x16x32_bf16 v[104:107], v[144:147], v[216:219], v[104:107]
	v_mfma_f32_16x16x32_bf16 v[132:135], v[108:111], v[224:227], v[132:135]
	v_mfma_f32_16x16x32_bf16 v[100:103], v[144:147], v[224:227], v[100:103]
	v_mfma_f32_16x16x32_bf16 v[128:131], v[108:111], v[242:245], v[128:131]
	v_mfma_f32_16x16x32_bf16 v[96:99], v[144:147], v[242:245], v[96:99]
	v_mfma_f32_16x16x32_bf16 v[124:127], v[108:111], v[250:253], v[124:127]
	v_mfma_f32_16x16x32_bf16 v[92:95], v[144:147], v[250:253], v[92:95]
	v_mfma_f32_16x16x32_bf16 v[72:75], v[148:151], v[212:215], v[72:75]
	v_mfma_f32_16x16x32_bf16 v[40:43], v[180:183], v[212:215], v[40:43]
	v_mfma_f32_16x16x32_bf16 v[68:71], v[148:151], v[220:223], v[68:71]
	v_mfma_f32_16x16x32_bf16 v[36:39], v[180:183], v[220:223], v[36:39]
	v_mfma_f32_16x16x32_bf16 v[64:67], v[148:151], v[238:241], v[64:67]
	v_mfma_f32_16x16x32_bf16 v[32:35], v[180:183], v[238:241], v[32:35]
	v_mfma_f32_16x16x32_bf16 v[60:63], v[148:151], v[246:249], v[60:63]
	v_mfma_f32_16x16x32_bf16 v[28:31], v[180:183], v[246:249], v[28:31]
	v_mfma_f32_16x16x32_bf16 v[72:75], v[152:155], v[216:219], v[72:75]
	v_mfma_f32_16x16x32_bf16 v[40:43], v[208:211], v[216:219], v[40:43]
	v_mfma_f32_16x16x32_bf16 v[68:71], v[152:155], v[224:227], v[68:71]
	v_mfma_f32_16x16x32_bf16 v[36:39], v[208:211], v[224:227], v[36:39]
	v_mfma_f32_16x16x32_bf16 v[64:67], v[152:155], v[242:245], v[64:67]
	v_mfma_f32_16x16x32_bf16 v[32:35], v[208:211], v[242:245], v[32:35]
	v_mfma_f32_16x16x32_bf16 v[60:63], v[152:155], v[250:253], v[60:63]
	v_mfma_f32_16x16x32_bf16 v[28:31], v[208:211], v[250:253], v[28:31]
	s_barrier
	s_setprio 0
	s_add_i32 s52, s91, s33
	v_lshl_add_u64 v[18:19], v[156:157], 0, s[58:59]
	s_mov_b32 m0, s52
	ds_read_b128 v[212:215], v206 offset:49152
	ds_read_b128 v[216:219], v206 offset:50176
	ds_read_b128 v[220:223], v206 offset:51200
	ds_read_b128 v[224:227], v206 offset:52224
	ds_read_b128 v[238:241], v206 offset:53248
	ds_read_b128 v[242:245], v206 offset:54272
	ds_read_b128 v[246:249], v206 offset:55296
	ds_read_b128 v[250:253], v206 offset:56320
	global_load_lds_dwordx4 v[18:19], off
	s_add_i32 m0, s52, 0x2000
	s_add_u32 s14, s14, 0x80080
	v_lshl_add_u64 v[18:19], v[184:185], 0, s[58:59]
	s_addc_u32 s15, s15, 0
	s_add_i32 s52, s96, s33
	global_load_lds_dwordx4 v[18:19], off
	s_mov_b32 m0, s52
	v_lshl_add_u64 v[18:19], s[14:15], 0, v[160:161]
	global_load_lds_dwordx4 v[18:19], off
	s_add_i32 m0, s52, 0x2000
	v_lshl_add_u64 v[18:19], s[14:15], 0, v[164:165]
	global_load_lds_dwordx4 v[18:19], off
	s_mov_b32 m0, s55
	v_lshl_add_u64 v[18:19], v[196:197], 0, s[58:59]
	global_load_lds_dwordx4 v[18:19], off
	s_mov_b32 m0, s77
	v_lshl_add_u64 v[18:19], v[198:199], 0, s[58:59]
	global_load_lds_dwordx4 v[18:19], off
	s_waitcnt vmcnt(8) lgkmcnt(0)
	s_setprio 1
	s_barrier
	v_mfma_f32_16x16x32_bf16 v[120:123], v[76:79], v[212:215], v[120:123]
	v_mfma_f32_16x16x32_bf16 v[116:119], v[76:79], v[220:223], v[116:119]
	v_mfma_f32_16x16x32_bf16 v[112:115], v[76:79], v[238:241], v[112:115]
	v_mfma_f32_16x16x32_bf16 v[6:9], v[76:79], v[246:249], v[6:9]
	v_mfma_f32_16x16x32_bf16 v[120:123], v[108:111], v[216:219], v[120:123]
	v_mfma_f32_16x16x32_bf16 v[88:91], v[140:143], v[212:215], v[88:91]
	v_mfma_f32_16x16x32_bf16 v[116:119], v[108:111], v[224:227], v[116:119]
	v_mfma_f32_16x16x32_bf16 v[84:87], v[140:143], v[220:223], v[84:87]
	v_mfma_f32_16x16x32_bf16 v[112:115], v[108:111], v[242:245], v[112:115]
	v_mfma_f32_16x16x32_bf16 v[80:83], v[140:143], v[238:241], v[80:83]
	v_mfma_f32_16x16x32_bf16 v[108:111], v[108:111], v[250:253], v[6:9]
	v_mfma_f32_16x16x32_bf16 v[6:9], v[140:143], v[246:249], v[10:13]
	v_mfma_f32_16x16x32_bf16 v[88:91], v[144:147], v[216:219], v[88:91]
	v_mfma_f32_16x16x32_bf16 v[84:87], v[144:147], v[224:227], v[84:87]
	v_mfma_f32_16x16x32_bf16 v[80:83], v[144:147], v[242:245], v[80:83]
	v_mfma_f32_16x16x32_bf16 v[76:79], v[144:147], v[250:253], v[6:9]
	v_mfma_f32_16x16x32_bf16 v[6:9], v[148:151], v[212:215], v[56:59]
	v_mfma_f32_16x16x32_bf16 v[56:59], v[152:155], v[216:219], v[6:9]
	v_mfma_f32_16x16x32_bf16 v[6:9], v[180:183], v[212:215], v[24:27]
	v_mfma_f32_16x16x32_bf16 v[24:27], v[208:211], v[216:219], v[6:9]
	v_mfma_f32_16x16x32_bf16 v[6:9], v[148:151], v[220:223], v[52:55]
	v_mfma_f32_16x16x32_bf16 v[52:55], v[152:155], v[224:227], v[6:9]
	v_mfma_f32_16x16x32_bf16 v[6:9], v[180:183], v[220:223], v[20:23]
	v_mfma_f32_16x16x32_bf16 v[20:23], v[208:211], v[224:227], v[6:9]
	v_mfma_f32_16x16x32_bf16 v[6:9], v[148:151], v[238:241], v[48:51]
	v_mfma_f32_16x16x32_bf16 v[48:51], v[152:155], v[242:245], v[6:9]
	v_mfma_f32_16x16x32_bf16 v[6:9], v[180:183], v[238:241], v[14:17]
	v_mfma_f32_16x16x32_bf16 v[16:19], v[208:211], v[242:245], v[6:9]
	v_mfma_f32_16x16x32_bf16 v[6:9], v[148:151], v[246:249], v[44:47]
	v_mfma_f32_16x16x32_bf16 v[2:5], v[180:183], v[246:249], v[2:5]
	v_mfma_f32_16x16x32_bf16 v[44:47], v[152:155], v[250:253], v[6:9]
	v_mfma_f32_16x16x32_bf16 v[2:5], v[208:211], v[250:253], v[2:5]
	s_barrier
	s_setprio 0
	s_add_i32 s90, s90, 2
	s_add_u32 s8, s8, 0x100
	s_addc_u32 s9, s9, 0
	s_add_u32 s68, s68, 0x100
	s_addc_u32 s69, s69, 0
	s_cmp_gt_u32 s90, 29
	s_cbranch_scc1 .Lpeel_done_0
.LBB0_176:
	s_add_u32 s14, s8, 0xfff80080
	s_addc_u32 s15, s9, -1
	s_add_i32 s91, 0, 0x10000
	s_cmp_eq_u32 s90, 28
	s_cselect_b32 s53, s11, s15
	s_cselect_b32 s52, s13, s14
	v_add_u32_e32 v14, s91, v188
	s_cselect_b32 s15, s57, s69
	s_cselect_b32 s14, s61, s68
	s_add_i32 s96, 0, 0x14000
	ds_read_b128 v[6:9], v14
	ds_read_b128 v[10:13], v14 offset:1024
	ds_read_b128 v[140:143], v14 offset:2048
	ds_read_b128 v[144:147], v14 offset:3072
	v_add_u32_e32 v14, s96, v188
	ds_read_b128 v[148:151], v14
	ds_read_b128 v[152:155], v14 offset:1024
	ds_read_b128 v[180:183], v14 offset:2048
	ds_read_b128 v[208:211], v14 offset:3072
	v_lshl_add_u64 v[14:15], s[8:9], 0, v[176:177]
	s_add_i32 m0, s40, 0xc000
	ds_read_b128 v[212:215], v206
	ds_read_b128 v[216:219], v206 offset:1024
	ds_read_b128 v[220:223], v206 offset:2048
	ds_read_b128 v[224:227], v206 offset:3072
	ds_read_b128 v[238:241], v206 offset:4096
	ds_read_b128 v[242:245], v206 offset:5120
	ds_read_b128 v[246:249], v206 offset:6144
	ds_read_b128 v[250:253], v206 offset:7168
	global_load_lds_dwordx4 v[14:15], off
	s_add_i32 m0, s40, 0xe000
	v_lshl_add_u64 v[14:15], s[8:9], 0, v[178:179]
	global_load_lds_dwordx4 v[14:15], off
	s_waitcnt vmcnt(8) lgkmcnt(0)
	s_setprio 1
	s_barrier
	v_mfma_f32_16x16x32_bf16 v[136:139], v[6:9], v[212:215], v[136:139]
	v_mfma_f32_16x16x32_bf16 v[104:107], v[140:143], v[212:215], v[104:107]
	v_mfma_f32_16x16x32_bf16 v[132:135], v[6:9], v[220:223], v[132:135]
	v_mfma_f32_16x16x32_bf16 v[100:103], v[140:143], v[220:223], v[100:103]
	v_mfma_f32_16x16x32_bf16 v[128:131], v[6:9], v[238:241], v[128:131]
	v_mfma_f32_16x16x32_bf16 v[96:99], v[140:143], v[238:241], v[96:99]
	v_mfma_f32_16x16x32_bf16 v[124:127], v[6:9], v[246:249], v[124:127]
	v_mfma_f32_16x16x32_bf16 v[92:95], v[140:143], v[246:249], v[92:95]
	v_mfma_f32_16x16x32_bf16 v[136:139], v[10:13], v[216:219], v[136:139]
	v_mfma_f32_16x16x32_bf16 v[104:107], v[144:147], v[216:219], v[104:107]
	v_mfma_f32_16x16x32_bf16 v[132:135], v[10:13], v[224:227], v[132:135]
	v_mfma_f32_16x16x32_bf16 v[100:103], v[144:147], v[224:227], v[100:103]
	v_mfma_f32_16x16x32_bf16 v[128:131], v[10:13], v[242:245], v[128:131]
	v_mfma_f32_16x16x32_bf16 v[96:99], v[144:147], v[242:245], v[96:99]
	v_mfma_f32_16x16x32_bf16 v[124:127], v[10:13], v[250:253], v[124:127]
	v_mfma_f32_16x16x32_bf16 v[92:95], v[144:147], v[250:253], v[92:95]
	v_mfma_f32_16x16x32_bf16 v[72:75], v[148:151], v[212:215], v[72:75]
	v_mfma_f32_16x16x32_bf16 v[40:43], v[180:183], v[212:215], v[40:43]
	v_mfma_f32_16x16x32_bf16 v[68:71], v[148:151], v[220:223], v[68:71]
	v_mfma_f32_16x16x32_bf16 v[36:39], v[180:183], v[220:223], v[36:39]
	v_mfma_f32_16x16x32_bf16 v[64:67], v[148:151], v[238:241], v[64:67]
	v_mfma_f32_16x16x32_bf16 v[32:35], v[180:183], v[238:241], v[32:35]
	v_mfma_f32_16x16x32_bf16 v[60:63], v[148:151], v[246:249], v[60:63]
	v_mfma_f32_16x16x32_bf16 v[28:31], v[180:183], v[246:249], v[28:31]
	v_mfma_f32_16x16x32_bf16 v[72:75], v[152:155], v[216:219], v[72:75]
	v_mfma_f32_16x16x32_bf16 v[40:43], v[208:211], v[216:219], v[40:43]
	v_mfma_f32_16x16x32_bf16 v[68:71], v[152:155], v[224:227], v[68:71]
	v_mfma_f32_16x16x32_bf16 v[36:39], v[208:211], v[224:227], v[36:39]
	v_mfma_f32_16x16x32_bf16 v[64:67], v[152:155], v[242:245], v[64:67]
	v_mfma_f32_16x16x32_bf16 v[32:35], v[208:211], v[242:245], v[32:35]
	v_mfma_f32_16x16x32_bf16 v[60:63], v[152:155], v[250:253], v[60:63]
	v_mfma_f32_16x16x32_bf16 v[28:31], v[208:211], v[250:253], v[28:31]
	s_setprio 0
	s_barrier
	s_add_i32 s91, s91, s33
	v_lshl_add_u64 v[156:157], s[14:15], 0, v[160:161]
	s_mov_b32 m0, s91
	ds_read_b128 v[212:215], v206 offset:16384
	ds_read_b128 v[216:219], v206 offset:17408
	ds_read_b128 v[220:223], v206 offset:18432
	ds_read_b128 v[224:227], v206 offset:19456
	ds_read_b128 v[238:241], v206 offset:20480
	ds_read_b128 v[242:245], v206 offset:21504
	ds_read_b128 v[246:249], v206 offset:22528
	ds_read_b128 v[250:253], v206 offset:23552
	global_load_lds_dwordx4 v[156:157], off
	s_add_i32 m0, s91, 0x2000
	s_add_u32 vcc_lo, s14, 0x80000
	v_lshl_add_u64 v[184:185], s[14:15], 0, v[164:165]
	s_addc_u32 vcc_hi, s15, 0
	s_add_i32 s91, s96, s33
	global_load_lds_dwordx4 v[184:185], off
	v_lshl_add_u64 v[14:15], vcc, 0, v[160:161]
	s_mov_b32 m0, s91
	v_lshl_add_u64 v[196:197], s[52:53], 0, v[158:159]
	global_load_lds_dwordx4 v[14:15], off
	v_lshl_add_u64 v[14:15], vcc, 0, v[164:165]
	s_add_i32 m0, s91, 0x2000
	v_lshl_add_u64 v[198:199], s[52:53], 0, v[162:163]
	global_load_lds_dwordx4 v[14:15], off
	s_mov_b32 m0, s40
	s_nop 0
	global_load_lds_dwordx4 v[196:197], off
	s_mov_b32 m0, s41
	s_nop 0
	global_load_lds_dwordx4 v[198:199], off
	s_waitcnt vmcnt(8) lgkmcnt(0)
	s_setprio 1
	s_barrier
	v_mfma_f32_16x16x32_bf16 v[120:123], v[6:9], v[212:215], v[120:123]
	v_mfma_f32_16x16x32_bf16 v[88:91], v[140:143], v[212:215], v[88:91]
	v_mfma_f32_16x16x32_bf16 v[116:119], v[6:9], v[220:223], v[116:119]
	v_mfma_f32_16x16x32_bf16 v[84:87], v[140:143], v[220:223], v[84:87]
	v_mfma_f32_16x16x32_bf16 v[112:115], v[6:9], v[238:241], v[112:115]
	v_mfma_f32_16x16x32_bf16 v[80:83], v[140:143], v[238:241], v[80:83]
	v_mfma_f32_16x16x32_bf16 v[6:9], v[6:9], v[246:249], v[108:111]
	v_mfma_f32_16x16x32_bf16 v[120:123], v[10:13], v[216:219], v[120:123]
	v_mfma_f32_16x16x32_bf16 v[88:91], v[144:147], v[216:219], v[88:91]
	v_mfma_f32_16x16x32_bf16 v[116:119], v[10:13], v[224:227], v[116:119]
	v_mfma_f32_16x16x32_bf16 v[84:87], v[144:147], v[224:227], v[84:87]
	v_mfma_f32_16x16x32_bf16 v[112:115], v[10:13], v[242:245], v[112:115]
	v_mfma_f32_16x16x32_bf16 v[80:83], v[144:147], v[242:245], v[80:83]
	v_mfma_f32_16x16x32_bf16 v[6:9], v[10:13], v[250:253], v[6:9]
	v_mfma_f32_16x16x32_bf16 v[10:13], v[140:143], v[246:249], v[76:79]
	v_mfma_f32_16x16x32_bf16 v[10:13], v[144:147], v[250:253], v[10:13]
	v_mfma_f32_16x16x32_bf16 v[56:59], v[148:151], v[212:215], v[56:59]
	v_mfma_f32_16x16x32_bf16 v[24:27], v[180:183], v[212:215], v[24:27]
	v_mfma_f32_16x16x32_bf16 v[52:55], v[148:151], v[220:223], v[52:55]
	v_mfma_f32_16x16x32_bf16 v[20:23], v[180:183], v[220:223], v[20:23]
	v_mfma_f32_16x16x32_bf16 v[48:51], v[148:151], v[238:241], v[48:51]
	v_mfma_f32_16x16x32_bf16 v[14:17], v[180:183], v[238:241], v[16:19]
	v_mfma_f32_16x16x32_bf16 v[44:47], v[148:151], v[246:249], v[44:47]
	v_mfma_f32_16x16x32_bf16 v[2:5], v[180:183], v[246:249], v[2:5]
	v_mfma_f32_16x16x32_bf16 v[56:59], v[152:155], v[216:219], v[56:59]
	v_mfma_f32_16x16x32_bf16 v[24:27], v[208:211], v[216:219], v[24:27]
	v_mfma_f32_16x16x32_bf16 v[52:55], v[152:155], v[224:227], v[52:55]
	v_mfma_f32_16x16x32_bf16 v[20:23], v[208:211], v[224:227], v[20:23]
	v_mfma_f32_16x16x32_bf16 v[48:51], v[152:155], v[242:245], v[48:51]
	v_mfma_f32_16x16x32_bf16 v[14:17], v[208:211], v[242:245], v[14:17]
	v_mfma_f32_16x16x32_bf16 v[44:47], v[152:155], v[250:253], v[44:47]
	v_mfma_f32_16x16x32_bf16 v[2:5], v[208:211], v[250:253], v[2:5]
	s_setprio 0
	s_barrier
	s_add_i32 s91, 0, 0x18000
	v_add_u32_e32 v18, s91, v188
	s_add_i32 s96, 0, 0x1c000
	ds_read_b128 v[76:79], v18
	ds_read_b128 v[108:111], v18 offset:1024
	ds_read_b128 v[140:143], v18 offset:2048
	ds_read_b128 v[144:147], v18 offset:3072
	v_add_u32_e32 v18, s96, v188
	ds_read_b128 v[148:151], v18
	ds_read_b128 v[152:155], v18 offset:1024
	ds_read_b128 v[180:183], v18 offset:2048
	ds_read_b128 v[208:211], v18 offset:3072
	s_add_u32 s52, s52, 0x80000
	s_addc_u32 s53, s53, 0
	s_mov_b32 m0, s42
	v_lshl_add_u64 v[18:19], s[52:53], 0, v[158:159]
	ds_read_b128 v[212:215], v206 offset:32768
	ds_read_b128 v[216:219], v206 offset:33792
	ds_read_b128 v[220:223], v206 offset:34816
	ds_read_b128 v[224:227], v206 offset:35840
	ds_read_b128 v[238:241], v206 offset:36864
	ds_read_b128 v[242:245], v206 offset:37888
	ds_read_b128 v[246:249], v206 offset:38912
	ds_read_b128 v[250:253], v206 offset:39936
	global_load_lds_dwordx4 v[18:19], off
	s_mov_b32 m0, s43
	v_lshl_add_u64 v[18:19], s[52:53], 0, v[162:163]
	global_load_lds_dwordx4 v[18:19], off
	s_waitcnt vmcnt(8) lgkmcnt(0)
	s_setprio 1
	s_barrier
	v_mfma_f32_16x16x32_bf16 v[136:139], v[76:79], v[212:215], v[136:139]
	v_mfma_f32_16x16x32_bf16 v[104:107], v[140:143], v[212:215], v[104:107]
	v_mfma_f32_16x16x32_bf16 v[132:135], v[76:79], v[220:223], v[132:135]
	v_mfma_f32_16x16x32_bf16 v[100:103], v[140:143], v[220:223], v[100:103]
	v_mfma_f32_16x16x32_bf16 v[128:131], v[76:79], v[238:241], v[128:131]
	v_mfma_f32_16x16x32_bf16 v[96:99], v[140:143], v[238:241], v[96:99]
	v_mfma_f32_16x16x32_bf16 v[124:127], v[76:79], v[246:249], v[124:127]
	v_mfma_f32_16x16x32_bf16 v[92:95], v[140:143], v[246:249], v[92:95]
	v_mfma_f32_16x16x32_bf16 v[136:139], v[108:111], v[216:219], v[136:139]
	v_mfma_f32_16x16x32_bf16 v[104:107], v[144:147], v[216:219], v[104:107]
	v_mfma_f32_16x16x32_bf16 v[132:135], v[108:111], v[224:227], v[132:135]
	v_mfma_f32_16x16x32_bf16 v[100:103], v[144:147], v[224:227], v[100:103]
	v_mfma_f32_16x16x32_bf16 v[128:131], v[108:111], v[242:245], v[128:131]
	v_mfma_f32_16x16x32_bf16 v[96:99], v[144:147], v[242:245], v[96:99]
	v_mfma_f32_16x16x32_bf16 v[124:127], v[108:111], v[250:253], v[124:127]
	v_mfma_f32_16x16x32_bf16 v[92:95], v[144:147], v[250:253], v[92:95]
	v_mfma_f32_16x16x32_bf16 v[72:75], v[148:151], v[212:215], v[72:75]
	v_mfma_f32_16x16x32_bf16 v[40:43], v[180:183], v[212:215], v[40:43]
	v_mfma_f32_16x16x32_bf16 v[68:71], v[148:151], v[220:223], v[68:71]
	v_mfma_f32_16x16x32_bf16 v[36:39], v[180:183], v[220:223], v[36:39]
	v_mfma_f32_16x16x32_bf16 v[64:67], v[148:151], v[238:241], v[64:67]
	v_mfma_f32_16x16x32_bf16 v[32:35], v[180:183], v[238:241], v[32:35]
	v_mfma_f32_16x16x32_bf16 v[60:63], v[148:151], v[246:249], v[60:63]
	v_mfma_f32_16x16x32_bf16 v[28:31], v[180:183], v[246:249], v[28:31]
	v_mfma_f32_16x16x32_bf16 v[72:75], v[152:155], v[216:219], v[72:75]
	v_mfma_f32_16x16x32_bf16 v[40:43], v[208:211], v[216:219], v[40:43]
	v_mfma_f32_16x16x32_bf16 v[68:71], v[152:155], v[224:227], v[68:71]
	v_mfma_f32_16x16x32_bf16 v[36:39], v[208:211], v[224:227], v[36:39]
	v_mfma_f32_16x16x32_bf16 v[64:67], v[152:155], v[242:245], v[64:67]
	v_mfma_f32_16x16x32_bf16 v[32:35], v[208:211], v[242:245], v[32:35]
	v_mfma_f32_16x16x32_bf16 v[60:63], v[152:155], v[250:253], v[60:63]
	v_mfma_f32_16x16x32_bf16 v[28:31], v[208:211], v[250:253], v[28:31]
	s_setprio 0
	s_barrier
	s_add_i32 s52, s91, s33
	v_lshl_add_u64 v[18:19], v[156:157], 0, s[58:59]
	s_mov_b32 m0, s52
	ds_read_b128 v[212:215], v206 offset:49152
	ds_read_b128 v[216:219], v206 offset:50176
	ds_read_b128 v[220:223], v206 offset:51200
	ds_read_b128 v[224:227], v206 offset:52224
	ds_read_b128 v[238:241], v206 offset:53248
	ds_read_b128 v[242:245], v206 offset:54272
	ds_read_b128 v[246:249], v206 offset:55296
	ds_read_b128 v[250:253], v206 offset:56320
	global_load_lds_dwordx4 v[18:19], off
	s_add_i32 m0, s52, 0x2000
	s_add_u32 s14, s14, 0x80080
	v_lshl_add_u64 v[18:19], v[184:185], 0, s[58:59]
	s_addc_u32 s15, s15, 0
	s_add_i32 s52, s96, s33
	global_load_lds_dwordx4 v[18:19], off
	s_mov_b32 m0, s52
	v_lshl_add_u64 v[18:19], s[14:15], 0, v[160:161]
	global_load_lds_dwordx4 v[18:19], off
	s_add_i32 m0, s52, 0x2000
	v_lshl_add_u64 v[18:19], s[14:15], 0, v[164:165]
	global_load_lds_dwordx4 v[18:19], off
	s_mov_b32 m0, s55
	v_lshl_add_u64 v[18:19], v[196:197], 0, s[58:59]
	global_load_lds_dwordx4 v[18:19], off
	s_mov_b32 m0, s77
	v_lshl_add_u64 v[18:19], v[198:199], 0, s[58:59]
	global_load_lds_dwordx4 v[18:19], off
	s_waitcnt vmcnt(8) lgkmcnt(0)
	s_setprio 1
	s_barrier
	v_mfma_f32_16x16x32_bf16 v[120:123], v[76:79], v[212:215], v[120:123]
	v_mfma_f32_16x16x32_bf16 v[116:119], v[76:79], v[220:223], v[116:119]
	v_mfma_f32_16x16x32_bf16 v[112:115], v[76:79], v[238:241], v[112:115]
	v_mfma_f32_16x16x32_bf16 v[6:9], v[76:79], v[246:249], v[6:9]
	v_mfma_f32_16x16x32_bf16 v[120:123], v[108:111], v[216:219], v[120:123]
	v_mfma_f32_16x16x32_bf16 v[88:91], v[140:143], v[212:215], v[88:91]
	v_mfma_f32_16x16x32_bf16 v[116:119], v[108:111], v[224:227], v[116:119]
	v_mfma_f32_16x16x32_bf16 v[84:87], v[140:143], v[220:223], v[84:87]
	v_mfma_f32_16x16x32_bf16 v[112:115], v[108:111], v[242:245], v[112:115]
	v_mfma_f32_16x16x32_bf16 v[80:83], v[140:143], v[238:241], v[80:83]
	v_mfma_f32_16x16x32_bf16 v[108:111], v[108:111], v[250:253], v[6:9]
	v_mfma_f32_16x16x32_bf16 v[6:9], v[140:143], v[246:249], v[10:13]
	v_mfma_f32_16x16x32_bf16 v[88:91], v[144:147], v[216:219], v[88:91]
	v_mfma_f32_16x16x32_bf16 v[84:87], v[144:147], v[224:227], v[84:87]
	v_mfma_f32_16x16x32_bf16 v[80:83], v[144:147], v[242:245], v[80:83]
	v_mfma_f32_16x16x32_bf16 v[76:79], v[144:147], v[250:253], v[6:9]
	v_mfma_f32_16x16x32_bf16 v[6:9], v[148:151], v[212:215], v[56:59]
	v_mfma_f32_16x16x32_bf16 v[56:59], v[152:155], v[216:219], v[6:9]
	v_mfma_f32_16x16x32_bf16 v[6:9], v[180:183], v[212:215], v[24:27]
	v_mfma_f32_16x16x32_bf16 v[24:27], v[208:211], v[216:219], v[6:9]
	v_mfma_f32_16x16x32_bf16 v[6:9], v[148:151], v[220:223], v[52:55]
	v_mfma_f32_16x16x32_bf16 v[52:55], v[152:155], v[224:227], v[6:9]
	v_mfma_f32_16x16x32_bf16 v[6:9], v[180:183], v[220:223], v[20:23]
	v_mfma_f32_16x16x32_bf16 v[20:23], v[208:211], v[224:227], v[6:9]
	v_mfma_f32_16x16x32_bf16 v[6:9], v[148:151], v[238:241], v[48:51]
	v_mfma_f32_16x16x32_bf16 v[48:51], v[152:155], v[242:245], v[6:9]
	v_mfma_f32_16x16x32_bf16 v[6:9], v[180:183], v[238:241], v[14:17]
	v_mfma_f32_16x16x32_bf16 v[16:19], v[208:211], v[242:245], v[6:9]
	v_mfma_f32_16x16x32_bf16 v[6:9], v[148:151], v[246:249], v[44:47]
	v_mfma_f32_16x16x32_bf16 v[2:5], v[180:183], v[246:249], v[2:5]
	v_mfma_f32_16x16x32_bf16 v[44:47], v[152:155], v[250:253], v[6:9]
	v_mfma_f32_16x16x32_bf16 v[2:5], v[208:211], v[250:253], v[2:5]
	s_setprio 0
	s_barrier
	s_add_i32 s90, s90, 2
	s_add_u32 s8, s8, 0x100
	s_addc_u32 s9, s9, 0
	s_add_u32 s68, s68, 0x100
	s_addc_u32 s69, s69, 0
	s_cmp_gt_u32 s90, 29
	s_cbranch_scc0 .LBB0_176

.LBB0_671:
	s_ashr_i32 s11, s10, 31
	s_lshl_b64 s[12:13], s[10:11], 20
	v_readlane_b32 s14, v254, 17
	v_readlane_b32 s15, v254, 18
	s_add_u32 s12, s14, s12
	s_addc_u32 s13, s15, s13
	s_and_b64 s[14:15], s[4:5], exec
	s_cselect_b32 s11, s13, s23
	s_cselect_b32 s18, s12, s22
	s_ashr_i32 s9, s8, 31
	s_lshl_b64 s[14:15], s[8:9], 20
	v_readlane_b32 s26, v254, 44
	v_readlane_b32 s27, v254, 45
	s_add_u32 s14, s26, s14
	s_addc_u32 s15, s27, s15
	s_and_b64 s[26:27], s[4:5], exec
	s_cselect_b32 s9, s15, s25
	s_cselect_b32 s19, s14, s24
	s_add_u32 s22, s22, 0x80080
	s_addc_u32 s23, s23, 0
	s_add_u32 s21, s24, 0x100
	s_addc_u32 s33, s25, 0
	s_mov_b32 s40, -2
	v_readlane_b32 s41, v255, 49
	s_nop 3
	s_cmp_eq_u32 s41, 2
	v_writelane_b32 v255, 2, 49
	s_cbranch_scc0 .Ltrip0_strict_1
	s_add_u32 s24, s22, 0xfff80080
	s_addc_u32 s25, s23, -1
	s_add_i32 s41, 0, 0x10000
	s_cmp_eq_u32 s40, 28
	s_cselect_b32 s27, s11, s25
	s_cselect_b32 s26, s18, s24
	s_cselect_b32 s25, s9, s33
	s_cselect_b32 s24, s19, s21
	s_add_i32 s46, 0, 0x14000
	v_add_u32_e32 v142, s41, v214
	v_add_u32_e32 v158, s46, v214
	ds_read_b128 v[130:133], v142
	ds_read_b128 v[134:137], v142 offset:1024
	ds_read_b128 v[138:141], v142 offset:2048
	ds_read_b128 v[142:145], v142 offset:3072
	ds_read_b128 v[146:149], v158
	ds_read_b128 v[150:153], v158 offset:1024
	ds_read_b128 v[154:157], v158 offset:2048
	ds_read_b128 v[158:161], v158 offset:3072
	v_lshl_add_u64 v[212:213], s[22:23], 0, v[182:183]
	s_add_i32 m0, s17, 0xc000
	ds_read_b128 v[162:165], v216
	ds_read_b128 v[166:169], v216 offset:1024
	ds_read_b128 v[170:173], v216 offset:2048
	ds_read_b128 v[186:189], v216 offset:3072
	ds_read_b128 v[196:199], v216 offset:4096
	ds_read_b128 v[200:203], v216 offset:5120
	ds_read_b128 v[204:207], v216 offset:6144
	ds_read_b128 v[208:211], v216 offset:7168
	global_load_lds_dwordx4 v[212:213], off
	s_add_i32 m0, s17, 0xe000
	v_lshl_add_u64 v[212:213], s[22:23], 0, v[184:185]
	global_load_lds_dwordx4 v[212:213], off
	s_waitcnt vmcnt(24) lgkmcnt(0)
	s_setprio 1
	s_barrier
	v_mfma_f32_16x16x32_bf16 v[126:129], v[130:133], v[162:165], 0
	v_mfma_f32_16x16x32_bf16 v[122:125], v[138:141], v[162:165], 0
	v_mfma_f32_16x16x32_bf16 v[110:113], v[130:133], v[170:173], 0
	v_mfma_f32_16x16x32_bf16 v[106:109], v[138:141], v[170:173], 0
	v_mfma_f32_16x16x32_bf16 v[94:97], v[130:133], v[196:199], 0
	v_mfma_f32_16x16x32_bf16 v[90:93], v[138:141], v[196:199], 0
	v_mfma_f32_16x16x32_bf16 v[78:81], v[130:133], v[204:207], 0
	v_mfma_f32_16x16x32_bf16 v[74:77], v[138:141], v[204:207], 0
	v_mfma_f32_16x16x32_bf16 v[126:129], v[134:137], v[166:169], v[126:129]
	v_mfma_f32_16x16x32_bf16 v[122:125], v[142:145], v[166:169], v[122:125]
	v_mfma_f32_16x16x32_bf16 v[110:113], v[134:137], v[186:189], v[110:113]
	v_mfma_f32_16x16x32_bf16 v[106:109], v[142:145], v[186:189], v[106:109]
	v_mfma_f32_16x16x32_bf16 v[94:97], v[134:137], v[200:203], v[94:97]
	v_mfma_f32_16x16x32_bf16 v[90:93], v[142:145], v[200:203], v[90:93]
	v_mfma_f32_16x16x32_bf16 v[78:81], v[134:137], v[208:211], v[78:81]
	v_mfma_f32_16x16x32_bf16 v[74:77], v[142:145], v[208:211], v[74:77]
	v_mfma_f32_16x16x32_bf16 v[118:121], v[146:149], v[162:165], 0
	v_mfma_f32_16x16x32_bf16 v[114:117], v[154:157], v[162:165], 0
	v_mfma_f32_16x16x32_bf16 v[102:105], v[146:149], v[170:173], 0
	v_mfma_f32_16x16x32_bf16 v[98:101], v[154:157], v[170:173], 0
	v_mfma_f32_16x16x32_bf16 v[86:89], v[146:149], v[196:199], 0
	v_mfma_f32_16x16x32_bf16 v[82:85], v[154:157], v[196:199], 0
	v_mfma_f32_16x16x32_bf16 v[70:73], v[146:149], v[204:207], 0
	v_mfma_f32_16x16x32_bf16 v[66:69], v[154:157], v[204:207], 0
	v_mfma_f32_16x16x32_bf16 v[118:121], v[150:153], v[166:169], v[118:121]
	v_mfma_f32_16x16x32_bf16 v[114:117], v[158:161], v[166:169], v[114:117]
	v_mfma_f32_16x16x32_bf16 v[102:105], v[150:153], v[186:189], v[102:105]
	v_mfma_f32_16x16x32_bf16 v[98:101], v[158:161], v[186:189], v[98:101]
	v_mfma_f32_16x16x32_bf16 v[86:89], v[150:153], v[200:203], v[86:89]
	v_mfma_f32_16x16x32_bf16 v[82:85], v[158:161], v[200:203], v[82:85]
	v_mfma_f32_16x16x32_bf16 v[70:73], v[150:153], v[208:211], v[70:73]
	v_mfma_f32_16x16x32_bf16 v[66:69], v[158:161], v[208:211], v[66:69]
	s_barrier
	s_setprio 0
	s_add_i32 s41, s41, s29
	v_lshl_add_u64 v[212:213], s[24:25], 0, v[178:179]
	s_mov_b32 m0, s41
	ds_read_b128 v[162:165], v216 offset:16384
	ds_read_b128 v[166:169], v216 offset:17408
	ds_read_b128 v[170:173], v216 offset:18432
	ds_read_b128 v[186:189], v216 offset:19456
	ds_read_b128 v[196:199], v216 offset:20480
	ds_read_b128 v[200:203], v216 offset:21504
	ds_read_b128 v[204:207], v216 offset:22528
	ds_read_b128 v[208:211], v216 offset:23552
	global_load_lds_dwordx4 v[212:213], off
	s_add_i32 m0, s41, 0x2000
	s_add_u32 s42, s24, 0x80000
	v_lshl_add_u64 v[218:219], s[24:25], 0, v[174:175]
	s_addc_u32 s43, s25, 0
	s_add_i32 s41, s46, s29
	global_load_lds_dwordx4 v[218:219], off
	v_lshl_add_u64 v[220:221], s[42:43], 0, v[178:179]
	s_mov_b32 m0, s41
	v_lshl_add_u64 v[222:223], s[26:27], 0, v[176:177]
	global_load_lds_dwordx4 v[220:221], off
	s_add_i32 m0, s41, 0x2000
	v_lshl_add_u64 v[220:221], s[42:43], 0, v[174:175]
	global_load_lds_dwordx4 v[220:221], off
	s_mov_b32 m0, s17
	v_lshl_add_u64 v[220:221], s[26:27], 0, v[180:181]
	global_load_lds_dwordx4 v[220:221], off
	s_mov_b32 m0, s31
	s_nop 0
	global_load_lds_dwordx4 v[222:223], off
	s_waitcnt vmcnt(24) lgkmcnt(0)
	s_setprio 1
	s_barrier
	v_mfma_f32_16x16x32_bf16 v[62:65], v[130:133], v[162:165], 0
	v_mfma_f32_16x16x32_bf16 v[58:61], v[138:141], v[162:165], 0
	v_mfma_f32_16x16x32_bf16 v[46:49], v[130:133], v[170:173], 0
	v_mfma_f32_16x16x32_bf16 v[42:45], v[138:141], v[170:173], 0
	v_mfma_f32_16x16x32_bf16 v[30:33], v[130:133], v[196:199], 0
	v_mfma_f32_16x16x32_bf16 v[26:29], v[138:141], v[196:199], 0
	v_mfma_f32_16x16x32_bf16 v[14:17], v[130:133], v[204:207], 0
	v_mfma_f32_16x16x32_bf16 v[10:13], v[138:141], v[204:207], 0
	v_mfma_f32_16x16x32_bf16 v[62:65], v[134:137], v[166:169], v[62:65]
	v_mfma_f32_16x16x32_bf16 v[58:61], v[142:145], v[166:169], v[58:61]
	v_mfma_f32_16x16x32_bf16 v[46:49], v[134:137], v[186:189], v[46:49]
	v_mfma_f32_16x16x32_bf16 v[42:45], v[142:145], v[186:189], v[42:45]
	v_mfma_f32_16x16x32_bf16 v[30:33], v[134:137], v[200:203], v[30:33]
	v_mfma_f32_16x16x32_bf16 v[26:29], v[142:145], v[200:203], v[26:29]
	v_mfma_f32_16x16x32_bf16 v[14:17], v[134:137], v[208:211], v[14:17]
	v_mfma_f32_16x16x32_bf16 v[10:13], v[142:145], v[208:211], v[10:13]
	v_mfma_f32_16x16x32_bf16 v[54:57], v[146:149], v[162:165], 0
	v_mfma_f32_16x16x32_bf16 v[50:53], v[154:157], v[162:165], 0
	v_mfma_f32_16x16x32_bf16 v[38:41], v[146:149], v[170:173], 0
	v_mfma_f32_16x16x32_bf16 v[34:37], v[154:157], v[170:173], 0
	v_mfma_f32_16x16x32_bf16 v[22:25], v[146:149], v[196:199], 0
	v_mfma_f32_16x16x32_bf16 v[18:21], v[154:157], v[196:199], 0
	v_mfma_f32_16x16x32_bf16 v[6:9], v[146:149], v[204:207], 0
	v_mfma_f32_16x16x32_bf16 v[2:5], v[154:157], v[204:207], 0
	v_mfma_f32_16x16x32_bf16 v[54:57], v[150:153], v[166:169], v[54:57]
	v_mfma_f32_16x16x32_bf16 v[50:53], v[158:161], v[166:169], v[50:53]
	v_mfma_f32_16x16x32_bf16 v[38:41], v[150:153], v[186:189], v[38:41]
	v_mfma_f32_16x16x32_bf16 v[34:37], v[158:161], v[186:189], v[34:37]
	v_mfma_f32_16x16x32_bf16 v[22:25], v[150:153], v[200:203], v[22:25]
	v_mfma_f32_16x16x32_bf16 v[18:21], v[158:161], v[200:203], v[18:21]
	v_mfma_f32_16x16x32_bf16 v[6:9], v[150:153], v[208:211], v[6:9]
	v_mfma_f32_16x16x32_bf16 v[2:5], v[158:161], v[208:211], v[2:5]
	s_barrier
	s_setprio 0
	s_add_i32 s41, 0, 0x18000
	s_add_i32 s42, 0, 0x1c000
	v_add_u32_e32 v142, s41, v214
	v_add_u32_e32 v158, s42, v214
	ds_read_b128 v[130:133], v142
	ds_read_b128 v[134:137], v142 offset:1024
	ds_read_b128 v[138:141], v142 offset:2048
	ds_read_b128 v[142:145], v142 offset:3072
	ds_read_b128 v[146:149], v158
	ds_read_b128 v[150:153], v158 offset:1024
	ds_read_b128 v[154:157], v158 offset:2048
	ds_read_b128 v[158:161], v158 offset:3072
	s_add_u32 s26, s26, 0x80000
	s_addc_u32 s27, s27, 0
	s_mov_b32 m0, s34
	v_lshl_add_u64 v[224:225], s[26:27], 0, v[180:181]
	ds_read_b128 v[162:165], v216 offset:32768
	ds_read_b128 v[166:169], v216 offset:33792
	ds_read_b128 v[170:173], v216 offset:34816
	ds_read_b128 v[186:189], v216 offset:35840
	ds_read_b128 v[196:199], v216 offset:36864
	ds_read_b128 v[200:203], v216 offset:37888
	ds_read_b128 v[204:207], v216 offset:38912
	ds_read_b128 v[208:211], v216 offset:39936
	global_load_lds_dwordx4 v[224:225], off
	s_mov_b32 m0, s35
	v_lshl_add_u64 v[224:225], s[26:27], 0, v[176:177]
	global_load_lds_dwordx4 v[224:225], off
	s_waitcnt vmcnt(8) lgkmcnt(0)
	s_setprio 1
	s_barrier
	v_mfma_f32_16x16x32_bf16 v[126:129], v[130:133], v[162:165], v[126:129]
	v_mfma_f32_16x16x32_bf16 v[122:125], v[138:141], v[162:165], v[122:125]
	v_mfma_f32_16x16x32_bf16 v[110:113], v[130:133], v[170:173], v[110:113]
	v_mfma_f32_16x16x32_bf16 v[106:109], v[138:141], v[170:173], v[106:109]
	v_mfma_f32_16x16x32_bf16 v[94:97], v[130:133], v[196:199], v[94:97]
	v_mfma_f32_16x16x32_bf16 v[90:93], v[138:141], v[196:199], v[90:93]
	v_mfma_f32_16x16x32_bf16 v[78:81], v[130:133], v[204:207], v[78:81]
	v_mfma_f32_16x16x32_bf16 v[74:77], v[138:141], v[204:207], v[74:77]
	v_mfma_f32_16x16x32_bf16 v[126:129], v[134:137], v[166:169], v[126:129]
	v_mfma_f32_16x16x32_bf16 v[122:125], v[142:145], v[166:169], v[122:125]
	v_mfma_f32_16x16x32_bf16 v[110:113], v[134:137], v[186:189], v[110:113]
	v_mfma_f32_16x16x32_bf16 v[106:109], v[142:145], v[186:189], v[106:109]
	v_mfma_f32_16x16x32_bf16 v[94:97], v[134:137], v[200:203], v[94:97]
	v_mfma_f32_16x16x32_bf16 v[90:93], v[142:145], v[200:203], v[90:93]
	v_mfma_f32_16x16x32_bf16 v[78:81], v[134:137], v[208:211], v[78:81]
	v_mfma_f32_16x16x32_bf16 v[74:77], v[142:145], v[208:211], v[74:77]
	v_mfma_f32_16x16x32_bf16 v[118:121], v[146:149], v[162:165], v[118:121]
	v_mfma_f32_16x16x32_bf16 v[114:117], v[154:157], v[162:165], v[114:117]
	v_mfma_f32_16x16x32_bf16 v[102:105], v[146:149], v[170:173], v[102:105]
	v_mfma_f32_16x16x32_bf16 v[98:101], v[154:157], v[170:173], v[98:101]
	v_mfma_f32_16x16x32_bf16 v[86:89], v[146:149], v[196:199], v[86:89]
	v_mfma_f32_16x16x32_bf16 v[82:85], v[154:157], v[196:199], v[82:85]
	v_mfma_f32_16x16x32_bf16 v[70:73], v[146:149], v[204:207], v[70:73]
	v_mfma_f32_16x16x32_bf16 v[66:69], v[154:157], v[204:207], v[66:69]
	v_mfma_f32_16x16x32_bf16 v[118:121], v[150:153], v[166:169], v[118:121]
	v_mfma_f32_16x16x32_bf16 v[114:117], v[158:161], v[166:169], v[114:117]
	v_mfma_f32_16x16x32_bf16 v[102:105], v[150:153], v[186:189], v[102:105]
	v_mfma_f32_16x16x32_bf16 v[98:101], v[158:161], v[186:189], v[98:101]
	v_mfma_f32_16x16x32_bf16 v[86:89], v[150:153], v[200:203], v[86:89]
	v_mfma_f32_16x16x32_bf16 v[82:85], v[158:161], v[200:203], v[82:85]
	v_mfma_f32_16x16x32_bf16 v[70:73], v[150:153], v[208:211], v[70:73]
	v_mfma_f32_16x16x32_bf16 v[66:69], v[158:161], v[208:211], v[66:69]
	s_barrier
	s_setprio 0
	s_add_i32 s26, s41, s29
	v_lshl_add_u64 v[212:213], v[212:213], 0, s[58:59]
	s_mov_b32 m0, s26
	ds_read_b128 v[162:165], v216 offset:49152
	ds_read_b128 v[166:169], v216 offset:50176
	ds_read_b128 v[170:173], v216 offset:51200
	ds_read_b128 v[186:189], v216 offset:52224
	ds_read_b128 v[196:199], v216 offset:53248
	ds_read_b128 v[200:203], v216 offset:54272
	ds_read_b128 v[204:207], v216 offset:55296
	ds_read_b128 v[208:211], v216 offset:56320
	global_load_lds_dwordx4 v[212:213], off
	s_add_i32 m0, s26, 0x2000
	s_add_u32 s24, s24, 0x80080
	v_lshl_add_u64 v[212:213], v[218:219], 0, s[58:59]
	s_addc_u32 s25, s25, 0
	s_add_i32 s26, s42, s29
	global_load_lds_dwordx4 v[212:213], off
	s_mov_b32 m0, s26
	v_lshl_add_u64 v[212:213], s[24:25], 0, v[178:179]
	global_load_lds_dwordx4 v[212:213], off
	s_add_i32 m0, s26, 0x2000
	v_lshl_add_u64 v[212:213], s[24:25], 0, v[174:175]
	global_load_lds_dwordx4 v[212:213], off
	s_mov_b32 m0, s38
	v_lshl_add_u64 v[212:213], v[220:221], 0, s[58:59]
	global_load_lds_dwordx4 v[212:213], off
	s_mov_b32 m0, s39
	v_lshl_add_u64 v[212:213], v[222:223], 0, s[58:59]
	global_load_lds_dwordx4 v[212:213], off
	s_waitcnt vmcnt(8) lgkmcnt(0)
	s_setprio 1
	s_barrier
	v_mfma_f32_16x16x32_bf16 v[62:65], v[130:133], v[162:165], v[62:65]
	v_mfma_f32_16x16x32_bf16 v[58:61], v[138:141], v[162:165], v[58:61]
	v_mfma_f32_16x16x32_bf16 v[46:49], v[130:133], v[170:173], v[46:49]
	v_mfma_f32_16x16x32_bf16 v[42:45], v[138:141], v[170:173], v[42:45]
	v_mfma_f32_16x16x32_bf16 v[30:33], v[130:133], v[196:199], v[30:33]
	v_mfma_f32_16x16x32_bf16 v[26:29], v[138:141], v[196:199], v[26:29]
	v_mfma_f32_16x16x32_bf16 v[14:17], v[130:133], v[204:207], v[14:17]
	v_mfma_f32_16x16x32_bf16 v[10:13], v[138:141], v[204:207], v[10:13]
	v_mfma_f32_16x16x32_bf16 v[62:65], v[134:137], v[166:169], v[62:65]
	v_mfma_f32_16x16x32_bf16 v[58:61], v[142:145], v[166:169], v[58:61]
	v_mfma_f32_16x16x32_bf16 v[46:49], v[134:137], v[186:189], v[46:49]
	v_mfma_f32_16x16x32_bf16 v[42:45], v[142:145], v[186:189], v[42:45]
	v_mfma_f32_16x16x32_bf16 v[30:33], v[134:137], v[200:203], v[30:33]
	v_mfma_f32_16x16x32_bf16 v[26:29], v[142:145], v[200:203], v[26:29]
	v_mfma_f32_16x16x32_bf16 v[14:17], v[134:137], v[208:211], v[14:17]
	v_mfma_f32_16x16x32_bf16 v[10:13], v[142:145], v[208:211], v[10:13]
	v_mfma_f32_16x16x32_bf16 v[54:57], v[146:149], v[162:165], v[54:57]
	v_mfma_f32_16x16x32_bf16 v[50:53], v[154:157], v[162:165], v[50:53]
	v_mfma_f32_16x16x32_bf16 v[38:41], v[146:149], v[170:173], v[38:41]
	v_mfma_f32_16x16x32_bf16 v[34:37], v[154:157], v[170:173], v[34:37]
	v_mfma_f32_16x16x32_bf16 v[22:25], v[146:149], v[196:199], v[22:25]
	v_mfma_f32_16x16x32_bf16 v[18:21], v[154:157], v[196:199], v[18:21]
	v_mfma_f32_16x16x32_bf16 v[6:9], v[146:149], v[204:207], v[6:9]
	v_mfma_f32_16x16x32_bf16 v[2:5], v[154:157], v[204:207], v[2:5]
	v_mfma_f32_16x16x32_bf16 v[54:57], v[150:153], v[166:169], v[54:57]
	v_mfma_f32_16x16x32_bf16 v[50:53], v[158:161], v[166:169], v[50:53]
	v_mfma_f32_16x16x32_bf16 v[38:41], v[150:153], v[186:189], v[38:41]
	v_mfma_f32_16x16x32_bf16 v[34:37], v[158:161], v[186:189], v[34:37]
	v_mfma_f32_16x16x32_bf16 v[22:25], v[150:153], v[200:203], v[22:25]
	v_mfma_f32_16x16x32_bf16 v[18:21], v[158:161], v[200:203], v[18:21]
	v_mfma_f32_16x16x32_bf16 v[6:9], v[150:153], v[208:211], v[6:9]
	v_mfma_f32_16x16x32_bf16 v[2:5], v[158:161], v[208:211], v[2:5]
	s_barrier
	s_setprio 0
	s_add_i32 s40, s40, 2
	s_add_u32 s22, s22, 0x100
	s_addc_u32 s23, s23, 0
	s_add_u32 s21, s21, 0x100
	s_addc_u32 s33, s33, 0
	s_cmp_gt_u32 s40, 29
	s_cbranch_scc1 .Lpeel_done_1
	s_branch .LBB0_672
.Ltrip0_strict_1:
	s_add_u32 s24, s22, 0xfff80080
	s_addc_u32 s25, s23, -1
	s_add_i32 s41, 0, 0x10000
	s_cmp_eq_u32 s40, 28
	s_cselect_b32 s27, s11, s25
	s_cselect_b32 s26, s18, s24
	s_cselect_b32 s25, s9, s33
	s_cselect_b32 s24, s19, s21
	s_add_i32 s46, 0, 0x14000
	v_add_u32_e32 v142, s41, v214
	v_add_u32_e32 v158, s46, v214
	ds_read_b128 v[130:133], v142
	ds_read_b128 v[134:137], v142 offset:1024
	ds_read_b128 v[138:141], v142 offset:2048
	ds_read_b128 v[142:145], v142 offset:3072
	ds_read_b128 v[146:149], v158
	ds_read_b128 v[150:153], v158 offset:1024
	ds_read_b128 v[154:157], v158 offset:2048
	ds_read_b128 v[158:161], v158 offset:3072
	v_lshl_add_u64 v[212:213], s[22:23], 0, v[182:183]
	s_add_i32 m0, s17, 0xc000
	ds_read_b128 v[162:165], v216
	ds_read_b128 v[166:169], v216 offset:1024
	ds_read_b128 v[170:173], v216 offset:2048
	ds_read_b128 v[186:189], v216 offset:3072
	ds_read_b128 v[196:199], v216 offset:4096
	ds_read_b128 v[200:203], v216 offset:5120
	ds_read_b128 v[204:207], v216 offset:6144
	ds_read_b128 v[208:211], v216 offset:7168
	global_load_lds_dwordx4 v[212:213], off
	s_add_i32 m0, s17, 0xe000
	v_lshl_add_u64 v[212:213], s[22:23], 0, v[184:185]
	global_load_lds_dwordx4 v[212:213], off
	s_waitcnt vmcnt(8) lgkmcnt(0)
	s_setprio 1
	s_barrier
	v_mfma_f32_16x16x32_bf16 v[126:129], v[130:133], v[162:165], 0
	v_mfma_f32_16x16x32_bf16 v[122:125], v[138:141], v[162:165], 0
	v_mfma_f32_16x16x32_bf16 v[110:113], v[130:133], v[170:173], 0
	v_mfma_f32_16x16x32_bf16 v[106:109], v[138:141], v[170:173], 0
	v_mfma_f32_16x16x32_bf16 v[94:97], v[130:133], v[196:199], 0
	v_mfma_f32_16x16x32_bf16 v[90:93], v[138:141], v[196:199], 0
	v_mfma_f32_16x16x32_bf16 v[78:81], v[130:133], v[204:207], 0
	v_mfma_f32_16x16x32_bf16 v[74:77], v[138:141], v[204:207], 0
	v_mfma_f32_16x16x32_bf16 v[126:129], v[134:137], v[166:169], v[126:129]
	v_mfma_f32_16x16x32_bf16 v[122:125], v[142:145], v[166:169], v[122:125]
	v_mfma_f32_16x16x32_bf16 v[110:113], v[134:137], v[186:189], v[110:113]
	v_mfma_f32_16x16x32_bf16 v[106:109], v[142:145], v[186:189], v[106:109]
	v_mfma_f32_16x16x32_bf16 v[94:97], v[134:137], v[200:203], v[94:97]
	v_mfma_f32_16x16x32_bf16 v[90:93], v[142:145], v[200:203], v[90:93]
	v_mfma_f32_16x16x32_bf16 v[78:81], v[134:137], v[208:211], v[78:81]
	v_mfma_f32_16x16x32_bf16 v[74:77], v[142:145], v[208:211], v[74:77]
	v_mfma_f32_16x16x32_bf16 v[118:121], v[146:149], v[162:165], 0
	v_mfma_f32_16x16x32_bf16 v[114:117], v[154:157], v[162:165], 0
	v_mfma_f32_16x16x32_bf16 v[102:105], v[146:149], v[170:173], 0
	v_mfma_f32_16x16x32_bf16 v[98:101], v[154:157], v[170:173], 0
	v_mfma_f32_16x16x32_bf16 v[86:89], v[146:149], v[196:199], 0
	v_mfma_f32_16x16x32_bf16 v[82:85], v[154:157], v[196:199], 0
	v_mfma_f32_16x16x32_bf16 v[70:73], v[146:149], v[204:207], 0
	v_mfma_f32_16x16x32_bf16 v[66:69], v[154:157], v[204:207], 0
	v_mfma_f32_16x16x32_bf16 v[118:121], v[150:153], v[166:169], v[118:121]
	v_mfma_f32_16x16x32_bf16 v[114:117], v[158:161], v[166:169], v[114:117]
	v_mfma_f32_16x16x32_bf16 v[102:105], v[150:153], v[186:189], v[102:105]
	v_mfma_f32_16x16x32_bf16 v[98:101], v[158:161], v[186:189], v[98:101]
	v_mfma_f32_16x16x32_bf16 v[86:89], v[150:153], v[200:203], v[86:89]
	v_mfma_f32_16x16x32_bf16 v[82:85], v[158:161], v[200:203], v[82:85]
	v_mfma_f32_16x16x32_bf16 v[70:73], v[150:153], v[208:211], v[70:73]
	v_mfma_f32_16x16x32_bf16 v[66:69], v[158:161], v[208:211], v[66:69]
	s_barrier
	s_setprio 0
	s_add_i32 s41, s41, s29
	v_lshl_add_u64 v[212:213], s[24:25], 0, v[178:179]
	s_mov_b32 m0, s41
	ds_read_b128 v[162:165], v216 offset:16384
	ds_read_b128 v[166:169], v216 offset:17408
	ds_read_b128 v[170:173], v216 offset:18432
	ds_read_b128 v[186:189], v216 offset:19456
	ds_read_b128 v[196:199], v216 offset:20480
	ds_read_b128 v[200:203], v216 offset:21504
	ds_read_b128 v[204:207], v216 offset:22528
	ds_read_b128 v[208:211], v216 offset:23552
	global_load_lds_dwordx4 v[212:213], off
	s_add_i32 m0, s41, 0x2000
	s_add_u32 s42, s24, 0x80000
	v_lshl_add_u64 v[218:219], s[24:25], 0, v[174:175]
	s_addc_u32 s43, s25, 0
	s_add_i32 s41, s46, s29
	global_load_lds_dwordx4 v[218:219], off
	v_lshl_add_u64 v[220:221], s[42:43], 0, v[178:179]
	s_mov_b32 m0, s41
	v_lshl_add_u64 v[222:223], s[26:27], 0, v[176:177]
	global_load_lds_dwordx4 v[220:221], off
	s_add_i32 m0, s41, 0x2000
	v_lshl_add_u64 v[220:221], s[42:43], 0, v[174:175]
	global_load_lds_dwordx4 v[220:221], off
	s_mov_b32 m0, s17
	v_lshl_add_u64 v[220:221], s[26:27], 0, v[180:181]
	global_load_lds_dwordx4 v[220:221], off
	s_mov_b32 m0, s31
	s_nop 0
	global_load_lds_dwordx4 v[222:223], off
	s_waitcnt vmcnt(8) lgkmcnt(0)
	s_setprio 1
	s_barrier
	v_mfma_f32_16x16x32_bf16 v[62:65], v[130:133], v[162:165], 0
	v_mfma_f32_16x16x32_bf16 v[58:61], v[138:141], v[162:165], 0
	v_mfma_f32_16x16x32_bf16 v[46:49], v[130:133], v[170:173], 0
	v_mfma_f32_16x16x32_bf16 v[42:45], v[138:141], v[170:173], 0
	v_mfma_f32_16x16x32_bf16 v[30:33], v[130:133], v[196:199], 0
	v_mfma_f32_16x16x32_bf16 v[26:29], v[138:141], v[196:199], 0
	v_mfma_f32_16x16x32_bf16 v[14:17], v[130:133], v[204:207], 0
	v_mfma_f32_16x16x32_bf16 v[10:13], v[138:141], v[204:207], 0
	v_mfma_f32_16x16x32_bf16 v[62:65], v[134:137], v[166:169], v[62:65]
	v_mfma_f32_16x16x32_bf16 v[58:61], v[142:145], v[166:169], v[58:61]
	v_mfma_f32_16x16x32_bf16 v[46:49], v[134:137], v[186:189], v[46:49]
	v_mfma_f32_16x16x32_bf16 v[42:45], v[142:145], v[186:189], v[42:45]
	v_mfma_f32_16x16x32_bf16 v[30:33], v[134:137], v[200:203], v[30:33]
	v_mfma_f32_16x16x32_bf16 v[26:29], v[142:145], v[200:203], v[26:29]
	v_mfma_f32_16x16x32_bf16 v[14:17], v[134:137], v[208:211], v[14:17]
	v_mfma_f32_16x16x32_bf16 v[10:13], v[142:145], v[208:211], v[10:13]
	v_mfma_f32_16x16x32_bf16 v[54:57], v[146:149], v[162:165], 0
	v_mfma_f32_16x16x32_bf16 v[50:53], v[154:157], v[162:165], 0
	v_mfma_f32_16x16x32_bf16 v[38:41], v[146:149], v[170:173], 0
	v_mfma_f32_16x16x32_bf16 v[34:37], v[154:157], v[170:173], 0
	v_mfma_f32_16x16x32_bf16 v[22:25], v[146:149], v[196:199], 0
	v_mfma_f32_16x16x32_bf16 v[18:21], v[154:157], v[196:199], 0
	v_mfma_f32_16x16x32_bf16 v[6:9], v[146:149], v[204:207], 0
	v_mfma_f32_16x16x32_bf16 v[2:5], v[154:157], v[204:207], 0
	v_mfma_f32_16x16x32_bf16 v[54:57], v[150:153], v[166:169], v[54:57]
	v_mfma_f32_16x16x32_bf16 v[50:53], v[158:161], v[166:169], v[50:53]
	v_mfma_f32_16x16x32_bf16 v[38:41], v[150:153], v[186:189], v[38:41]
	v_mfma_f32_16x16x32_bf16 v[34:37], v[158:161], v[186:189], v[34:37]
	v_mfma_f32_16x16x32_bf16 v[22:25], v[150:153], v[200:203], v[22:25]
	v_mfma_f32_16x16x32_bf16 v[18:21], v[158:161], v[200:203], v[18:21]
	v_mfma_f32_16x16x32_bf16 v[6:9], v[150:153], v[208:211], v[6:9]
	v_mfma_f32_16x16x32_bf16 v[2:5], v[158:161], v[208:211], v[2:5]
	s_barrier
	s_setprio 0
	s_add_i32 s41, 0, 0x18000
	s_add_i32 s42, 0, 0x1c000
	v_add_u32_e32 v142, s41, v214
	v_add_u32_e32 v158, s42, v214
	ds_read_b128 v[130:133], v142
	ds_read_b128 v[134:137], v142 offset:1024
	ds_read_b128 v[138:141], v142 offset:2048
	ds_read_b128 v[142:145], v142 offset:3072
	ds_read_b128 v[146:149], v158
	ds_read_b128 v[150:153], v158 offset:1024
	ds_read_b128 v[154:157], v158 offset:2048
	ds_read_b128 v[158:161], v158 offset:3072
	s_add_u32 s26, s26, 0x80000
	s_addc_u32 s27, s27, 0
	s_mov_b32 m0, s34
	v_lshl_add_u64 v[224:225], s[26:27], 0, v[180:181]
	ds_read_b128 v[162:165], v216 offset:32768
	ds_read_b128 v[166:169], v216 offset:33792
	ds_read_b128 v[170:173], v216 offset:34816
	ds_read_b128 v[186:189], v216 offset:35840
	ds_read_b128 v[196:199], v216 offset:36864
	ds_read_b128 v[200:203], v216 offset:37888
	ds_read_b128 v[204:207], v216 offset:38912
	ds_read_b128 v[208:211], v216 offset:39936
	global_load_lds_dwordx4 v[224:225], off
	s_mov_b32 m0, s35
	v_lshl_add_u64 v[224:225], s[26:27], 0, v[176:177]
	global_load_lds_dwordx4 v[224:225], off
	s_waitcnt vmcnt(8) lgkmcnt(0)
	s_setprio 1
	s_barrier
	v_mfma_f32_16x16x32_bf16 v[126:129], v[130:133], v[162:165], v[126:129]
	v_mfma_f32_16x16x32_bf16 v[122:125], v[138:141], v[162:165], v[122:125]
	v_mfma_f32_16x16x32_bf16 v[110:113], v[130:133], v[170:173], v[110:113]
	v_mfma_f32_16x16x32_bf16 v[106:109], v[138:141], v[170:173], v[106:109]
	v_mfma_f32_16x16x32_bf16 v[94:97], v[130:133], v[196:199], v[94:97]
	v_mfma_f32_16x16x32_bf16 v[90:93], v[138:141], v[196:199], v[90:93]
	v_mfma_f32_16x16x32_bf16 v[78:81], v[130:133], v[204:207], v[78:81]
	v_mfma_f32_16x16x32_bf16 v[74:77], v[138:141], v[204:207], v[74:77]
	v_mfma_f32_16x16x32_bf16 v[126:129], v[134:137], v[166:169], v[126:129]
	v_mfma_f32_16x16x32_bf16 v[122:125], v[142:145], v[166:169], v[122:125]
	v_mfma_f32_16x16x32_bf16 v[110:113], v[134:137], v[186:189], v[110:113]
	v_mfma_f32_16x16x32_bf16 v[106:109], v[142:145], v[186:189], v[106:109]
	v_mfma_f32_16x16x32_bf16 v[94:97], v[134:137], v[200:203], v[94:97]
	v_mfma_f32_16x16x32_bf16 v[90:93], v[142:145], v[200:203], v[90:93]
	v_mfma_f32_16x16x32_bf16 v[78:81], v[134:137], v[208:211], v[78:81]
	v_mfma_f32_16x16x32_bf16 v[74:77], v[142:145], v[208:211], v[74:77]
	v_mfma_f32_16x16x32_bf16 v[118:121], v[146:149], v[162:165], v[118:121]
	v_mfma_f32_16x16x32_bf16 v[114:117], v[154:157], v[162:165], v[114:117]
	v_mfma_f32_16x16x32_bf16 v[102:105], v[146:149], v[170:173], v[102:105]
	v_mfma_f32_16x16x32_bf16 v[98:101], v[154:157], v[170:173], v[98:101]
	v_mfma_f32_16x16x32_bf16 v[86:89], v[146:149], v[196:199], v[86:89]
	v_mfma_f32_16x16x32_bf16 v[82:85], v[154:157], v[196:199], v[82:85]
	v_mfma_f32_16x16x32_bf16 v[70:73], v[146:149], v[204:207], v[70:73]
	v_mfma_f32_16x16x32_bf16 v[66:69], v[154:157], v[204:207], v[66:69]
	v_mfma_f32_16x16x32_bf16 v[118:121], v[150:153], v[166:169], v[118:121]
	v_mfma_f32_16x16x32_bf16 v[114:117], v[158:161], v[166:169], v[114:117]
	v_mfma_f32_16x16x32_bf16 v[102:105], v[150:153], v[186:189], v[102:105]
	v_mfma_f32_16x16x32_bf16 v[98:101], v[158:161], v[186:189], v[98:101]
	v_mfma_f32_16x16x32_bf16 v[86:89], v[150:153], v[200:203], v[86:89]
	v_mfma_f32_16x16x32_bf16 v[82:85], v[158:161], v[200:203], v[82:85]
	v_mfma_f32_16x16x32_bf16 v[70:73], v[150:153], v[208:211], v[70:73]
	v_mfma_f32_16x16x32_bf16 v[66:69], v[158:161], v[208:211], v[66:69]
	s_barrier
	s_setprio 0
	s_add_i32 s26, s41, s29
	v_lshl_add_u64 v[212:213], v[212:213], 0, s[58:59]
	s_mov_b32 m0, s26
	ds_read_b128 v[162:165], v216 offset:49152
	ds_read_b128 v[166:169], v216 offset:50176
	ds_read_b128 v[170:173], v216 offset:51200
	ds_read_b128 v[186:189], v216 offset:52224
	ds_read_b128 v[196:199], v216 offset:53248
	ds_read_b128 v[200:203], v216 offset:54272
	ds_read_b128 v[204:207], v216 offset:55296
	ds_read_b128 v[208:211], v216 offset:56320
	global_load_lds_dwordx4 v[212:213], off
	s_add_i32 m0, s26, 0x2000
	s_add_u32 s24, s24, 0x80080
	v_lshl_add_u64 v[212:213], v[218:219], 0, s[58:59]
	s_addc_u32 s25, s25, 0
	s_add_i32 s26, s42, s29
	global_load_lds_dwordx4 v[212:213], off
	s_mov_b32 m0, s26
	v_lshl_add_u64 v[212:213], s[24:25], 0, v[178:179]
	global_load_lds_dwordx4 v[212:213], off
	s_add_i32 m0, s26, 0x2000
	v_lshl_add_u64 v[212:213], s[24:25], 0, v[174:175]
	global_load_lds_dwordx4 v[212:213], off
	s_mov_b32 m0, s38
	v_lshl_add_u64 v[212:213], v[220:221], 0, s[58:59]
	global_load_lds_dwordx4 v[212:213], off
	s_mov_b32 m0, s39
	v_lshl_add_u64 v[212:213], v[222:223], 0, s[58:59]
	global_load_lds_dwordx4 v[212:213], off
	s_waitcnt vmcnt(8) lgkmcnt(0)
	s_setprio 1
	s_barrier
	v_mfma_f32_16x16x32_bf16 v[62:65], v[130:133], v[162:165], v[62:65]
	v_mfma_f32_16x16x32_bf16 v[58:61], v[138:141], v[162:165], v[58:61]
	v_mfma_f32_16x16x32_bf16 v[46:49], v[130:133], v[170:173], v[46:49]
	v_mfma_f32_16x16x32_bf16 v[42:45], v[138:141], v[170:173], v[42:45]
	v_mfma_f32_16x16x32_bf16 v[30:33], v[130:133], v[196:199], v[30:33]
	v_mfma_f32_16x16x32_bf16 v[26:29], v[138:141], v[196:199], v[26:29]
	v_mfma_f32_16x16x32_bf16 v[14:17], v[130:133], v[204:207], v[14:17]
	v_mfma_f32_16x16x32_bf16 v[10:13], v[138:141], v[204:207], v[10:13]
	v_mfma_f32_16x16x32_bf16 v[62:65], v[134:137], v[166:169], v[62:65]
	v_mfma_f32_16x16x32_bf16 v[58:61], v[142:145], v[166:169], v[58:61]
	v_mfma_f32_16x16x32_bf16 v[46:49], v[134:137], v[186:189], v[46:49]
	v_mfma_f32_16x16x32_bf16 v[42:45], v[142:145], v[186:189], v[42:45]
	v_mfma_f32_16x16x32_bf16 v[30:33], v[134:137], v[200:203], v[30:33]
	v_mfma_f32_16x16x32_bf16 v[26:29], v[142:145], v[200:203], v[26:29]
	v_mfma_f32_16x16x32_bf16 v[14:17], v[134:137], v[208:211], v[14:17]
	v_mfma_f32_16x16x32_bf16 v[10:13], v[142:145], v[208:211], v[10:13]
	v_mfma_f32_16x16x32_bf16 v[54:57], v[146:149], v[162:165], v[54:57]
	v_mfma_f32_16x16x32_bf16 v[50:53], v[154:157], v[162:165], v[50:53]
	v_mfma_f32_16x16x32_bf16 v[38:41], v[146:149], v[170:173], v[38:41]
	v_mfma_f32_16x16x32_bf16 v[34:37], v[154:157], v[170:173], v[34:37]
	v_mfma_f32_16x16x32_bf16 v[22:25], v[146:149], v[196:199], v[22:25]
	v_mfma_f32_16x16x32_bf16 v[18:21], v[154:157], v[196:199], v[18:21]
	v_mfma_f32_16x16x32_bf16 v[6:9], v[146:149], v[204:207], v[6:9]
	v_mfma_f32_16x16x32_bf16 v[2:5], v[154:157], v[204:207], v[2:5]
	v_mfma_f32_16x16x32_bf16 v[54:57], v[150:153], v[166:169], v[54:57]
	v_mfma_f32_16x16x32_bf16 v[50:53], v[158:161], v[166:169], v[50:53]
	v_mfma_f32_16x16x32_bf16 v[38:41], v[150:153], v[186:189], v[38:41]
	v_mfma_f32_16x16x32_bf16 v[34:37], v[158:161], v[186:189], v[34:37]
	v_mfma_f32_16x16x32_bf16 v[22:25], v[150:153], v[200:203], v[22:25]
	v_mfma_f32_16x16x32_bf16 v[18:21], v[158:161], v[200:203], v[18:21]
	v_mfma_f32_16x16x32_bf16 v[6:9], v[150:153], v[208:211], v[6:9]
	v_mfma_f32_16x16x32_bf16 v[2:5], v[158:161], v[208:211], v[2:5]
	s_barrier
	s_setprio 0
	s_add_i32 s40, s40, 2
	s_add_u32 s22, s22, 0x100
	s_addc_u32 s23, s23, 0
	s_add_u32 s21, s21, 0x100
	s_addc_u32 s33, s33, 0
	s_cmp_gt_u32 s40, 29
	s_cbranch_scc1 .Lpeel_done_1
.LBB0_672:
	s_add_u32 s24, s22, 0xfff80080
	s_addc_u32 s25, s23, -1
	s_add_i32 s41, 0, 0x10000
	s_cmp_eq_u32 s40, 28
	s_cselect_b32 s27, s11, s25
	s_cselect_b32 s26, s18, s24
	s_cselect_b32 s25, s9, s33
	s_cselect_b32 s24, s19, s21
	s_add_i32 s46, 0, 0x14000
	v_add_u32_e32 v142, s41, v214
	v_add_u32_e32 v158, s46, v214
	ds_read_b128 v[130:133], v142
	ds_read_b128 v[134:137], v142 offset:1024
	ds_read_b128 v[138:141], v142 offset:2048
	ds_read_b128 v[142:145], v142 offset:3072
	ds_read_b128 v[146:149], v158
	ds_read_b128 v[150:153], v158 offset:1024
	ds_read_b128 v[154:157], v158 offset:2048
	ds_read_b128 v[158:161], v158 offset:3072
	v_lshl_add_u64 v[212:213], s[22:23], 0, v[182:183]
	s_add_i32 m0, s17, 0xc000
	ds_read_b128 v[162:165], v216
	ds_read_b128 v[166:169], v216 offset:1024
	ds_read_b128 v[170:173], v216 offset:2048
	ds_read_b128 v[186:189], v216 offset:3072
	ds_read_b128 v[196:199], v216 offset:4096
	ds_read_b128 v[200:203], v216 offset:5120
	ds_read_b128 v[204:207], v216 offset:6144
	ds_read_b128 v[208:211], v216 offset:7168
	global_load_lds_dwordx4 v[212:213], off
	s_add_i32 m0, s17, 0xe000
	v_lshl_add_u64 v[212:213], s[22:23], 0, v[184:185]
	global_load_lds_dwordx4 v[212:213], off
	s_waitcnt vmcnt(8) lgkmcnt(0)
	s_setprio 1
	s_barrier
	v_mfma_f32_16x16x32_bf16 v[126:129], v[130:133], v[162:165], v[126:129]
	v_mfma_f32_16x16x32_bf16 v[122:125], v[138:141], v[162:165], v[122:125]
	v_mfma_f32_16x16x32_bf16 v[110:113], v[130:133], v[170:173], v[110:113]
	v_mfma_f32_16x16x32_bf16 v[106:109], v[138:141], v[170:173], v[106:109]
	v_mfma_f32_16x16x32_bf16 v[94:97], v[130:133], v[196:199], v[94:97]
	v_mfma_f32_16x16x32_bf16 v[90:93], v[138:141], v[196:199], v[90:93]
	v_mfma_f32_16x16x32_bf16 v[78:81], v[130:133], v[204:207], v[78:81]
	v_mfma_f32_16x16x32_bf16 v[74:77], v[138:141], v[204:207], v[74:77]
	v_mfma_f32_16x16x32_bf16 v[126:129], v[134:137], v[166:169], v[126:129]
	v_mfma_f32_16x16x32_bf16 v[122:125], v[142:145], v[166:169], v[122:125]
	v_mfma_f32_16x16x32_bf16 v[110:113], v[134:137], v[186:189], v[110:113]
	v_mfma_f32_16x16x32_bf16 v[106:109], v[142:145], v[186:189], v[106:109]
	v_mfma_f32_16x16x32_bf16 v[94:97], v[134:137], v[200:203], v[94:97]
	v_mfma_f32_16x16x32_bf16 v[90:93], v[142:145], v[200:203], v[90:93]
	v_mfma_f32_16x16x32_bf16 v[78:81], v[134:137], v[208:211], v[78:81]
	v_mfma_f32_16x16x32_bf16 v[74:77], v[142:145], v[208:211], v[74:77]
	v_mfma_f32_16x16x32_bf16 v[118:121], v[146:149], v[162:165], v[118:121]
	v_mfma_f32_16x16x32_bf16 v[114:117], v[154:157], v[162:165], v[114:117]
	v_mfma_f32_16x16x32_bf16 v[102:105], v[146:149], v[170:173], v[102:105]
	v_mfma_f32_16x16x32_bf16 v[98:101], v[154:157], v[170:173], v[98:101]
	v_mfma_f32_16x16x32_bf16 v[86:89], v[146:149], v[196:199], v[86:89]
	v_mfma_f32_16x16x32_bf16 v[82:85], v[154:157], v[196:199], v[82:85]
	v_mfma_f32_16x16x32_bf16 v[70:73], v[146:149], v[204:207], v[70:73]
	v_mfma_f32_16x16x32_bf16 v[66:69], v[154:157], v[204:207], v[66:69]
	v_mfma_f32_16x16x32_bf16 v[118:121], v[150:153], v[166:169], v[118:121]
	v_mfma_f32_16x16x32_bf16 v[114:117], v[158:161], v[166:169], v[114:117]
	v_mfma_f32_16x16x32_bf16 v[102:105], v[150:153], v[186:189], v[102:105]
	v_mfma_f32_16x16x32_bf16 v[98:101], v[158:161], v[186:189], v[98:101]
	v_mfma_f32_16x16x32_bf16 v[86:89], v[150:153], v[200:203], v[86:89]
	v_mfma_f32_16x16x32_bf16 v[82:85], v[158:161], v[200:203], v[82:85]
	v_mfma_f32_16x16x32_bf16 v[70:73], v[150:153], v[208:211], v[70:73]
	v_mfma_f32_16x16x32_bf16 v[66:69], v[158:161], v[208:211], v[66:69]
	s_setprio 0
	s_barrier
	s_add_i32 s41, s41, s29
	v_lshl_add_u64 v[212:213], s[24:25], 0, v[178:179]
	s_mov_b32 m0, s41
	ds_read_b128 v[162:165], v216 offset:16384
	ds_read_b128 v[166:169], v216 offset:17408
	ds_read_b128 v[170:173], v216 offset:18432
	ds_read_b128 v[186:189], v216 offset:19456
	ds_read_b128 v[196:199], v216 offset:20480
	ds_read_b128 v[200:203], v216 offset:21504
	ds_read_b128 v[204:207], v216 offset:22528
	ds_read_b128 v[208:211], v216 offset:23552
	global_load_lds_dwordx4 v[212:213], off
	s_add_i32 m0, s41, 0x2000
	s_add_u32 s42, s24, 0x80000
	v_lshl_add_u64 v[218:219], s[24:25], 0, v[174:175]
	s_addc_u32 s43, s25, 0
	s_add_i32 s41, s46, s29
	global_load_lds_dwordx4 v[218:219], off
	v_lshl_add_u64 v[220:221], s[42:43], 0, v[178:179]
	s_mov_b32 m0, s41
	v_lshl_add_u64 v[222:223], s[26:27], 0, v[176:177]
	global_load_lds_dwordx4 v[220:221], off
	s_add_i32 m0, s41, 0x2000
	v_lshl_add_u64 v[220:221], s[42:43], 0, v[174:175]
	global_load_lds_dwordx4 v[220:221], off
	s_mov_b32 m0, s17
	v_lshl_add_u64 v[220:221], s[26:27], 0, v[180:181]
	global_load_lds_dwordx4 v[220:221], off
	s_mov_b32 m0, s31
	s_nop 0
	global_load_lds_dwordx4 v[222:223], off
	s_waitcnt vmcnt(8) lgkmcnt(0)
	s_setprio 1
	s_barrier
	v_mfma_f32_16x16x32_bf16 v[62:65], v[130:133], v[162:165], v[62:65]
	v_mfma_f32_16x16x32_bf16 v[58:61], v[138:141], v[162:165], v[58:61]
	v_mfma_f32_16x16x32_bf16 v[46:49], v[130:133], v[170:173], v[46:49]
	v_mfma_f32_16x16x32_bf16 v[42:45], v[138:141], v[170:173], v[42:45]
	v_mfma_f32_16x16x32_bf16 v[30:33], v[130:133], v[196:199], v[30:33]
	v_mfma_f32_16x16x32_bf16 v[26:29], v[138:141], v[196:199], v[26:29]
	v_mfma_f32_16x16x32_bf16 v[14:17], v[130:133], v[204:207], v[14:17]
	v_mfma_f32_16x16x32_bf16 v[10:13], v[138:141], v[204:207], v[10:13]
	v_mfma_f32_16x16x32_bf16 v[62:65], v[134:137], v[166:169], v[62:65]
	v_mfma_f32_16x16x32_bf16 v[58:61], v[142:145], v[166:169], v[58:61]
	v_mfma_f32_16x16x32_bf16 v[46:49], v[134:137], v[186:189], v[46:49]
	v_mfma_f32_16x16x32_bf16 v[42:45], v[142:145], v[186:189], v[42:45]
	v_mfma_f32_16x16x32_bf16 v[30:33], v[134:137], v[200:203], v[30:33]
	v_mfma_f32_16x16x32_bf16 v[26:29], v[142:145], v[200:203], v[26:29]
	v_mfma_f32_16x16x32_bf16 v[14:17], v[134:137], v[208:211], v[14:17]
	v_mfma_f32_16x16x32_bf16 v[10:13], v[142:145], v[208:211], v[10:13]
	v_mfma_f32_16x16x32_bf16 v[54:57], v[146:149], v[162:165], v[54:57]
	v_mfma_f32_16x16x32_bf16 v[50:53], v[154:157], v[162:165], v[50:53]
	v_mfma_f32_16x16x32_bf16 v[38:41], v[146:149], v[170:173], v[38:41]
	v_mfma_f32_16x16x32_bf16 v[34:37], v[154:157], v[170:173], v[34:37]
	v_mfma_f32_16x16x32_bf16 v[22:25], v[146:149], v[196:199], v[22:25]
	v_mfma_f32_16x16x32_bf16 v[18:21], v[154:157], v[196:199], v[18:21]
	v_mfma_f32_16x16x32_bf16 v[6:9], v[146:149], v[204:207], v[6:9]
	v_mfma_f32_16x16x32_bf16 v[2:5], v[154:157], v[204:207], v[2:5]
	v_mfma_f32_16x16x32_bf16 v[54:57], v[150:153], v[166:169], v[54:57]
	v_mfma_f32_16x16x32_bf16 v[50:53], v[158:161], v[166:169], v[50:53]
	v_mfma_f32_16x16x32_bf16 v[38:41], v[150:153], v[186:189], v[38:41]
	v_mfma_f32_16x16x32_bf16 v[34:37], v[158:161], v[186:189], v[34:37]
	v_mfma_f32_16x16x32_bf16 v[22:25], v[150:153], v[200:203], v[22:25]
	v_mfma_f32_16x16x32_bf16 v[18:21], v[158:161], v[200:203], v[18:21]
	v_mfma_f32_16x16x32_bf16 v[6:9], v[150:153], v[208:211], v[6:9]
	v_mfma_f32_16x16x32_bf16 v[2:5], v[158:161], v[208:211], v[2:5]
	s_setprio 0
	s_barrier
	s_add_i32 s41, 0, 0x18000
	s_add_i32 s42, 0, 0x1c000
	v_add_u32_e32 v142, s41, v214
	v_add_u32_e32 v158, s42, v214
	ds_read_b128 v[130:133], v142
	ds_read_b128 v[134:137], v142 offset:1024
	ds_read_b128 v[138:141], v142 offset:2048
	ds_read_b128 v[142:145], v142 offset:3072
	ds_read_b128 v[146:149], v158
	ds_read_b128 v[150:153], v158 offset:1024
	ds_read_b128 v[154:157], v158 offset:2048
	ds_read_b128 v[158:161], v158 offset:3072
	s_add_u32 s26, s26, 0x80000
	s_addc_u32 s27, s27, 0
	s_mov_b32 m0, s34
	v_lshl_add_u64 v[224:225], s[26:27], 0, v[180:181]
	ds_read_b128 v[162:165], v216 offset:32768
	ds_read_b128 v[166:169], v216 offset:33792
	ds_read_b128 v[170:173], v216 offset:34816
	ds_read_b128 v[186:189], v216 offset:35840
	ds_read_b128 v[196:199], v216 offset:36864
	ds_read_b128 v[200:203], v216 offset:37888
	ds_read_b128 v[204:207], v216 offset:38912
	ds_read_b128 v[208:211], v216 offset:39936
	global_load_lds_dwordx4 v[224:225], off
	s_mov_b32 m0, s35
	v_lshl_add_u64 v[224:225], s[26:27], 0, v[176:177]
	global_load_lds_dwordx4 v[224:225], off
	s_waitcnt vmcnt(8) lgkmcnt(0)
	s_setprio 1
	s_barrier
	v_mfma_f32_16x16x32_bf16 v[126:129], v[130:133], v[162:165], v[126:129]
	v_mfma_f32_16x16x32_bf16 v[122:125], v[138:141], v[162:165], v[122:125]
	v_mfma_f32_16x16x32_bf16 v[110:113], v[130:133], v[170:173], v[110:113]
	v_mfma_f32_16x16x32_bf16 v[106:109], v[138:141], v[170:173], v[106:109]
	v_mfma_f32_16x16x32_bf16 v[94:97], v[130:133], v[196:199], v[94:97]
	v_mfma_f32_16x16x32_bf16 v[90:93], v[138:141], v[196:199], v[90:93]
	v_mfma_f32_16x16x32_bf16 v[78:81], v[130:133], v[204:207], v[78:81]
	v_mfma_f32_16x16x32_bf16 v[74:77], v[138:141], v[204:207], v[74:77]
	v_mfma_f32_16x16x32_bf16 v[126:129], v[134:137], v[166:169], v[126:129]
	v_mfma_f32_16x16x32_bf16 v[122:125], v[142:145], v[166:169], v[122:125]
	v_mfma_f32_16x16x32_bf16 v[110:113], v[134:137], v[186:189], v[110:113]
	v_mfma_f32_16x16x32_bf16 v[106:109], v[142:145], v[186:189], v[106:109]
	v_mfma_f32_16x16x32_bf16 v[94:97], v[134:137], v[200:203], v[94:97]
	v_mfma_f32_16x16x32_bf16 v[90:93], v[142:145], v[200:203], v[90:93]
	v_mfma_f32_16x16x32_bf16 v[78:81], v[134:137], v[208:211], v[78:81]
	v_mfma_f32_16x16x32_bf16 v[74:77], v[142:145], v[208:211], v[74:77]
	v_mfma_f32_16x16x32_bf16 v[118:121], v[146:149], v[162:165], v[118:121]
	v_mfma_f32_16x16x32_bf16 v[114:117], v[154:157], v[162:165], v[114:117]
	v_mfma_f32_16x16x32_bf16 v[102:105], v[146:149], v[170:173], v[102:105]
	v_mfma_f32_16x16x32_bf16 v[98:101], v[154:157], v[170:173], v[98:101]
	v_mfma_f32_16x16x32_bf16 v[86:89], v[146:149], v[196:199], v[86:89]
	v_mfma_f32_16x16x32_bf16 v[82:85], v[154:157], v[196:199], v[82:85]
	v_mfma_f32_16x16x32_bf16 v[70:73], v[146:149], v[204:207], v[70:73]
	v_mfma_f32_16x16x32_bf16 v[66:69], v[154:157], v[204:207], v[66:69]
	v_mfma_f32_16x16x32_bf16 v[118:121], v[150:153], v[166:169], v[118:121]
	v_mfma_f32_16x16x32_bf16 v[114:117], v[158:161], v[166:169], v[114:117]
	v_mfma_f32_16x16x32_bf16 v[102:105], v[150:153], v[186:189], v[102:105]
	v_mfma_f32_16x16x32_bf16 v[98:101], v[158:161], v[186:189], v[98:101]
	v_mfma_f32_16x16x32_bf16 v[86:89], v[150:153], v[200:203], v[86:89]
	v_mfma_f32_16x16x32_bf16 v[82:85], v[158:161], v[200:203], v[82:85]
	v_mfma_f32_16x16x32_bf16 v[70:73], v[150:153], v[208:211], v[70:73]
	v_mfma_f32_16x16x32_bf16 v[66:69], v[158:161], v[208:211], v[66:69]
	s_setprio 0
	s_barrier
	s_add_i32 s26, s41, s29
	v_lshl_add_u64 v[212:213], v[212:213], 0, s[58:59]
	s_mov_b32 m0, s26
	ds_read_b128 v[162:165], v216 offset:49152
	ds_read_b128 v[166:169], v216 offset:50176
	ds_read_b128 v[170:173], v216 offset:51200
	ds_read_b128 v[186:189], v216 offset:52224
	ds_read_b128 v[196:199], v216 offset:53248
	ds_read_b128 v[200:203], v216 offset:54272
	ds_read_b128 v[204:207], v216 offset:55296
	ds_read_b128 v[208:211], v216 offset:56320
	global_load_lds_dwordx4 v[212:213], off
	s_add_i32 m0, s26, 0x2000
	s_add_u32 s24, s24, 0x80080
	v_lshl_add_u64 v[212:213], v[218:219], 0, s[58:59]
	s_addc_u32 s25, s25, 0
	s_add_i32 s26, s42, s29
	global_load_lds_dwordx4 v[212:213], off
	s_mov_b32 m0, s26
	v_lshl_add_u64 v[212:213], s[24:25], 0, v[178:179]
	global_load_lds_dwordx4 v[212:213], off
	s_add_i32 m0, s26, 0x2000
	v_lshl_add_u64 v[212:213], s[24:25], 0, v[174:175]
	global_load_lds_dwordx4 v[212:213], off
	s_mov_b32 m0, s38
	v_lshl_add_u64 v[212:213], v[220:221], 0, s[58:59]
	global_load_lds_dwordx4 v[212:213], off
	s_mov_b32 m0, s39
	v_lshl_add_u64 v[212:213], v[222:223], 0, s[58:59]
	global_load_lds_dwordx4 v[212:213], off
	s_waitcnt vmcnt(8) lgkmcnt(0)
	s_setprio 1
	s_barrier
	v_mfma_f32_16x16x32_bf16 v[62:65], v[130:133], v[162:165], v[62:65]
	v_mfma_f32_16x16x32_bf16 v[58:61], v[138:141], v[162:165], v[58:61]
	v_mfma_f32_16x16x32_bf16 v[46:49], v[130:133], v[170:173], v[46:49]
	v_mfma_f32_16x16x32_bf16 v[42:45], v[138:141], v[170:173], v[42:45]
	v_mfma_f32_16x16x32_bf16 v[30:33], v[130:133], v[196:199], v[30:33]
	v_mfma_f32_16x16x32_bf16 v[26:29], v[138:141], v[196:199], v[26:29]
	v_mfma_f32_16x16x32_bf16 v[14:17], v[130:133], v[204:207], v[14:17]
	v_mfma_f32_16x16x32_bf16 v[10:13], v[138:141], v[204:207], v[10:13]
	v_mfma_f32_16x16x32_bf16 v[62:65], v[134:137], v[166:169], v[62:65]
	v_mfma_f32_16x16x32_bf16 v[58:61], v[142:145], v[166:169], v[58:61]
	v_mfma_f32_16x16x32_bf16 v[46:49], v[134:137], v[186:189], v[46:49]
	v_mfma_f32_16x16x32_bf16 v[42:45], v[142:145], v[186:189], v[42:45]
	v_mfma_f32_16x16x32_bf16 v[30:33], v[134:137], v[200:203], v[30:33]
	v_mfma_f32_16x16x32_bf16 v[26:29], v[142:145], v[200:203], v[26:29]
	v_mfma_f32_16x16x32_bf16 v[14:17], v[134:137], v[208:211], v[14:17]
	v_mfma_f32_16x16x32_bf16 v[10:13], v[142:145], v[208:211], v[10:13]
	v_mfma_f32_16x16x32_bf16 v[54:57], v[146:149], v[162:165], v[54:57]
	v_mfma_f32_16x16x32_bf16 v[50:53], v[154:157], v[162:165], v[50:53]
	v_mfma_f32_16x16x32_bf16 v[38:41], v[146:149], v[170:173], v[38:41]
	v_mfma_f32_16x16x32_bf16 v[34:37], v[154:157], v[170:173], v[34:37]
	v_mfma_f32_16x16x32_bf16 v[22:25], v[146:149], v[196:199], v[22:25]
	v_mfma_f32_16x16x32_bf16 v[18:21], v[154:157], v[196:199], v[18:21]
	v_mfma_f32_16x16x32_bf16 v[6:9], v[146:149], v[204:207], v[6:9]
	v_mfma_f32_16x16x32_bf16 v[2:5], v[154:157], v[204:207], v[2:5]
	v_mfma_f32_16x16x32_bf16 v[54:57], v[150:153], v[166:169], v[54:57]
	v_mfma_f32_16x16x32_bf16 v[50:53], v[158:161], v[166:169], v[50:53]
	v_mfma_f32_16x16x32_bf16 v[38:41], v[150:153], v[186:189], v[38:41]
	v_mfma_f32_16x16x32_bf16 v[34:37], v[158:161], v[186:189], v[34:37]
	v_mfma_f32_16x16x32_bf16 v[22:25], v[150:153], v[200:203], v[22:25]
	v_mfma_f32_16x16x32_bf16 v[18:21], v[158:161], v[200:203], v[18:21]
	v_mfma_f32_16x16x32_bf16 v[6:9], v[150:153], v[208:211], v[6:9]
	v_mfma_f32_16x16x32_bf16 v[2:5], v[158:161], v[208:211], v[2:5]
	s_setprio 0
	s_barrier
	s_add_i32 s40, s40, 2
	s_add_u32 s22, s22, 0x100
	s_addc_u32 s23, s23, 0
	s_add_u32 s21, s21, 0x100
	s_addc_u32 s33, s33, 0
	s_cmp_gt_u32 s40, 29
	s_cbranch_scc0 .LBB0_672

.LBB0_747:
	s_ashr_i32 s9, s8, 31
	s_lshl_b64 s[10:11], s[8:9], 20
	s_add_u32 s10, s69, s10
	s_addc_u32 s11, s77, s11
	s_and_b64 s[12:13], s[4:5], exec
	s_cselect_b32 s9, s11, s17
	s_cselect_b32 s31, s10, s16
	s_ashr_i32 s7, s6, 31
	s_lshl_b64 s[12:13], s[6:7], 20
	v_readlane_b32 s22, v254, 42
	v_readlane_b32 s23, v254, 43
	s_add_u32 s12, s22, s12
	s_addc_u32 s13, s23, s13
	s_and_b64 s[22:23], s[4:5], exec
	s_cselect_b32 s7, s13, s21
	s_cselect_b32 s33, s12, s20
	s_add_u32 s16, s16, 0x80080
	s_addc_u32 s17, s17, 0
	s_add_u32 s34, s20, 0x100
	s_addc_u32 s35, s21, 0
	s_mov_b32 s36, -2
	v_readlane_b32 s37, v255, 49
	s_nop 3
	s_cmp_eq_u32 s37, 3
	v_writelane_b32 v255, 3, 49
	s_cbranch_scc0 .Ltrip0_strict_2
	s_add_u32 s20, s16, 0xfff80080
	s_addc_u32 s21, s17, -1
	s_add_i32 s37, 0, 0x10000
	s_cmp_eq_u32 s36, 28
	s_cselect_b32 s23, s9, s21
	s_cselect_b32 s22, s31, s20
	s_cselect_b32 s21, s7, s35
	s_cselect_b32 s20, s33, s34
	s_add_i32 s40, 0, 0x14000
	v_add_u32_e32 v142, s37, v238
	v_add_u32_e32 v158, s40, v238
	ds_read_b128 v[130:133], v142
	ds_read_b128 v[134:137], v142 offset:1024
	ds_read_b128 v[138:141], v142 offset:2048
	ds_read_b128 v[142:145], v142 offset:3072
	ds_read_b128 v[146:149], v158
	ds_read_b128 v[150:153], v158 offset:1024
	ds_read_b128 v[154:157], v158 offset:2048
	ds_read_b128 v[158:161], v158 offset:3072
	v_lshl_add_u64 v[210:211], s[16:17], 0, v[206:207]
	s_add_i32 m0, s25, 0xc000
	ds_read_b128 v[162:165], v240
	ds_read_b128 v[166:169], v240 offset:1024
	ds_read_b128 v[170:173], v240 offset:2048
	ds_read_b128 v[174:177], v240 offset:3072
	ds_read_b128 v[178:181], v240 offset:4096
	ds_read_b128 v[182:185], v240 offset:5120
	ds_read_b128 v[186:189], v240 offset:6144
	ds_read_b128 v[196:199], v240 offset:7168
	global_load_lds_dwordx4 v[210:211], off
	s_add_i32 m0, s25, 0xe000
	v_lshl_add_u64 v[210:211], s[16:17], 0, v[208:209]
	global_load_lds_dwordx4 v[210:211], off
	s_waitcnt vmcnt(24) lgkmcnt(0)
	s_setprio 1
	s_barrier
	v_mfma_f32_16x16x32_bf16 v[126:129], v[130:133], v[162:165], 0
	v_mfma_f32_16x16x32_bf16 v[122:125], v[138:141], v[162:165], 0
	v_mfma_f32_16x16x32_bf16 v[110:113], v[130:133], v[170:173], 0
	v_mfma_f32_16x16x32_bf16 v[106:109], v[138:141], v[170:173], 0
	v_mfma_f32_16x16x32_bf16 v[98:101], v[130:133], v[178:181], 0
	v_mfma_f32_16x16x32_bf16 v[90:93], v[138:141], v[178:181], 0
	v_mfma_f32_16x16x32_bf16 v[82:85], v[130:133], v[186:189], 0
	v_mfma_f32_16x16x32_bf16 v[74:77], v[138:141], v[186:189], 0
	v_mfma_f32_16x16x32_bf16 v[126:129], v[134:137], v[166:169], v[126:129]
	v_mfma_f32_16x16x32_bf16 v[122:125], v[142:145], v[166:169], v[122:125]
	v_mfma_f32_16x16x32_bf16 v[110:113], v[134:137], v[174:177], v[110:113]
	v_mfma_f32_16x16x32_bf16 v[106:109], v[142:145], v[174:177], v[106:109]
	v_mfma_f32_16x16x32_bf16 v[98:101], v[134:137], v[182:185], v[98:101]
	v_mfma_f32_16x16x32_bf16 v[90:93], v[142:145], v[182:185], v[90:93]
	v_mfma_f32_16x16x32_bf16 v[82:85], v[134:137], v[196:199], v[82:85]
	v_mfma_f32_16x16x32_bf16 v[74:77], v[142:145], v[196:199], v[74:77]
	v_mfma_f32_16x16x32_bf16 v[118:121], v[146:149], v[162:165], 0
	v_mfma_f32_16x16x32_bf16 v[114:117], v[154:157], v[162:165], 0
	v_mfma_f32_16x16x32_bf16 v[102:105], v[146:149], v[170:173], 0
	v_mfma_f32_16x16x32_bf16 v[94:97], v[154:157], v[170:173], 0
	v_mfma_f32_16x16x32_bf16 v[86:89], v[146:149], v[178:181], 0
	v_mfma_f32_16x16x32_bf16 v[78:81], v[154:157], v[178:181], 0
	v_mfma_f32_16x16x32_bf16 v[70:73], v[146:149], v[186:189], 0
	v_mfma_f32_16x16x32_bf16 v[66:69], v[154:157], v[186:189], 0
	v_mfma_f32_16x16x32_bf16 v[118:121], v[150:153], v[166:169], v[118:121]
	v_mfma_f32_16x16x32_bf16 v[114:117], v[158:161], v[166:169], v[114:117]
	v_mfma_f32_16x16x32_bf16 v[102:105], v[150:153], v[174:177], v[102:105]
	v_mfma_f32_16x16x32_bf16 v[94:97], v[158:161], v[174:177], v[94:97]
	v_mfma_f32_16x16x32_bf16 v[86:89], v[150:153], v[182:185], v[86:89]
	v_mfma_f32_16x16x32_bf16 v[78:81], v[158:161], v[182:185], v[78:81]
	v_mfma_f32_16x16x32_bf16 v[70:73], v[150:153], v[196:199], v[70:73]
	v_mfma_f32_16x16x32_bf16 v[66:69], v[158:161], v[196:199], v[66:69]
	s_barrier
	s_setprio 0
	s_add_i32 s37, s37, s24
	v_lshl_add_u64 v[210:211], s[20:21], 0, v[190:191]
	s_mov_b32 m0, s37
	ds_read_b128 v[162:165], v240 offset:16384
	ds_read_b128 v[166:169], v240 offset:17408
	ds_read_b128 v[170:173], v240 offset:18432
	ds_read_b128 v[174:177], v240 offset:19456
	ds_read_b128 v[178:181], v240 offset:20480
	ds_read_b128 v[182:185], v240 offset:21504
	ds_read_b128 v[186:189], v240 offset:22528
	ds_read_b128 v[196:199], v240 offset:23552
	global_load_lds_dwordx4 v[210:211], off
	s_add_i32 m0, s37, 0x2000
	s_add_u32 s38, s20, 0x80000
	v_lshl_add_u64 v[212:213], s[20:21], 0, v[204:205]
	s_addc_u32 s39, s21, 0
	s_add_i32 s37, s40, s24
	global_load_lds_dwordx4 v[212:213], off
	v_lshl_add_u64 v[214:215], s[38:39], 0, v[190:191]
	s_mov_b32 m0, s37
	v_lshl_add_u64 v[216:217], s[22:23], 0, v[202:203]
	global_load_lds_dwordx4 v[214:215], off
	s_add_i32 m0, s37, 0x2000
	v_lshl_add_u64 v[214:215], s[38:39], 0, v[204:205]
	global_load_lds_dwordx4 v[214:215], off
	s_mov_b32 m0, s25
	v_lshl_add_u64 v[214:215], s[22:23], 0, v[200:201]
	global_load_lds_dwordx4 v[214:215], off
	s_mov_b32 m0, s26
	s_nop 0
	global_load_lds_dwordx4 v[216:217], off
	s_waitcnt vmcnt(24) lgkmcnt(0)
	s_setprio 1
	s_barrier
	v_mfma_f32_16x16x32_bf16 v[62:65], v[130:133], v[162:165], 0
	v_mfma_f32_16x16x32_bf16 v[58:61], v[138:141], v[162:165], 0
	v_mfma_f32_16x16x32_bf16 v[50:53], v[130:133], v[170:173], 0
	v_mfma_f32_16x16x32_bf16 v[42:45], v[138:141], v[170:173], 0
	v_mfma_f32_16x16x32_bf16 v[34:37], v[130:133], v[178:181], 0
	v_mfma_f32_16x16x32_bf16 v[26:29], v[138:141], v[178:181], 0
	v_mfma_f32_16x16x32_bf16 v[18:21], v[130:133], v[186:189], 0
	v_mfma_f32_16x16x32_bf16 v[10:13], v[138:141], v[186:189], 0
	v_mfma_f32_16x16x32_bf16 v[62:65], v[134:137], v[166:169], v[62:65]
	v_mfma_f32_16x16x32_bf16 v[58:61], v[142:145], v[166:169], v[58:61]
	v_mfma_f32_16x16x32_bf16 v[50:53], v[134:137], v[174:177], v[50:53]
	v_mfma_f32_16x16x32_bf16 v[42:45], v[142:145], v[174:177], v[42:45]
	v_mfma_f32_16x16x32_bf16 v[34:37], v[134:137], v[182:185], v[34:37]
	v_mfma_f32_16x16x32_bf16 v[26:29], v[142:145], v[182:185], v[26:29]
	v_mfma_f32_16x16x32_bf16 v[18:21], v[134:137], v[196:199], v[18:21]
	v_mfma_f32_16x16x32_bf16 v[10:13], v[142:145], v[196:199], v[10:13]
	v_mfma_f32_16x16x32_bf16 v[54:57], v[146:149], v[162:165], 0
	v_mfma_f32_16x16x32_bf16 v[46:49], v[154:157], v[162:165], 0
	v_mfma_f32_16x16x32_bf16 v[38:41], v[146:149], v[170:173], 0
	v_mfma_f32_16x16x32_bf16 v[30:33], v[154:157], v[170:173], 0
	v_mfma_f32_16x16x32_bf16 v[22:25], v[146:149], v[178:181], 0
	v_mfma_f32_16x16x32_bf16 v[14:17], v[154:157], v[178:181], 0
	v_mfma_f32_16x16x32_bf16 v[6:9], v[146:149], v[186:189], 0
	v_mfma_f32_16x16x32_bf16 v[2:5], v[154:157], v[186:189], 0
	v_mfma_f32_16x16x32_bf16 v[54:57], v[150:153], v[166:169], v[54:57]
	v_mfma_f32_16x16x32_bf16 v[46:49], v[158:161], v[166:169], v[46:49]
	v_mfma_f32_16x16x32_bf16 v[38:41], v[150:153], v[174:177], v[38:41]
	v_mfma_f32_16x16x32_bf16 v[30:33], v[158:161], v[174:177], v[30:33]
	v_mfma_f32_16x16x32_bf16 v[22:25], v[150:153], v[182:185], v[22:25]
	v_mfma_f32_16x16x32_bf16 v[14:17], v[158:161], v[182:185], v[14:17]
	v_mfma_f32_16x16x32_bf16 v[6:9], v[150:153], v[196:199], v[6:9]
	v_mfma_f32_16x16x32_bf16 v[2:5], v[158:161], v[196:199], v[2:5]
	s_barrier
	s_setprio 0
	s_add_i32 s37, 0, 0x18000
	s_add_i32 s38, 0, 0x1c000
	v_add_u32_e32 v142, s37, v238
	v_add_u32_e32 v158, s38, v238
	ds_read_b128 v[130:133], v142
	ds_read_b128 v[134:137], v142 offset:1024
	ds_read_b128 v[138:141], v142 offset:2048
	ds_read_b128 v[142:145], v142 offset:3072
	ds_read_b128 v[146:149], v158
	ds_read_b128 v[150:153], v158 offset:1024
	ds_read_b128 v[154:157], v158 offset:2048
	ds_read_b128 v[158:161], v158 offset:3072
	s_add_u32 s22, s22, 0x80000
	s_addc_u32 s23, s23, 0
	s_mov_b32 m0, s27
	v_lshl_add_u64 v[218:219], s[22:23], 0, v[200:201]
	ds_read_b128 v[162:165], v240 offset:32768
	ds_read_b128 v[166:169], v240 offset:33792
	ds_read_b128 v[170:173], v240 offset:34816
	ds_read_b128 v[174:177], v240 offset:35840
	ds_read_b128 v[178:181], v240 offset:36864
	ds_read_b128 v[182:185], v240 offset:37888
	ds_read_b128 v[186:189], v240 offset:38912
	ds_read_b128 v[196:199], v240 offset:39936
	global_load_lds_dwordx4 v[218:219], off
	s_mov_b32 m0, s28
	v_lshl_add_u64 v[218:219], s[22:23], 0, v[202:203]
	global_load_lds_dwordx4 v[218:219], off
	s_waitcnt vmcnt(8) lgkmcnt(0)
	s_setprio 1
	s_barrier
	v_mfma_f32_16x16x32_bf16 v[126:129], v[130:133], v[162:165], v[126:129]
	v_mfma_f32_16x16x32_bf16 v[122:125], v[138:141], v[162:165], v[122:125]
	v_mfma_f32_16x16x32_bf16 v[110:113], v[130:133], v[170:173], v[110:113]
	v_mfma_f32_16x16x32_bf16 v[106:109], v[138:141], v[170:173], v[106:109]
	v_mfma_f32_16x16x32_bf16 v[98:101], v[130:133], v[178:181], v[98:101]
	v_mfma_f32_16x16x32_bf16 v[90:93], v[138:141], v[178:181], v[90:93]
	v_mfma_f32_16x16x32_bf16 v[82:85], v[130:133], v[186:189], v[82:85]
	v_mfma_f32_16x16x32_bf16 v[74:77], v[138:141], v[186:189], v[74:77]
	v_mfma_f32_16x16x32_bf16 v[126:129], v[134:137], v[166:169], v[126:129]
	v_mfma_f32_16x16x32_bf16 v[122:125], v[142:145], v[166:169], v[122:125]
	v_mfma_f32_16x16x32_bf16 v[110:113], v[134:137], v[174:177], v[110:113]
	v_mfma_f32_16x16x32_bf16 v[106:109], v[142:145], v[174:177], v[106:109]
	v_mfma_f32_16x16x32_bf16 v[98:101], v[134:137], v[182:185], v[98:101]
	v_mfma_f32_16x16x32_bf16 v[90:93], v[142:145], v[182:185], v[90:93]
	v_mfma_f32_16x16x32_bf16 v[82:85], v[134:137], v[196:199], v[82:85]
	v_mfma_f32_16x16x32_bf16 v[74:77], v[142:145], v[196:199], v[74:77]
	v_mfma_f32_16x16x32_bf16 v[118:121], v[146:149], v[162:165], v[118:121]
	v_mfma_f32_16x16x32_bf16 v[114:117], v[154:157], v[162:165], v[114:117]
	v_mfma_f32_16x16x32_bf16 v[102:105], v[146:149], v[170:173], v[102:105]
	v_mfma_f32_16x16x32_bf16 v[94:97], v[154:157], v[170:173], v[94:97]
	v_mfma_f32_16x16x32_bf16 v[86:89], v[146:149], v[178:181], v[86:89]
	v_mfma_f32_16x16x32_bf16 v[78:81], v[154:157], v[178:181], v[78:81]
	v_mfma_f32_16x16x32_bf16 v[70:73], v[146:149], v[186:189], v[70:73]
	v_mfma_f32_16x16x32_bf16 v[66:69], v[154:157], v[186:189], v[66:69]
	v_mfma_f32_16x16x32_bf16 v[118:121], v[150:153], v[166:169], v[118:121]
	v_mfma_f32_16x16x32_bf16 v[114:117], v[158:161], v[166:169], v[114:117]
	v_mfma_f32_16x16x32_bf16 v[102:105], v[150:153], v[174:177], v[102:105]
	v_mfma_f32_16x16x32_bf16 v[94:97], v[158:161], v[174:177], v[94:97]
	v_mfma_f32_16x16x32_bf16 v[86:89], v[150:153], v[182:185], v[86:89]
	v_mfma_f32_16x16x32_bf16 v[78:81], v[158:161], v[182:185], v[78:81]
	v_mfma_f32_16x16x32_bf16 v[70:73], v[150:153], v[196:199], v[70:73]
	v_mfma_f32_16x16x32_bf16 v[66:69], v[158:161], v[196:199], v[66:69]
	s_barrier
	s_setprio 0
	s_add_i32 s22, s37, s24
	v_lshl_add_u64 v[210:211], v[210:211], 0, s[58:59]
	s_mov_b32 m0, s22
	ds_read_b128 v[162:165], v240 offset:49152
	ds_read_b128 v[166:169], v240 offset:50176
	ds_read_b128 v[170:173], v240 offset:51200
	ds_read_b128 v[174:177], v240 offset:52224
	ds_read_b128 v[178:181], v240 offset:53248
	ds_read_b128 v[182:185], v240 offset:54272
	ds_read_b128 v[186:189], v240 offset:55296
	ds_read_b128 v[196:199], v240 offset:56320
	global_load_lds_dwordx4 v[210:211], off
	s_add_i32 m0, s22, 0x2000
	s_add_u32 s20, s20, 0x80080
	v_lshl_add_u64 v[210:211], v[212:213], 0, s[58:59]
	s_addc_u32 s21, s21, 0
	s_add_i32 s22, s38, s24
	global_load_lds_dwordx4 v[210:211], off
	s_mov_b32 m0, s22
	v_lshl_add_u64 v[210:211], s[20:21], 0, v[190:191]
	global_load_lds_dwordx4 v[210:211], off
	s_add_i32 m0, s22, 0x2000
	v_lshl_add_u64 v[210:211], s[20:21], 0, v[204:205]
	global_load_lds_dwordx4 v[210:211], off
	s_mov_b32 m0, s29
	v_lshl_add_u64 v[210:211], v[214:215], 0, s[58:59]
	global_load_lds_dwordx4 v[210:211], off
	s_mov_b32 m0, s30
	v_lshl_add_u64 v[210:211], v[216:217], 0, s[58:59]
	global_load_lds_dwordx4 v[210:211], off
	s_waitcnt vmcnt(8) lgkmcnt(0)
	s_setprio 1
	s_barrier
	v_mfma_f32_16x16x32_bf16 v[62:65], v[130:133], v[162:165], v[62:65]
	v_mfma_f32_16x16x32_bf16 v[58:61], v[138:141], v[162:165], v[58:61]
	v_mfma_f32_16x16x32_bf16 v[50:53], v[130:133], v[170:173], v[50:53]
	v_mfma_f32_16x16x32_bf16 v[42:45], v[138:141], v[170:173], v[42:45]
	v_mfma_f32_16x16x32_bf16 v[34:37], v[130:133], v[178:181], v[34:37]
	v_mfma_f32_16x16x32_bf16 v[26:29], v[138:141], v[178:181], v[26:29]
	v_mfma_f32_16x16x32_bf16 v[18:21], v[130:133], v[186:189], v[18:21]
	v_mfma_f32_16x16x32_bf16 v[10:13], v[138:141], v[186:189], v[10:13]
	v_mfma_f32_16x16x32_bf16 v[62:65], v[134:137], v[166:169], v[62:65]
	v_mfma_f32_16x16x32_bf16 v[58:61], v[142:145], v[166:169], v[58:61]
	v_mfma_f32_16x16x32_bf16 v[50:53], v[134:137], v[174:177], v[50:53]
	v_mfma_f32_16x16x32_bf16 v[42:45], v[142:145], v[174:177], v[42:45]
	v_mfma_f32_16x16x32_bf16 v[34:37], v[134:137], v[182:185], v[34:37]
	v_mfma_f32_16x16x32_bf16 v[26:29], v[142:145], v[182:185], v[26:29]
	v_mfma_f32_16x16x32_bf16 v[18:21], v[134:137], v[196:199], v[18:21]
	v_mfma_f32_16x16x32_bf16 v[10:13], v[142:145], v[196:199], v[10:13]
	v_mfma_f32_16x16x32_bf16 v[54:57], v[146:149], v[162:165], v[54:57]
	v_mfma_f32_16x16x32_bf16 v[46:49], v[154:157], v[162:165], v[46:49]
	v_mfma_f32_16x16x32_bf16 v[38:41], v[146:149], v[170:173], v[38:41]
	v_mfma_f32_16x16x32_bf16 v[30:33], v[154:157], v[170:173], v[30:33]
	v_mfma_f32_16x16x32_bf16 v[22:25], v[146:149], v[178:181], v[22:25]
	v_mfma_f32_16x16x32_bf16 v[14:17], v[154:157], v[178:181], v[14:17]
	v_mfma_f32_16x16x32_bf16 v[6:9], v[146:149], v[186:189], v[6:9]
	v_mfma_f32_16x16x32_bf16 v[2:5], v[154:157], v[186:189], v[2:5]
	v_mfma_f32_16x16x32_bf16 v[54:57], v[150:153], v[166:169], v[54:57]
	v_mfma_f32_16x16x32_bf16 v[46:49], v[158:161], v[166:169], v[46:49]
	v_mfma_f32_16x16x32_bf16 v[38:41], v[150:153], v[174:177], v[38:41]
	v_mfma_f32_16x16x32_bf16 v[30:33], v[158:161], v[174:177], v[30:33]
	v_mfma_f32_16x16x32_bf16 v[22:25], v[150:153], v[182:185], v[22:25]
	v_mfma_f32_16x16x32_bf16 v[14:17], v[158:161], v[182:185], v[14:17]
	v_mfma_f32_16x16x32_bf16 v[6:9], v[150:153], v[196:199], v[6:9]
	v_mfma_f32_16x16x32_bf16 v[2:5], v[158:161], v[196:199], v[2:5]
	s_barrier
	s_setprio 0
	s_add_i32 s36, s36, 2
	s_add_u32 s16, s16, 0x100
	s_addc_u32 s17, s17, 0
	s_add_u32 s34, s34, 0x100
	s_addc_u32 s35, s35, 0
	s_cmp_gt_u32 s36, 29
	s_cbranch_scc1 .Lpeel_done_2
	s_branch .LBB0_748
.Ltrip0_strict_2:
	s_add_u32 s20, s16, 0xfff80080
	s_addc_u32 s21, s17, -1
	s_add_i32 s37, 0, 0x10000
	s_cmp_eq_u32 s36, 28
	s_cselect_b32 s23, s9, s21
	s_cselect_b32 s22, s31, s20
	s_cselect_b32 s21, s7, s35
	s_cselect_b32 s20, s33, s34
	s_add_i32 s40, 0, 0x14000
	v_add_u32_e32 v142, s37, v238
	v_add_u32_e32 v158, s40, v238
	ds_read_b128 v[130:133], v142
	ds_read_b128 v[134:137], v142 offset:1024
	ds_read_b128 v[138:141], v142 offset:2048
	ds_read_b128 v[142:145], v142 offset:3072
	ds_read_b128 v[146:149], v158
	ds_read_b128 v[150:153], v158 offset:1024
	ds_read_b128 v[154:157], v158 offset:2048
	ds_read_b128 v[158:161], v158 offset:3072
	v_lshl_add_u64 v[210:211], s[16:17], 0, v[206:207]
	s_add_i32 m0, s25, 0xc000
	ds_read_b128 v[162:165], v240
	ds_read_b128 v[166:169], v240 offset:1024
	ds_read_b128 v[170:173], v240 offset:2048
	ds_read_b128 v[174:177], v240 offset:3072
	ds_read_b128 v[178:181], v240 offset:4096
	ds_read_b128 v[182:185], v240 offset:5120
	ds_read_b128 v[186:189], v240 offset:6144
	ds_read_b128 v[196:199], v240 offset:7168
	global_load_lds_dwordx4 v[210:211], off
	s_add_i32 m0, s25, 0xe000
	v_lshl_add_u64 v[210:211], s[16:17], 0, v[208:209]
	global_load_lds_dwordx4 v[210:211], off
	s_waitcnt vmcnt(8) lgkmcnt(0)
	s_setprio 1
	s_barrier
	v_mfma_f32_16x16x32_bf16 v[126:129], v[130:133], v[162:165], 0
	v_mfma_f32_16x16x32_bf16 v[122:125], v[138:141], v[162:165], 0
	v_mfma_f32_16x16x32_bf16 v[110:113], v[130:133], v[170:173], 0
	v_mfma_f32_16x16x32_bf16 v[106:109], v[138:141], v[170:173], 0
	v_mfma_f32_16x16x32_bf16 v[98:101], v[130:133], v[178:181], 0
	v_mfma_f32_16x16x32_bf16 v[90:93], v[138:141], v[178:181], 0
	v_mfma_f32_16x16x32_bf16 v[82:85], v[130:133], v[186:189], 0
	v_mfma_f32_16x16x32_bf16 v[74:77], v[138:141], v[186:189], 0
	v_mfma_f32_16x16x32_bf16 v[126:129], v[134:137], v[166:169], v[126:129]
	v_mfma_f32_16x16x32_bf16 v[122:125], v[142:145], v[166:169], v[122:125]
	v_mfma_f32_16x16x32_bf16 v[110:113], v[134:137], v[174:177], v[110:113]
	v_mfma_f32_16x16x32_bf16 v[106:109], v[142:145], v[174:177], v[106:109]
	v_mfma_f32_16x16x32_bf16 v[98:101], v[134:137], v[182:185], v[98:101]
	v_mfma_f32_16x16x32_bf16 v[90:93], v[142:145], v[182:185], v[90:93]
	v_mfma_f32_16x16x32_bf16 v[82:85], v[134:137], v[196:199], v[82:85]
	v_mfma_f32_16x16x32_bf16 v[74:77], v[142:145], v[196:199], v[74:77]
	v_mfma_f32_16x16x32_bf16 v[118:121], v[146:149], v[162:165], 0
	v_mfma_f32_16x16x32_bf16 v[114:117], v[154:157], v[162:165], 0
	v_mfma_f32_16x16x32_bf16 v[102:105], v[146:149], v[170:173], 0
	v_mfma_f32_16x16x32_bf16 v[94:97], v[154:157], v[170:173], 0
	v_mfma_f32_16x16x32_bf16 v[86:89], v[146:149], v[178:181], 0
	v_mfma_f32_16x16x32_bf16 v[78:81], v[154:157], v[178:181], 0
	v_mfma_f32_16x16x32_bf16 v[70:73], v[146:149], v[186:189], 0
	v_mfma_f32_16x16x32_bf16 v[66:69], v[154:157], v[186:189], 0
	v_mfma_f32_16x16x32_bf16 v[118:121], v[150:153], v[166:169], v[118:121]
	v_mfma_f32_16x16x32_bf16 v[114:117], v[158:161], v[166:169], v[114:117]
	v_mfma_f32_16x16x32_bf16 v[102:105], v[150:153], v[174:177], v[102:105]
	v_mfma_f32_16x16x32_bf16 v[94:97], v[158:161], v[174:177], v[94:97]
	v_mfma_f32_16x16x32_bf16 v[86:89], v[150:153], v[182:185], v[86:89]
	v_mfma_f32_16x16x32_bf16 v[78:81], v[158:161], v[182:185], v[78:81]
	v_mfma_f32_16x16x32_bf16 v[70:73], v[150:153], v[196:199], v[70:73]
	v_mfma_f32_16x16x32_bf16 v[66:69], v[158:161], v[196:199], v[66:69]
	s_barrier
	s_setprio 0
	s_add_i32 s37, s37, s24
	v_lshl_add_u64 v[210:211], s[20:21], 0, v[190:191]
	s_mov_b32 m0, s37
	ds_read_b128 v[162:165], v240 offset:16384
	ds_read_b128 v[166:169], v240 offset:17408
	ds_read_b128 v[170:173], v240 offset:18432
	ds_read_b128 v[174:177], v240 offset:19456
	ds_read_b128 v[178:181], v240 offset:20480
	ds_read_b128 v[182:185], v240 offset:21504
	ds_read_b128 v[186:189], v240 offset:22528
	ds_read_b128 v[196:199], v240 offset:23552
	global_load_lds_dwordx4 v[210:211], off
	s_add_i32 m0, s37, 0x2000
	s_add_u32 s38, s20, 0x80000
	v_lshl_add_u64 v[212:213], s[20:21], 0, v[204:205]
	s_addc_u32 s39, s21, 0
	s_add_i32 s37, s40, s24
	global_load_lds_dwordx4 v[212:213], off
	v_lshl_add_u64 v[214:215], s[38:39], 0, v[190:191]
	s_mov_b32 m0, s37
	v_lshl_add_u64 v[216:217], s[22:23], 0, v[202:203]
	global_load_lds_dwordx4 v[214:215], off
	s_add_i32 m0, s37, 0x2000
	v_lshl_add_u64 v[214:215], s[38:39], 0, v[204:205]
	global_load_lds_dwordx4 v[214:215], off
	s_mov_b32 m0, s25
	v_lshl_add_u64 v[214:215], s[22:23], 0, v[200:201]
	global_load_lds_dwordx4 v[214:215], off
	s_mov_b32 m0, s26
	s_nop 0
	global_load_lds_dwordx4 v[216:217], off
	s_waitcnt vmcnt(8) lgkmcnt(0)
	s_setprio 1
	s_barrier
	v_mfma_f32_16x16x32_bf16 v[62:65], v[130:133], v[162:165], 0
	v_mfma_f32_16x16x32_bf16 v[58:61], v[138:141], v[162:165], 0
	v_mfma_f32_16x16x32_bf16 v[50:53], v[130:133], v[170:173], 0
	v_mfma_f32_16x16x32_bf16 v[42:45], v[138:141], v[170:173], 0
	v_mfma_f32_16x16x32_bf16 v[34:37], v[130:133], v[178:181], 0
	v_mfma_f32_16x16x32_bf16 v[26:29], v[138:141], v[178:181], 0
	v_mfma_f32_16x16x32_bf16 v[18:21], v[130:133], v[186:189], 0
	v_mfma_f32_16x16x32_bf16 v[10:13], v[138:141], v[186:189], 0
	v_mfma_f32_16x16x32_bf16 v[62:65], v[134:137], v[166:169], v[62:65]
	v_mfma_f32_16x16x32_bf16 v[58:61], v[142:145], v[166:169], v[58:61]
	v_mfma_f32_16x16x32_bf16 v[50:53], v[134:137], v[174:177], v[50:53]
	v_mfma_f32_16x16x32_bf16 v[42:45], v[142:145], v[174:177], v[42:45]
	v_mfma_f32_16x16x32_bf16 v[34:37], v[134:137], v[182:185], v[34:37]
	v_mfma_f32_16x16x32_bf16 v[26:29], v[142:145], v[182:185], v[26:29]
	v_mfma_f32_16x16x32_bf16 v[18:21], v[134:137], v[196:199], v[18:21]
	v_mfma_f32_16x16x32_bf16 v[10:13], v[142:145], v[196:199], v[10:13]
	v_mfma_f32_16x16x32_bf16 v[54:57], v[146:149], v[162:165], 0
	v_mfma_f32_16x16x32_bf16 v[46:49], v[154:157], v[162:165], 0
	v_mfma_f32_16x16x32_bf16 v[38:41], v[146:149], v[170:173], 0
	v_mfma_f32_16x16x32_bf16 v[30:33], v[154:157], v[170:173], 0
	v_mfma_f32_16x16x32_bf16 v[22:25], v[146:149], v[178:181], 0
	v_mfma_f32_16x16x32_bf16 v[14:17], v[154:157], v[178:181], 0
	v_mfma_f32_16x16x32_bf16 v[6:9], v[146:149], v[186:189], 0
	v_mfma_f32_16x16x32_bf16 v[2:5], v[154:157], v[186:189], 0
	v_mfma_f32_16x16x32_bf16 v[54:57], v[150:153], v[166:169], v[54:57]
	v_mfma_f32_16x16x32_bf16 v[46:49], v[158:161], v[166:169], v[46:49]
	v_mfma_f32_16x16x32_bf16 v[38:41], v[150:153], v[174:177], v[38:41]
	v_mfma_f32_16x16x32_bf16 v[30:33], v[158:161], v[174:177], v[30:33]
	v_mfma_f32_16x16x32_bf16 v[22:25], v[150:153], v[182:185], v[22:25]
	v_mfma_f32_16x16x32_bf16 v[14:17], v[158:161], v[182:185], v[14:17]
	v_mfma_f32_16x16x32_bf16 v[6:9], v[150:153], v[196:199], v[6:9]
	v_mfma_f32_16x16x32_bf16 v[2:5], v[158:161], v[196:199], v[2:5]
	s_barrier
	s_setprio 0
	s_add_i32 s37, 0, 0x18000
	s_add_i32 s38, 0, 0x1c000
	v_add_u32_e32 v142, s37, v238
	v_add_u32_e32 v158, s38, v238
	ds_read_b128 v[130:133], v142
	ds_read_b128 v[134:137], v142 offset:1024
	ds_read_b128 v[138:141], v142 offset:2048
	ds_read_b128 v[142:145], v142 offset:3072
	ds_read_b128 v[146:149], v158
	ds_read_b128 v[150:153], v158 offset:1024
	ds_read_b128 v[154:157], v158 offset:2048
	ds_read_b128 v[158:161], v158 offset:3072
	s_add_u32 s22, s22, 0x80000
	s_addc_u32 s23, s23, 0
	s_mov_b32 m0, s27
	v_lshl_add_u64 v[218:219], s[22:23], 0, v[200:201]
	ds_read_b128 v[162:165], v240 offset:32768
	ds_read_b128 v[166:169], v240 offset:33792
	ds_read_b128 v[170:173], v240 offset:34816
	ds_read_b128 v[174:177], v240 offset:35840
	ds_read_b128 v[178:181], v240 offset:36864
	ds_read_b128 v[182:185], v240 offset:37888
	ds_read_b128 v[186:189], v240 offset:38912
	ds_read_b128 v[196:199], v240 offset:39936
	global_load_lds_dwordx4 v[218:219], off
	s_mov_b32 m0, s28
	v_lshl_add_u64 v[218:219], s[22:23], 0, v[202:203]
	global_load_lds_dwordx4 v[218:219], off
	s_waitcnt vmcnt(8) lgkmcnt(0)
	s_setprio 1
	s_barrier
	v_mfma_f32_16x16x32_bf16 v[126:129], v[130:133], v[162:165], v[126:129]
	v_mfma_f32_16x16x32_bf16 v[122:125], v[138:141], v[162:165], v[122:125]
	v_mfma_f32_16x16x32_bf16 v[110:113], v[130:133], v[170:173], v[110:113]
	v_mfma_f32_16x16x32_bf16 v[106:109], v[138:141], v[170:173], v[106:109]
	v_mfma_f32_16x16x32_bf16 v[98:101], v[130:133], v[178:181], v[98:101]
	v_mfma_f32_16x16x32_bf16 v[90:93], v[138:141], v[178:181], v[90:93]
	v_mfma_f32_16x16x32_bf16 v[82:85], v[130:133], v[186:189], v[82:85]
	v_mfma_f32_16x16x32_bf16 v[74:77], v[138:141], v[186:189], v[74:77]
	v_mfma_f32_16x16x32_bf16 v[126:129], v[134:137], v[166:169], v[126:129]
	v_mfma_f32_16x16x32_bf16 v[122:125], v[142:145], v[166:169], v[122:125]
	v_mfma_f32_16x16x32_bf16 v[110:113], v[134:137], v[174:177], v[110:113]
	v_mfma_f32_16x16x32_bf16 v[106:109], v[142:145], v[174:177], v[106:109]
	v_mfma_f32_16x16x32_bf16 v[98:101], v[134:137], v[182:185], v[98:101]
	v_mfma_f32_16x16x32_bf16 v[90:93], v[142:145], v[182:185], v[90:93]
	v_mfma_f32_16x16x32_bf16 v[82:85], v[134:137], v[196:199], v[82:85]
	v_mfma_f32_16x16x32_bf16 v[74:77], v[142:145], v[196:199], v[74:77]
	v_mfma_f32_16x16x32_bf16 v[118:121], v[146:149], v[162:165], v[118:121]
	v_mfma_f32_16x16x32_bf16 v[114:117], v[154:157], v[162:165], v[114:117]
	v_mfma_f32_16x16x32_bf16 v[102:105], v[146:149], v[170:173], v[102:105]
	v_mfma_f32_16x16x32_bf16 v[94:97], v[154:157], v[170:173], v[94:97]
	v_mfma_f32_16x16x32_bf16 v[86:89], v[146:149], v[178:181], v[86:89]
	v_mfma_f32_16x16x32_bf16 v[78:81], v[154:157], v[178:181], v[78:81]
	v_mfma_f32_16x16x32_bf16 v[70:73], v[146:149], v[186:189], v[70:73]
	v_mfma_f32_16x16x32_bf16 v[66:69], v[154:157], v[186:189], v[66:69]
	v_mfma_f32_16x16x32_bf16 v[118:121], v[150:153], v[166:169], v[118:121]
	v_mfma_f32_16x16x32_bf16 v[114:117], v[158:161], v[166:169], v[114:117]
	v_mfma_f32_16x16x32_bf16 v[102:105], v[150:153], v[174:177], v[102:105]
	v_mfma_f32_16x16x32_bf16 v[94:97], v[158:161], v[174:177], v[94:97]
	v_mfma_f32_16x16x32_bf16 v[86:89], v[150:153], v[182:185], v[86:89]
	v_mfma_f32_16x16x32_bf16 v[78:81], v[158:161], v[182:185], v[78:81]
	v_mfma_f32_16x16x32_bf16 v[70:73], v[150:153], v[196:199], v[70:73]
	v_mfma_f32_16x16x32_bf16 v[66:69], v[158:161], v[196:199], v[66:69]
	s_barrier
	s_setprio 0
	s_add_i32 s22, s37, s24
	v_lshl_add_u64 v[210:211], v[210:211], 0, s[58:59]
	s_mov_b32 m0, s22
	ds_read_b128 v[162:165], v240 offset:49152
	ds_read_b128 v[166:169], v240 offset:50176
	ds_read_b128 v[170:173], v240 offset:51200
	ds_read_b128 v[174:177], v240 offset:52224
	ds_read_b128 v[178:181], v240 offset:53248
	ds_read_b128 v[182:185], v240 offset:54272
	ds_read_b128 v[186:189], v240 offset:55296
	ds_read_b128 v[196:199], v240 offset:56320
	global_load_lds_dwordx4 v[210:211], off
	s_add_i32 m0, s22, 0x2000
	s_add_u32 s20, s20, 0x80080
	v_lshl_add_u64 v[210:211], v[212:213], 0, s[58:59]
	s_addc_u32 s21, s21, 0
	s_add_i32 s22, s38, s24
	global_load_lds_dwordx4 v[210:211], off
	s_mov_b32 m0, s22
	v_lshl_add_u64 v[210:211], s[20:21], 0, v[190:191]
	global_load_lds_dwordx4 v[210:211], off
	s_add_i32 m0, s22, 0x2000
	v_lshl_add_u64 v[210:211], s[20:21], 0, v[204:205]
	global_load_lds_dwordx4 v[210:211], off
	s_mov_b32 m0, s29
	v_lshl_add_u64 v[210:211], v[214:215], 0, s[58:59]
	global_load_lds_dwordx4 v[210:211], off
	s_mov_b32 m0, s30
	v_lshl_add_u64 v[210:211], v[216:217], 0, s[58:59]
	global_load_lds_dwordx4 v[210:211], off
	s_waitcnt vmcnt(8) lgkmcnt(0)
	s_setprio 1
	s_barrier
	v_mfma_f32_16x16x32_bf16 v[62:65], v[130:133], v[162:165], v[62:65]
	v_mfma_f32_16x16x32_bf16 v[58:61], v[138:141], v[162:165], v[58:61]
	v_mfma_f32_16x16x32_bf16 v[50:53], v[130:133], v[170:173], v[50:53]
	v_mfma_f32_16x16x32_bf16 v[42:45], v[138:141], v[170:173], v[42:45]
	v_mfma_f32_16x16x32_bf16 v[34:37], v[130:133], v[178:181], v[34:37]
	v_mfma_f32_16x16x32_bf16 v[26:29], v[138:141], v[178:181], v[26:29]
	v_mfma_f32_16x16x32_bf16 v[18:21], v[130:133], v[186:189], v[18:21]
	v_mfma_f32_16x16x32_bf16 v[10:13], v[138:141], v[186:189], v[10:13]
	v_mfma_f32_16x16x32_bf16 v[62:65], v[134:137], v[166:169], v[62:65]
	v_mfma_f32_16x16x32_bf16 v[58:61], v[142:145], v[166:169], v[58:61]
	v_mfma_f32_16x16x32_bf16 v[50:53], v[134:137], v[174:177], v[50:53]
	v_mfma_f32_16x16x32_bf16 v[42:45], v[142:145], v[174:177], v[42:45]
	v_mfma_f32_16x16x32_bf16 v[34:37], v[134:137], v[182:185], v[34:37]
	v_mfma_f32_16x16x32_bf16 v[26:29], v[142:145], v[182:185], v[26:29]
	v_mfma_f32_16x16x32_bf16 v[18:21], v[134:137], v[196:199], v[18:21]
	v_mfma_f32_16x16x32_bf16 v[10:13], v[142:145], v[196:199], v[10:13]
	v_mfma_f32_16x16x32_bf16 v[54:57], v[146:149], v[162:165], v[54:57]
	v_mfma_f32_16x16x32_bf16 v[46:49], v[154:157], v[162:165], v[46:49]
	v_mfma_f32_16x16x32_bf16 v[38:41], v[146:149], v[170:173], v[38:41]
	v_mfma_f32_16x16x32_bf16 v[30:33], v[154:157], v[170:173], v[30:33]
	v_mfma_f32_16x16x32_bf16 v[22:25], v[146:149], v[178:181], v[22:25]
	v_mfma_f32_16x16x32_bf16 v[14:17], v[154:157], v[178:181], v[14:17]
	v_mfma_f32_16x16x32_bf16 v[6:9], v[146:149], v[186:189], v[6:9]
	v_mfma_f32_16x16x32_bf16 v[2:5], v[154:157], v[186:189], v[2:5]
	v_mfma_f32_16x16x32_bf16 v[54:57], v[150:153], v[166:169], v[54:57]
	v_mfma_f32_16x16x32_bf16 v[46:49], v[158:161], v[166:169], v[46:49]
	v_mfma_f32_16x16x32_bf16 v[38:41], v[150:153], v[174:177], v[38:41]
	v_mfma_f32_16x16x32_bf16 v[30:33], v[158:161], v[174:177], v[30:33]
	v_mfma_f32_16x16x32_bf16 v[22:25], v[150:153], v[182:185], v[22:25]
	v_mfma_f32_16x16x32_bf16 v[14:17], v[158:161], v[182:185], v[14:17]
	v_mfma_f32_16x16x32_bf16 v[6:9], v[150:153], v[196:199], v[6:9]
	v_mfma_f32_16x16x32_bf16 v[2:5], v[158:161], v[196:199], v[2:5]
	s_barrier
	s_setprio 0
	s_add_i32 s36, s36, 2
	s_add_u32 s16, s16, 0x100
	s_addc_u32 s17, s17, 0
	s_add_u32 s34, s34, 0x100
	s_addc_u32 s35, s35, 0
	s_cmp_gt_u32 s36, 29
	s_cbranch_scc1 .Lpeel_done_2
.LBB0_748:
	s_add_u32 s20, s16, 0xfff80080
	s_addc_u32 s21, s17, -1
	s_add_i32 s37, 0, 0x10000
	s_cmp_eq_u32 s36, 28
	s_cselect_b32 s23, s9, s21
	s_cselect_b32 s22, s31, s20
	s_cselect_b32 s21, s7, s35
	s_cselect_b32 s20, s33, s34
	s_add_i32 s40, 0, 0x14000
	v_add_u32_e32 v142, s37, v238
	v_add_u32_e32 v158, s40, v238
	ds_read_b128 v[130:133], v142
	ds_read_b128 v[134:137], v142 offset:1024
	ds_read_b128 v[138:141], v142 offset:2048
	ds_read_b128 v[142:145], v142 offset:3072
	ds_read_b128 v[146:149], v158
	ds_read_b128 v[150:153], v158 offset:1024
	ds_read_b128 v[154:157], v158 offset:2048
	ds_read_b128 v[158:161], v158 offset:3072
	v_lshl_add_u64 v[210:211], s[16:17], 0, v[206:207]
	s_add_i32 m0, s25, 0xc000
	ds_read_b128 v[162:165], v240
	ds_read_b128 v[166:169], v240 offset:1024
	ds_read_b128 v[170:173], v240 offset:2048
	ds_read_b128 v[174:177], v240 offset:3072
	ds_read_b128 v[178:181], v240 offset:4096
	ds_read_b128 v[182:185], v240 offset:5120
	ds_read_b128 v[186:189], v240 offset:6144
	ds_read_b128 v[196:199], v240 offset:7168
	global_load_lds_dwordx4 v[210:211], off
	s_add_i32 m0, s25, 0xe000
	v_lshl_add_u64 v[210:211], s[16:17], 0, v[208:209]
	global_load_lds_dwordx4 v[210:211], off
	s_waitcnt vmcnt(8) lgkmcnt(0)
	s_setprio 1
	s_barrier
	v_mfma_f32_16x16x32_bf16 v[126:129], v[130:133], v[162:165], v[126:129]
	v_mfma_f32_16x16x32_bf16 v[122:125], v[138:141], v[162:165], v[122:125]
	v_mfma_f32_16x16x32_bf16 v[110:113], v[130:133], v[170:173], v[110:113]
	v_mfma_f32_16x16x32_bf16 v[106:109], v[138:141], v[170:173], v[106:109]
	v_mfma_f32_16x16x32_bf16 v[98:101], v[130:133], v[178:181], v[98:101]
	v_mfma_f32_16x16x32_bf16 v[90:93], v[138:141], v[178:181], v[90:93]
	v_mfma_f32_16x16x32_bf16 v[82:85], v[130:133], v[186:189], v[82:85]
	v_mfma_f32_16x16x32_bf16 v[74:77], v[138:141], v[186:189], v[74:77]
	v_mfma_f32_16x16x32_bf16 v[126:129], v[134:137], v[166:169], v[126:129]
	v_mfma_f32_16x16x32_bf16 v[122:125], v[142:145], v[166:169], v[122:125]
	v_mfma_f32_16x16x32_bf16 v[110:113], v[134:137], v[174:177], v[110:113]
	v_mfma_f32_16x16x32_bf16 v[106:109], v[142:145], v[174:177], v[106:109]
	v_mfma_f32_16x16x32_bf16 v[98:101], v[134:137], v[182:185], v[98:101]
	v_mfma_f32_16x16x32_bf16 v[90:93], v[142:145], v[182:185], v[90:93]
	v_mfma_f32_16x16x32_bf16 v[82:85], v[134:137], v[196:199], v[82:85]
	v_mfma_f32_16x16x32_bf16 v[74:77], v[142:145], v[196:199], v[74:77]
	v_mfma_f32_16x16x32_bf16 v[118:121], v[146:149], v[162:165], v[118:121]
	v_mfma_f32_16x16x32_bf16 v[114:117], v[154:157], v[162:165], v[114:117]
	v_mfma_f32_16x16x32_bf16 v[102:105], v[146:149], v[170:173], v[102:105]
	v_mfma_f32_16x16x32_bf16 v[94:97], v[154:157], v[170:173], v[94:97]
	v_mfma_f32_16x16x32_bf16 v[86:89], v[146:149], v[178:181], v[86:89]
	v_mfma_f32_16x16x32_bf16 v[78:81], v[154:157], v[178:181], v[78:81]
	v_mfma_f32_16x16x32_bf16 v[70:73], v[146:149], v[186:189], v[70:73]
	v_mfma_f32_16x16x32_bf16 v[66:69], v[154:157], v[186:189], v[66:69]
	v_mfma_f32_16x16x32_bf16 v[118:121], v[150:153], v[166:169], v[118:121]
	v_mfma_f32_16x16x32_bf16 v[114:117], v[158:161], v[166:169], v[114:117]
	v_mfma_f32_16x16x32_bf16 v[102:105], v[150:153], v[174:177], v[102:105]
	v_mfma_f32_16x16x32_bf16 v[94:97], v[158:161], v[174:177], v[94:97]
	v_mfma_f32_16x16x32_bf16 v[86:89], v[150:153], v[182:185], v[86:89]
	v_mfma_f32_16x16x32_bf16 v[78:81], v[158:161], v[182:185], v[78:81]
	v_mfma_f32_16x16x32_bf16 v[70:73], v[150:153], v[196:199], v[70:73]
	v_mfma_f32_16x16x32_bf16 v[66:69], v[158:161], v[196:199], v[66:69]
	s_setprio 0
	s_barrier
	s_add_i32 s37, s37, s24
	v_lshl_add_u64 v[210:211], s[20:21], 0, v[190:191]
	s_mov_b32 m0, s37
	ds_read_b128 v[162:165], v240 offset:16384
	ds_read_b128 v[166:169], v240 offset:17408
	ds_read_b128 v[170:173], v240 offset:18432
	ds_read_b128 v[174:177], v240 offset:19456
	ds_read_b128 v[178:181], v240 offset:20480
	ds_read_b128 v[182:185], v240 offset:21504
	ds_read_b128 v[186:189], v240 offset:22528
	ds_read_b128 v[196:199], v240 offset:23552
	global_load_lds_dwordx4 v[210:211], off
	s_add_i32 m0, s37, 0x2000
	s_add_u32 s38, s20, 0x80000
	v_lshl_add_u64 v[212:213], s[20:21], 0, v[204:205]
	s_addc_u32 s39, s21, 0
	s_add_i32 s37, s40, s24
	global_load_lds_dwordx4 v[212:213], off
	v_lshl_add_u64 v[214:215], s[38:39], 0, v[190:191]
	s_mov_b32 m0, s37
	v_lshl_add_u64 v[216:217], s[22:23], 0, v[202:203]
	global_load_lds_dwordx4 v[214:215], off
	s_add_i32 m0, s37, 0x2000
	v_lshl_add_u64 v[214:215], s[38:39], 0, v[204:205]
	global_load_lds_dwordx4 v[214:215], off
	s_mov_b32 m0, s25
	v_lshl_add_u64 v[214:215], s[22:23], 0, v[200:201]
	global_load_lds_dwordx4 v[214:215], off
	s_mov_b32 m0, s26
	s_nop 0
	global_load_lds_dwordx4 v[216:217], off
	s_waitcnt vmcnt(8) lgkmcnt(0)
	s_setprio 1
	s_barrier
	v_mfma_f32_16x16x32_bf16 v[62:65], v[130:133], v[162:165], v[62:65]
	v_mfma_f32_16x16x32_bf16 v[58:61], v[138:141], v[162:165], v[58:61]
	v_mfma_f32_16x16x32_bf16 v[50:53], v[130:133], v[170:173], v[50:53]
	v_mfma_f32_16x16x32_bf16 v[42:45], v[138:141], v[170:173], v[42:45]
	v_mfma_f32_16x16x32_bf16 v[34:37], v[130:133], v[178:181], v[34:37]
	v_mfma_f32_16x16x32_bf16 v[26:29], v[138:141], v[178:181], v[26:29]
	v_mfma_f32_16x16x32_bf16 v[18:21], v[130:133], v[186:189], v[18:21]
	v_mfma_f32_16x16x32_bf16 v[10:13], v[138:141], v[186:189], v[10:13]
	v_mfma_f32_16x16x32_bf16 v[62:65], v[134:137], v[166:169], v[62:65]
	v_mfma_f32_16x16x32_bf16 v[58:61], v[142:145], v[166:169], v[58:61]
	v_mfma_f32_16x16x32_bf16 v[50:53], v[134:137], v[174:177], v[50:53]
	v_mfma_f32_16x16x32_bf16 v[42:45], v[142:145], v[174:177], v[42:45]
	v_mfma_f32_16x16x32_bf16 v[34:37], v[134:137], v[182:185], v[34:37]
	v_mfma_f32_16x16x32_bf16 v[26:29], v[142:145], v[182:185], v[26:29]
	v_mfma_f32_16x16x32_bf16 v[18:21], v[134:137], v[196:199], v[18:21]
	v_mfma_f32_16x16x32_bf16 v[10:13], v[142:145], v[196:199], v[10:13]
	v_mfma_f32_16x16x32_bf16 v[54:57], v[146:149], v[162:165], v[54:57]
	v_mfma_f32_16x16x32_bf16 v[46:49], v[154:157], v[162:165], v[46:49]
	v_mfma_f32_16x16x32_bf16 v[38:41], v[146:149], v[170:173], v[38:41]
	v_mfma_f32_16x16x32_bf16 v[30:33], v[154:157], v[170:173], v[30:33]
	v_mfma_f32_16x16x32_bf16 v[22:25], v[146:149], v[178:181], v[22:25]
	v_mfma_f32_16x16x32_bf16 v[14:17], v[154:157], v[178:181], v[14:17]
	v_mfma_f32_16x16x32_bf16 v[6:9], v[146:149], v[186:189], v[6:9]
	v_mfma_f32_16x16x32_bf16 v[2:5], v[154:157], v[186:189], v[2:5]
	v_mfma_f32_16x16x32_bf16 v[54:57], v[150:153], v[166:169], v[54:57]
	v_mfma_f32_16x16x32_bf16 v[46:49], v[158:161], v[166:169], v[46:49]
	v_mfma_f32_16x16x32_bf16 v[38:41], v[150:153], v[174:177], v[38:41]
	v_mfma_f32_16x16x32_bf16 v[30:33], v[158:161], v[174:177], v[30:33]
	v_mfma_f32_16x16x32_bf16 v[22:25], v[150:153], v[182:185], v[22:25]
	v_mfma_f32_16x16x32_bf16 v[14:17], v[158:161], v[182:185], v[14:17]
	v_mfma_f32_16x16x32_bf16 v[6:9], v[150:153], v[196:199], v[6:9]
	v_mfma_f32_16x16x32_bf16 v[2:5], v[158:161], v[196:199], v[2:5]
	s_setprio 0
	s_barrier
	s_add_i32 s37, 0, 0x18000
	s_add_i32 s38, 0, 0x1c000
	v_add_u32_e32 v142, s37, v238
	v_add_u32_e32 v158, s38, v238
	ds_read_b128 v[130:133], v142
	ds_read_b128 v[134:137], v142 offset:1024
	ds_read_b128 v[138:141], v142 offset:2048
	ds_read_b128 v[142:145], v142 offset:3072
	ds_read_b128 v[146:149], v158
	ds_read_b128 v[150:153], v158 offset:1024
	ds_read_b128 v[154:157], v158 offset:2048
	ds_read_b128 v[158:161], v158 offset:3072
	s_add_u32 s22, s22, 0x80000
	s_addc_u32 s23, s23, 0
	s_mov_b32 m0, s27
	v_lshl_add_u64 v[218:219], s[22:23], 0, v[200:201]
	ds_read_b128 v[162:165], v240 offset:32768
	ds_read_b128 v[166:169], v240 offset:33792
	ds_read_b128 v[170:173], v240 offset:34816
	ds_read_b128 v[174:177], v240 offset:35840
	ds_read_b128 v[178:181], v240 offset:36864
	ds_read_b128 v[182:185], v240 offset:37888
	ds_read_b128 v[186:189], v240 offset:38912
	ds_read_b128 v[196:199], v240 offset:39936
	global_load_lds_dwordx4 v[218:219], off
	s_mov_b32 m0, s28
	v_lshl_add_u64 v[218:219], s[22:23], 0, v[202:203]
	global_load_lds_dwordx4 v[218:219], off
	s_waitcnt vmcnt(8) lgkmcnt(0)
	s_setprio 1
	s_barrier
	v_mfma_f32_16x16x32_bf16 v[126:129], v[130:133], v[162:165], v[126:129]
	v_mfma_f32_16x16x32_bf16 v[122:125], v[138:141], v[162:165], v[122:125]
	v_mfma_f32_16x16x32_bf16 v[110:113], v[130:133], v[170:173], v[110:113]
	v_mfma_f32_16x16x32_bf16 v[106:109], v[138:141], v[170:173], v[106:109]
	v_mfma_f32_16x16x32_bf16 v[98:101], v[130:133], v[178:181], v[98:101]
	v_mfma_f32_16x16x32_bf16 v[90:93], v[138:141], v[178:181], v[90:93]
	v_mfma_f32_16x16x32_bf16 v[82:85], v[130:133], v[186:189], v[82:85]
	v_mfma_f32_16x16x32_bf16 v[74:77], v[138:141], v[186:189], v[74:77]
	v_mfma_f32_16x16x32_bf16 v[126:129], v[134:137], v[166:169], v[126:129]
	v_mfma_f32_16x16x32_bf16 v[122:125], v[142:145], v[166:169], v[122:125]
	v_mfma_f32_16x16x32_bf16 v[110:113], v[134:137], v[174:177], v[110:113]
	v_mfma_f32_16x16x32_bf16 v[106:109], v[142:145], v[174:177], v[106:109]
	v_mfma_f32_16x16x32_bf16 v[98:101], v[134:137], v[182:185], v[98:101]
	v_mfma_f32_16x16x32_bf16 v[90:93], v[142:145], v[182:185], v[90:93]
	v_mfma_f32_16x16x32_bf16 v[82:85], v[134:137], v[196:199], v[82:85]
	v_mfma_f32_16x16x32_bf16 v[74:77], v[142:145], v[196:199], v[74:77]
	v_mfma_f32_16x16x32_bf16 v[118:121], v[146:149], v[162:165], v[118:121]
	v_mfma_f32_16x16x32_bf16 v[114:117], v[154:157], v[162:165], v[114:117]
	v_mfma_f32_16x16x32_bf16 v[102:105], v[146:149], v[170:173], v[102:105]
	v_mfma_f32_16x16x32_bf16 v[94:97], v[154:157], v[170:173], v[94:97]
	v_mfma_f32_16x16x32_bf16 v[86:89], v[146:149], v[178:181], v[86:89]
	v_mfma_f32_16x16x32_bf16 v[78:81], v[154:157], v[178:181], v[78:81]
	v_mfma_f32_16x16x32_bf16 v[70:73], v[146:149], v[186:189], v[70:73]
	v_mfma_f32_16x16x32_bf16 v[66:69], v[154:157], v[186:189], v[66:69]
	v_mfma_f32_16x16x32_bf16 v[118:121], v[150:153], v[166:169], v[118:121]
	v_mfma_f32_16x16x32_bf16 v[114:117], v[158:161], v[166:169], v[114:117]
	v_mfma_f32_16x16x32_bf16 v[102:105], v[150:153], v[174:177], v[102:105]
	v_mfma_f32_16x16x32_bf16 v[94:97], v[158:161], v[174:177], v[94:97]
	v_mfma_f32_16x16x32_bf16 v[86:89], v[150:153], v[182:185], v[86:89]
	v_mfma_f32_16x16x32_bf16 v[78:81], v[158:161], v[182:185], v[78:81]
	v_mfma_f32_16x16x32_bf16 v[70:73], v[150:153], v[196:199], v[70:73]
	v_mfma_f32_16x16x32_bf16 v[66:69], v[158:161], v[196:199], v[66:69]
	s_setprio 0
	s_barrier
	s_add_i32 s22, s37, s24
	v_lshl_add_u64 v[210:211], v[210:211], 0, s[58:59]
	s_mov_b32 m0, s22
	ds_read_b128 v[162:165], v240 offset:49152
	ds_read_b128 v[166:169], v240 offset:50176
	ds_read_b128 v[170:173], v240 offset:51200
	ds_read_b128 v[174:177], v240 offset:52224
	ds_read_b128 v[178:181], v240 offset:53248
	ds_read_b128 v[182:185], v240 offset:54272
	ds_read_b128 v[186:189], v240 offset:55296
	ds_read_b128 v[196:199], v240 offset:56320
	global_load_lds_dwordx4 v[210:211], off
	s_add_i32 m0, s22, 0x2000
	s_add_u32 s20, s20, 0x80080
	v_lshl_add_u64 v[210:211], v[212:213], 0, s[58:59]
	s_addc_u32 s21, s21, 0
	s_add_i32 s22, s38, s24
	global_load_lds_dwordx4 v[210:211], off
	s_mov_b32 m0, s22
	v_lshl_add_u64 v[210:211], s[20:21], 0, v[190:191]
	global_load_lds_dwordx4 v[210:211], off
	s_add_i32 m0, s22, 0x2000
	v_lshl_add_u64 v[210:211], s[20:21], 0, v[204:205]
	global_load_lds_dwordx4 v[210:211], off
	s_mov_b32 m0, s29
	v_lshl_add_u64 v[210:211], v[214:215], 0, s[58:59]
	global_load_lds_dwordx4 v[210:211], off
	s_mov_b32 m0, s30
	v_lshl_add_u64 v[210:211], v[216:217], 0, s[58:59]
	global_load_lds_dwordx4 v[210:211], off
	s_waitcnt vmcnt(8) lgkmcnt(0)
	s_setprio 1
	s_barrier
	v_mfma_f32_16x16x32_bf16 v[62:65], v[130:133], v[162:165], v[62:65]
	v_mfma_f32_16x16x32_bf16 v[58:61], v[138:141], v[162:165], v[58:61]
	v_mfma_f32_16x16x32_bf16 v[50:53], v[130:133], v[170:173], v[50:53]
	v_mfma_f32_16x16x32_bf16 v[42:45], v[138:141], v[170:173], v[42:45]
	v_mfma_f32_16x16x32_bf16 v[34:37], v[130:133], v[178:181], v[34:37]
	v_mfma_f32_16x16x32_bf16 v[26:29], v[138:141], v[178:181], v[26:29]
	v_mfma_f32_16x16x32_bf16 v[18:21], v[130:133], v[186:189], v[18:21]
	v_mfma_f32_16x16x32_bf16 v[10:13], v[138:141], v[186:189], v[10:13]
	v_mfma_f32_16x16x32_bf16 v[62:65], v[134:137], v[166:169], v[62:65]
	v_mfma_f32_16x16x32_bf16 v[58:61], v[142:145], v[166:169], v[58:61]
	v_mfma_f32_16x16x32_bf16 v[50:53], v[134:137], v[174:177], v[50:53]
	v_mfma_f32_16x16x32_bf16 v[42:45], v[142:145], v[174:177], v[42:45]
	v_mfma_f32_16x16x32_bf16 v[34:37], v[134:137], v[182:185], v[34:37]
	v_mfma_f32_16x16x32_bf16 v[26:29], v[142:145], v[182:185], v[26:29]
	v_mfma_f32_16x16x32_bf16 v[18:21], v[134:137], v[196:199], v[18:21]
	v_mfma_f32_16x16x32_bf16 v[10:13], v[142:145], v[196:199], v[10:13]
	v_mfma_f32_16x16x32_bf16 v[54:57], v[146:149], v[162:165], v[54:57]
	v_mfma_f32_16x16x32_bf16 v[46:49], v[154:157], v[162:165], v[46:49]
	v_mfma_f32_16x16x32_bf16 v[38:41], v[146:149], v[170:173], v[38:41]
	v_mfma_f32_16x16x32_bf16 v[30:33], v[154:157], v[170:173], v[30:33]
	v_mfma_f32_16x16x32_bf16 v[22:25], v[146:149], v[178:181], v[22:25]
	v_mfma_f32_16x16x32_bf16 v[14:17], v[154:157], v[178:181], v[14:17]
	v_mfma_f32_16x16x32_bf16 v[6:9], v[146:149], v[186:189], v[6:9]
	v_mfma_f32_16x16x32_bf16 v[2:5], v[154:157], v[186:189], v[2:5]
	v_mfma_f32_16x16x32_bf16 v[54:57], v[150:153], v[166:169], v[54:57]
	v_mfma_f32_16x16x32_bf16 v[46:49], v[158:161], v[166:169], v[46:49]
	v_mfma_f32_16x16x32_bf16 v[38:41], v[150:153], v[174:177], v[38:41]
	v_mfma_f32_16x16x32_bf16 v[30:33], v[158:161], v[174:177], v[30:33]
	v_mfma_f32_16x16x32_bf16 v[22:25], v[150:153], v[182:185], v[22:25]
	v_mfma_f32_16x16x32_bf16 v[14:17], v[158:161], v[182:185], v[14:17]
	v_mfma_f32_16x16x32_bf16 v[6:9], v[150:153], v[196:199], v[6:9]
	v_mfma_f32_16x16x32_bf16 v[2:5], v[158:161], v[196:199], v[2:5]
	s_setprio 0
	s_barrier
	s_add_i32 s36, s36, 2
	s_add_u32 s16, s16, 0x100
	s_addc_u32 s17, s17, 0
	s_add_u32 s34, s34, 0x100
	s_addc_u32 s35, s35, 0
	s_cmp_gt_u32 s36, 29
	s_cbranch_scc0 .LBB0_748

.LBB0_771:
	s_ashr_i32 s17, s16, 31
	s_lshl_b64 s[20:21], s[16:17], 20
	v_readlane_b32 s0, v254, 60
	s_add_u32 s20, s0, s20
	v_readlane_b32 s0, v254, 61
	s_addc_u32 s21, s0, s21
	s_and_b64 s[22:23], s[6:7], exec
	s_cselect_b32 s17, s21, s27
	s_cselect_b32 s40, s20, s26
	s_ashr_i32 s15, s14, 31
	s_lshl_b64 s[22:23], s[14:15], 20
	v_readlane_b32 s0, v254, 40
	v_readlane_b32 s1, v254, 41
	s_add_u32 s22, s0, s22
	s_addc_u32 s23, s1, s23
	s_and_b64 s[30:31], s[6:7], exec
	s_cselect_b32 s15, s23, s29
	s_cselect_b32 s41, s22, s28
	s_add_u32 s26, s26, 0x80080
	s_addc_u32 s27, s27, 0
	s_add_u32 s42, s28, 0x100
	s_addc_u32 s43, s29, 0
	s_mov_b32 s46, -2
	v_readlane_b32 s47, v255, 49
	s_nop 3
	s_cmp_eq_u32 s47, 4
	v_writelane_b32 v255, 4, 49
	s_cbranch_scc0 .Ltrip0_strict_3
	s_add_u32 s28, s26, 0xfff80080
	s_addc_u32 s29, s27, -1
	s_add_i32 s47, 0, 0x10000
	s_cmp_eq_u32 s46, 28
	s_cselect_b32 s31, s17, s29
	s_cselect_b32 s30, s40, s28
	s_cselect_b32 s29, s15, s43
	s_cselect_b32 s28, s41, s42
	s_add_i32 s55, 0, 0x14000
	v_add_u32_e32 v142, s47, v220
	v_add_u32_e32 v158, s55, v220
	ds_read_b128 v[130:133], v142
	ds_read_b128 v[134:137], v142 offset:1024
	ds_read_b128 v[138:141], v142 offset:2048
	ds_read_b128 v[142:145], v142 offset:3072
	ds_read_b128 v[146:149], v158
	ds_read_b128 v[150:153], v158 offset:1024
	ds_read_b128 v[154:157], v158 offset:2048
	ds_read_b128 v[158:161], v158 offset:3072
	v_lshl_add_u64 v[210:211], s[26:27], 0, v[202:203]
	s_add_i32 m0, s34, 0xc000
	ds_read_b128 v[162:165], v222
	ds_read_b128 v[166:169], v222 offset:1024
	ds_read_b128 v[170:173], v222 offset:2048
	ds_read_b128 v[174:177], v222 offset:3072
	ds_read_b128 v[178:181], v222 offset:4096
	ds_read_b128 v[182:185], v222 offset:5120
	ds_read_b128 v[196:199], v222 offset:6144
	ds_read_b128 v[206:209], v222 offset:7168
	global_load_lds_dwordx4 v[210:211], off
	s_add_i32 m0, s34, 0xe000
	v_lshl_add_u64 v[210:211], s[26:27], 0, v[204:205]
	global_load_lds_dwordx4 v[210:211], off
	s_waitcnt vmcnt(24) lgkmcnt(0)
	s_setprio 1
	s_barrier
	v_mfma_f32_16x16x32_bf16 v[126:129], v[130:133], v[162:165], 0
	v_mfma_f32_16x16x32_bf16 v[122:125], v[138:141], v[162:165], 0
	v_mfma_f32_16x16x32_bf16 v[110:113], v[130:133], v[170:173], 0
	v_mfma_f32_16x16x32_bf16 v[106:109], v[138:141], v[170:173], 0
	v_mfma_f32_16x16x32_bf16 v[94:97], v[130:133], v[178:181], 0
	v_mfma_f32_16x16x32_bf16 v[90:93], v[138:141], v[178:181], 0
	v_mfma_f32_16x16x32_bf16 v[78:81], v[130:133], v[196:199], 0
	v_mfma_f32_16x16x32_bf16 v[74:77], v[138:141], v[196:199], 0
	v_mfma_f32_16x16x32_bf16 v[126:129], v[134:137], v[166:169], v[126:129]
	v_mfma_f32_16x16x32_bf16 v[122:125], v[142:145], v[166:169], v[122:125]
	v_mfma_f32_16x16x32_bf16 v[110:113], v[134:137], v[174:177], v[110:113]
	v_mfma_f32_16x16x32_bf16 v[106:109], v[142:145], v[174:177], v[106:109]
	v_mfma_f32_16x16x32_bf16 v[94:97], v[134:137], v[182:185], v[94:97]
	v_mfma_f32_16x16x32_bf16 v[90:93], v[142:145], v[182:185], v[90:93]
	v_mfma_f32_16x16x32_bf16 v[78:81], v[134:137], v[206:209], v[78:81]
	v_mfma_f32_16x16x32_bf16 v[74:77], v[142:145], v[206:209], v[74:77]
	v_mfma_f32_16x16x32_bf16 v[118:121], v[146:149], v[162:165], 0
	v_mfma_f32_16x16x32_bf16 v[114:117], v[154:157], v[162:165], 0
	v_mfma_f32_16x16x32_bf16 v[102:105], v[146:149], v[170:173], 0
	v_mfma_f32_16x16x32_bf16 v[98:101], v[154:157], v[170:173], 0
	v_mfma_f32_16x16x32_bf16 v[86:89], v[146:149], v[178:181], 0
	v_mfma_f32_16x16x32_bf16 v[82:85], v[154:157], v[178:181], 0
	v_mfma_f32_16x16x32_bf16 v[70:73], v[146:149], v[196:199], 0
	v_mfma_f32_16x16x32_bf16 v[66:69], v[154:157], v[196:199], 0
	v_mfma_f32_16x16x32_bf16 v[118:121], v[150:153], v[166:169], v[118:121]
	v_mfma_f32_16x16x32_bf16 v[114:117], v[158:161], v[166:169], v[114:117]
	v_mfma_f32_16x16x32_bf16 v[102:105], v[150:153], v[174:177], v[102:105]
	v_mfma_f32_16x16x32_bf16 v[98:101], v[158:161], v[174:177], v[98:101]
	v_mfma_f32_16x16x32_bf16 v[86:89], v[150:153], v[182:185], v[86:89]
	v_mfma_f32_16x16x32_bf16 v[82:85], v[158:161], v[182:185], v[82:85]
	v_mfma_f32_16x16x32_bf16 v[70:73], v[150:153], v[206:209], v[70:73]
	v_mfma_f32_16x16x32_bf16 v[66:69], v[158:161], v[206:209], v[66:69]
	s_barrier
	s_setprio 0
	s_add_i32 s47, s47, s33
	v_lshl_add_u64 v[210:211], s[28:29], 0, v[190:191]
	s_mov_b32 m0, s47
	ds_read_b128 v[162:165], v222 offset:16384
	ds_read_b128 v[166:169], v222 offset:17408
	ds_read_b128 v[170:173], v222 offset:18432
	ds_read_b128 v[174:177], v222 offset:19456
	ds_read_b128 v[178:181], v222 offset:20480
	ds_read_b128 v[182:185], v222 offset:21504
	ds_read_b128 v[196:199], v222 offset:22528
	ds_read_b128 v[206:209], v222 offset:23552
	global_load_lds_dwordx4 v[210:211], off
	s_add_i32 m0, s47, 0x2000
	s_add_u32 s52, s28, 0x80000
	v_lshl_add_u64 v[212:213], s[28:29], 0, v[200:201]
	s_addc_u32 s53, s29, 0
	s_add_i32 s47, s55, s33
	global_load_lds_dwordx4 v[212:213], off
	v_lshl_add_u64 v[214:215], s[52:53], 0, v[190:191]
	s_mov_b32 m0, s47
	v_lshl_add_u64 v[216:217], s[30:31], 0, v[188:189]
	global_load_lds_dwordx4 v[214:215], off
	s_add_i32 m0, s47, 0x2000
	v_lshl_add_u64 v[214:215], s[52:53], 0, v[200:201]
	global_load_lds_dwordx4 v[214:215], off
	s_mov_b32 m0, s34
	v_lshl_add_u64 v[214:215], s[30:31], 0, v[186:187]
	global_load_lds_dwordx4 v[214:215], off
	s_mov_b32 m0, s35
	s_nop 0
	global_load_lds_dwordx4 v[216:217], off
	s_waitcnt vmcnt(24) lgkmcnt(0)
	s_setprio 1
	s_barrier
	v_mfma_f32_16x16x32_bf16 v[62:65], v[130:133], v[162:165], 0
	v_mfma_f32_16x16x32_bf16 v[58:61], v[138:141], v[162:165], 0
	v_mfma_f32_16x16x32_bf16 v[46:49], v[130:133], v[170:173], 0
	v_mfma_f32_16x16x32_bf16 v[42:45], v[138:141], v[170:173], 0
	v_mfma_f32_16x16x32_bf16 v[30:33], v[130:133], v[178:181], 0
	v_mfma_f32_16x16x32_bf16 v[26:29], v[138:141], v[178:181], 0
	v_mfma_f32_16x16x32_bf16 v[14:17], v[130:133], v[196:199], 0
	v_mfma_f32_16x16x32_bf16 v[10:13], v[138:141], v[196:199], 0
	v_mfma_f32_16x16x32_bf16 v[62:65], v[134:137], v[166:169], v[62:65]
	v_mfma_f32_16x16x32_bf16 v[58:61], v[142:145], v[166:169], v[58:61]
	v_mfma_f32_16x16x32_bf16 v[46:49], v[134:137], v[174:177], v[46:49]
	v_mfma_f32_16x16x32_bf16 v[42:45], v[142:145], v[174:177], v[42:45]
	v_mfma_f32_16x16x32_bf16 v[30:33], v[134:137], v[182:185], v[30:33]
	v_mfma_f32_16x16x32_bf16 v[26:29], v[142:145], v[182:185], v[26:29]
	v_mfma_f32_16x16x32_bf16 v[14:17], v[134:137], v[206:209], v[14:17]
	v_mfma_f32_16x16x32_bf16 v[10:13], v[142:145], v[206:209], v[10:13]
	v_mfma_f32_16x16x32_bf16 v[54:57], v[146:149], v[162:165], 0
	v_mfma_f32_16x16x32_bf16 v[50:53], v[154:157], v[162:165], 0
	v_mfma_f32_16x16x32_bf16 v[38:41], v[146:149], v[170:173], 0
	v_mfma_f32_16x16x32_bf16 v[34:37], v[154:157], v[170:173], 0
	v_mfma_f32_16x16x32_bf16 v[22:25], v[146:149], v[178:181], 0
	v_mfma_f32_16x16x32_bf16 v[18:21], v[154:157], v[178:181], 0
	v_mfma_f32_16x16x32_bf16 v[6:9], v[146:149], v[196:199], 0
	v_mfma_f32_16x16x32_bf16 v[2:5], v[154:157], v[196:199], 0
	v_mfma_f32_16x16x32_bf16 v[54:57], v[150:153], v[166:169], v[54:57]
	v_mfma_f32_16x16x32_bf16 v[50:53], v[158:161], v[166:169], v[50:53]
	v_mfma_f32_16x16x32_bf16 v[38:41], v[150:153], v[174:177], v[38:41]
	v_mfma_f32_16x16x32_bf16 v[34:37], v[158:161], v[174:177], v[34:37]
	v_mfma_f32_16x16x32_bf16 v[22:25], v[150:153], v[182:185], v[22:25]
	v_mfma_f32_16x16x32_bf16 v[18:21], v[158:161], v[182:185], v[18:21]
	v_mfma_f32_16x16x32_bf16 v[6:9], v[150:153], v[206:209], v[6:9]
	v_mfma_f32_16x16x32_bf16 v[2:5], v[158:161], v[206:209], v[2:5]
	s_barrier
	s_setprio 0
	s_add_i32 s47, 0, 0x18000
	s_add_i32 s52, 0, 0x1c000
	v_add_u32_e32 v142, s47, v220
	v_add_u32_e32 v158, s52, v220
	ds_read_b128 v[130:133], v142
	ds_read_b128 v[134:137], v142 offset:1024
	ds_read_b128 v[138:141], v142 offset:2048
	ds_read_b128 v[142:145], v142 offset:3072
	ds_read_b128 v[146:149], v158
	ds_read_b128 v[150:153], v158 offset:1024
	ds_read_b128 v[154:157], v158 offset:2048
	ds_read_b128 v[158:161], v158 offset:3072
	s_add_u32 s30, s30, 0x80000
	s_addc_u32 s31, s31, 0
	s_mov_b32 m0, s36
	v_lshl_add_u64 v[218:219], s[30:31], 0, v[186:187]
	ds_read_b128 v[162:165], v222 offset:32768
	ds_read_b128 v[166:169], v222 offset:33792
	ds_read_b128 v[170:173], v222 offset:34816
	ds_read_b128 v[174:177], v222 offset:35840
	ds_read_b128 v[178:181], v222 offset:36864
	ds_read_b128 v[182:185], v222 offset:37888
	ds_read_b128 v[196:199], v222 offset:38912
	ds_read_b128 v[206:209], v222 offset:39936
	global_load_lds_dwordx4 v[218:219], off
	s_mov_b32 m0, s37
	v_lshl_add_u64 v[218:219], s[30:31], 0, v[188:189]
	global_load_lds_dwordx4 v[218:219], off
	s_waitcnt vmcnt(8) lgkmcnt(0)
	s_setprio 1
	s_barrier
	v_mfma_f32_16x16x32_bf16 v[126:129], v[130:133], v[162:165], v[126:129]
	v_mfma_f32_16x16x32_bf16 v[122:125], v[138:141], v[162:165], v[122:125]
	v_mfma_f32_16x16x32_bf16 v[110:113], v[130:133], v[170:173], v[110:113]
	v_mfma_f32_16x16x32_bf16 v[106:109], v[138:141], v[170:173], v[106:109]
	v_mfma_f32_16x16x32_bf16 v[94:97], v[130:133], v[178:181], v[94:97]
	v_mfma_f32_16x16x32_bf16 v[90:93], v[138:141], v[178:181], v[90:93]
	v_mfma_f32_16x16x32_bf16 v[78:81], v[130:133], v[196:199], v[78:81]
	v_mfma_f32_16x16x32_bf16 v[74:77], v[138:141], v[196:199], v[74:77]
	v_mfma_f32_16x16x32_bf16 v[126:129], v[134:137], v[166:169], v[126:129]
	v_mfma_f32_16x16x32_bf16 v[122:125], v[142:145], v[166:169], v[122:125]
	v_mfma_f32_16x16x32_bf16 v[110:113], v[134:137], v[174:177], v[110:113]
	v_mfma_f32_16x16x32_bf16 v[106:109], v[142:145], v[174:177], v[106:109]
	v_mfma_f32_16x16x32_bf16 v[94:97], v[134:137], v[182:185], v[94:97]
	v_mfma_f32_16x16x32_bf16 v[90:93], v[142:145], v[182:185], v[90:93]
	v_mfma_f32_16x16x32_bf16 v[78:81], v[134:137], v[206:209], v[78:81]
	v_mfma_f32_16x16x32_bf16 v[74:77], v[142:145], v[206:209], v[74:77]
	v_mfma_f32_16x16x32_bf16 v[118:121], v[146:149], v[162:165], v[118:121]
	v_mfma_f32_16x16x32_bf16 v[114:117], v[154:157], v[162:165], v[114:117]
	v_mfma_f32_16x16x32_bf16 v[102:105], v[146:149], v[170:173], v[102:105]
	v_mfma_f32_16x16x32_bf16 v[98:101], v[154:157], v[170:173], v[98:101]
	v_mfma_f32_16x16x32_bf16 v[86:89], v[146:149], v[178:181], v[86:89]
	v_mfma_f32_16x16x32_bf16 v[82:85], v[154:157], v[178:181], v[82:85]
	v_mfma_f32_16x16x32_bf16 v[70:73], v[146:149], v[196:199], v[70:73]
	v_mfma_f32_16x16x32_bf16 v[66:69], v[154:157], v[196:199], v[66:69]
	v_mfma_f32_16x16x32_bf16 v[118:121], v[150:153], v[166:169], v[118:121]
	v_mfma_f32_16x16x32_bf16 v[114:117], v[158:161], v[166:169], v[114:117]
	v_mfma_f32_16x16x32_bf16 v[102:105], v[150:153], v[174:177], v[102:105]
	v_mfma_f32_16x16x32_bf16 v[98:101], v[158:161], v[174:177], v[98:101]
	v_mfma_f32_16x16x32_bf16 v[86:89], v[150:153], v[182:185], v[86:89]
	v_mfma_f32_16x16x32_bf16 v[82:85], v[158:161], v[182:185], v[82:85]
	v_mfma_f32_16x16x32_bf16 v[70:73], v[150:153], v[206:209], v[70:73]
	v_mfma_f32_16x16x32_bf16 v[66:69], v[158:161], v[206:209], v[66:69]
	s_barrier
	s_setprio 0
	s_add_i32 s30, s47, s33
	v_lshl_add_u64 v[210:211], v[210:211], 0, s[58:59]
	s_mov_b32 m0, s30
	ds_read_b128 v[162:165], v222 offset:49152
	ds_read_b128 v[166:169], v222 offset:50176
	ds_read_b128 v[170:173], v222 offset:51200
	ds_read_b128 v[174:177], v222 offset:52224
	ds_read_b128 v[178:181], v222 offset:53248
	ds_read_b128 v[182:185], v222 offset:54272
	ds_read_b128 v[196:199], v222 offset:55296
	ds_read_b128 v[206:209], v222 offset:56320
	global_load_lds_dwordx4 v[210:211], off
	s_add_i32 m0, s30, 0x2000
	s_add_u32 s28, s28, 0x80080
	v_lshl_add_u64 v[210:211], v[212:213], 0, s[58:59]
	s_addc_u32 s29, s29, 0
	s_add_i32 s30, s52, s33
	global_load_lds_dwordx4 v[210:211], off
	s_mov_b32 m0, s30
	v_lshl_add_u64 v[210:211], s[28:29], 0, v[190:191]
	global_load_lds_dwordx4 v[210:211], off
	s_add_i32 m0, s30, 0x2000
	v_lshl_add_u64 v[210:211], s[28:29], 0, v[200:201]
	global_load_lds_dwordx4 v[210:211], off
	s_mov_b32 m0, s38
	v_lshl_add_u64 v[210:211], v[214:215], 0, s[58:59]
	global_load_lds_dwordx4 v[210:211], off
	s_mov_b32 m0, s39
	v_lshl_add_u64 v[210:211], v[216:217], 0, s[58:59]
	global_load_lds_dwordx4 v[210:211], off
	s_waitcnt vmcnt(8) lgkmcnt(0)
	s_setprio 1
	s_barrier
	v_mfma_f32_16x16x32_bf16 v[62:65], v[130:133], v[162:165], v[62:65]
	v_mfma_f32_16x16x32_bf16 v[58:61], v[138:141], v[162:165], v[58:61]
	v_mfma_f32_16x16x32_bf16 v[46:49], v[130:133], v[170:173], v[46:49]
	v_mfma_f32_16x16x32_bf16 v[42:45], v[138:141], v[170:173], v[42:45]
	v_mfma_f32_16x16x32_bf16 v[30:33], v[130:133], v[178:181], v[30:33]
	v_mfma_f32_16x16x32_bf16 v[26:29], v[138:141], v[178:181], v[26:29]
	v_mfma_f32_16x16x32_bf16 v[14:17], v[130:133], v[196:199], v[14:17]
	v_mfma_f32_16x16x32_bf16 v[10:13], v[138:141], v[196:199], v[10:13]
	v_mfma_f32_16x16x32_bf16 v[62:65], v[134:137], v[166:169], v[62:65]
	v_mfma_f32_16x16x32_bf16 v[58:61], v[142:145], v[166:169], v[58:61]
	v_mfma_f32_16x16x32_bf16 v[46:49], v[134:137], v[174:177], v[46:49]
	v_mfma_f32_16x16x32_bf16 v[42:45], v[142:145], v[174:177], v[42:45]
	v_mfma_f32_16x16x32_bf16 v[30:33], v[134:137], v[182:185], v[30:33]
	v_mfma_f32_16x16x32_bf16 v[26:29], v[142:145], v[182:185], v[26:29]
	v_mfma_f32_16x16x32_bf16 v[14:17], v[134:137], v[206:209], v[14:17]
	v_mfma_f32_16x16x32_bf16 v[10:13], v[142:145], v[206:209], v[10:13]
	v_mfma_f32_16x16x32_bf16 v[54:57], v[146:149], v[162:165], v[54:57]
	v_mfma_f32_16x16x32_bf16 v[50:53], v[154:157], v[162:165], v[50:53]
	v_mfma_f32_16x16x32_bf16 v[38:41], v[146:149], v[170:173], v[38:41]
	v_mfma_f32_16x16x32_bf16 v[34:37], v[154:157], v[170:173], v[34:37]
	v_mfma_f32_16x16x32_bf16 v[22:25], v[146:149], v[178:181], v[22:25]
	v_mfma_f32_16x16x32_bf16 v[18:21], v[154:157], v[178:181], v[18:21]
	v_mfma_f32_16x16x32_bf16 v[6:9], v[146:149], v[196:199], v[6:9]
	v_mfma_f32_16x16x32_bf16 v[2:5], v[154:157], v[196:199], v[2:5]
	v_mfma_f32_16x16x32_bf16 v[54:57], v[150:153], v[166:169], v[54:57]
	v_mfma_f32_16x16x32_bf16 v[50:53], v[158:161], v[166:169], v[50:53]
	v_mfma_f32_16x16x32_bf16 v[38:41], v[150:153], v[174:177], v[38:41]
	v_mfma_f32_16x16x32_bf16 v[34:37], v[158:161], v[174:177], v[34:37]
	v_mfma_f32_16x16x32_bf16 v[22:25], v[150:153], v[182:185], v[22:25]
	v_mfma_f32_16x16x32_bf16 v[18:21], v[158:161], v[182:185], v[18:21]
	v_mfma_f32_16x16x32_bf16 v[6:9], v[150:153], v[206:209], v[6:9]
	v_mfma_f32_16x16x32_bf16 v[2:5], v[158:161], v[206:209], v[2:5]
	s_barrier
	s_setprio 0
	s_add_i32 s46, s46, 2
	s_add_u32 s26, s26, 0x100
	s_addc_u32 s27, s27, 0
	s_add_u32 s42, s42, 0x100
	s_addc_u32 s43, s43, 0
	s_cmp_gt_u32 s46, 29
	s_cbranch_scc1 .Lpeel_done_3
	s_branch .LBB0_772
.Ltrip0_strict_3:
	s_add_u32 s28, s26, 0xfff80080
	s_addc_u32 s29, s27, -1
	s_add_i32 s47, 0, 0x10000
	s_cmp_eq_u32 s46, 28
	s_cselect_b32 s31, s17, s29
	s_cselect_b32 s30, s40, s28
	s_cselect_b32 s29, s15, s43
	s_cselect_b32 s28, s41, s42
	s_add_i32 s55, 0, 0x14000
	v_add_u32_e32 v142, s47, v220
	v_add_u32_e32 v158, s55, v220
	ds_read_b128 v[130:133], v142
	ds_read_b128 v[134:137], v142 offset:1024
	ds_read_b128 v[138:141], v142 offset:2048
	ds_read_b128 v[142:145], v142 offset:3072
	ds_read_b128 v[146:149], v158
	ds_read_b128 v[150:153], v158 offset:1024
	ds_read_b128 v[154:157], v158 offset:2048
	ds_read_b128 v[158:161], v158 offset:3072
	v_lshl_add_u64 v[210:211], s[26:27], 0, v[202:203]
	s_add_i32 m0, s34, 0xc000
	ds_read_b128 v[162:165], v222
	ds_read_b128 v[166:169], v222 offset:1024
	ds_read_b128 v[170:173], v222 offset:2048
	ds_read_b128 v[174:177], v222 offset:3072
	ds_read_b128 v[178:181], v222 offset:4096
	ds_read_b128 v[182:185], v222 offset:5120
	ds_read_b128 v[196:199], v222 offset:6144
	ds_read_b128 v[206:209], v222 offset:7168
	global_load_lds_dwordx4 v[210:211], off
	s_add_i32 m0, s34, 0xe000
	v_lshl_add_u64 v[210:211], s[26:27], 0, v[204:205]
	global_load_lds_dwordx4 v[210:211], off
	s_waitcnt vmcnt(8) lgkmcnt(0)
	s_setprio 1
	s_barrier
	v_mfma_f32_16x16x32_bf16 v[126:129], v[130:133], v[162:165], 0
	v_mfma_f32_16x16x32_bf16 v[122:125], v[138:141], v[162:165], 0
	v_mfma_f32_16x16x32_bf16 v[110:113], v[130:133], v[170:173], 0
	v_mfma_f32_16x16x32_bf16 v[106:109], v[138:141], v[170:173], 0
	v_mfma_f32_16x16x32_bf16 v[94:97], v[130:133], v[178:181], 0
	v_mfma_f32_16x16x32_bf16 v[90:93], v[138:141], v[178:181], 0
	v_mfma_f32_16x16x32_bf16 v[78:81], v[130:133], v[196:199], 0
	v_mfma_f32_16x16x32_bf16 v[74:77], v[138:141], v[196:199], 0
	v_mfma_f32_16x16x32_bf16 v[126:129], v[134:137], v[166:169], v[126:129]
	v_mfma_f32_16x16x32_bf16 v[122:125], v[142:145], v[166:169], v[122:125]
	v_mfma_f32_16x16x32_bf16 v[110:113], v[134:137], v[174:177], v[110:113]
	v_mfma_f32_16x16x32_bf16 v[106:109], v[142:145], v[174:177], v[106:109]
	v_mfma_f32_16x16x32_bf16 v[94:97], v[134:137], v[182:185], v[94:97]
	v_mfma_f32_16x16x32_bf16 v[90:93], v[142:145], v[182:185], v[90:93]
	v_mfma_f32_16x16x32_bf16 v[78:81], v[134:137], v[206:209], v[78:81]
	v_mfma_f32_16x16x32_bf16 v[74:77], v[142:145], v[206:209], v[74:77]
	v_mfma_f32_16x16x32_bf16 v[118:121], v[146:149], v[162:165], 0
	v_mfma_f32_16x16x32_bf16 v[114:117], v[154:157], v[162:165], 0
	v_mfma_f32_16x16x32_bf16 v[102:105], v[146:149], v[170:173], 0
	v_mfma_f32_16x16x32_bf16 v[98:101], v[154:157], v[170:173], 0
	v_mfma_f32_16x16x32_bf16 v[86:89], v[146:149], v[178:181], 0
	v_mfma_f32_16x16x32_bf16 v[82:85], v[154:157], v[178:181], 0
	v_mfma_f32_16x16x32_bf16 v[70:73], v[146:149], v[196:199], 0
	v_mfma_f32_16x16x32_bf16 v[66:69], v[154:157], v[196:199], 0
	v_mfma_f32_16x16x32_bf16 v[118:121], v[150:153], v[166:169], v[118:121]
	v_mfma_f32_16x16x32_bf16 v[114:117], v[158:161], v[166:169], v[114:117]
	v_mfma_f32_16x16x32_bf16 v[102:105], v[150:153], v[174:177], v[102:105]
	v_mfma_f32_16x16x32_bf16 v[98:101], v[158:161], v[174:177], v[98:101]
	v_mfma_f32_16x16x32_bf16 v[86:89], v[150:153], v[182:185], v[86:89]
	v_mfma_f32_16x16x32_bf16 v[82:85], v[158:161], v[182:185], v[82:85]
	v_mfma_f32_16x16x32_bf16 v[70:73], v[150:153], v[206:209], v[70:73]
	v_mfma_f32_16x16x32_bf16 v[66:69], v[158:161], v[206:209], v[66:69]
	s_barrier
	s_setprio 0
	s_add_i32 s47, s47, s33
	v_lshl_add_u64 v[210:211], s[28:29], 0, v[190:191]
	s_mov_b32 m0, s47
	ds_read_b128 v[162:165], v222 offset:16384
	ds_read_b128 v[166:169], v222 offset:17408
	ds_read_b128 v[170:173], v222 offset:18432
	ds_read_b128 v[174:177], v222 offset:19456
	ds_read_b128 v[178:181], v222 offset:20480
	ds_read_b128 v[182:185], v222 offset:21504
	ds_read_b128 v[196:199], v222 offset:22528
	ds_read_b128 v[206:209], v222 offset:23552
	global_load_lds_dwordx4 v[210:211], off
	s_add_i32 m0, s47, 0x2000
	s_add_u32 s52, s28, 0x80000
	v_lshl_add_u64 v[212:213], s[28:29], 0, v[200:201]
	s_addc_u32 s53, s29, 0
	s_add_i32 s47, s55, s33
	global_load_lds_dwordx4 v[212:213], off
	v_lshl_add_u64 v[214:215], s[52:53], 0, v[190:191]
	s_mov_b32 m0, s47
	v_lshl_add_u64 v[216:217], s[30:31], 0, v[188:189]
	global_load_lds_dwordx4 v[214:215], off
	s_add_i32 m0, s47, 0x2000
	v_lshl_add_u64 v[214:215], s[52:53], 0, v[200:201]
	global_load_lds_dwordx4 v[214:215], off
	s_mov_b32 m0, s34
	v_lshl_add_u64 v[214:215], s[30:31], 0, v[186:187]
	global_load_lds_dwordx4 v[214:215], off
	s_mov_b32 m0, s35
	s_nop 0
	global_load_lds_dwordx4 v[216:217], off
	s_waitcnt vmcnt(8) lgkmcnt(0)
	s_setprio 1
	s_barrier
	v_mfma_f32_16x16x32_bf16 v[62:65], v[130:133], v[162:165], 0
	v_mfma_f32_16x16x32_bf16 v[58:61], v[138:141], v[162:165], 0
	v_mfma_f32_16x16x32_bf16 v[46:49], v[130:133], v[170:173], 0
	v_mfma_f32_16x16x32_bf16 v[42:45], v[138:141], v[170:173], 0
	v_mfma_f32_16x16x32_bf16 v[30:33], v[130:133], v[178:181], 0
	v_mfma_f32_16x16x32_bf16 v[26:29], v[138:141], v[178:181], 0
	v_mfma_f32_16x16x32_bf16 v[14:17], v[130:133], v[196:199], 0
	v_mfma_f32_16x16x32_bf16 v[10:13], v[138:141], v[196:199], 0
	v_mfma_f32_16x16x32_bf16 v[62:65], v[134:137], v[166:169], v[62:65]
	v_mfma_f32_16x16x32_bf16 v[58:61], v[142:145], v[166:169], v[58:61]
	v_mfma_f32_16x16x32_bf16 v[46:49], v[134:137], v[174:177], v[46:49]
	v_mfma_f32_16x16x32_bf16 v[42:45], v[142:145], v[174:177], v[42:45]
	v_mfma_f32_16x16x32_bf16 v[30:33], v[134:137], v[182:185], v[30:33]
	v_mfma_f32_16x16x32_bf16 v[26:29], v[142:145], v[182:185], v[26:29]
	v_mfma_f32_16x16x32_bf16 v[14:17], v[134:137], v[206:209], v[14:17]
	v_mfma_f32_16x16x32_bf16 v[10:13], v[142:145], v[206:209], v[10:13]
	v_mfma_f32_16x16x32_bf16 v[54:57], v[146:149], v[162:165], 0
	v_mfma_f32_16x16x32_bf16 v[50:53], v[154:157], v[162:165], 0
	v_mfma_f32_16x16x32_bf16 v[38:41], v[146:149], v[170:173], 0
	v_mfma_f32_16x16x32_bf16 v[34:37], v[154:157], v[170:173], 0
	v_mfma_f32_16x16x32_bf16 v[22:25], v[146:149], v[178:181], 0
	v_mfma_f32_16x16x32_bf16 v[18:21], v[154:157], v[178:181], 0
	v_mfma_f32_16x16x32_bf16 v[6:9], v[146:149], v[196:199], 0
	v_mfma_f32_16x16x32_bf16 v[2:5], v[154:157], v[196:199], 0
	v_mfma_f32_16x16x32_bf16 v[54:57], v[150:153], v[166:169], v[54:57]
	v_mfma_f32_16x16x32_bf16 v[50:53], v[158:161], v[166:169], v[50:53]
	v_mfma_f32_16x16x32_bf16 v[38:41], v[150:153], v[174:177], v[38:41]
	v_mfma_f32_16x16x32_bf16 v[34:37], v[158:161], v[174:177], v[34:37]
	v_mfma_f32_16x16x32_bf16 v[22:25], v[150:153], v[182:185], v[22:25]
	v_mfma_f32_16x16x32_bf16 v[18:21], v[158:161], v[182:185], v[18:21]
	v_mfma_f32_16x16x32_bf16 v[6:9], v[150:153], v[206:209], v[6:9]
	v_mfma_f32_16x16x32_bf16 v[2:5], v[158:161], v[206:209], v[2:5]
	s_barrier
	s_setprio 0
	s_add_i32 s47, 0, 0x18000
	s_add_i32 s52, 0, 0x1c000
	v_add_u32_e32 v142, s47, v220
	v_add_u32_e32 v158, s52, v220
	ds_read_b128 v[130:133], v142
	ds_read_b128 v[134:137], v142 offset:1024
	ds_read_b128 v[138:141], v142 offset:2048
	ds_read_b128 v[142:145], v142 offset:3072
	ds_read_b128 v[146:149], v158
	ds_read_b128 v[150:153], v158 offset:1024
	ds_read_b128 v[154:157], v158 offset:2048
	ds_read_b128 v[158:161], v158 offset:3072
	s_add_u32 s30, s30, 0x80000
	s_addc_u32 s31, s31, 0
	s_mov_b32 m0, s36
	v_lshl_add_u64 v[218:219], s[30:31], 0, v[186:187]
	ds_read_b128 v[162:165], v222 offset:32768
	ds_read_b128 v[166:169], v222 offset:33792
	ds_read_b128 v[170:173], v222 offset:34816
	ds_read_b128 v[174:177], v222 offset:35840
	ds_read_b128 v[178:181], v222 offset:36864
	ds_read_b128 v[182:185], v222 offset:37888
	ds_read_b128 v[196:199], v222 offset:38912
	ds_read_b128 v[206:209], v222 offset:39936
	global_load_lds_dwordx4 v[218:219], off
	s_mov_b32 m0, s37
	v_lshl_add_u64 v[218:219], s[30:31], 0, v[188:189]
	global_load_lds_dwordx4 v[218:219], off
	s_waitcnt vmcnt(8) lgkmcnt(0)
	s_setprio 1
	s_barrier
	v_mfma_f32_16x16x32_bf16 v[126:129], v[130:133], v[162:165], v[126:129]
	v_mfma_f32_16x16x32_bf16 v[122:125], v[138:141], v[162:165], v[122:125]
	v_mfma_f32_16x16x32_bf16 v[110:113], v[130:133], v[170:173], v[110:113]
	v_mfma_f32_16x16x32_bf16 v[106:109], v[138:141], v[170:173], v[106:109]
	v_mfma_f32_16x16x32_bf16 v[94:97], v[130:133], v[178:181], v[94:97]
	v_mfma_f32_16x16x32_bf16 v[90:93], v[138:141], v[178:181], v[90:93]
	v_mfma_f32_16x16x32_bf16 v[78:81], v[130:133], v[196:199], v[78:81]
	v_mfma_f32_16x16x32_bf16 v[74:77], v[138:141], v[196:199], v[74:77]
	v_mfma_f32_16x16x32_bf16 v[126:129], v[134:137], v[166:169], v[126:129]
	v_mfma_f32_16x16x32_bf16 v[122:125], v[142:145], v[166:169], v[122:125]
	v_mfma_f32_16x16x32_bf16 v[110:113], v[134:137], v[174:177], v[110:113]
	v_mfma_f32_16x16x32_bf16 v[106:109], v[142:145], v[174:177], v[106:109]
	v_mfma_f32_16x16x32_bf16 v[94:97], v[134:137], v[182:185], v[94:97]
	v_mfma_f32_16x16x32_bf16 v[90:93], v[142:145], v[182:185], v[90:93]
	v_mfma_f32_16x16x32_bf16 v[78:81], v[134:137], v[206:209], v[78:81]
	v_mfma_f32_16x16x32_bf16 v[74:77], v[142:145], v[206:209], v[74:77]
	v_mfma_f32_16x16x32_bf16 v[118:121], v[146:149], v[162:165], v[118:121]
	v_mfma_f32_16x16x32_bf16 v[114:117], v[154:157], v[162:165], v[114:117]
	v_mfma_f32_16x16x32_bf16 v[102:105], v[146:149], v[170:173], v[102:105]
	v_mfma_f32_16x16x32_bf16 v[98:101], v[154:157], v[170:173], v[98:101]
	v_mfma_f32_16x16x32_bf16 v[86:89], v[146:149], v[178:181], v[86:89]
	v_mfma_f32_16x16x32_bf16 v[82:85], v[154:157], v[178:181], v[82:85]
	v_mfma_f32_16x16x32_bf16 v[70:73], v[146:149], v[196:199], v[70:73]
	v_mfma_f32_16x16x32_bf16 v[66:69], v[154:157], v[196:199], v[66:69]
	v_mfma_f32_16x16x32_bf16 v[118:121], v[150:153], v[166:169], v[118:121]
	v_mfma_f32_16x16x32_bf16 v[114:117], v[158:161], v[166:169], v[114:117]
	v_mfma_f32_16x16x32_bf16 v[102:105], v[150:153], v[174:177], v[102:105]
	v_mfma_f32_16x16x32_bf16 v[98:101], v[158:161], v[174:177], v[98:101]
	v_mfma_f32_16x16x32_bf16 v[86:89], v[150:153], v[182:185], v[86:89]
	v_mfma_f32_16x16x32_bf16 v[82:85], v[158:161], v[182:185], v[82:85]
	v_mfma_f32_16x16x32_bf16 v[70:73], v[150:153], v[206:209], v[70:73]
	v_mfma_f32_16x16x32_bf16 v[66:69], v[158:161], v[206:209], v[66:69]
	s_barrier
	s_setprio 0
	s_add_i32 s30, s47, s33
	v_lshl_add_u64 v[210:211], v[210:211], 0, s[58:59]
	s_mov_b32 m0, s30
	ds_read_b128 v[162:165], v222 offset:49152
	ds_read_b128 v[166:169], v222 offset:50176
	ds_read_b128 v[170:173], v222 offset:51200
	ds_read_b128 v[174:177], v222 offset:52224
	ds_read_b128 v[178:181], v222 offset:53248
	ds_read_b128 v[182:185], v222 offset:54272
	ds_read_b128 v[196:199], v222 offset:55296
	ds_read_b128 v[206:209], v222 offset:56320
	global_load_lds_dwordx4 v[210:211], off
	s_add_i32 m0, s30, 0x2000
	s_add_u32 s28, s28, 0x80080
	v_lshl_add_u64 v[210:211], v[212:213], 0, s[58:59]
	s_addc_u32 s29, s29, 0
	s_add_i32 s30, s52, s33
	global_load_lds_dwordx4 v[210:211], off
	s_mov_b32 m0, s30
	v_lshl_add_u64 v[210:211], s[28:29], 0, v[190:191]
	global_load_lds_dwordx4 v[210:211], off
	s_add_i32 m0, s30, 0x2000
	v_lshl_add_u64 v[210:211], s[28:29], 0, v[200:201]
	global_load_lds_dwordx4 v[210:211], off
	s_mov_b32 m0, s38
	v_lshl_add_u64 v[210:211], v[214:215], 0, s[58:59]
	global_load_lds_dwordx4 v[210:211], off
	s_mov_b32 m0, s39
	v_lshl_add_u64 v[210:211], v[216:217], 0, s[58:59]
	global_load_lds_dwordx4 v[210:211], off
	s_waitcnt vmcnt(8) lgkmcnt(0)
	s_setprio 1
	s_barrier
	v_mfma_f32_16x16x32_bf16 v[62:65], v[130:133], v[162:165], v[62:65]
	v_mfma_f32_16x16x32_bf16 v[58:61], v[138:141], v[162:165], v[58:61]
	v_mfma_f32_16x16x32_bf16 v[46:49], v[130:133], v[170:173], v[46:49]
	v_mfma_f32_16x16x32_bf16 v[42:45], v[138:141], v[170:173], v[42:45]
	v_mfma_f32_16x16x32_bf16 v[30:33], v[130:133], v[178:181], v[30:33]
	v_mfma_f32_16x16x32_bf16 v[26:29], v[138:141], v[178:181], v[26:29]
	v_mfma_f32_16x16x32_bf16 v[14:17], v[130:133], v[196:199], v[14:17]
	v_mfma_f32_16x16x32_bf16 v[10:13], v[138:141], v[196:199], v[10:13]
	v_mfma_f32_16x16x32_bf16 v[62:65], v[134:137], v[166:169], v[62:65]
	v_mfma_f32_16x16x32_bf16 v[58:61], v[142:145], v[166:169], v[58:61]
	v_mfma_f32_16x16x32_bf16 v[46:49], v[134:137], v[174:177], v[46:49]
	v_mfma_f32_16x16x32_bf16 v[42:45], v[142:145], v[174:177], v[42:45]
	v_mfma_f32_16x16x32_bf16 v[30:33], v[134:137], v[182:185], v[30:33]
	v_mfma_f32_16x16x32_bf16 v[26:29], v[142:145], v[182:185], v[26:29]
	v_mfma_f32_16x16x32_bf16 v[14:17], v[134:137], v[206:209], v[14:17]
	v_mfma_f32_16x16x32_bf16 v[10:13], v[142:145], v[206:209], v[10:13]
	v_mfma_f32_16x16x32_bf16 v[54:57], v[146:149], v[162:165], v[54:57]
	v_mfma_f32_16x16x32_bf16 v[50:53], v[154:157], v[162:165], v[50:53]
	v_mfma_f32_16x16x32_bf16 v[38:41], v[146:149], v[170:173], v[38:41]
	v_mfma_f32_16x16x32_bf16 v[34:37], v[154:157], v[170:173], v[34:37]
	v_mfma_f32_16x16x32_bf16 v[22:25], v[146:149], v[178:181], v[22:25]
	v_mfma_f32_16x16x32_bf16 v[18:21], v[154:157], v[178:181], v[18:21]
	v_mfma_f32_16x16x32_bf16 v[6:9], v[146:149], v[196:199], v[6:9]
	v_mfma_f32_16x16x32_bf16 v[2:5], v[154:157], v[196:199], v[2:5]
	v_mfma_f32_16x16x32_bf16 v[54:57], v[150:153], v[166:169], v[54:57]
	v_mfma_f32_16x16x32_bf16 v[50:53], v[158:161], v[166:169], v[50:53]
	v_mfma_f32_16x16x32_bf16 v[38:41], v[150:153], v[174:177], v[38:41]
	v_mfma_f32_16x16x32_bf16 v[34:37], v[158:161], v[174:177], v[34:37]
	v_mfma_f32_16x16x32_bf16 v[22:25], v[150:153], v[182:185], v[22:25]
	v_mfma_f32_16x16x32_bf16 v[18:21], v[158:161], v[182:185], v[18:21]
	v_mfma_f32_16x16x32_bf16 v[6:9], v[150:153], v[206:209], v[6:9]
	v_mfma_f32_16x16x32_bf16 v[2:5], v[158:161], v[206:209], v[2:5]
	s_barrier
	s_setprio 0
	s_add_i32 s46, s46, 2
	s_add_u32 s26, s26, 0x100
	s_addc_u32 s27, s27, 0
	s_add_u32 s42, s42, 0x100
	s_addc_u32 s43, s43, 0
	s_cmp_gt_u32 s46, 29
	s_cbranch_scc1 .Lpeel_done_3
.LBB0_772:
	s_add_u32 s28, s26, 0xfff80080
	s_addc_u32 s29, s27, -1
	s_add_i32 s47, 0, 0x10000
	s_cmp_eq_u32 s46, 28
	s_cselect_b32 s31, s17, s29
	s_cselect_b32 s30, s40, s28
	s_cselect_b32 s29, s15, s43
	s_cselect_b32 s28, s41, s42
	s_add_i32 s55, 0, 0x14000
	v_add_u32_e32 v142, s47, v220
	v_add_u32_e32 v158, s55, v220
	ds_read_b128 v[130:133], v142
	ds_read_b128 v[134:137], v142 offset:1024
	ds_read_b128 v[138:141], v142 offset:2048
	ds_read_b128 v[142:145], v142 offset:3072
	ds_read_b128 v[146:149], v158
	ds_read_b128 v[150:153], v158 offset:1024
	ds_read_b128 v[154:157], v158 offset:2048
	ds_read_b128 v[158:161], v158 offset:3072
	v_lshl_add_u64 v[210:211], s[26:27], 0, v[202:203]
	s_add_i32 m0, s34, 0xc000
	ds_read_b128 v[162:165], v222
	ds_read_b128 v[166:169], v222 offset:1024
	ds_read_b128 v[170:173], v222 offset:2048
	ds_read_b128 v[174:177], v222 offset:3072
	ds_read_b128 v[178:181], v222 offset:4096
	ds_read_b128 v[182:185], v222 offset:5120
	ds_read_b128 v[196:199], v222 offset:6144
	ds_read_b128 v[206:209], v222 offset:7168
	global_load_lds_dwordx4 v[210:211], off
	s_add_i32 m0, s34, 0xe000
	v_lshl_add_u64 v[210:211], s[26:27], 0, v[204:205]
	global_load_lds_dwordx4 v[210:211], off
	s_waitcnt vmcnt(8) lgkmcnt(0)
	s_setprio 1
	s_barrier
	v_mfma_f32_16x16x32_bf16 v[126:129], v[130:133], v[162:165], v[126:129]
	v_mfma_f32_16x16x32_bf16 v[122:125], v[138:141], v[162:165], v[122:125]
	v_mfma_f32_16x16x32_bf16 v[110:113], v[130:133], v[170:173], v[110:113]
	v_mfma_f32_16x16x32_bf16 v[106:109], v[138:141], v[170:173], v[106:109]
	v_mfma_f32_16x16x32_bf16 v[94:97], v[130:133], v[178:181], v[94:97]
	v_mfma_f32_16x16x32_bf16 v[90:93], v[138:141], v[178:181], v[90:93]
	v_mfma_f32_16x16x32_bf16 v[78:81], v[130:133], v[196:199], v[78:81]
	v_mfma_f32_16x16x32_bf16 v[74:77], v[138:141], v[196:199], v[74:77]
	v_mfma_f32_16x16x32_bf16 v[126:129], v[134:137], v[166:169], v[126:129]
	v_mfma_f32_16x16x32_bf16 v[122:125], v[142:145], v[166:169], v[122:125]
	v_mfma_f32_16x16x32_bf16 v[110:113], v[134:137], v[174:177], v[110:113]
	v_mfma_f32_16x16x32_bf16 v[106:109], v[142:145], v[174:177], v[106:109]
	v_mfma_f32_16x16x32_bf16 v[94:97], v[134:137], v[182:185], v[94:97]
	v_mfma_f32_16x16x32_bf16 v[90:93], v[142:145], v[182:185], v[90:93]
	v_mfma_f32_16x16x32_bf16 v[78:81], v[134:137], v[206:209], v[78:81]
	v_mfma_f32_16x16x32_bf16 v[74:77], v[142:145], v[206:209], v[74:77]
	v_mfma_f32_16x16x32_bf16 v[118:121], v[146:149], v[162:165], v[118:121]
	v_mfma_f32_16x16x32_bf16 v[114:117], v[154:157], v[162:165], v[114:117]
	v_mfma_f32_16x16x32_bf16 v[102:105], v[146:149], v[170:173], v[102:105]
	v_mfma_f32_16x16x32_bf16 v[98:101], v[154:157], v[170:173], v[98:101]
	v_mfma_f32_16x16x32_bf16 v[86:89], v[146:149], v[178:181], v[86:89]
	v_mfma_f32_16x16x32_bf16 v[82:85], v[154:157], v[178:181], v[82:85]
	v_mfma_f32_16x16x32_bf16 v[70:73], v[146:149], v[196:199], v[70:73]
	v_mfma_f32_16x16x32_bf16 v[66:69], v[154:157], v[196:199], v[66:69]
	v_mfma_f32_16x16x32_bf16 v[118:121], v[150:153], v[166:169], v[118:121]
	v_mfma_f32_16x16x32_bf16 v[114:117], v[158:161], v[166:169], v[114:117]
	v_mfma_f32_16x16x32_bf16 v[102:105], v[150:153], v[174:177], v[102:105]
	v_mfma_f32_16x16x32_bf16 v[98:101], v[158:161], v[174:177], v[98:101]
	v_mfma_f32_16x16x32_bf16 v[86:89], v[150:153], v[182:185], v[86:89]
	v_mfma_f32_16x16x32_bf16 v[82:85], v[158:161], v[182:185], v[82:85]
	v_mfma_f32_16x16x32_bf16 v[70:73], v[150:153], v[206:209], v[70:73]
	v_mfma_f32_16x16x32_bf16 v[66:69], v[158:161], v[206:209], v[66:69]
	s_setprio 0
	s_barrier
	s_add_i32 s47, s47, s33
	v_lshl_add_u64 v[210:211], s[28:29], 0, v[190:191]
	s_mov_b32 m0, s47
	ds_read_b128 v[162:165], v222 offset:16384
	ds_read_b128 v[166:169], v222 offset:17408
	ds_read_b128 v[170:173], v222 offset:18432
	ds_read_b128 v[174:177], v222 offset:19456
	ds_read_b128 v[178:181], v222 offset:20480
	ds_read_b128 v[182:185], v222 offset:21504
	ds_read_b128 v[196:199], v222 offset:22528
	ds_read_b128 v[206:209], v222 offset:23552
	global_load_lds_dwordx4 v[210:211], off
	s_add_i32 m0, s47, 0x2000
	s_add_u32 s52, s28, 0x80000
	v_lshl_add_u64 v[212:213], s[28:29], 0, v[200:201]
	s_addc_u32 s53, s29, 0
	s_add_i32 s47, s55, s33
	global_load_lds_dwordx4 v[212:213], off
	v_lshl_add_u64 v[214:215], s[52:53], 0, v[190:191]
	s_mov_b32 m0, s47
	v_lshl_add_u64 v[216:217], s[30:31], 0, v[188:189]
	global_load_lds_dwordx4 v[214:215], off
	s_add_i32 m0, s47, 0x2000
	v_lshl_add_u64 v[214:215], s[52:53], 0, v[200:201]
	global_load_lds_dwordx4 v[214:215], off
	s_mov_b32 m0, s34
	v_lshl_add_u64 v[214:215], s[30:31], 0, v[186:187]
	global_load_lds_dwordx4 v[214:215], off
	s_mov_b32 m0, s35
	s_nop 0
	global_load_lds_dwordx4 v[216:217], off
	s_waitcnt vmcnt(8) lgkmcnt(0)
	s_setprio 1
	s_barrier
	v_mfma_f32_16x16x32_bf16 v[62:65], v[130:133], v[162:165], v[62:65]
	v_mfma_f32_16x16x32_bf16 v[58:61], v[138:141], v[162:165], v[58:61]
	v_mfma_f32_16x16x32_bf16 v[46:49], v[130:133], v[170:173], v[46:49]
	v_mfma_f32_16x16x32_bf16 v[42:45], v[138:141], v[170:173], v[42:45]
	v_mfma_f32_16x16x32_bf16 v[30:33], v[130:133], v[178:181], v[30:33]
	v_mfma_f32_16x16x32_bf16 v[26:29], v[138:141], v[178:181], v[26:29]
	v_mfma_f32_16x16x32_bf16 v[14:17], v[130:133], v[196:199], v[14:17]
	v_mfma_f32_16x16x32_bf16 v[10:13], v[138:141], v[196:199], v[10:13]
	v_mfma_f32_16x16x32_bf16 v[62:65], v[134:137], v[166:169], v[62:65]
	v_mfma_f32_16x16x32_bf16 v[58:61], v[142:145], v[166:169], v[58:61]
	v_mfma_f32_16x16x32_bf16 v[46:49], v[134:137], v[174:177], v[46:49]
	v_mfma_f32_16x16x32_bf16 v[42:45], v[142:145], v[174:177], v[42:45]
	v_mfma_f32_16x16x32_bf16 v[30:33], v[134:137], v[182:185], v[30:33]
	v_mfma_f32_16x16x32_bf16 v[26:29], v[142:145], v[182:185], v[26:29]
	v_mfma_f32_16x16x32_bf16 v[14:17], v[134:137], v[206:209], v[14:17]
	v_mfma_f32_16x16x32_bf16 v[10:13], v[142:145], v[206:209], v[10:13]
	v_mfma_f32_16x16x32_bf16 v[54:57], v[146:149], v[162:165], v[54:57]
	v_mfma_f32_16x16x32_bf16 v[50:53], v[154:157], v[162:165], v[50:53]
	v_mfma_f32_16x16x32_bf16 v[38:41], v[146:149], v[170:173], v[38:41]
	v_mfma_f32_16x16x32_bf16 v[34:37], v[154:157], v[170:173], v[34:37]
	v_mfma_f32_16x16x32_bf16 v[22:25], v[146:149], v[178:181], v[22:25]
	v_mfma_f32_16x16x32_bf16 v[18:21], v[154:157], v[178:181], v[18:21]
	v_mfma_f32_16x16x32_bf16 v[6:9], v[146:149], v[196:199], v[6:9]
	v_mfma_f32_16x16x32_bf16 v[2:5], v[154:157], v[196:199], v[2:5]
	v_mfma_f32_16x16x32_bf16 v[54:57], v[150:153], v[166:169], v[54:57]
	v_mfma_f32_16x16x32_bf16 v[50:53], v[158:161], v[166:169], v[50:53]
	v_mfma_f32_16x16x32_bf16 v[38:41], v[150:153], v[174:177], v[38:41]
	v_mfma_f32_16x16x32_bf16 v[34:37], v[158:161], v[174:177], v[34:37]
	v_mfma_f32_16x16x32_bf16 v[22:25], v[150:153], v[182:185], v[22:25]
	v_mfma_f32_16x16x32_bf16 v[18:21], v[158:161], v[182:185], v[18:21]
	v_mfma_f32_16x16x32_bf16 v[6:9], v[150:153], v[206:209], v[6:9]
	v_mfma_f32_16x16x32_bf16 v[2:5], v[158:161], v[206:209], v[2:5]
	s_setprio 0
	s_barrier
	s_add_i32 s47, 0, 0x18000
	s_add_i32 s52, 0, 0x1c000
	v_add_u32_e32 v142, s47, v220
	v_add_u32_e32 v158, s52, v220
	ds_read_b128 v[130:133], v142
	ds_read_b128 v[134:137], v142 offset:1024
	ds_read_b128 v[138:141], v142 offset:2048
	ds_read_b128 v[142:145], v142 offset:3072
	ds_read_b128 v[146:149], v158
	ds_read_b128 v[150:153], v158 offset:1024
	ds_read_b128 v[154:157], v158 offset:2048
	ds_read_b128 v[158:161], v158 offset:3072
	s_add_u32 s30, s30, 0x80000
	s_addc_u32 s31, s31, 0
	s_mov_b32 m0, s36
	v_lshl_add_u64 v[218:219], s[30:31], 0, v[186:187]
	ds_read_b128 v[162:165], v222 offset:32768
	ds_read_b128 v[166:169], v222 offset:33792
	ds_read_b128 v[170:173], v222 offset:34816
	ds_read_b128 v[174:177], v222 offset:35840
	ds_read_b128 v[178:181], v222 offset:36864
	ds_read_b128 v[182:185], v222 offset:37888
	ds_read_b128 v[196:199], v222 offset:38912
	ds_read_b128 v[206:209], v222 offset:39936
	global_load_lds_dwordx4 v[218:219], off
	s_mov_b32 m0, s37
	v_lshl_add_u64 v[218:219], s[30:31], 0, v[188:189]
	global_load_lds_dwordx4 v[218:219], off
	s_waitcnt vmcnt(8) lgkmcnt(0)
	s_setprio 1
	s_barrier
	v_mfma_f32_16x16x32_bf16 v[126:129], v[130:133], v[162:165], v[126:129]
	v_mfma_f32_16x16x32_bf16 v[122:125], v[138:141], v[162:165], v[122:125]
	v_mfma_f32_16x16x32_bf16 v[110:113], v[130:133], v[170:173], v[110:113]
	v_mfma_f32_16x16x32_bf16 v[106:109], v[138:141], v[170:173], v[106:109]
	v_mfma_f32_16x16x32_bf16 v[94:97], v[130:133], v[178:181], v[94:97]
	v_mfma_f32_16x16x32_bf16 v[90:93], v[138:141], v[178:181], v[90:93]
	v_mfma_f32_16x16x32_bf16 v[78:81], v[130:133], v[196:199], v[78:81]
	v_mfma_f32_16x16x32_bf16 v[74:77], v[138:141], v[196:199], v[74:77]
	v_mfma_f32_16x16x32_bf16 v[126:129], v[134:137], v[166:169], v[126:129]
	v_mfma_f32_16x16x32_bf16 v[122:125], v[142:145], v[166:169], v[122:125]
	v_mfma_f32_16x16x32_bf16 v[110:113], v[134:137], v[174:177], v[110:113]
	v_mfma_f32_16x16x32_bf16 v[106:109], v[142:145], v[174:177], v[106:109]
	v_mfma_f32_16x16x32_bf16 v[94:97], v[134:137], v[182:185], v[94:97]
	v_mfma_f32_16x16x32_bf16 v[90:93], v[142:145], v[182:185], v[90:93]
	v_mfma_f32_16x16x32_bf16 v[78:81], v[134:137], v[206:209], v[78:81]
	v_mfma_f32_16x16x32_bf16 v[74:77], v[142:145], v[206:209], v[74:77]
	v_mfma_f32_16x16x32_bf16 v[118:121], v[146:149], v[162:165], v[118:121]
	v_mfma_f32_16x16x32_bf16 v[114:117], v[154:157], v[162:165], v[114:117]
	v_mfma_f32_16x16x32_bf16 v[102:105], v[146:149], v[170:173], v[102:105]
	v_mfma_f32_16x16x32_bf16 v[98:101], v[154:157], v[170:173], v[98:101]
	v_mfma_f32_16x16x32_bf16 v[86:89], v[146:149], v[178:181], v[86:89]
	v_mfma_f32_16x16x32_bf16 v[82:85], v[154:157], v[178:181], v[82:85]
	v_mfma_f32_16x16x32_bf16 v[70:73], v[146:149], v[196:199], v[70:73]
	v_mfma_f32_16x16x32_bf16 v[66:69], v[154:157], v[196:199], v[66:69]
	v_mfma_f32_16x16x32_bf16 v[118:121], v[150:153], v[166:169], v[118:121]
	v_mfma_f32_16x16x32_bf16 v[114:117], v[158:161], v[166:169], v[114:117]
	v_mfma_f32_16x16x32_bf16 v[102:105], v[150:153], v[174:177], v[102:105]
	v_mfma_f32_16x16x32_bf16 v[98:101], v[158:161], v[174:177], v[98:101]
	v_mfma_f32_16x16x32_bf16 v[86:89], v[150:153], v[182:185], v[86:89]
	v_mfma_f32_16x16x32_bf16 v[82:85], v[158:161], v[182:185], v[82:85]
	v_mfma_f32_16x16x32_bf16 v[70:73], v[150:153], v[206:209], v[70:73]
	v_mfma_f32_16x16x32_bf16 v[66:69], v[158:161], v[206:209], v[66:69]
	s_setprio 0
	s_barrier
	s_add_i32 s30, s47, s33
	v_lshl_add_u64 v[210:211], v[210:211], 0, s[58:59]
	s_mov_b32 m0, s30
	ds_read_b128 v[162:165], v222 offset:49152
	ds_read_b128 v[166:169], v222 offset:50176
	ds_read_b128 v[170:173], v222 offset:51200
	ds_read_b128 v[174:177], v222 offset:52224
	ds_read_b128 v[178:181], v222 offset:53248
	ds_read_b128 v[182:185], v222 offset:54272
	ds_read_b128 v[196:199], v222 offset:55296
	ds_read_b128 v[206:209], v222 offset:56320
	global_load_lds_dwordx4 v[210:211], off
	s_add_i32 m0, s30, 0x2000
	s_add_u32 s28, s28, 0x80080
	v_lshl_add_u64 v[210:211], v[212:213], 0, s[58:59]
	s_addc_u32 s29, s29, 0
	s_add_i32 s30, s52, s33
	global_load_lds_dwordx4 v[210:211], off
	s_mov_b32 m0, s30
	v_lshl_add_u64 v[210:211], s[28:29], 0, v[190:191]
	global_load_lds_dwordx4 v[210:211], off
	s_add_i32 m0, s30, 0x2000
	v_lshl_add_u64 v[210:211], s[28:29], 0, v[200:201]
	global_load_lds_dwordx4 v[210:211], off
	s_mov_b32 m0, s38
	v_lshl_add_u64 v[210:211], v[214:215], 0, s[58:59]
	global_load_lds_dwordx4 v[210:211], off
	s_mov_b32 m0, s39
	v_lshl_add_u64 v[210:211], v[216:217], 0, s[58:59]
	global_load_lds_dwordx4 v[210:211], off
	s_waitcnt vmcnt(8) lgkmcnt(0)
	s_setprio 1
	s_barrier
	v_mfma_f32_16x16x32_bf16 v[62:65], v[130:133], v[162:165], v[62:65]
	v_mfma_f32_16x16x32_bf16 v[58:61], v[138:141], v[162:165], v[58:61]
	v_mfma_f32_16x16x32_bf16 v[46:49], v[130:133], v[170:173], v[46:49]
	v_mfma_f32_16x16x32_bf16 v[42:45], v[138:141], v[170:173], v[42:45]
	v_mfma_f32_16x16x32_bf16 v[30:33], v[130:133], v[178:181], v[30:33]
	v_mfma_f32_16x16x32_bf16 v[26:29], v[138:141], v[178:181], v[26:29]
	v_mfma_f32_16x16x32_bf16 v[14:17], v[130:133], v[196:199], v[14:17]
	v_mfma_f32_16x16x32_bf16 v[10:13], v[138:141], v[196:199], v[10:13]
	v_mfma_f32_16x16x32_bf16 v[62:65], v[134:137], v[166:169], v[62:65]
	v_mfma_f32_16x16x32_bf16 v[58:61], v[142:145], v[166:169], v[58:61]
	v_mfma_f32_16x16x32_bf16 v[46:49], v[134:137], v[174:177], v[46:49]
	v_mfma_f32_16x16x32_bf16 v[42:45], v[142:145], v[174:177], v[42:45]
	v_mfma_f32_16x16x32_bf16 v[30:33], v[134:137], v[182:185], v[30:33]
	v_mfma_f32_16x16x32_bf16 v[26:29], v[142:145], v[182:185], v[26:29]
	v_mfma_f32_16x16x32_bf16 v[14:17], v[134:137], v[206:209], v[14:17]
	v_mfma_f32_16x16x32_bf16 v[10:13], v[142:145], v[206:209], v[10:13]
	v_mfma_f32_16x16x32_bf16 v[54:57], v[146:149], v[162:165], v[54:57]
	v_mfma_f32_16x16x32_bf16 v[50:53], v[154:157], v[162:165], v[50:53]
	v_mfma_f32_16x16x32_bf16 v[38:41], v[146:149], v[170:173], v[38:41]
	v_mfma_f32_16x16x32_bf16 v[34:37], v[154:157], v[170:173], v[34:37]
	v_mfma_f32_16x16x32_bf16 v[22:25], v[146:149], v[178:181], v[22:25]
	v_mfma_f32_16x16x32_bf16 v[18:21], v[154:157], v[178:181], v[18:21]
	v_mfma_f32_16x16x32_bf16 v[6:9], v[146:149], v[196:199], v[6:9]
	v_mfma_f32_16x16x32_bf16 v[2:5], v[154:157], v[196:199], v[2:5]
	v_mfma_f32_16x16x32_bf16 v[54:57], v[150:153], v[166:169], v[54:57]
	v_mfma_f32_16x16x32_bf16 v[50:53], v[158:161], v[166:169], v[50:53]
	v_mfma_f32_16x16x32_bf16 v[38:41], v[150:153], v[174:177], v[38:41]
	v_mfma_f32_16x16x32_bf16 v[34:37], v[158:161], v[174:177], v[34:37]
	v_mfma_f32_16x16x32_bf16 v[22:25], v[150:153], v[182:185], v[22:25]
	v_mfma_f32_16x16x32_bf16 v[18:21], v[158:161], v[182:185], v[18:21]
	v_mfma_f32_16x16x32_bf16 v[6:9], v[150:153], v[206:209], v[6:9]
	v_mfma_f32_16x16x32_bf16 v[2:5], v[158:161], v[206:209], v[2:5]
	s_setprio 0
	s_barrier
	s_add_i32 s46, s46, 2
	s_add_u32 s26, s26, 0x100
	s_addc_u32 s27, s27, 0
	s_add_u32 s42, s42, 0x100
	s_addc_u32 s43, s43, 0
	s_cmp_gt_u32 s46, 29
	s_cbranch_scc0 .LBB0_772

.LBB0_799:
	s_ashr_i32 s11, s10, 31
	s_lshl_b64 s[14:15], s[10:11], 20
	s_add_u32 s14, s69, s14
	s_addc_u32 s15, s77, s15
	s_and_b64 s[16:17], s[12:13], exec
	s_cselect_b32 s11, s15, s25
	s_cselect_b32 s21, s14, s24
	s_ashr_i32 s9, s8, 31
	s_lshl_b64 s[16:17], s[8:9], 20
	v_readlane_b32 s0, v254, 42
	v_readlane_b32 s1, v254, 43
	s_add_u32 s16, s0, s16
	s_addc_u32 s17, s1, s17
	s_and_b64 s[28:29], s[12:13], exec
	s_cselect_b32 s9, s17, s27
	s_cselect_b32 s47, s16, s26
	s_add_u32 s24, s24, 0x80080
	s_addc_u32 s25, s25, 0
	s_add_u32 s52, s26, 0x100
	s_addc_u32 s53, s27, 0
	s_mov_b32 s55, -2
	v_readlane_b32 s56, v255, 49
	s_nop 3
	s_cmp_eq_u32 s56, 5
	v_writelane_b32 v255, 5, 49
	s_cbranch_scc0 .Ltrip0_strict_4
	s_add_u32 s26, s24, 0xfff80080
	s_addc_u32 s27, s25, -1
	s_add_i32 s56, 0, 0x10000
	s_cmp_eq_u32 s55, 28
	s_cselect_b32 s29, s11, s27
	s_cselect_b32 s28, s21, s26
	s_cselect_b32 s27, s9, s53
	s_cselect_b32 s26, s47, s52
	s_add_i32 s60, 0, 0x14000
	v_add_u32_e32 v142, s56, v238
	v_add_u32_e32 v158, s60, v238
	ds_read_b128 v[130:133], v142
	ds_read_b128 v[134:137], v142 offset:1024
	ds_read_b128 v[138:141], v142 offset:2048
	ds_read_b128 v[142:145], v142 offset:3072
	ds_read_b128 v[146:149], v158
	ds_read_b128 v[150:153], v158 offset:1024
	ds_read_b128 v[154:157], v158 offset:2048
	ds_read_b128 v[158:161], v158 offset:3072
	v_lshl_add_u64 v[210:211], s[24:25], 0, v[206:207]
	s_add_i32 m0, s23, 0xc000
	ds_read_b128 v[162:165], v240
	ds_read_b128 v[166:169], v240 offset:1024
	ds_read_b128 v[170:173], v240 offset:2048
	ds_read_b128 v[174:177], v240 offset:3072
	ds_read_b128 v[178:181], v240 offset:4096
	ds_read_b128 v[182:185], v240 offset:5120
	ds_read_b128 v[186:189], v240 offset:6144
	ds_read_b128 v[196:199], v240 offset:7168
	global_load_lds_dwordx4 v[210:211], off
	s_add_i32 m0, s23, 0xe000
	v_lshl_add_u64 v[210:211], s[24:25], 0, v[208:209]
	global_load_lds_dwordx4 v[210:211], off
	s_waitcnt vmcnt(24) lgkmcnt(0)
	s_setprio 1
	s_barrier
	v_mfma_f32_16x16x32_bf16 v[126:129], v[130:133], v[162:165], 0
	v_mfma_f32_16x16x32_bf16 v[122:125], v[138:141], v[162:165], 0
	v_mfma_f32_16x16x32_bf16 v[110:113], v[130:133], v[170:173], 0
	v_mfma_f32_16x16x32_bf16 v[106:109], v[138:141], v[170:173], 0
	v_mfma_f32_16x16x32_bf16 v[98:101], v[130:133], v[178:181], 0
	v_mfma_f32_16x16x32_bf16 v[90:93], v[138:141], v[178:181], 0
	v_mfma_f32_16x16x32_bf16 v[82:85], v[130:133], v[186:189], 0
	v_mfma_f32_16x16x32_bf16 v[74:77], v[138:141], v[186:189], 0
	v_mfma_f32_16x16x32_bf16 v[126:129], v[134:137], v[166:169], v[126:129]
	v_mfma_f32_16x16x32_bf16 v[122:125], v[142:145], v[166:169], v[122:125]
	v_mfma_f32_16x16x32_bf16 v[110:113], v[134:137], v[174:177], v[110:113]
	v_mfma_f32_16x16x32_bf16 v[106:109], v[142:145], v[174:177], v[106:109]
	v_mfma_f32_16x16x32_bf16 v[98:101], v[134:137], v[182:185], v[98:101]
	v_mfma_f32_16x16x32_bf16 v[90:93], v[142:145], v[182:185], v[90:93]
	v_mfma_f32_16x16x32_bf16 v[82:85], v[134:137], v[196:199], v[82:85]
	v_mfma_f32_16x16x32_bf16 v[74:77], v[142:145], v[196:199], v[74:77]
	v_mfma_f32_16x16x32_bf16 v[118:121], v[146:149], v[162:165], 0
	v_mfma_f32_16x16x32_bf16 v[114:117], v[154:157], v[162:165], 0
	v_mfma_f32_16x16x32_bf16 v[102:105], v[146:149], v[170:173], 0
	v_mfma_f32_16x16x32_bf16 v[94:97], v[154:157], v[170:173], 0
	v_mfma_f32_16x16x32_bf16 v[86:89], v[146:149], v[178:181], 0
	v_mfma_f32_16x16x32_bf16 v[78:81], v[154:157], v[178:181], 0
	v_mfma_f32_16x16x32_bf16 v[70:73], v[146:149], v[186:189], 0
	v_mfma_f32_16x16x32_bf16 v[66:69], v[154:157], v[186:189], 0
	v_mfma_f32_16x16x32_bf16 v[118:121], v[150:153], v[166:169], v[118:121]
	v_mfma_f32_16x16x32_bf16 v[114:117], v[158:161], v[166:169], v[114:117]
	v_mfma_f32_16x16x32_bf16 v[102:105], v[150:153], v[174:177], v[102:105]
	v_mfma_f32_16x16x32_bf16 v[94:97], v[158:161], v[174:177], v[94:97]
	v_mfma_f32_16x16x32_bf16 v[86:89], v[150:153], v[182:185], v[86:89]
	v_mfma_f32_16x16x32_bf16 v[78:81], v[158:161], v[182:185], v[78:81]
	v_mfma_f32_16x16x32_bf16 v[70:73], v[150:153], v[196:199], v[70:73]
	v_mfma_f32_16x16x32_bf16 v[66:69], v[158:161], v[196:199], v[66:69]
	s_barrier
	s_setprio 0
	s_add_i32 s56, s56, s34
	v_lshl_add_u64 v[210:211], s[26:27], 0, v[190:191]
	s_mov_b32 m0, s56
	ds_read_b128 v[162:165], v240 offset:16384
	ds_read_b128 v[166:169], v240 offset:17408
	ds_read_b128 v[170:173], v240 offset:18432
	ds_read_b128 v[174:177], v240 offset:19456
	ds_read_b128 v[178:181], v240 offset:20480
	ds_read_b128 v[182:185], v240 offset:21504
	ds_read_b128 v[186:189], v240 offset:22528
	ds_read_b128 v[196:199], v240 offset:23552
	global_load_lds_dwordx4 v[210:211], off
	s_add_i32 m0, s56, 0x2000
	s_add_u32 s56, s26, 0x80000
	v_lshl_add_u64 v[212:213], s[26:27], 0, v[204:205]
	s_addc_u32 s57, s27, 0
	s_add_i32 s60, s60, s34
	global_load_lds_dwordx4 v[212:213], off
	v_lshl_add_u64 v[214:215], s[56:57], 0, v[190:191]
	s_mov_b32 m0, s60
	v_lshl_add_u64 v[216:217], s[28:29], 0, v[202:203]
	global_load_lds_dwordx4 v[214:215], off
	s_add_i32 m0, s60, 0x2000
	v_lshl_add_u64 v[214:215], s[56:57], 0, v[204:205]
	global_load_lds_dwordx4 v[214:215], off
	s_mov_b32 m0, s23
	v_lshl_add_u64 v[214:215], s[28:29], 0, v[200:201]
	global_load_lds_dwordx4 v[214:215], off
	s_mov_b32 m0, s35
	s_nop 0
	global_load_lds_dwordx4 v[216:217], off
	s_waitcnt vmcnt(24) lgkmcnt(0)
	s_setprio 1
	s_barrier
	v_mfma_f32_16x16x32_bf16 v[62:65], v[130:133], v[162:165], 0
	v_mfma_f32_16x16x32_bf16 v[58:61], v[138:141], v[162:165], 0
	v_mfma_f32_16x16x32_bf16 v[50:53], v[130:133], v[170:173], 0
	v_mfma_f32_16x16x32_bf16 v[42:45], v[138:141], v[170:173], 0
	v_mfma_f32_16x16x32_bf16 v[34:37], v[130:133], v[178:181], 0
	v_mfma_f32_16x16x32_bf16 v[26:29], v[138:141], v[178:181], 0
	v_mfma_f32_16x16x32_bf16 v[18:21], v[130:133], v[186:189], 0
	v_mfma_f32_16x16x32_bf16 v[10:13], v[138:141], v[186:189], 0
	v_mfma_f32_16x16x32_bf16 v[62:65], v[134:137], v[166:169], v[62:65]
	v_mfma_f32_16x16x32_bf16 v[58:61], v[142:145], v[166:169], v[58:61]
	v_mfma_f32_16x16x32_bf16 v[50:53], v[134:137], v[174:177], v[50:53]
	v_mfma_f32_16x16x32_bf16 v[42:45], v[142:145], v[174:177], v[42:45]
	v_mfma_f32_16x16x32_bf16 v[34:37], v[134:137], v[182:185], v[34:37]
	v_mfma_f32_16x16x32_bf16 v[26:29], v[142:145], v[182:185], v[26:29]
	v_mfma_f32_16x16x32_bf16 v[18:21], v[134:137], v[196:199], v[18:21]
	v_mfma_f32_16x16x32_bf16 v[10:13], v[142:145], v[196:199], v[10:13]
	v_mfma_f32_16x16x32_bf16 v[54:57], v[146:149], v[162:165], 0
	v_mfma_f32_16x16x32_bf16 v[46:49], v[154:157], v[162:165], 0
	v_mfma_f32_16x16x32_bf16 v[38:41], v[146:149], v[170:173], 0
	v_mfma_f32_16x16x32_bf16 v[30:33], v[154:157], v[170:173], 0
	v_mfma_f32_16x16x32_bf16 v[22:25], v[146:149], v[178:181], 0
	v_mfma_f32_16x16x32_bf16 v[14:17], v[154:157], v[178:181], 0
	v_mfma_f32_16x16x32_bf16 v[6:9], v[146:149], v[186:189], 0
	v_mfma_f32_16x16x32_bf16 v[2:5], v[154:157], v[186:189], 0
	v_mfma_f32_16x16x32_bf16 v[54:57], v[150:153], v[166:169], v[54:57]
	v_mfma_f32_16x16x32_bf16 v[46:49], v[158:161], v[166:169], v[46:49]
	v_mfma_f32_16x16x32_bf16 v[38:41], v[150:153], v[174:177], v[38:41]
	v_mfma_f32_16x16x32_bf16 v[30:33], v[158:161], v[174:177], v[30:33]
	v_mfma_f32_16x16x32_bf16 v[22:25], v[150:153], v[182:185], v[22:25]
	v_mfma_f32_16x16x32_bf16 v[14:17], v[158:161], v[182:185], v[14:17]
	v_mfma_f32_16x16x32_bf16 v[6:9], v[150:153], v[196:199], v[6:9]
	v_mfma_f32_16x16x32_bf16 v[2:5], v[158:161], v[196:199], v[2:5]
	s_barrier
	s_setprio 0
	s_add_i32 s56, 0, 0x18000
	s_add_i32 s57, 0, 0x1c000
	v_add_u32_e32 v142, s56, v238
	v_add_u32_e32 v158, s57, v238
	ds_read_b128 v[130:133], v142
	ds_read_b128 v[134:137], v142 offset:1024
	ds_read_b128 v[138:141], v142 offset:2048
	ds_read_b128 v[142:145], v142 offset:3072
	ds_read_b128 v[146:149], v158
	ds_read_b128 v[150:153], v158 offset:1024
	ds_read_b128 v[154:157], v158 offset:2048
	ds_read_b128 v[158:161], v158 offset:3072
	s_add_u32 s28, s28, 0x80000
	s_addc_u32 s29, s29, 0
	s_mov_b32 m0, s41
	v_lshl_add_u64 v[218:219], s[28:29], 0, v[200:201]
	ds_read_b128 v[162:165], v240 offset:32768
	ds_read_b128 v[166:169], v240 offset:33792
	ds_read_b128 v[170:173], v240 offset:34816
	ds_read_b128 v[174:177], v240 offset:35840
	ds_read_b128 v[178:181], v240 offset:36864
	ds_read_b128 v[182:185], v240 offset:37888
	ds_read_b128 v[186:189], v240 offset:38912
	ds_read_b128 v[196:199], v240 offset:39936
	global_load_lds_dwordx4 v[218:219], off
	s_mov_b32 m0, s42
	v_lshl_add_u64 v[218:219], s[28:29], 0, v[202:203]
	global_load_lds_dwordx4 v[218:219], off
	s_waitcnt vmcnt(8) lgkmcnt(0)
	s_setprio 1
	s_barrier
	v_mfma_f32_16x16x32_bf16 v[126:129], v[130:133], v[162:165], v[126:129]
	v_mfma_f32_16x16x32_bf16 v[122:125], v[138:141], v[162:165], v[122:125]
	v_mfma_f32_16x16x32_bf16 v[110:113], v[130:133], v[170:173], v[110:113]
	v_mfma_f32_16x16x32_bf16 v[106:109], v[138:141], v[170:173], v[106:109]
	v_mfma_f32_16x16x32_bf16 v[98:101], v[130:133], v[178:181], v[98:101]
	v_mfma_f32_16x16x32_bf16 v[90:93], v[138:141], v[178:181], v[90:93]
	v_mfma_f32_16x16x32_bf16 v[82:85], v[130:133], v[186:189], v[82:85]
	v_mfma_f32_16x16x32_bf16 v[74:77], v[138:141], v[186:189], v[74:77]
	v_mfma_f32_16x16x32_bf16 v[126:129], v[134:137], v[166:169], v[126:129]
	v_mfma_f32_16x16x32_bf16 v[122:125], v[142:145], v[166:169], v[122:125]
	v_mfma_f32_16x16x32_bf16 v[110:113], v[134:137], v[174:177], v[110:113]
	v_mfma_f32_16x16x32_bf16 v[106:109], v[142:145], v[174:177], v[106:109]
	v_mfma_f32_16x16x32_bf16 v[98:101], v[134:137], v[182:185], v[98:101]
	v_mfma_f32_16x16x32_bf16 v[90:93], v[142:145], v[182:185], v[90:93]
	v_mfma_f32_16x16x32_bf16 v[82:85], v[134:137], v[196:199], v[82:85]
	v_mfma_f32_16x16x32_bf16 v[74:77], v[142:145], v[196:199], v[74:77]
	v_mfma_f32_16x16x32_bf16 v[118:121], v[146:149], v[162:165], v[118:121]
	v_mfma_f32_16x16x32_bf16 v[114:117], v[154:157], v[162:165], v[114:117]
	v_mfma_f32_16x16x32_bf16 v[102:105], v[146:149], v[170:173], v[102:105]
	v_mfma_f32_16x16x32_bf16 v[94:97], v[154:157], v[170:173], v[94:97]
	v_mfma_f32_16x16x32_bf16 v[86:89], v[146:149], v[178:181], v[86:89]
	v_mfma_f32_16x16x32_bf16 v[78:81], v[154:157], v[178:181], v[78:81]
	v_mfma_f32_16x16x32_bf16 v[70:73], v[146:149], v[186:189], v[70:73]
	v_mfma_f32_16x16x32_bf16 v[66:69], v[154:157], v[186:189], v[66:69]
	v_mfma_f32_16x16x32_bf16 v[118:121], v[150:153], v[166:169], v[118:121]
	v_mfma_f32_16x16x32_bf16 v[114:117], v[158:161], v[166:169], v[114:117]
	v_mfma_f32_16x16x32_bf16 v[102:105], v[150:153], v[174:177], v[102:105]
	v_mfma_f32_16x16x32_bf16 v[94:97], v[158:161], v[174:177], v[94:97]
	v_mfma_f32_16x16x32_bf16 v[86:89], v[150:153], v[182:185], v[86:89]
	v_mfma_f32_16x16x32_bf16 v[78:81], v[158:161], v[182:185], v[78:81]
	v_mfma_f32_16x16x32_bf16 v[70:73], v[150:153], v[196:199], v[70:73]
	v_mfma_f32_16x16x32_bf16 v[66:69], v[158:161], v[196:199], v[66:69]
	s_barrier
	s_setprio 0
	s_add_i32 s28, s56, s34
	v_lshl_add_u64 v[210:211], v[210:211], 0, s[58:59]
	s_mov_b32 m0, s28
	ds_read_b128 v[162:165], v240 offset:49152
	ds_read_b128 v[166:169], v240 offset:50176
	ds_read_b128 v[170:173], v240 offset:51200
	ds_read_b128 v[174:177], v240 offset:52224
	ds_read_b128 v[178:181], v240 offset:53248
	ds_read_b128 v[182:185], v240 offset:54272
	ds_read_b128 v[186:189], v240 offset:55296
	ds_read_b128 v[196:199], v240 offset:56320
	global_load_lds_dwordx4 v[210:211], off
	s_add_i32 m0, s28, 0x2000
	s_add_u32 s26, s26, 0x80080
	v_lshl_add_u64 v[210:211], v[212:213], 0, s[58:59]
	s_addc_u32 s27, s27, 0
	s_add_i32 s28, s57, s34
	global_load_lds_dwordx4 v[210:211], off
	s_mov_b32 m0, s28
	v_lshl_add_u64 v[210:211], s[26:27], 0, v[190:191]
	global_load_lds_dwordx4 v[210:211], off
	s_add_i32 m0, s28, 0x2000
	v_lshl_add_u64 v[210:211], s[26:27], 0, v[204:205]
	global_load_lds_dwordx4 v[210:211], off
	s_mov_b32 m0, s43
	v_lshl_add_u64 v[210:211], v[214:215], 0, s[58:59]
	global_load_lds_dwordx4 v[210:211], off
	s_mov_b32 m0, s46
	v_lshl_add_u64 v[210:211], v[216:217], 0, s[58:59]
	global_load_lds_dwordx4 v[210:211], off
	s_waitcnt vmcnt(8) lgkmcnt(0)
	s_setprio 1
	s_barrier
	v_mfma_f32_16x16x32_bf16 v[62:65], v[130:133], v[162:165], v[62:65]
	v_mfma_f32_16x16x32_bf16 v[58:61], v[138:141], v[162:165], v[58:61]
	v_mfma_f32_16x16x32_bf16 v[50:53], v[130:133], v[170:173], v[50:53]
	v_mfma_f32_16x16x32_bf16 v[42:45], v[138:141], v[170:173], v[42:45]
	v_mfma_f32_16x16x32_bf16 v[34:37], v[130:133], v[178:181], v[34:37]
	v_mfma_f32_16x16x32_bf16 v[26:29], v[138:141], v[178:181], v[26:29]
	v_mfma_f32_16x16x32_bf16 v[18:21], v[130:133], v[186:189], v[18:21]
	v_mfma_f32_16x16x32_bf16 v[10:13], v[138:141], v[186:189], v[10:13]
	v_mfma_f32_16x16x32_bf16 v[62:65], v[134:137], v[166:169], v[62:65]
	v_mfma_f32_16x16x32_bf16 v[58:61], v[142:145], v[166:169], v[58:61]
	v_mfma_f32_16x16x32_bf16 v[50:53], v[134:137], v[174:177], v[50:53]
	v_mfma_f32_16x16x32_bf16 v[42:45], v[142:145], v[174:177], v[42:45]
	v_mfma_f32_16x16x32_bf16 v[34:37], v[134:137], v[182:185], v[34:37]
	v_mfma_f32_16x16x32_bf16 v[26:29], v[142:145], v[182:185], v[26:29]
	v_mfma_f32_16x16x32_bf16 v[18:21], v[134:137], v[196:199], v[18:21]
	v_mfma_f32_16x16x32_bf16 v[10:13], v[142:145], v[196:199], v[10:13]
	v_mfma_f32_16x16x32_bf16 v[54:57], v[146:149], v[162:165], v[54:57]
	v_mfma_f32_16x16x32_bf16 v[46:49], v[154:157], v[162:165], v[46:49]
	v_mfma_f32_16x16x32_bf16 v[38:41], v[146:149], v[170:173], v[38:41]
	v_mfma_f32_16x16x32_bf16 v[30:33], v[154:157], v[170:173], v[30:33]
	v_mfma_f32_16x16x32_bf16 v[22:25], v[146:149], v[178:181], v[22:25]
	v_mfma_f32_16x16x32_bf16 v[14:17], v[154:157], v[178:181], v[14:17]
	v_mfma_f32_16x16x32_bf16 v[6:9], v[146:149], v[186:189], v[6:9]
	v_mfma_f32_16x16x32_bf16 v[2:5], v[154:157], v[186:189], v[2:5]
	v_mfma_f32_16x16x32_bf16 v[54:57], v[150:153], v[166:169], v[54:57]
	v_mfma_f32_16x16x32_bf16 v[46:49], v[158:161], v[166:169], v[46:49]
	v_mfma_f32_16x16x32_bf16 v[38:41], v[150:153], v[174:177], v[38:41]
	v_mfma_f32_16x16x32_bf16 v[30:33], v[158:161], v[174:177], v[30:33]
	v_mfma_f32_16x16x32_bf16 v[22:25], v[150:153], v[182:185], v[22:25]
	v_mfma_f32_16x16x32_bf16 v[14:17], v[158:161], v[182:185], v[14:17]
	v_mfma_f32_16x16x32_bf16 v[6:9], v[150:153], v[196:199], v[6:9]
	v_mfma_f32_16x16x32_bf16 v[2:5], v[158:161], v[196:199], v[2:5]
	s_barrier
	s_setprio 0
	s_add_i32 s55, s55, 2
	s_add_u32 s24, s24, 0x100
	s_addc_u32 s25, s25, 0
	s_add_u32 s52, s52, 0x100
	s_addc_u32 s53, s53, 0
	s_cmp_gt_u32 s55, 29
	s_cbranch_scc1 .Lpeel_done_4
	s_branch .LBB0_800
.Ltrip0_strict_4:
	s_add_u32 s26, s24, 0xfff80080
	s_addc_u32 s27, s25, -1
	s_add_i32 s56, 0, 0x10000
	s_cmp_eq_u32 s55, 28
	s_cselect_b32 s29, s11, s27
	s_cselect_b32 s28, s21, s26
	s_cselect_b32 s27, s9, s53
	s_cselect_b32 s26, s47, s52
	s_add_i32 s60, 0, 0x14000
	v_add_u32_e32 v142, s56, v238
	v_add_u32_e32 v158, s60, v238
	ds_read_b128 v[130:133], v142
	ds_read_b128 v[134:137], v142 offset:1024
	ds_read_b128 v[138:141], v142 offset:2048
	ds_read_b128 v[142:145], v142 offset:3072
	ds_read_b128 v[146:149], v158
	ds_read_b128 v[150:153], v158 offset:1024
	ds_read_b128 v[154:157], v158 offset:2048
	ds_read_b128 v[158:161], v158 offset:3072
	v_lshl_add_u64 v[210:211], s[24:25], 0, v[206:207]
	s_add_i32 m0, s23, 0xc000
	ds_read_b128 v[162:165], v240
	ds_read_b128 v[166:169], v240 offset:1024
	ds_read_b128 v[170:173], v240 offset:2048
	ds_read_b128 v[174:177], v240 offset:3072
	ds_read_b128 v[178:181], v240 offset:4096
	ds_read_b128 v[182:185], v240 offset:5120
	ds_read_b128 v[186:189], v240 offset:6144
	ds_read_b128 v[196:199], v240 offset:7168
	global_load_lds_dwordx4 v[210:211], off
	s_add_i32 m0, s23, 0xe000
	v_lshl_add_u64 v[210:211], s[24:25], 0, v[208:209]
	global_load_lds_dwordx4 v[210:211], off
	s_waitcnt vmcnt(8) lgkmcnt(0)
	s_setprio 1
	s_barrier
	v_mfma_f32_16x16x32_bf16 v[126:129], v[130:133], v[162:165], 0
	v_mfma_f32_16x16x32_bf16 v[122:125], v[138:141], v[162:165], 0
	v_mfma_f32_16x16x32_bf16 v[110:113], v[130:133], v[170:173], 0
	v_mfma_f32_16x16x32_bf16 v[106:109], v[138:141], v[170:173], 0
	v_mfma_f32_16x16x32_bf16 v[98:101], v[130:133], v[178:181], 0
	v_mfma_f32_16x16x32_bf16 v[90:93], v[138:141], v[178:181], 0
	v_mfma_f32_16x16x32_bf16 v[82:85], v[130:133], v[186:189], 0
	v_mfma_f32_16x16x32_bf16 v[74:77], v[138:141], v[186:189], 0
	v_mfma_f32_16x16x32_bf16 v[126:129], v[134:137], v[166:169], v[126:129]
	v_mfma_f32_16x16x32_bf16 v[122:125], v[142:145], v[166:169], v[122:125]
	v_mfma_f32_16x16x32_bf16 v[110:113], v[134:137], v[174:177], v[110:113]
	v_mfma_f32_16x16x32_bf16 v[106:109], v[142:145], v[174:177], v[106:109]
	v_mfma_f32_16x16x32_bf16 v[98:101], v[134:137], v[182:185], v[98:101]
	v_mfma_f32_16x16x32_bf16 v[90:93], v[142:145], v[182:185], v[90:93]
	v_mfma_f32_16x16x32_bf16 v[82:85], v[134:137], v[196:199], v[82:85]
	v_mfma_f32_16x16x32_bf16 v[74:77], v[142:145], v[196:199], v[74:77]
	v_mfma_f32_16x16x32_bf16 v[118:121], v[146:149], v[162:165], 0
	v_mfma_f32_16x16x32_bf16 v[114:117], v[154:157], v[162:165], 0
	v_mfma_f32_16x16x32_bf16 v[102:105], v[146:149], v[170:173], 0
	v_mfma_f32_16x16x32_bf16 v[94:97], v[154:157], v[170:173], 0
	v_mfma_f32_16x16x32_bf16 v[86:89], v[146:149], v[178:181], 0
	v_mfma_f32_16x16x32_bf16 v[78:81], v[154:157], v[178:181], 0
	v_mfma_f32_16x16x32_bf16 v[70:73], v[146:149], v[186:189], 0
	v_mfma_f32_16x16x32_bf16 v[66:69], v[154:157], v[186:189], 0
	v_mfma_f32_16x16x32_bf16 v[118:121], v[150:153], v[166:169], v[118:121]
	v_mfma_f32_16x16x32_bf16 v[114:117], v[158:161], v[166:169], v[114:117]
	v_mfma_f32_16x16x32_bf16 v[102:105], v[150:153], v[174:177], v[102:105]
	v_mfma_f32_16x16x32_bf16 v[94:97], v[158:161], v[174:177], v[94:97]
	v_mfma_f32_16x16x32_bf16 v[86:89], v[150:153], v[182:185], v[86:89]
	v_mfma_f32_16x16x32_bf16 v[78:81], v[158:161], v[182:185], v[78:81]
	v_mfma_f32_16x16x32_bf16 v[70:73], v[150:153], v[196:199], v[70:73]
	v_mfma_f32_16x16x32_bf16 v[66:69], v[158:161], v[196:199], v[66:69]
	s_barrier
	s_setprio 0
	s_add_i32 s56, s56, s34
	v_lshl_add_u64 v[210:211], s[26:27], 0, v[190:191]
	s_mov_b32 m0, s56
	ds_read_b128 v[162:165], v240 offset:16384
	ds_read_b128 v[166:169], v240 offset:17408
	ds_read_b128 v[170:173], v240 offset:18432
	ds_read_b128 v[174:177], v240 offset:19456
	ds_read_b128 v[178:181], v240 offset:20480
	ds_read_b128 v[182:185], v240 offset:21504
	ds_read_b128 v[186:189], v240 offset:22528
	ds_read_b128 v[196:199], v240 offset:23552
	global_load_lds_dwordx4 v[210:211], off
	s_add_i32 m0, s56, 0x2000
	s_add_u32 s56, s26, 0x80000
	v_lshl_add_u64 v[212:213], s[26:27], 0, v[204:205]
	s_addc_u32 s57, s27, 0
	s_add_i32 s60, s60, s34
	global_load_lds_dwordx4 v[212:213], off
	v_lshl_add_u64 v[214:215], s[56:57], 0, v[190:191]
	s_mov_b32 m0, s60
	v_lshl_add_u64 v[216:217], s[28:29], 0, v[202:203]
	global_load_lds_dwordx4 v[214:215], off
	s_add_i32 m0, s60, 0x2000
	v_lshl_add_u64 v[214:215], s[56:57], 0, v[204:205]
	global_load_lds_dwordx4 v[214:215], off
	s_mov_b32 m0, s23
	v_lshl_add_u64 v[214:215], s[28:29], 0, v[200:201]
	global_load_lds_dwordx4 v[214:215], off
	s_mov_b32 m0, s35
	s_nop 0
	global_load_lds_dwordx4 v[216:217], off
	s_waitcnt vmcnt(8) lgkmcnt(0)
	s_setprio 1
	s_barrier
	v_mfma_f32_16x16x32_bf16 v[62:65], v[130:133], v[162:165], 0
	v_mfma_f32_16x16x32_bf16 v[58:61], v[138:141], v[162:165], 0
	v_mfma_f32_16x16x32_bf16 v[50:53], v[130:133], v[170:173], 0
	v_mfma_f32_16x16x32_bf16 v[42:45], v[138:141], v[170:173], 0
	v_mfma_f32_16x16x32_bf16 v[34:37], v[130:133], v[178:181], 0
	v_mfma_f32_16x16x32_bf16 v[26:29], v[138:141], v[178:181], 0
	v_mfma_f32_16x16x32_bf16 v[18:21], v[130:133], v[186:189], 0
	v_mfma_f32_16x16x32_bf16 v[10:13], v[138:141], v[186:189], 0
	v_mfma_f32_16x16x32_bf16 v[62:65], v[134:137], v[166:169], v[62:65]
	v_mfma_f32_16x16x32_bf16 v[58:61], v[142:145], v[166:169], v[58:61]
	v_mfma_f32_16x16x32_bf16 v[50:53], v[134:137], v[174:177], v[50:53]
	v_mfma_f32_16x16x32_bf16 v[42:45], v[142:145], v[174:177], v[42:45]
	v_mfma_f32_16x16x32_bf16 v[34:37], v[134:137], v[182:185], v[34:37]
	v_mfma_f32_16x16x32_bf16 v[26:29], v[142:145], v[182:185], v[26:29]
	v_mfma_f32_16x16x32_bf16 v[18:21], v[134:137], v[196:199], v[18:21]
	v_mfma_f32_16x16x32_bf16 v[10:13], v[142:145], v[196:199], v[10:13]
	v_mfma_f32_16x16x32_bf16 v[54:57], v[146:149], v[162:165], 0
	v_mfma_f32_16x16x32_bf16 v[46:49], v[154:157], v[162:165], 0
	v_mfma_f32_16x16x32_bf16 v[38:41], v[146:149], v[170:173], 0
	v_mfma_f32_16x16x32_bf16 v[30:33], v[154:157], v[170:173], 0
	v_mfma_f32_16x16x32_bf16 v[22:25], v[146:149], v[178:181], 0
	v_mfma_f32_16x16x32_bf16 v[14:17], v[154:157], v[178:181], 0
	v_mfma_f32_16x16x32_bf16 v[6:9], v[146:149], v[186:189], 0
	v_mfma_f32_16x16x32_bf16 v[2:5], v[154:157], v[186:189], 0
	v_mfma_f32_16x16x32_bf16 v[54:57], v[150:153], v[166:169], v[54:57]
	v_mfma_f32_16x16x32_bf16 v[46:49], v[158:161], v[166:169], v[46:49]
	v_mfma_f32_16x16x32_bf16 v[38:41], v[150:153], v[174:177], v[38:41]
	v_mfma_f32_16x16x32_bf16 v[30:33], v[158:161], v[174:177], v[30:33]
	v_mfma_f32_16x16x32_bf16 v[22:25], v[150:153], v[182:185], v[22:25]
	v_mfma_f32_16x16x32_bf16 v[14:17], v[158:161], v[182:185], v[14:17]
	v_mfma_f32_16x16x32_bf16 v[6:9], v[150:153], v[196:199], v[6:9]
	v_mfma_f32_16x16x32_bf16 v[2:5], v[158:161], v[196:199], v[2:5]
	s_barrier
	s_setprio 0
	s_add_i32 s56, 0, 0x18000
	s_add_i32 s57, 0, 0x1c000
	v_add_u32_e32 v142, s56, v238
	v_add_u32_e32 v158, s57, v238
	ds_read_b128 v[130:133], v142
	ds_read_b128 v[134:137], v142 offset:1024
	ds_read_b128 v[138:141], v142 offset:2048
	ds_read_b128 v[142:145], v142 offset:3072
	ds_read_b128 v[146:149], v158
	ds_read_b128 v[150:153], v158 offset:1024
	ds_read_b128 v[154:157], v158 offset:2048
	ds_read_b128 v[158:161], v158 offset:3072
	s_add_u32 s28, s28, 0x80000
	s_addc_u32 s29, s29, 0
	s_mov_b32 m0, s41
	v_lshl_add_u64 v[218:219], s[28:29], 0, v[200:201]
	ds_read_b128 v[162:165], v240 offset:32768
	ds_read_b128 v[166:169], v240 offset:33792
	ds_read_b128 v[170:173], v240 offset:34816
	ds_read_b128 v[174:177], v240 offset:35840
	ds_read_b128 v[178:181], v240 offset:36864
	ds_read_b128 v[182:185], v240 offset:37888
	ds_read_b128 v[186:189], v240 offset:38912
	ds_read_b128 v[196:199], v240 offset:39936
	global_load_lds_dwordx4 v[218:219], off
	s_mov_b32 m0, s42
	v_lshl_add_u64 v[218:219], s[28:29], 0, v[202:203]
	global_load_lds_dwordx4 v[218:219], off
	s_waitcnt vmcnt(8) lgkmcnt(0)
	s_setprio 1
	s_barrier
	v_mfma_f32_16x16x32_bf16 v[126:129], v[130:133], v[162:165], v[126:129]
	v_mfma_f32_16x16x32_bf16 v[122:125], v[138:141], v[162:165], v[122:125]
	v_mfma_f32_16x16x32_bf16 v[110:113], v[130:133], v[170:173], v[110:113]
	v_mfma_f32_16x16x32_bf16 v[106:109], v[138:141], v[170:173], v[106:109]
	v_mfma_f32_16x16x32_bf16 v[98:101], v[130:133], v[178:181], v[98:101]
	v_mfma_f32_16x16x32_bf16 v[90:93], v[138:141], v[178:181], v[90:93]
	v_mfma_f32_16x16x32_bf16 v[82:85], v[130:133], v[186:189], v[82:85]
	v_mfma_f32_16x16x32_bf16 v[74:77], v[138:141], v[186:189], v[74:77]
	v_mfma_f32_16x16x32_bf16 v[126:129], v[134:137], v[166:169], v[126:129]
	v_mfma_f32_16x16x32_bf16 v[122:125], v[142:145], v[166:169], v[122:125]
	v_mfma_f32_16x16x32_bf16 v[110:113], v[134:137], v[174:177], v[110:113]
	v_mfma_f32_16x16x32_bf16 v[106:109], v[142:145], v[174:177], v[106:109]
	v_mfma_f32_16x16x32_bf16 v[98:101], v[134:137], v[182:185], v[98:101]
	v_mfma_f32_16x16x32_bf16 v[90:93], v[142:145], v[182:185], v[90:93]
	v_mfma_f32_16x16x32_bf16 v[82:85], v[134:137], v[196:199], v[82:85]
	v_mfma_f32_16x16x32_bf16 v[74:77], v[142:145], v[196:199], v[74:77]
	v_mfma_f32_16x16x32_bf16 v[118:121], v[146:149], v[162:165], v[118:121]
	v_mfma_f32_16x16x32_bf16 v[114:117], v[154:157], v[162:165], v[114:117]
	v_mfma_f32_16x16x32_bf16 v[102:105], v[146:149], v[170:173], v[102:105]
	v_mfma_f32_16x16x32_bf16 v[94:97], v[154:157], v[170:173], v[94:97]
	v_mfma_f32_16x16x32_bf16 v[86:89], v[146:149], v[178:181], v[86:89]
	v_mfma_f32_16x16x32_bf16 v[78:81], v[154:157], v[178:181], v[78:81]
	v_mfma_f32_16x16x32_bf16 v[70:73], v[146:149], v[186:189], v[70:73]
	v_mfma_f32_16x16x32_bf16 v[66:69], v[154:157], v[186:189], v[66:69]
	v_mfma_f32_16x16x32_bf16 v[118:121], v[150:153], v[166:169], v[118:121]
	v_mfma_f32_16x16x32_bf16 v[114:117], v[158:161], v[166:169], v[114:117]
	v_mfma_f32_16x16x32_bf16 v[102:105], v[150:153], v[174:177], v[102:105]
	v_mfma_f32_16x16x32_bf16 v[94:97], v[158:161], v[174:177], v[94:97]
	v_mfma_f32_16x16x32_bf16 v[86:89], v[150:153], v[182:185], v[86:89]
	v_mfma_f32_16x16x32_bf16 v[78:81], v[158:161], v[182:185], v[78:81]
	v_mfma_f32_16x16x32_bf16 v[70:73], v[150:153], v[196:199], v[70:73]
	v_mfma_f32_16x16x32_bf16 v[66:69], v[158:161], v[196:199], v[66:69]
	s_barrier
	s_setprio 0
	s_add_i32 s28, s56, s34
	v_lshl_add_u64 v[210:211], v[210:211], 0, s[58:59]
	s_mov_b32 m0, s28
	ds_read_b128 v[162:165], v240 offset:49152
	ds_read_b128 v[166:169], v240 offset:50176
	ds_read_b128 v[170:173], v240 offset:51200
	ds_read_b128 v[174:177], v240 offset:52224
	ds_read_b128 v[178:181], v240 offset:53248
	ds_read_b128 v[182:185], v240 offset:54272
	ds_read_b128 v[186:189], v240 offset:55296
	ds_read_b128 v[196:199], v240 offset:56320
	global_load_lds_dwordx4 v[210:211], off
	s_add_i32 m0, s28, 0x2000
	s_add_u32 s26, s26, 0x80080
	v_lshl_add_u64 v[210:211], v[212:213], 0, s[58:59]
	s_addc_u32 s27, s27, 0
	s_add_i32 s28, s57, s34
	global_load_lds_dwordx4 v[210:211], off
	s_mov_b32 m0, s28
	v_lshl_add_u64 v[210:211], s[26:27], 0, v[190:191]
	global_load_lds_dwordx4 v[210:211], off
	s_add_i32 m0, s28, 0x2000
	v_lshl_add_u64 v[210:211], s[26:27], 0, v[204:205]
	global_load_lds_dwordx4 v[210:211], off
	s_mov_b32 m0, s43
	v_lshl_add_u64 v[210:211], v[214:215], 0, s[58:59]
	global_load_lds_dwordx4 v[210:211], off
	s_mov_b32 m0, s46
	v_lshl_add_u64 v[210:211], v[216:217], 0, s[58:59]
	global_load_lds_dwordx4 v[210:211], off
	s_waitcnt vmcnt(8) lgkmcnt(0)
	s_setprio 1
	s_barrier
	v_mfma_f32_16x16x32_bf16 v[62:65], v[130:133], v[162:165], v[62:65]
	v_mfma_f32_16x16x32_bf16 v[58:61], v[138:141], v[162:165], v[58:61]
	v_mfma_f32_16x16x32_bf16 v[50:53], v[130:133], v[170:173], v[50:53]
	v_mfma_f32_16x16x32_bf16 v[42:45], v[138:141], v[170:173], v[42:45]
	v_mfma_f32_16x16x32_bf16 v[34:37], v[130:133], v[178:181], v[34:37]
	v_mfma_f32_16x16x32_bf16 v[26:29], v[138:141], v[178:181], v[26:29]
	v_mfma_f32_16x16x32_bf16 v[18:21], v[130:133], v[186:189], v[18:21]
	v_mfma_f32_16x16x32_bf16 v[10:13], v[138:141], v[186:189], v[10:13]
	v_mfma_f32_16x16x32_bf16 v[62:65], v[134:137], v[166:169], v[62:65]
	v_mfma_f32_16x16x32_bf16 v[58:61], v[142:145], v[166:169], v[58:61]
	v_mfma_f32_16x16x32_bf16 v[50:53], v[134:137], v[174:177], v[50:53]
	v_mfma_f32_16x16x32_bf16 v[42:45], v[142:145], v[174:177], v[42:45]
	v_mfma_f32_16x16x32_bf16 v[34:37], v[134:137], v[182:185], v[34:37]
	v_mfma_f32_16x16x32_bf16 v[26:29], v[142:145], v[182:185], v[26:29]
	v_mfma_f32_16x16x32_bf16 v[18:21], v[134:137], v[196:199], v[18:21]
	v_mfma_f32_16x16x32_bf16 v[10:13], v[142:145], v[196:199], v[10:13]
	v_mfma_f32_16x16x32_bf16 v[54:57], v[146:149], v[162:165], v[54:57]
	v_mfma_f32_16x16x32_bf16 v[46:49], v[154:157], v[162:165], v[46:49]
	v_mfma_f32_16x16x32_bf16 v[38:41], v[146:149], v[170:173], v[38:41]
	v_mfma_f32_16x16x32_bf16 v[30:33], v[154:157], v[170:173], v[30:33]
	v_mfma_f32_16x16x32_bf16 v[22:25], v[146:149], v[178:181], v[22:25]
	v_mfma_f32_16x16x32_bf16 v[14:17], v[154:157], v[178:181], v[14:17]
	v_mfma_f32_16x16x32_bf16 v[6:9], v[146:149], v[186:189], v[6:9]
	v_mfma_f32_16x16x32_bf16 v[2:5], v[154:157], v[186:189], v[2:5]
	v_mfma_f32_16x16x32_bf16 v[54:57], v[150:153], v[166:169], v[54:57]
	v_mfma_f32_16x16x32_bf16 v[46:49], v[158:161], v[166:169], v[46:49]
	v_mfma_f32_16x16x32_bf16 v[38:41], v[150:153], v[174:177], v[38:41]
	v_mfma_f32_16x16x32_bf16 v[30:33], v[158:161], v[174:177], v[30:33]
	v_mfma_f32_16x16x32_bf16 v[22:25], v[150:153], v[182:185], v[22:25]
	v_mfma_f32_16x16x32_bf16 v[14:17], v[158:161], v[182:185], v[14:17]
	v_mfma_f32_16x16x32_bf16 v[6:9], v[150:153], v[196:199], v[6:9]
	v_mfma_f32_16x16x32_bf16 v[2:5], v[158:161], v[196:199], v[2:5]
	s_barrier
	s_setprio 0
	s_add_i32 s55, s55, 2
	s_add_u32 s24, s24, 0x100
	s_addc_u32 s25, s25, 0
	s_add_u32 s52, s52, 0x100
	s_addc_u32 s53, s53, 0
	s_cmp_gt_u32 s55, 29
	s_cbranch_scc1 .Lpeel_done_4
.LBB0_800:
	s_add_u32 s26, s24, 0xfff80080
	s_addc_u32 s27, s25, -1
	s_add_i32 s56, 0, 0x10000
	s_cmp_eq_u32 s55, 28
	s_cselect_b32 s29, s11, s27
	s_cselect_b32 s28, s21, s26
	s_cselect_b32 s27, s9, s53
	s_cselect_b32 s26, s47, s52
	s_add_i32 s60, 0, 0x14000
	v_add_u32_e32 v142, s56, v238
	v_add_u32_e32 v158, s60, v238
	ds_read_b128 v[130:133], v142
	ds_read_b128 v[134:137], v142 offset:1024
	ds_read_b128 v[138:141], v142 offset:2048
	ds_read_b128 v[142:145], v142 offset:3072
	ds_read_b128 v[146:149], v158
	ds_read_b128 v[150:153], v158 offset:1024
	ds_read_b128 v[154:157], v158 offset:2048
	ds_read_b128 v[158:161], v158 offset:3072
	v_lshl_add_u64 v[210:211], s[24:25], 0, v[206:207]
	s_add_i32 m0, s23, 0xc000
	ds_read_b128 v[162:165], v240
	ds_read_b128 v[166:169], v240 offset:1024
	ds_read_b128 v[170:173], v240 offset:2048
	ds_read_b128 v[174:177], v240 offset:3072
	ds_read_b128 v[178:181], v240 offset:4096
	ds_read_b128 v[182:185], v240 offset:5120
	ds_read_b128 v[186:189], v240 offset:6144
	ds_read_b128 v[196:199], v240 offset:7168
	global_load_lds_dwordx4 v[210:211], off
	s_add_i32 m0, s23, 0xe000
	v_lshl_add_u64 v[210:211], s[24:25], 0, v[208:209]
	global_load_lds_dwordx4 v[210:211], off
	s_waitcnt vmcnt(8) lgkmcnt(0)
	s_setprio 1
	s_barrier
	v_mfma_f32_16x16x32_bf16 v[126:129], v[130:133], v[162:165], v[126:129]
	v_mfma_f32_16x16x32_bf16 v[122:125], v[138:141], v[162:165], v[122:125]
	v_mfma_f32_16x16x32_bf16 v[110:113], v[130:133], v[170:173], v[110:113]
	v_mfma_f32_16x16x32_bf16 v[106:109], v[138:141], v[170:173], v[106:109]
	v_mfma_f32_16x16x32_bf16 v[98:101], v[130:133], v[178:181], v[98:101]
	v_mfma_f32_16x16x32_bf16 v[90:93], v[138:141], v[178:181], v[90:93]
	v_mfma_f32_16x16x32_bf16 v[82:85], v[130:133], v[186:189], v[82:85]
	v_mfma_f32_16x16x32_bf16 v[74:77], v[138:141], v[186:189], v[74:77]
	v_mfma_f32_16x16x32_bf16 v[126:129], v[134:137], v[166:169], v[126:129]
	v_mfma_f32_16x16x32_bf16 v[122:125], v[142:145], v[166:169], v[122:125]
	v_mfma_f32_16x16x32_bf16 v[110:113], v[134:137], v[174:177], v[110:113]
	v_mfma_f32_16x16x32_bf16 v[106:109], v[142:145], v[174:177], v[106:109]
	v_mfma_f32_16x16x32_bf16 v[98:101], v[134:137], v[182:185], v[98:101]
	v_mfma_f32_16x16x32_bf16 v[90:93], v[142:145], v[182:185], v[90:93]
	v_mfma_f32_16x16x32_bf16 v[82:85], v[134:137], v[196:199], v[82:85]
	v_mfma_f32_16x16x32_bf16 v[74:77], v[142:145], v[196:199], v[74:77]
	v_mfma_f32_16x16x32_bf16 v[118:121], v[146:149], v[162:165], v[118:121]
	v_mfma_f32_16x16x32_bf16 v[114:117], v[154:157], v[162:165], v[114:117]
	v_mfma_f32_16x16x32_bf16 v[102:105], v[146:149], v[170:173], v[102:105]
	v_mfma_f32_16x16x32_bf16 v[94:97], v[154:157], v[170:173], v[94:97]
	v_mfma_f32_16x16x32_bf16 v[86:89], v[146:149], v[178:181], v[86:89]
	v_mfma_f32_16x16x32_bf16 v[78:81], v[154:157], v[178:181], v[78:81]
	v_mfma_f32_16x16x32_bf16 v[70:73], v[146:149], v[186:189], v[70:73]
	v_mfma_f32_16x16x32_bf16 v[66:69], v[154:157], v[186:189], v[66:69]
	v_mfma_f32_16x16x32_bf16 v[118:121], v[150:153], v[166:169], v[118:121]
	v_mfma_f32_16x16x32_bf16 v[114:117], v[158:161], v[166:169], v[114:117]
	v_mfma_f32_16x16x32_bf16 v[102:105], v[150:153], v[174:177], v[102:105]
	v_mfma_f32_16x16x32_bf16 v[94:97], v[158:161], v[174:177], v[94:97]
	v_mfma_f32_16x16x32_bf16 v[86:89], v[150:153], v[182:185], v[86:89]
	v_mfma_f32_16x16x32_bf16 v[78:81], v[158:161], v[182:185], v[78:81]
	v_mfma_f32_16x16x32_bf16 v[70:73], v[150:153], v[196:199], v[70:73]
	v_mfma_f32_16x16x32_bf16 v[66:69], v[158:161], v[196:199], v[66:69]
	s_setprio 0
	s_barrier
	s_add_i32 s56, s56, s34
	v_lshl_add_u64 v[210:211], s[26:27], 0, v[190:191]
	s_mov_b32 m0, s56
	ds_read_b128 v[162:165], v240 offset:16384
	ds_read_b128 v[166:169], v240 offset:17408
	ds_read_b128 v[170:173], v240 offset:18432
	ds_read_b128 v[174:177], v240 offset:19456
	ds_read_b128 v[178:181], v240 offset:20480
	ds_read_b128 v[182:185], v240 offset:21504
	ds_read_b128 v[186:189], v240 offset:22528
	ds_read_b128 v[196:199], v240 offset:23552
	global_load_lds_dwordx4 v[210:211], off
	s_add_i32 m0, s56, 0x2000
	s_add_u32 s56, s26, 0x80000
	v_lshl_add_u64 v[212:213], s[26:27], 0, v[204:205]
	s_addc_u32 s57, s27, 0
	s_add_i32 s60, s60, s34
	global_load_lds_dwordx4 v[212:213], off
	v_lshl_add_u64 v[214:215], s[56:57], 0, v[190:191]
	s_mov_b32 m0, s60
	v_lshl_add_u64 v[216:217], s[28:29], 0, v[202:203]
	global_load_lds_dwordx4 v[214:215], off
	s_add_i32 m0, s60, 0x2000
	v_lshl_add_u64 v[214:215], s[56:57], 0, v[204:205]
	global_load_lds_dwordx4 v[214:215], off
	s_mov_b32 m0, s23
	v_lshl_add_u64 v[214:215], s[28:29], 0, v[200:201]
	global_load_lds_dwordx4 v[214:215], off
	s_mov_b32 m0, s35
	s_nop 0
	global_load_lds_dwordx4 v[216:217], off
	s_waitcnt vmcnt(8) lgkmcnt(0)
	s_setprio 1
	s_barrier
	v_mfma_f32_16x16x32_bf16 v[62:65], v[130:133], v[162:165], v[62:65]
	v_mfma_f32_16x16x32_bf16 v[58:61], v[138:141], v[162:165], v[58:61]
	v_mfma_f32_16x16x32_bf16 v[50:53], v[130:133], v[170:173], v[50:53]
	v_mfma_f32_16x16x32_bf16 v[42:45], v[138:141], v[170:173], v[42:45]
	v_mfma_f32_16x16x32_bf16 v[34:37], v[130:133], v[178:181], v[34:37]
	v_mfma_f32_16x16x32_bf16 v[26:29], v[138:141], v[178:181], v[26:29]
	v_mfma_f32_16x16x32_bf16 v[18:21], v[130:133], v[186:189], v[18:21]
	v_mfma_f32_16x16x32_bf16 v[10:13], v[138:141], v[186:189], v[10:13]
	v_mfma_f32_16x16x32_bf16 v[62:65], v[134:137], v[166:169], v[62:65]
	v_mfma_f32_16x16x32_bf16 v[58:61], v[142:145], v[166:169], v[58:61]
	v_mfma_f32_16x16x32_bf16 v[50:53], v[134:137], v[174:177], v[50:53]
	v_mfma_f32_16x16x32_bf16 v[42:45], v[142:145], v[174:177], v[42:45]
	v_mfma_f32_16x16x32_bf16 v[34:37], v[134:137], v[182:185], v[34:37]
	v_mfma_f32_16x16x32_bf16 v[26:29], v[142:145], v[182:185], v[26:29]
	v_mfma_f32_16x16x32_bf16 v[18:21], v[134:137], v[196:199], v[18:21]
	v_mfma_f32_16x16x32_bf16 v[10:13], v[142:145], v[196:199], v[10:13]
	v_mfma_f32_16x16x32_bf16 v[54:57], v[146:149], v[162:165], v[54:57]
	v_mfma_f32_16x16x32_bf16 v[46:49], v[154:157], v[162:165], v[46:49]
	v_mfma_f32_16x16x32_bf16 v[38:41], v[146:149], v[170:173], v[38:41]
	v_mfma_f32_16x16x32_bf16 v[30:33], v[154:157], v[170:173], v[30:33]
	v_mfma_f32_16x16x32_bf16 v[22:25], v[146:149], v[178:181], v[22:25]
	v_mfma_f32_16x16x32_bf16 v[14:17], v[154:157], v[178:181], v[14:17]
	v_mfma_f32_16x16x32_bf16 v[6:9], v[146:149], v[186:189], v[6:9]
	v_mfma_f32_16x16x32_bf16 v[2:5], v[154:157], v[186:189], v[2:5]
	v_mfma_f32_16x16x32_bf16 v[54:57], v[150:153], v[166:169], v[54:57]
	v_mfma_f32_16x16x32_bf16 v[46:49], v[158:161], v[166:169], v[46:49]
	v_mfma_f32_16x16x32_bf16 v[38:41], v[150:153], v[174:177], v[38:41]
	v_mfma_f32_16x16x32_bf16 v[30:33], v[158:161], v[174:177], v[30:33]
	v_mfma_f32_16x16x32_bf16 v[22:25], v[150:153], v[182:185], v[22:25]
	v_mfma_f32_16x16x32_bf16 v[14:17], v[158:161], v[182:185], v[14:17]
	v_mfma_f32_16x16x32_bf16 v[6:9], v[150:153], v[196:199], v[6:9]
	v_mfma_f32_16x16x32_bf16 v[2:5], v[158:161], v[196:199], v[2:5]
	s_setprio 0
	s_barrier
	s_add_i32 s56, 0, 0x18000
	s_add_i32 s57, 0, 0x1c000
	v_add_u32_e32 v142, s56, v238
	v_add_u32_e32 v158, s57, v238
	ds_read_b128 v[130:133], v142
	ds_read_b128 v[134:137], v142 offset:1024
	ds_read_b128 v[138:141], v142 offset:2048
	ds_read_b128 v[142:145], v142 offset:3072
	ds_read_b128 v[146:149], v158
	ds_read_b128 v[150:153], v158 offset:1024
	ds_read_b128 v[154:157], v158 offset:2048
	ds_read_b128 v[158:161], v158 offset:3072
	s_add_u32 s28, s28, 0x80000
	s_addc_u32 s29, s29, 0
	s_mov_b32 m0, s41
	v_lshl_add_u64 v[218:219], s[28:29], 0, v[200:201]
	ds_read_b128 v[162:165], v240 offset:32768
	ds_read_b128 v[166:169], v240 offset:33792
	ds_read_b128 v[170:173], v240 offset:34816
	ds_read_b128 v[174:177], v240 offset:35840
	ds_read_b128 v[178:181], v240 offset:36864
	ds_read_b128 v[182:185], v240 offset:37888
	ds_read_b128 v[186:189], v240 offset:38912
	ds_read_b128 v[196:199], v240 offset:39936
	global_load_lds_dwordx4 v[218:219], off
	s_mov_b32 m0, s42
	v_lshl_add_u64 v[218:219], s[28:29], 0, v[202:203]
	global_load_lds_dwordx4 v[218:219], off
	s_waitcnt vmcnt(8) lgkmcnt(0)
	s_setprio 1
	s_barrier
	v_mfma_f32_16x16x32_bf16 v[126:129], v[130:133], v[162:165], v[126:129]
	v_mfma_f32_16x16x32_bf16 v[122:125], v[138:141], v[162:165], v[122:125]
	v_mfma_f32_16x16x32_bf16 v[110:113], v[130:133], v[170:173], v[110:113]
	v_mfma_f32_16x16x32_bf16 v[106:109], v[138:141], v[170:173], v[106:109]
	v_mfma_f32_16x16x32_bf16 v[98:101], v[130:133], v[178:181], v[98:101]
	v_mfma_f32_16x16x32_bf16 v[90:93], v[138:141], v[178:181], v[90:93]
	v_mfma_f32_16x16x32_bf16 v[82:85], v[130:133], v[186:189], v[82:85]
	v_mfma_f32_16x16x32_bf16 v[74:77], v[138:141], v[186:189], v[74:77]
	v_mfma_f32_16x16x32_bf16 v[126:129], v[134:137], v[166:169], v[126:129]
	v_mfma_f32_16x16x32_bf16 v[122:125], v[142:145], v[166:169], v[122:125]
	v_mfma_f32_16x16x32_bf16 v[110:113], v[134:137], v[174:177], v[110:113]
	v_mfma_f32_16x16x32_bf16 v[106:109], v[142:145], v[174:177], v[106:109]
	v_mfma_f32_16x16x32_bf16 v[98:101], v[134:137], v[182:185], v[98:101]
	v_mfma_f32_16x16x32_bf16 v[90:93], v[142:145], v[182:185], v[90:93]
	v_mfma_f32_16x16x32_bf16 v[82:85], v[134:137], v[196:199], v[82:85]
	v_mfma_f32_16x16x32_bf16 v[74:77], v[142:145], v[196:199], v[74:77]
	v_mfma_f32_16x16x32_bf16 v[118:121], v[146:149], v[162:165], v[118:121]
	v_mfma_f32_16x16x32_bf16 v[114:117], v[154:157], v[162:165], v[114:117]
	v_mfma_f32_16x16x32_bf16 v[102:105], v[146:149], v[170:173], v[102:105]
	v_mfma_f32_16x16x32_bf16 v[94:97], v[154:157], v[170:173], v[94:97]
	v_mfma_f32_16x16x32_bf16 v[86:89], v[146:149], v[178:181], v[86:89]
	v_mfma_f32_16x16x32_bf16 v[78:81], v[154:157], v[178:181], v[78:81]
	v_mfma_f32_16x16x32_bf16 v[70:73], v[146:149], v[186:189], v[70:73]
	v_mfma_f32_16x16x32_bf16 v[66:69], v[154:157], v[186:189], v[66:69]
	v_mfma_f32_16x16x32_bf16 v[118:121], v[150:153], v[166:169], v[118:121]
	v_mfma_f32_16x16x32_bf16 v[114:117], v[158:161], v[166:169], v[114:117]
	v_mfma_f32_16x16x32_bf16 v[102:105], v[150:153], v[174:177], v[102:105]
	v_mfma_f32_16x16x32_bf16 v[94:97], v[158:161], v[174:177], v[94:97]
	v_mfma_f32_16x16x32_bf16 v[86:89], v[150:153], v[182:185], v[86:89]
	v_mfma_f32_16x16x32_bf16 v[78:81], v[158:161], v[182:185], v[78:81]
	v_mfma_f32_16x16x32_bf16 v[70:73], v[150:153], v[196:199], v[70:73]
	v_mfma_f32_16x16x32_bf16 v[66:69], v[158:161], v[196:199], v[66:69]
	s_setprio 0
	s_barrier
	s_add_i32 s28, s56, s34
	v_lshl_add_u64 v[210:211], v[210:211], 0, s[58:59]
	s_mov_b32 m0, s28
	ds_read_b128 v[162:165], v240 offset:49152
	ds_read_b128 v[166:169], v240 offset:50176
	ds_read_b128 v[170:173], v240 offset:51200
	ds_read_b128 v[174:177], v240 offset:52224
	ds_read_b128 v[178:181], v240 offset:53248
	ds_read_b128 v[182:185], v240 offset:54272
	ds_read_b128 v[186:189], v240 offset:55296
	ds_read_b128 v[196:199], v240 offset:56320
	global_load_lds_dwordx4 v[210:211], off
	s_add_i32 m0, s28, 0x2000
	s_add_u32 s26, s26, 0x80080
	v_lshl_add_u64 v[210:211], v[212:213], 0, s[58:59]
	s_addc_u32 s27, s27, 0
	s_add_i32 s28, s57, s34
	global_load_lds_dwordx4 v[210:211], off
	s_mov_b32 m0, s28
	v_lshl_add_u64 v[210:211], s[26:27], 0, v[190:191]
	global_load_lds_dwordx4 v[210:211], off
	s_add_i32 m0, s28, 0x2000
	v_lshl_add_u64 v[210:211], s[26:27], 0, v[204:205]
	global_load_lds_dwordx4 v[210:211], off
	s_mov_b32 m0, s43
	v_lshl_add_u64 v[210:211], v[214:215], 0, s[58:59]
	global_load_lds_dwordx4 v[210:211], off
	s_mov_b32 m0, s46
	v_lshl_add_u64 v[210:211], v[216:217], 0, s[58:59]
	global_load_lds_dwordx4 v[210:211], off
	s_waitcnt vmcnt(8) lgkmcnt(0)
	s_setprio 1
	s_barrier
	v_mfma_f32_16x16x32_bf16 v[62:65], v[130:133], v[162:165], v[62:65]
	v_mfma_f32_16x16x32_bf16 v[58:61], v[138:141], v[162:165], v[58:61]
	v_mfma_f32_16x16x32_bf16 v[50:53], v[130:133], v[170:173], v[50:53]
	v_mfma_f32_16x16x32_bf16 v[42:45], v[138:141], v[170:173], v[42:45]
	v_mfma_f32_16x16x32_bf16 v[34:37], v[130:133], v[178:181], v[34:37]
	v_mfma_f32_16x16x32_bf16 v[26:29], v[138:141], v[178:181], v[26:29]
	v_mfma_f32_16x16x32_bf16 v[18:21], v[130:133], v[186:189], v[18:21]
	v_mfma_f32_16x16x32_bf16 v[10:13], v[138:141], v[186:189], v[10:13]
	v_mfma_f32_16x16x32_bf16 v[62:65], v[134:137], v[166:169], v[62:65]
	v_mfma_f32_16x16x32_bf16 v[58:61], v[142:145], v[166:169], v[58:61]
	v_mfma_f32_16x16x32_bf16 v[50:53], v[134:137], v[174:177], v[50:53]
	v_mfma_f32_16x16x32_bf16 v[42:45], v[142:145], v[174:177], v[42:45]
	v_mfma_f32_16x16x32_bf16 v[34:37], v[134:137], v[182:185], v[34:37]
	v_mfma_f32_16x16x32_bf16 v[26:29], v[142:145], v[182:185], v[26:29]
	v_mfma_f32_16x16x32_bf16 v[18:21], v[134:137], v[196:199], v[18:21]
	v_mfma_f32_16x16x32_bf16 v[10:13], v[142:145], v[196:199], v[10:13]
	v_mfma_f32_16x16x32_bf16 v[54:57], v[146:149], v[162:165], v[54:57]
	v_mfma_f32_16x16x32_bf16 v[46:49], v[154:157], v[162:165], v[46:49]
	v_mfma_f32_16x16x32_bf16 v[38:41], v[146:149], v[170:173], v[38:41]
	v_mfma_f32_16x16x32_bf16 v[30:33], v[154:157], v[170:173], v[30:33]
	v_mfma_f32_16x16x32_bf16 v[22:25], v[146:149], v[178:181], v[22:25]
	v_mfma_f32_16x16x32_bf16 v[14:17], v[154:157], v[178:181], v[14:17]
	v_mfma_f32_16x16x32_bf16 v[6:9], v[146:149], v[186:189], v[6:9]
	v_mfma_f32_16x16x32_bf16 v[2:5], v[154:157], v[186:189], v[2:5]
	v_mfma_f32_16x16x32_bf16 v[54:57], v[150:153], v[166:169], v[54:57]
	v_mfma_f32_16x16x32_bf16 v[46:49], v[158:161], v[166:169], v[46:49]
	v_mfma_f32_16x16x32_bf16 v[38:41], v[150:153], v[174:177], v[38:41]
	v_mfma_f32_16x16x32_bf16 v[30:33], v[158:161], v[174:177], v[30:33]
	v_mfma_f32_16x16x32_bf16 v[22:25], v[150:153], v[182:185], v[22:25]
	v_mfma_f32_16x16x32_bf16 v[14:17], v[158:161], v[182:185], v[14:17]
	v_mfma_f32_16x16x32_bf16 v[6:9], v[150:153], v[196:199], v[6:9]
	v_mfma_f32_16x16x32_bf16 v[2:5], v[158:161], v[196:199], v[2:5]
	s_setprio 0
	s_barrier
	s_add_i32 s55, s55, 2
	s_add_u32 s24, s24, 0x100
	s_addc_u32 s25, s25, 0
	s_add_u32 s52, s52, 0x100
	s_addc_u32 s53, s53, 0
	s_cmp_gt_u32 s55, 29
	s_cbranch_scc0 .LBB0_800

.LBB0_822:
	s_ashr_i32 s17, s16, 31
	s_lshl_b64 s[22:23], s[16:17], 20
	v_readlane_b32 s0, v254, 60
	s_add_u32 s22, s0, s22
	v_readlane_b32 s0, v254, 61
	s_addc_u32 s23, s0, s23
	s_and_b64 s[24:25], s[20:21], exec
	s_cselect_b32 s17, s23, s31
	s_cselect_b32 s27, s22, s30
	s_ashr_i32 s15, s14, 31
	s_lshl_b64 s[24:25], s[14:15], 20
	v_readlane_b32 s0, v254, 40
	v_readlane_b32 s1, v254, 41
	s_add_u32 s24, s0, s24
	s_addc_u32 s25, s1, s25
	s_and_b64 s[52:53], s[20:21], exec
	s_cselect_b32 s15, s25, s35
	s_cselect_b32 s29, s24, s34
	s_add_u32 s30, s30, 0x80080
	s_addc_u32 s31, s31, 0
	s_add_u32 s81, s34, 0x100
	s_addc_u32 s88, s35, 0
	s_mov_b32 s89, -2
	v_readlane_b32 s90, v255, 49
	s_nop 3
	s_cmp_eq_u32 s90, 6
	v_writelane_b32 v255, 6, 49
	s_cbranch_scc0 .Ltrip0_strict_5
	s_add_u32 s34, s30, 0xfff80080
	s_addc_u32 s35, s31, -1
	s_add_i32 s90, 0, 0x10000
	s_cmp_eq_u32 s89, 28
	s_cselect_b32 s53, s17, s35
	s_cselect_b32 s52, s27, s34
	s_cselect_b32 s35, s15, s88
	s_cselect_b32 s34, s29, s81
	s_add_i32 s96, 0, 0x14000
	v_add_u32_e32 v142, s90, v220
	v_add_u32_e32 v158, s96, v220
	ds_read_b128 v[130:133], v142
	ds_read_b128 v[134:137], v142 offset:1024
	ds_read_b128 v[138:141], v142 offset:2048
	ds_read_b128 v[142:145], v142 offset:3072
	ds_read_b128 v[146:149], v158
	ds_read_b128 v[150:153], v158 offset:1024
	ds_read_b128 v[154:157], v158 offset:2048
	ds_read_b128 v[158:161], v158 offset:3072
	v_lshl_add_u64 v[210:211], s[30:31], 0, v[202:203]
	s_add_i32 m0, s55, 0xc000
	ds_read_b128 v[162:165], v222
	ds_read_b128 v[166:169], v222 offset:1024
	ds_read_b128 v[170:173], v222 offset:2048
	ds_read_b128 v[174:177], v222 offset:3072
	ds_read_b128 v[178:181], v222 offset:4096
	ds_read_b128 v[182:185], v222 offset:5120
	ds_read_b128 v[196:199], v222 offset:6144
	ds_read_b128 v[206:209], v222 offset:7168
	global_load_lds_dwordx4 v[210:211], off
	s_add_i32 m0, s55, 0xe000
	v_lshl_add_u64 v[210:211], s[30:31], 0, v[204:205]
	global_load_lds_dwordx4 v[210:211], off
	s_waitcnt vmcnt(24) lgkmcnt(0)
	s_setprio 1
	s_barrier
	v_mfma_f32_16x16x32_bf16 v[126:129], v[130:133], v[162:165], 0
	v_mfma_f32_16x16x32_bf16 v[122:125], v[138:141], v[162:165], 0
	v_mfma_f32_16x16x32_bf16 v[110:113], v[130:133], v[170:173], 0
	v_mfma_f32_16x16x32_bf16 v[106:109], v[138:141], v[170:173], 0
	v_mfma_f32_16x16x32_bf16 v[94:97], v[130:133], v[178:181], 0
	v_mfma_f32_16x16x32_bf16 v[90:93], v[138:141], v[178:181], 0
	v_mfma_f32_16x16x32_bf16 v[78:81], v[130:133], v[196:199], 0
	v_mfma_f32_16x16x32_bf16 v[74:77], v[138:141], v[196:199], 0
	v_mfma_f32_16x16x32_bf16 v[126:129], v[134:137], v[166:169], v[126:129]
	v_mfma_f32_16x16x32_bf16 v[122:125], v[142:145], v[166:169], v[122:125]
	v_mfma_f32_16x16x32_bf16 v[110:113], v[134:137], v[174:177], v[110:113]
	v_mfma_f32_16x16x32_bf16 v[106:109], v[142:145], v[174:177], v[106:109]
	v_mfma_f32_16x16x32_bf16 v[94:97], v[134:137], v[182:185], v[94:97]
	v_mfma_f32_16x16x32_bf16 v[90:93], v[142:145], v[182:185], v[90:93]
	v_mfma_f32_16x16x32_bf16 v[78:81], v[134:137], v[206:209], v[78:81]
	v_mfma_f32_16x16x32_bf16 v[74:77], v[142:145], v[206:209], v[74:77]
	v_mfma_f32_16x16x32_bf16 v[118:121], v[146:149], v[162:165], 0
	v_mfma_f32_16x16x32_bf16 v[114:117], v[154:157], v[162:165], 0
	v_mfma_f32_16x16x32_bf16 v[102:105], v[146:149], v[170:173], 0
	v_mfma_f32_16x16x32_bf16 v[98:101], v[154:157], v[170:173], 0
	v_mfma_f32_16x16x32_bf16 v[86:89], v[146:149], v[178:181], 0
	v_mfma_f32_16x16x32_bf16 v[82:85], v[154:157], v[178:181], 0
	v_mfma_f32_16x16x32_bf16 v[70:73], v[146:149], v[196:199], 0
	v_mfma_f32_16x16x32_bf16 v[66:69], v[154:157], v[196:199], 0
	v_mfma_f32_16x16x32_bf16 v[118:121], v[150:153], v[166:169], v[118:121]
	v_mfma_f32_16x16x32_bf16 v[114:117], v[158:161], v[166:169], v[114:117]
	v_mfma_f32_16x16x32_bf16 v[102:105], v[150:153], v[174:177], v[102:105]
	v_mfma_f32_16x16x32_bf16 v[98:101], v[158:161], v[174:177], v[98:101]
	v_mfma_f32_16x16x32_bf16 v[86:89], v[150:153], v[182:185], v[86:89]
	v_mfma_f32_16x16x32_bf16 v[82:85], v[158:161], v[182:185], v[82:85]
	v_mfma_f32_16x16x32_bf16 v[70:73], v[150:153], v[206:209], v[70:73]
	v_mfma_f32_16x16x32_bf16 v[66:69], v[158:161], v[206:209], v[66:69]
	s_barrier
	s_setprio 0
	s_add_i32 s90, s90, s47
	v_lshl_add_u64 v[210:211], s[34:35], 0, v[190:191]
	s_mov_b32 m0, s90
	ds_read_b128 v[162:165], v222 offset:16384
	ds_read_b128 v[166:169], v222 offset:17408
	ds_read_b128 v[170:173], v222 offset:18432
	ds_read_b128 v[174:177], v222 offset:19456
	ds_read_b128 v[178:181], v222 offset:20480
	ds_read_b128 v[182:185], v222 offset:21504
	ds_read_b128 v[196:199], v222 offset:22528
	ds_read_b128 v[206:209], v222 offset:23552
	global_load_lds_dwordx4 v[210:211], off
	s_add_i32 m0, s90, 0x2000
	s_add_u32 s90, s34, 0x80000
	v_lshl_add_u64 v[212:213], s[34:35], 0, v[200:201]
	s_addc_u32 s91, s35, 0
	s_add_i32 s96, s96, s47
	global_load_lds_dwordx4 v[212:213], off
	v_lshl_add_u64 v[214:215], s[90:91], 0, v[190:191]
	s_mov_b32 m0, s96
	v_lshl_add_u64 v[216:217], s[52:53], 0, v[188:189]
	global_load_lds_dwordx4 v[214:215], off
	s_add_i32 m0, s96, 0x2000
	v_lshl_add_u64 v[214:215], s[90:91], 0, v[200:201]
	global_load_lds_dwordx4 v[214:215], off
	s_mov_b32 m0, s55
	v_lshl_add_u64 v[214:215], s[52:53], 0, v[186:187]
	global_load_lds_dwordx4 v[214:215], off
	s_mov_b32 m0, s56
	s_nop 0
	global_load_lds_dwordx4 v[216:217], off
	s_waitcnt vmcnt(24) lgkmcnt(0)
	s_setprio 1
	s_barrier
	v_mfma_f32_16x16x32_bf16 v[62:65], v[130:133], v[162:165], 0
	v_mfma_f32_16x16x32_bf16 v[58:61], v[138:141], v[162:165], 0
	v_mfma_f32_16x16x32_bf16 v[46:49], v[130:133], v[170:173], 0
	v_mfma_f32_16x16x32_bf16 v[42:45], v[138:141], v[170:173], 0
	v_mfma_f32_16x16x32_bf16 v[30:33], v[130:133], v[178:181], 0
	v_mfma_f32_16x16x32_bf16 v[26:29], v[138:141], v[178:181], 0
	v_mfma_f32_16x16x32_bf16 v[14:17], v[130:133], v[196:199], 0
	v_mfma_f32_16x16x32_bf16 v[10:13], v[138:141], v[196:199], 0
	v_mfma_f32_16x16x32_bf16 v[62:65], v[134:137], v[166:169], v[62:65]
	v_mfma_f32_16x16x32_bf16 v[58:61], v[142:145], v[166:169], v[58:61]
	v_mfma_f32_16x16x32_bf16 v[46:49], v[134:137], v[174:177], v[46:49]
	v_mfma_f32_16x16x32_bf16 v[42:45], v[142:145], v[174:177], v[42:45]
	v_mfma_f32_16x16x32_bf16 v[30:33], v[134:137], v[182:185], v[30:33]
	v_mfma_f32_16x16x32_bf16 v[26:29], v[142:145], v[182:185], v[26:29]
	v_mfma_f32_16x16x32_bf16 v[14:17], v[134:137], v[206:209], v[14:17]
	v_mfma_f32_16x16x32_bf16 v[10:13], v[142:145], v[206:209], v[10:13]
	v_mfma_f32_16x16x32_bf16 v[54:57], v[146:149], v[162:165], 0
	v_mfma_f32_16x16x32_bf16 v[50:53], v[154:157], v[162:165], 0
	v_mfma_f32_16x16x32_bf16 v[38:41], v[146:149], v[170:173], 0
	v_mfma_f32_16x16x32_bf16 v[34:37], v[154:157], v[170:173], 0
	v_mfma_f32_16x16x32_bf16 v[22:25], v[146:149], v[178:181], 0
	v_mfma_f32_16x16x32_bf16 v[18:21], v[154:157], v[178:181], 0
	v_mfma_f32_16x16x32_bf16 v[6:9], v[146:149], v[196:199], 0
	v_mfma_f32_16x16x32_bf16 v[2:5], v[154:157], v[196:199], 0
	v_mfma_f32_16x16x32_bf16 v[54:57], v[150:153], v[166:169], v[54:57]
	v_mfma_f32_16x16x32_bf16 v[50:53], v[158:161], v[166:169], v[50:53]
	v_mfma_f32_16x16x32_bf16 v[38:41], v[150:153], v[174:177], v[38:41]
	v_mfma_f32_16x16x32_bf16 v[34:37], v[158:161], v[174:177], v[34:37]
	v_mfma_f32_16x16x32_bf16 v[22:25], v[150:153], v[182:185], v[22:25]
	v_mfma_f32_16x16x32_bf16 v[18:21], v[158:161], v[182:185], v[18:21]
	v_mfma_f32_16x16x32_bf16 v[6:9], v[150:153], v[206:209], v[6:9]
	v_mfma_f32_16x16x32_bf16 v[2:5], v[158:161], v[206:209], v[2:5]
	s_barrier
	s_setprio 0
	s_add_i32 s90, 0, 0x18000
	s_add_i32 s91, 0, 0x1c000
	v_add_u32_e32 v142, s90, v220
	v_add_u32_e32 v158, s91, v220
	ds_read_b128 v[130:133], v142
	ds_read_b128 v[134:137], v142 offset:1024
	ds_read_b128 v[138:141], v142 offset:2048
	ds_read_b128 v[142:145], v142 offset:3072
	ds_read_b128 v[146:149], v158
	ds_read_b128 v[150:153], v158 offset:1024
	ds_read_b128 v[154:157], v158 offset:2048
	ds_read_b128 v[158:161], v158 offset:3072
	s_add_u32 s52, s52, 0x80000
	s_addc_u32 s53, s53, 0
	s_mov_b32 m0, s57
	v_lshl_add_u64 v[218:219], s[52:53], 0, v[186:187]
	ds_read_b128 v[162:165], v222 offset:32768
	ds_read_b128 v[166:169], v222 offset:33792
	ds_read_b128 v[170:173], v222 offset:34816
	ds_read_b128 v[174:177], v222 offset:35840
	ds_read_b128 v[178:181], v222 offset:36864
	ds_read_b128 v[182:185], v222 offset:37888
	ds_read_b128 v[196:199], v222 offset:38912
	ds_read_b128 v[206:209], v222 offset:39936
	global_load_lds_dwordx4 v[218:219], off
	s_mov_b32 m0, s60
	v_lshl_add_u64 v[218:219], s[52:53], 0, v[188:189]
	global_load_lds_dwordx4 v[218:219], off
	s_waitcnt vmcnt(8) lgkmcnt(0)
	s_setprio 1
	s_barrier
	v_mfma_f32_16x16x32_bf16 v[126:129], v[130:133], v[162:165], v[126:129]
	v_mfma_f32_16x16x32_bf16 v[122:125], v[138:141], v[162:165], v[122:125]
	v_mfma_f32_16x16x32_bf16 v[110:113], v[130:133], v[170:173], v[110:113]
	v_mfma_f32_16x16x32_bf16 v[106:109], v[138:141], v[170:173], v[106:109]
	v_mfma_f32_16x16x32_bf16 v[94:97], v[130:133], v[178:181], v[94:97]
	v_mfma_f32_16x16x32_bf16 v[90:93], v[138:141], v[178:181], v[90:93]
	v_mfma_f32_16x16x32_bf16 v[78:81], v[130:133], v[196:199], v[78:81]
	v_mfma_f32_16x16x32_bf16 v[74:77], v[138:141], v[196:199], v[74:77]
	v_mfma_f32_16x16x32_bf16 v[126:129], v[134:137], v[166:169], v[126:129]
	v_mfma_f32_16x16x32_bf16 v[122:125], v[142:145], v[166:169], v[122:125]
	v_mfma_f32_16x16x32_bf16 v[110:113], v[134:137], v[174:177], v[110:113]
	v_mfma_f32_16x16x32_bf16 v[106:109], v[142:145], v[174:177], v[106:109]
	v_mfma_f32_16x16x32_bf16 v[94:97], v[134:137], v[182:185], v[94:97]
	v_mfma_f32_16x16x32_bf16 v[90:93], v[142:145], v[182:185], v[90:93]
	v_mfma_f32_16x16x32_bf16 v[78:81], v[134:137], v[206:209], v[78:81]
	v_mfma_f32_16x16x32_bf16 v[74:77], v[142:145], v[206:209], v[74:77]
	v_mfma_f32_16x16x32_bf16 v[118:121], v[146:149], v[162:165], v[118:121]
	v_mfma_f32_16x16x32_bf16 v[114:117], v[154:157], v[162:165], v[114:117]
	v_mfma_f32_16x16x32_bf16 v[102:105], v[146:149], v[170:173], v[102:105]
	v_mfma_f32_16x16x32_bf16 v[98:101], v[154:157], v[170:173], v[98:101]
	v_mfma_f32_16x16x32_bf16 v[86:89], v[146:149], v[178:181], v[86:89]
	v_mfma_f32_16x16x32_bf16 v[82:85], v[154:157], v[178:181], v[82:85]
	v_mfma_f32_16x16x32_bf16 v[70:73], v[146:149], v[196:199], v[70:73]
	v_mfma_f32_16x16x32_bf16 v[66:69], v[154:157], v[196:199], v[66:69]
	v_mfma_f32_16x16x32_bf16 v[118:121], v[150:153], v[166:169], v[118:121]
	v_mfma_f32_16x16x32_bf16 v[114:117], v[158:161], v[166:169], v[114:117]
	v_mfma_f32_16x16x32_bf16 v[102:105], v[150:153], v[174:177], v[102:105]
	v_mfma_f32_16x16x32_bf16 v[98:101], v[158:161], v[174:177], v[98:101]
	v_mfma_f32_16x16x32_bf16 v[86:89], v[150:153], v[182:185], v[86:89]
	v_mfma_f32_16x16x32_bf16 v[82:85], v[158:161], v[182:185], v[82:85]
	v_mfma_f32_16x16x32_bf16 v[70:73], v[150:153], v[206:209], v[70:73]
	v_mfma_f32_16x16x32_bf16 v[66:69], v[158:161], v[206:209], v[66:69]
	s_barrier
	s_setprio 0
	s_add_i32 s52, s90, s47
	v_lshl_add_u64 v[210:211], v[210:211], 0, s[58:59]
	s_mov_b32 m0, s52
	ds_read_b128 v[162:165], v222 offset:49152
	ds_read_b128 v[166:169], v222 offset:50176
	ds_read_b128 v[170:173], v222 offset:51200
	ds_read_b128 v[174:177], v222 offset:52224
	ds_read_b128 v[178:181], v222 offset:53248
	ds_read_b128 v[182:185], v222 offset:54272
	ds_read_b128 v[196:199], v222 offset:55296
	ds_read_b128 v[206:209], v222 offset:56320
	global_load_lds_dwordx4 v[210:211], off
	s_add_i32 m0, s52, 0x2000
	s_add_u32 s34, s34, 0x80080
	v_lshl_add_u64 v[210:211], v[212:213], 0, s[58:59]
	s_addc_u32 s35, s35, 0
	s_add_i32 s52, s91, s47
	global_load_lds_dwordx4 v[210:211], off
	s_mov_b32 m0, s52
	v_lshl_add_u64 v[210:211], s[34:35], 0, v[190:191]
	global_load_lds_dwordx4 v[210:211], off
	s_add_i32 m0, s52, 0x2000
	v_lshl_add_u64 v[210:211], s[34:35], 0, v[200:201]
	global_load_lds_dwordx4 v[210:211], off
	s_mov_b32 m0, s61
	v_lshl_add_u64 v[210:211], v[214:215], 0, s[58:59]
	global_load_lds_dwordx4 v[210:211], off
	s_mov_b32 m0, s69
	v_lshl_add_u64 v[210:211], v[216:217], 0, s[58:59]
	global_load_lds_dwordx4 v[210:211], off
	s_waitcnt vmcnt(8) lgkmcnt(0)
	s_setprio 1
	s_barrier
	v_mfma_f32_16x16x32_bf16 v[62:65], v[130:133], v[162:165], v[62:65]
	v_mfma_f32_16x16x32_bf16 v[58:61], v[138:141], v[162:165], v[58:61]
	v_mfma_f32_16x16x32_bf16 v[46:49], v[130:133], v[170:173], v[46:49]
	v_mfma_f32_16x16x32_bf16 v[42:45], v[138:141], v[170:173], v[42:45]
	v_mfma_f32_16x16x32_bf16 v[30:33], v[130:133], v[178:181], v[30:33]
	v_mfma_f32_16x16x32_bf16 v[26:29], v[138:141], v[178:181], v[26:29]
	v_mfma_f32_16x16x32_bf16 v[14:17], v[130:133], v[196:199], v[14:17]
	v_mfma_f32_16x16x32_bf16 v[10:13], v[138:141], v[196:199], v[10:13]
	v_mfma_f32_16x16x32_bf16 v[62:65], v[134:137], v[166:169], v[62:65]
	v_mfma_f32_16x16x32_bf16 v[58:61], v[142:145], v[166:169], v[58:61]
	v_mfma_f32_16x16x32_bf16 v[46:49], v[134:137], v[174:177], v[46:49]
	v_mfma_f32_16x16x32_bf16 v[42:45], v[142:145], v[174:177], v[42:45]
	v_mfma_f32_16x16x32_bf16 v[30:33], v[134:137], v[182:185], v[30:33]
	v_mfma_f32_16x16x32_bf16 v[26:29], v[142:145], v[182:185], v[26:29]
	v_mfma_f32_16x16x32_bf16 v[14:17], v[134:137], v[206:209], v[14:17]
	v_mfma_f32_16x16x32_bf16 v[10:13], v[142:145], v[206:209], v[10:13]
	v_mfma_f32_16x16x32_bf16 v[54:57], v[146:149], v[162:165], v[54:57]
	v_mfma_f32_16x16x32_bf16 v[50:53], v[154:157], v[162:165], v[50:53]
	v_mfma_f32_16x16x32_bf16 v[38:41], v[146:149], v[170:173], v[38:41]
	v_mfma_f32_16x16x32_bf16 v[34:37], v[154:157], v[170:173], v[34:37]
	v_mfma_f32_16x16x32_bf16 v[22:25], v[146:149], v[178:181], v[22:25]
	v_mfma_f32_16x16x32_bf16 v[18:21], v[154:157], v[178:181], v[18:21]
	v_mfma_f32_16x16x32_bf16 v[6:9], v[146:149], v[196:199], v[6:9]
	v_mfma_f32_16x16x32_bf16 v[2:5], v[154:157], v[196:199], v[2:5]
	v_mfma_f32_16x16x32_bf16 v[54:57], v[150:153], v[166:169], v[54:57]
	v_mfma_f32_16x16x32_bf16 v[50:53], v[158:161], v[166:169], v[50:53]
	v_mfma_f32_16x16x32_bf16 v[38:41], v[150:153], v[174:177], v[38:41]
	v_mfma_f32_16x16x32_bf16 v[34:37], v[158:161], v[174:177], v[34:37]
	v_mfma_f32_16x16x32_bf16 v[22:25], v[150:153], v[182:185], v[22:25]
	v_mfma_f32_16x16x32_bf16 v[18:21], v[158:161], v[182:185], v[18:21]
	v_mfma_f32_16x16x32_bf16 v[6:9], v[150:153], v[206:209], v[6:9]
	v_mfma_f32_16x16x32_bf16 v[2:5], v[158:161], v[206:209], v[2:5]
	s_barrier
	s_setprio 0
	s_add_i32 s89, s89, 2
	s_add_u32 s30, s30, 0x100
	s_addc_u32 s31, s31, 0
	s_add_u32 s81, s81, 0x100
	s_addc_u32 s88, s88, 0
	s_cmp_gt_u32 s89, 29
	s_cbranch_scc1 .Lpeel_done_5
	s_branch .LBB0_823
.Ltrip0_strict_5:
	s_add_u32 s34, s30, 0xfff80080
	s_addc_u32 s35, s31, -1
	s_add_i32 s90, 0, 0x10000
	s_cmp_eq_u32 s89, 28
	s_cselect_b32 s53, s17, s35
	s_cselect_b32 s52, s27, s34
	s_cselect_b32 s35, s15, s88
	s_cselect_b32 s34, s29, s81
	s_add_i32 s96, 0, 0x14000
	v_add_u32_e32 v142, s90, v220
	v_add_u32_e32 v158, s96, v220
	ds_read_b128 v[130:133], v142
	ds_read_b128 v[134:137], v142 offset:1024
	ds_read_b128 v[138:141], v142 offset:2048
	ds_read_b128 v[142:145], v142 offset:3072
	ds_read_b128 v[146:149], v158
	ds_read_b128 v[150:153], v158 offset:1024
	ds_read_b128 v[154:157], v158 offset:2048
	ds_read_b128 v[158:161], v158 offset:3072
	v_lshl_add_u64 v[210:211], s[30:31], 0, v[202:203]
	s_add_i32 m0, s55, 0xc000
	ds_read_b128 v[162:165], v222
	ds_read_b128 v[166:169], v222 offset:1024
	ds_read_b128 v[170:173], v222 offset:2048
	ds_read_b128 v[174:177], v222 offset:3072
	ds_read_b128 v[178:181], v222 offset:4096
	ds_read_b128 v[182:185], v222 offset:5120
	ds_read_b128 v[196:199], v222 offset:6144
	ds_read_b128 v[206:209], v222 offset:7168
	global_load_lds_dwordx4 v[210:211], off
	s_add_i32 m0, s55, 0xe000
	v_lshl_add_u64 v[210:211], s[30:31], 0, v[204:205]
	global_load_lds_dwordx4 v[210:211], off
	s_waitcnt vmcnt(8) lgkmcnt(0)
	s_setprio 1
	s_barrier
	v_mfma_f32_16x16x32_bf16 v[126:129], v[130:133], v[162:165], 0
	v_mfma_f32_16x16x32_bf16 v[122:125], v[138:141], v[162:165], 0
	v_mfma_f32_16x16x32_bf16 v[110:113], v[130:133], v[170:173], 0
	v_mfma_f32_16x16x32_bf16 v[106:109], v[138:141], v[170:173], 0
	v_mfma_f32_16x16x32_bf16 v[94:97], v[130:133], v[178:181], 0
	v_mfma_f32_16x16x32_bf16 v[90:93], v[138:141], v[178:181], 0
	v_mfma_f32_16x16x32_bf16 v[78:81], v[130:133], v[196:199], 0
	v_mfma_f32_16x16x32_bf16 v[74:77], v[138:141], v[196:199], 0
	v_mfma_f32_16x16x32_bf16 v[126:129], v[134:137], v[166:169], v[126:129]
	v_mfma_f32_16x16x32_bf16 v[122:125], v[142:145], v[166:169], v[122:125]
	v_mfma_f32_16x16x32_bf16 v[110:113], v[134:137], v[174:177], v[110:113]
	v_mfma_f32_16x16x32_bf16 v[106:109], v[142:145], v[174:177], v[106:109]
	v_mfma_f32_16x16x32_bf16 v[94:97], v[134:137], v[182:185], v[94:97]
	v_mfma_f32_16x16x32_bf16 v[90:93], v[142:145], v[182:185], v[90:93]
	v_mfma_f32_16x16x32_bf16 v[78:81], v[134:137], v[206:209], v[78:81]
	v_mfma_f32_16x16x32_bf16 v[74:77], v[142:145], v[206:209], v[74:77]
	v_mfma_f32_16x16x32_bf16 v[118:121], v[146:149], v[162:165], 0
	v_mfma_f32_16x16x32_bf16 v[114:117], v[154:157], v[162:165], 0
	v_mfma_f32_16x16x32_bf16 v[102:105], v[146:149], v[170:173], 0
	v_mfma_f32_16x16x32_bf16 v[98:101], v[154:157], v[170:173], 0
	v_mfma_f32_16x16x32_bf16 v[86:89], v[146:149], v[178:181], 0
	v_mfma_f32_16x16x32_bf16 v[82:85], v[154:157], v[178:181], 0
	v_mfma_f32_16x16x32_bf16 v[70:73], v[146:149], v[196:199], 0
	v_mfma_f32_16x16x32_bf16 v[66:69], v[154:157], v[196:199], 0
	v_mfma_f32_16x16x32_bf16 v[118:121], v[150:153], v[166:169], v[118:121]
	v_mfma_f32_16x16x32_bf16 v[114:117], v[158:161], v[166:169], v[114:117]
	v_mfma_f32_16x16x32_bf16 v[102:105], v[150:153], v[174:177], v[102:105]
	v_mfma_f32_16x16x32_bf16 v[98:101], v[158:161], v[174:177], v[98:101]
	v_mfma_f32_16x16x32_bf16 v[86:89], v[150:153], v[182:185], v[86:89]
	v_mfma_f32_16x16x32_bf16 v[82:85], v[158:161], v[182:185], v[82:85]
	v_mfma_f32_16x16x32_bf16 v[70:73], v[150:153], v[206:209], v[70:73]
	v_mfma_f32_16x16x32_bf16 v[66:69], v[158:161], v[206:209], v[66:69]
	s_barrier
	s_setprio 0
	s_add_i32 s90, s90, s47
	v_lshl_add_u64 v[210:211], s[34:35], 0, v[190:191]
	s_mov_b32 m0, s90
	ds_read_b128 v[162:165], v222 offset:16384
	ds_read_b128 v[166:169], v222 offset:17408
	ds_read_b128 v[170:173], v222 offset:18432
	ds_read_b128 v[174:177], v222 offset:19456
	ds_read_b128 v[178:181], v222 offset:20480
	ds_read_b128 v[182:185], v222 offset:21504
	ds_read_b128 v[196:199], v222 offset:22528
	ds_read_b128 v[206:209], v222 offset:23552
	global_load_lds_dwordx4 v[210:211], off
	s_add_i32 m0, s90, 0x2000
	s_add_u32 s90, s34, 0x80000
	v_lshl_add_u64 v[212:213], s[34:35], 0, v[200:201]
	s_addc_u32 s91, s35, 0
	s_add_i32 s96, s96, s47
	global_load_lds_dwordx4 v[212:213], off
	v_lshl_add_u64 v[214:215], s[90:91], 0, v[190:191]
	s_mov_b32 m0, s96
	v_lshl_add_u64 v[216:217], s[52:53], 0, v[188:189]
	global_load_lds_dwordx4 v[214:215], off
	s_add_i32 m0, s96, 0x2000
	v_lshl_add_u64 v[214:215], s[90:91], 0, v[200:201]
	global_load_lds_dwordx4 v[214:215], off
	s_mov_b32 m0, s55
	v_lshl_add_u64 v[214:215], s[52:53], 0, v[186:187]
	global_load_lds_dwordx4 v[214:215], off
	s_mov_b32 m0, s56
	s_nop 0
	global_load_lds_dwordx4 v[216:217], off
	s_waitcnt vmcnt(8) lgkmcnt(0)
	s_setprio 1
	s_barrier
	v_mfma_f32_16x16x32_bf16 v[62:65], v[130:133], v[162:165], 0
	v_mfma_f32_16x16x32_bf16 v[58:61], v[138:141], v[162:165], 0
	v_mfma_f32_16x16x32_bf16 v[46:49], v[130:133], v[170:173], 0
	v_mfma_f32_16x16x32_bf16 v[42:45], v[138:141], v[170:173], 0
	v_mfma_f32_16x16x32_bf16 v[30:33], v[130:133], v[178:181], 0
	v_mfma_f32_16x16x32_bf16 v[26:29], v[138:141], v[178:181], 0
	v_mfma_f32_16x16x32_bf16 v[14:17], v[130:133], v[196:199], 0
	v_mfma_f32_16x16x32_bf16 v[10:13], v[138:141], v[196:199], 0
	v_mfma_f32_16x16x32_bf16 v[62:65], v[134:137], v[166:169], v[62:65]
	v_mfma_f32_16x16x32_bf16 v[58:61], v[142:145], v[166:169], v[58:61]
	v_mfma_f32_16x16x32_bf16 v[46:49], v[134:137], v[174:177], v[46:49]
	v_mfma_f32_16x16x32_bf16 v[42:45], v[142:145], v[174:177], v[42:45]
	v_mfma_f32_16x16x32_bf16 v[30:33], v[134:137], v[182:185], v[30:33]
	v_mfma_f32_16x16x32_bf16 v[26:29], v[142:145], v[182:185], v[26:29]
	v_mfma_f32_16x16x32_bf16 v[14:17], v[134:137], v[206:209], v[14:17]
	v_mfma_f32_16x16x32_bf16 v[10:13], v[142:145], v[206:209], v[10:13]
	v_mfma_f32_16x16x32_bf16 v[54:57], v[146:149], v[162:165], 0
	v_mfma_f32_16x16x32_bf16 v[50:53], v[154:157], v[162:165], 0
	v_mfma_f32_16x16x32_bf16 v[38:41], v[146:149], v[170:173], 0
	v_mfma_f32_16x16x32_bf16 v[34:37], v[154:157], v[170:173], 0
	v_mfma_f32_16x16x32_bf16 v[22:25], v[146:149], v[178:181], 0
	v_mfma_f32_16x16x32_bf16 v[18:21], v[154:157], v[178:181], 0
	v_mfma_f32_16x16x32_bf16 v[6:9], v[146:149], v[196:199], 0
	v_mfma_f32_16x16x32_bf16 v[2:5], v[154:157], v[196:199], 0
	v_mfma_f32_16x16x32_bf16 v[54:57], v[150:153], v[166:169], v[54:57]
	v_mfma_f32_16x16x32_bf16 v[50:53], v[158:161], v[166:169], v[50:53]
	v_mfma_f32_16x16x32_bf16 v[38:41], v[150:153], v[174:177], v[38:41]
	v_mfma_f32_16x16x32_bf16 v[34:37], v[158:161], v[174:177], v[34:37]
	v_mfma_f32_16x16x32_bf16 v[22:25], v[150:153], v[182:185], v[22:25]
	v_mfma_f32_16x16x32_bf16 v[18:21], v[158:161], v[182:185], v[18:21]
	v_mfma_f32_16x16x32_bf16 v[6:9], v[150:153], v[206:209], v[6:9]
	v_mfma_f32_16x16x32_bf16 v[2:5], v[158:161], v[206:209], v[2:5]
	s_barrier
	s_setprio 0
	s_add_i32 s90, 0, 0x18000
	s_add_i32 s91, 0, 0x1c000
	v_add_u32_e32 v142, s90, v220
	v_add_u32_e32 v158, s91, v220
	ds_read_b128 v[130:133], v142
	ds_read_b128 v[134:137], v142 offset:1024
	ds_read_b128 v[138:141], v142 offset:2048
	ds_read_b128 v[142:145], v142 offset:3072
	ds_read_b128 v[146:149], v158
	ds_read_b128 v[150:153], v158 offset:1024
	ds_read_b128 v[154:157], v158 offset:2048
	ds_read_b128 v[158:161], v158 offset:3072
	s_add_u32 s52, s52, 0x80000
	s_addc_u32 s53, s53, 0
	s_mov_b32 m0, s57
	v_lshl_add_u64 v[218:219], s[52:53], 0, v[186:187]
	ds_read_b128 v[162:165], v222 offset:32768
	ds_read_b128 v[166:169], v222 offset:33792
	ds_read_b128 v[170:173], v222 offset:34816
	ds_read_b128 v[174:177], v222 offset:35840
	ds_read_b128 v[178:181], v222 offset:36864
	ds_read_b128 v[182:185], v222 offset:37888
	ds_read_b128 v[196:199], v222 offset:38912
	ds_read_b128 v[206:209], v222 offset:39936
	global_load_lds_dwordx4 v[218:219], off
	s_mov_b32 m0, s60
	v_lshl_add_u64 v[218:219], s[52:53], 0, v[188:189]
	global_load_lds_dwordx4 v[218:219], off
	s_waitcnt vmcnt(8) lgkmcnt(0)
	s_setprio 1
	s_barrier
	v_mfma_f32_16x16x32_bf16 v[126:129], v[130:133], v[162:165], v[126:129]
	v_mfma_f32_16x16x32_bf16 v[122:125], v[138:141], v[162:165], v[122:125]
	v_mfma_f32_16x16x32_bf16 v[110:113], v[130:133], v[170:173], v[110:113]
	v_mfma_f32_16x16x32_bf16 v[106:109], v[138:141], v[170:173], v[106:109]
	v_mfma_f32_16x16x32_bf16 v[94:97], v[130:133], v[178:181], v[94:97]
	v_mfma_f32_16x16x32_bf16 v[90:93], v[138:141], v[178:181], v[90:93]
	v_mfma_f32_16x16x32_bf16 v[78:81], v[130:133], v[196:199], v[78:81]
	v_mfma_f32_16x16x32_bf16 v[74:77], v[138:141], v[196:199], v[74:77]
	v_mfma_f32_16x16x32_bf16 v[126:129], v[134:137], v[166:169], v[126:129]
	v_mfma_f32_16x16x32_bf16 v[122:125], v[142:145], v[166:169], v[122:125]
	v_mfma_f32_16x16x32_bf16 v[110:113], v[134:137], v[174:177], v[110:113]
	v_mfma_f32_16x16x32_bf16 v[106:109], v[142:145], v[174:177], v[106:109]
	v_mfma_f32_16x16x32_bf16 v[94:97], v[134:137], v[182:185], v[94:97]
	v_mfma_f32_16x16x32_bf16 v[90:93], v[142:145], v[182:185], v[90:93]
	v_mfma_f32_16x16x32_bf16 v[78:81], v[134:137], v[206:209], v[78:81]
	v_mfma_f32_16x16x32_bf16 v[74:77], v[142:145], v[206:209], v[74:77]
	v_mfma_f32_16x16x32_bf16 v[118:121], v[146:149], v[162:165], v[118:121]
	v_mfma_f32_16x16x32_bf16 v[114:117], v[154:157], v[162:165], v[114:117]
	v_mfma_f32_16x16x32_bf16 v[102:105], v[146:149], v[170:173], v[102:105]
	v_mfma_f32_16x16x32_bf16 v[98:101], v[154:157], v[170:173], v[98:101]
	v_mfma_f32_16x16x32_bf16 v[86:89], v[146:149], v[178:181], v[86:89]
	v_mfma_f32_16x16x32_bf16 v[82:85], v[154:157], v[178:181], v[82:85]
	v_mfma_f32_16x16x32_bf16 v[70:73], v[146:149], v[196:199], v[70:73]
	v_mfma_f32_16x16x32_bf16 v[66:69], v[154:157], v[196:199], v[66:69]
	v_mfma_f32_16x16x32_bf16 v[118:121], v[150:153], v[166:169], v[118:121]
	v_mfma_f32_16x16x32_bf16 v[114:117], v[158:161], v[166:169], v[114:117]
	v_mfma_f32_16x16x32_bf16 v[102:105], v[150:153], v[174:177], v[102:105]
	v_mfma_f32_16x16x32_bf16 v[98:101], v[158:161], v[174:177], v[98:101]
	v_mfma_f32_16x16x32_bf16 v[86:89], v[150:153], v[182:185], v[86:89]
	v_mfma_f32_16x16x32_bf16 v[82:85], v[158:161], v[182:185], v[82:85]
	v_mfma_f32_16x16x32_bf16 v[70:73], v[150:153], v[206:209], v[70:73]
	v_mfma_f32_16x16x32_bf16 v[66:69], v[158:161], v[206:209], v[66:69]
	s_barrier
	s_setprio 0
	s_add_i32 s52, s90, s47
	v_lshl_add_u64 v[210:211], v[210:211], 0, s[58:59]
	s_mov_b32 m0, s52
	ds_read_b128 v[162:165], v222 offset:49152
	ds_read_b128 v[166:169], v222 offset:50176
	ds_read_b128 v[170:173], v222 offset:51200
	ds_read_b128 v[174:177], v222 offset:52224
	ds_read_b128 v[178:181], v222 offset:53248
	ds_read_b128 v[182:185], v222 offset:54272
	ds_read_b128 v[196:199], v222 offset:55296
	ds_read_b128 v[206:209], v222 offset:56320
	global_load_lds_dwordx4 v[210:211], off
	s_add_i32 m0, s52, 0x2000
	s_add_u32 s34, s34, 0x80080
	v_lshl_add_u64 v[210:211], v[212:213], 0, s[58:59]
	s_addc_u32 s35, s35, 0
	s_add_i32 s52, s91, s47
	global_load_lds_dwordx4 v[210:211], off
	s_mov_b32 m0, s52
	v_lshl_add_u64 v[210:211], s[34:35], 0, v[190:191]
	global_load_lds_dwordx4 v[210:211], off
	s_add_i32 m0, s52, 0x2000
	v_lshl_add_u64 v[210:211], s[34:35], 0, v[200:201]
	global_load_lds_dwordx4 v[210:211], off
	s_mov_b32 m0, s61
	v_lshl_add_u64 v[210:211], v[214:215], 0, s[58:59]
	global_load_lds_dwordx4 v[210:211], off
	s_mov_b32 m0, s69
	v_lshl_add_u64 v[210:211], v[216:217], 0, s[58:59]
	global_load_lds_dwordx4 v[210:211], off
	s_waitcnt vmcnt(8) lgkmcnt(0)
	s_setprio 1
	s_barrier
	v_mfma_f32_16x16x32_bf16 v[62:65], v[130:133], v[162:165], v[62:65]
	v_mfma_f32_16x16x32_bf16 v[58:61], v[138:141], v[162:165], v[58:61]
	v_mfma_f32_16x16x32_bf16 v[46:49], v[130:133], v[170:173], v[46:49]
	v_mfma_f32_16x16x32_bf16 v[42:45], v[138:141], v[170:173], v[42:45]
	v_mfma_f32_16x16x32_bf16 v[30:33], v[130:133], v[178:181], v[30:33]
	v_mfma_f32_16x16x32_bf16 v[26:29], v[138:141], v[178:181], v[26:29]
	v_mfma_f32_16x16x32_bf16 v[14:17], v[130:133], v[196:199], v[14:17]
	v_mfma_f32_16x16x32_bf16 v[10:13], v[138:141], v[196:199], v[10:13]
	v_mfma_f32_16x16x32_bf16 v[62:65], v[134:137], v[166:169], v[62:65]
	v_mfma_f32_16x16x32_bf16 v[58:61], v[142:145], v[166:169], v[58:61]
	v_mfma_f32_16x16x32_bf16 v[46:49], v[134:137], v[174:177], v[46:49]
	v_mfma_f32_16x16x32_bf16 v[42:45], v[142:145], v[174:177], v[42:45]
	v_mfma_f32_16x16x32_bf16 v[30:33], v[134:137], v[182:185], v[30:33]
	v_mfma_f32_16x16x32_bf16 v[26:29], v[142:145], v[182:185], v[26:29]
	v_mfma_f32_16x16x32_bf16 v[14:17], v[134:137], v[206:209], v[14:17]
	v_mfma_f32_16x16x32_bf16 v[10:13], v[142:145], v[206:209], v[10:13]
	v_mfma_f32_16x16x32_bf16 v[54:57], v[146:149], v[162:165], v[54:57]
	v_mfma_f32_16x16x32_bf16 v[50:53], v[154:157], v[162:165], v[50:53]
	v_mfma_f32_16x16x32_bf16 v[38:41], v[146:149], v[170:173], v[38:41]
	v_mfma_f32_16x16x32_bf16 v[34:37], v[154:157], v[170:173], v[34:37]
	v_mfma_f32_16x16x32_bf16 v[22:25], v[146:149], v[178:181], v[22:25]
	v_mfma_f32_16x16x32_bf16 v[18:21], v[154:157], v[178:181], v[18:21]
	v_mfma_f32_16x16x32_bf16 v[6:9], v[146:149], v[196:199], v[6:9]
	v_mfma_f32_16x16x32_bf16 v[2:5], v[154:157], v[196:199], v[2:5]
	v_mfma_f32_16x16x32_bf16 v[54:57], v[150:153], v[166:169], v[54:57]
	v_mfma_f32_16x16x32_bf16 v[50:53], v[158:161], v[166:169], v[50:53]
	v_mfma_f32_16x16x32_bf16 v[38:41], v[150:153], v[174:177], v[38:41]
	v_mfma_f32_16x16x32_bf16 v[34:37], v[158:161], v[174:177], v[34:37]
	v_mfma_f32_16x16x32_bf16 v[22:25], v[150:153], v[182:185], v[22:25]
	v_mfma_f32_16x16x32_bf16 v[18:21], v[158:161], v[182:185], v[18:21]
	v_mfma_f32_16x16x32_bf16 v[6:9], v[150:153], v[206:209], v[6:9]
	v_mfma_f32_16x16x32_bf16 v[2:5], v[158:161], v[206:209], v[2:5]
	s_barrier
	s_setprio 0
	s_add_i32 s89, s89, 2
	s_add_u32 s30, s30, 0x100
	s_addc_u32 s31, s31, 0
	s_add_u32 s81, s81, 0x100
	s_addc_u32 s88, s88, 0
	s_cmp_gt_u32 s89, 29
	s_cbranch_scc1 .Lpeel_done_5
.LBB0_823:
	s_add_u32 s34, s30, 0xfff80080
	s_addc_u32 s35, s31, -1
	s_add_i32 s90, 0, 0x10000
	s_cmp_eq_u32 s89, 28
	s_cselect_b32 s53, s17, s35
	s_cselect_b32 s52, s27, s34
	s_cselect_b32 s35, s15, s88
	s_cselect_b32 s34, s29, s81
	s_add_i32 s96, 0, 0x14000
	v_add_u32_e32 v142, s90, v220
	v_add_u32_e32 v158, s96, v220
	ds_read_b128 v[130:133], v142
	ds_read_b128 v[134:137], v142 offset:1024
	ds_read_b128 v[138:141], v142 offset:2048
	ds_read_b128 v[142:145], v142 offset:3072
	ds_read_b128 v[146:149], v158
	ds_read_b128 v[150:153], v158 offset:1024
	ds_read_b128 v[154:157], v158 offset:2048
	ds_read_b128 v[158:161], v158 offset:3072
	v_lshl_add_u64 v[210:211], s[30:31], 0, v[202:203]
	s_add_i32 m0, s55, 0xc000
	ds_read_b128 v[162:165], v222
	ds_read_b128 v[166:169], v222 offset:1024
	ds_read_b128 v[170:173], v222 offset:2048
	ds_read_b128 v[174:177], v222 offset:3072
	ds_read_b128 v[178:181], v222 offset:4096
	ds_read_b128 v[182:185], v222 offset:5120
	ds_read_b128 v[196:199], v222 offset:6144
	ds_read_b128 v[206:209], v222 offset:7168
	global_load_lds_dwordx4 v[210:211], off
	s_add_i32 m0, s55, 0xe000
	v_lshl_add_u64 v[210:211], s[30:31], 0, v[204:205]
	global_load_lds_dwordx4 v[210:211], off
	s_waitcnt vmcnt(8) lgkmcnt(0)
	s_setprio 1
	s_barrier
	v_mfma_f32_16x16x32_bf16 v[126:129], v[130:133], v[162:165], v[126:129]
	v_mfma_f32_16x16x32_bf16 v[122:125], v[138:141], v[162:165], v[122:125]
	v_mfma_f32_16x16x32_bf16 v[110:113], v[130:133], v[170:173], v[110:113]
	v_mfma_f32_16x16x32_bf16 v[106:109], v[138:141], v[170:173], v[106:109]
	v_mfma_f32_16x16x32_bf16 v[94:97], v[130:133], v[178:181], v[94:97]
	v_mfma_f32_16x16x32_bf16 v[90:93], v[138:141], v[178:181], v[90:93]
	v_mfma_f32_16x16x32_bf16 v[78:81], v[130:133], v[196:199], v[78:81]
	v_mfma_f32_16x16x32_bf16 v[74:77], v[138:141], v[196:199], v[74:77]
	v_mfma_f32_16x16x32_bf16 v[126:129], v[134:137], v[166:169], v[126:129]
	v_mfma_f32_16x16x32_bf16 v[122:125], v[142:145], v[166:169], v[122:125]
	v_mfma_f32_16x16x32_bf16 v[110:113], v[134:137], v[174:177], v[110:113]
	v_mfma_f32_16x16x32_bf16 v[106:109], v[142:145], v[174:177], v[106:109]
	v_mfma_f32_16x16x32_bf16 v[94:97], v[134:137], v[182:185], v[94:97]
	v_mfma_f32_16x16x32_bf16 v[90:93], v[142:145], v[182:185], v[90:93]
	v_mfma_f32_16x16x32_bf16 v[78:81], v[134:137], v[206:209], v[78:81]
	v_mfma_f32_16x16x32_bf16 v[74:77], v[142:145], v[206:209], v[74:77]
	v_mfma_f32_16x16x32_bf16 v[118:121], v[146:149], v[162:165], v[118:121]
	v_mfma_f32_16x16x32_bf16 v[114:117], v[154:157], v[162:165], v[114:117]
	v_mfma_f32_16x16x32_bf16 v[102:105], v[146:149], v[170:173], v[102:105]
	v_mfma_f32_16x16x32_bf16 v[98:101], v[154:157], v[170:173], v[98:101]
	v_mfma_f32_16x16x32_bf16 v[86:89], v[146:149], v[178:181], v[86:89]
	v_mfma_f32_16x16x32_bf16 v[82:85], v[154:157], v[178:181], v[82:85]
	v_mfma_f32_16x16x32_bf16 v[70:73], v[146:149], v[196:199], v[70:73]
	v_mfma_f32_16x16x32_bf16 v[66:69], v[154:157], v[196:199], v[66:69]
	v_mfma_f32_16x16x32_bf16 v[118:121], v[150:153], v[166:169], v[118:121]
	v_mfma_f32_16x16x32_bf16 v[114:117], v[158:161], v[166:169], v[114:117]
	v_mfma_f32_16x16x32_bf16 v[102:105], v[150:153], v[174:177], v[102:105]
	v_mfma_f32_16x16x32_bf16 v[98:101], v[158:161], v[174:177], v[98:101]
	v_mfma_f32_16x16x32_bf16 v[86:89], v[150:153], v[182:185], v[86:89]
	v_mfma_f32_16x16x32_bf16 v[82:85], v[158:161], v[182:185], v[82:85]
	v_mfma_f32_16x16x32_bf16 v[70:73], v[150:153], v[206:209], v[70:73]
	v_mfma_f32_16x16x32_bf16 v[66:69], v[158:161], v[206:209], v[66:69]
	s_setprio 0
	s_barrier
	s_add_i32 s90, s90, s47
	v_lshl_add_u64 v[210:211], s[34:35], 0, v[190:191]
	s_mov_b32 m0, s90
	ds_read_b128 v[162:165], v222 offset:16384
	ds_read_b128 v[166:169], v222 offset:17408
	ds_read_b128 v[170:173], v222 offset:18432
	ds_read_b128 v[174:177], v222 offset:19456
	ds_read_b128 v[178:181], v222 offset:20480
	ds_read_b128 v[182:185], v222 offset:21504
	ds_read_b128 v[196:199], v222 offset:22528
	ds_read_b128 v[206:209], v222 offset:23552
	global_load_lds_dwordx4 v[210:211], off
	s_add_i32 m0, s90, 0x2000
	s_add_u32 s90, s34, 0x80000
	v_lshl_add_u64 v[212:213], s[34:35], 0, v[200:201]
	s_addc_u32 s91, s35, 0
	s_add_i32 s96, s96, s47
	global_load_lds_dwordx4 v[212:213], off
	v_lshl_add_u64 v[214:215], s[90:91], 0, v[190:191]
	s_mov_b32 m0, s96
	v_lshl_add_u64 v[216:217], s[52:53], 0, v[188:189]
	global_load_lds_dwordx4 v[214:215], off
	s_add_i32 m0, s96, 0x2000
	v_lshl_add_u64 v[214:215], s[90:91], 0, v[200:201]
	global_load_lds_dwordx4 v[214:215], off
	s_mov_b32 m0, s55
	v_lshl_add_u64 v[214:215], s[52:53], 0, v[186:187]
	global_load_lds_dwordx4 v[214:215], off
	s_mov_b32 m0, s56
	s_nop 0
	global_load_lds_dwordx4 v[216:217], off
	s_waitcnt vmcnt(8) lgkmcnt(0)
	s_setprio 1
	s_barrier
	v_mfma_f32_16x16x32_bf16 v[62:65], v[130:133], v[162:165], v[62:65]
	v_mfma_f32_16x16x32_bf16 v[58:61], v[138:141], v[162:165], v[58:61]
	v_mfma_f32_16x16x32_bf16 v[46:49], v[130:133], v[170:173], v[46:49]
	v_mfma_f32_16x16x32_bf16 v[42:45], v[138:141], v[170:173], v[42:45]
	v_mfma_f32_16x16x32_bf16 v[30:33], v[130:133], v[178:181], v[30:33]
	v_mfma_f32_16x16x32_bf16 v[26:29], v[138:141], v[178:181], v[26:29]
	v_mfma_f32_16x16x32_bf16 v[14:17], v[130:133], v[196:199], v[14:17]
	v_mfma_f32_16x16x32_bf16 v[10:13], v[138:141], v[196:199], v[10:13]
	v_mfma_f32_16x16x32_bf16 v[62:65], v[134:137], v[166:169], v[62:65]
	v_mfma_f32_16x16x32_bf16 v[58:61], v[142:145], v[166:169], v[58:61]
	v_mfma_f32_16x16x32_bf16 v[46:49], v[134:137], v[174:177], v[46:49]
	v_mfma_f32_16x16x32_bf16 v[42:45], v[142:145], v[174:177], v[42:45]
	v_mfma_f32_16x16x32_bf16 v[30:33], v[134:137], v[182:185], v[30:33]
	v_mfma_f32_16x16x32_bf16 v[26:29], v[142:145], v[182:185], v[26:29]
	v_mfma_f32_16x16x32_bf16 v[14:17], v[134:137], v[206:209], v[14:17]
	v_mfma_f32_16x16x32_bf16 v[10:13], v[142:145], v[206:209], v[10:13]
	v_mfma_f32_16x16x32_bf16 v[54:57], v[146:149], v[162:165], v[54:57]
	v_mfma_f32_16x16x32_bf16 v[50:53], v[154:157], v[162:165], v[50:53]
	v_mfma_f32_16x16x32_bf16 v[38:41], v[146:149], v[170:173], v[38:41]
	v_mfma_f32_16x16x32_bf16 v[34:37], v[154:157], v[170:173], v[34:37]
	v_mfma_f32_16x16x32_bf16 v[22:25], v[146:149], v[178:181], v[22:25]
	v_mfma_f32_16x16x32_bf16 v[18:21], v[154:157], v[178:181], v[18:21]
	v_mfma_f32_16x16x32_bf16 v[6:9], v[146:149], v[196:199], v[6:9]
	v_mfma_f32_16x16x32_bf16 v[2:5], v[154:157], v[196:199], v[2:5]
	v_mfma_f32_16x16x32_bf16 v[54:57], v[150:153], v[166:169], v[54:57]
	v_mfma_f32_16x16x32_bf16 v[50:53], v[158:161], v[166:169], v[50:53]
	v_mfma_f32_16x16x32_bf16 v[38:41], v[150:153], v[174:177], v[38:41]
	v_mfma_f32_16x16x32_bf16 v[34:37], v[158:161], v[174:177], v[34:37]
	v_mfma_f32_16x16x32_bf16 v[22:25], v[150:153], v[182:185], v[22:25]
	v_mfma_f32_16x16x32_bf16 v[18:21], v[158:161], v[182:185], v[18:21]
	v_mfma_f32_16x16x32_bf16 v[6:9], v[150:153], v[206:209], v[6:9]
	v_mfma_f32_16x16x32_bf16 v[2:5], v[158:161], v[206:209], v[2:5]
	s_setprio 0
	s_barrier
	s_add_i32 s90, 0, 0x18000
	s_add_i32 s91, 0, 0x1c000
	v_add_u32_e32 v142, s90, v220
	v_add_u32_e32 v158, s91, v220
	ds_read_b128 v[130:133], v142
	ds_read_b128 v[134:137], v142 offset:1024
	ds_read_b128 v[138:141], v142 offset:2048
	ds_read_b128 v[142:145], v142 offset:3072
	ds_read_b128 v[146:149], v158
	ds_read_b128 v[150:153], v158 offset:1024
	ds_read_b128 v[154:157], v158 offset:2048
	ds_read_b128 v[158:161], v158 offset:3072
	s_add_u32 s52, s52, 0x80000
	s_addc_u32 s53, s53, 0
	s_mov_b32 m0, s57
	v_lshl_add_u64 v[218:219], s[52:53], 0, v[186:187]
	ds_read_b128 v[162:165], v222 offset:32768
	ds_read_b128 v[166:169], v222 offset:33792
	ds_read_b128 v[170:173], v222 offset:34816
	ds_read_b128 v[174:177], v222 offset:35840
	ds_read_b128 v[178:181], v222 offset:36864
	ds_read_b128 v[182:185], v222 offset:37888
	ds_read_b128 v[196:199], v222 offset:38912
	ds_read_b128 v[206:209], v222 offset:39936
	global_load_lds_dwordx4 v[218:219], off
	s_mov_b32 m0, s60
	v_lshl_add_u64 v[218:219], s[52:53], 0, v[188:189]
	global_load_lds_dwordx4 v[218:219], off
	s_waitcnt vmcnt(8) lgkmcnt(0)
	s_setprio 1
	s_barrier
	v_mfma_f32_16x16x32_bf16 v[126:129], v[130:133], v[162:165], v[126:129]
	v_mfma_f32_16x16x32_bf16 v[122:125], v[138:141], v[162:165], v[122:125]
	v_mfma_f32_16x16x32_bf16 v[110:113], v[130:133], v[170:173], v[110:113]
	v_mfma_f32_16x16x32_bf16 v[106:109], v[138:141], v[170:173], v[106:109]
	v_mfma_f32_16x16x32_bf16 v[94:97], v[130:133], v[178:181], v[94:97]
	v_mfma_f32_16x16x32_bf16 v[90:93], v[138:141], v[178:181], v[90:93]
	v_mfma_f32_16x16x32_bf16 v[78:81], v[130:133], v[196:199], v[78:81]
	v_mfma_f32_16x16x32_bf16 v[74:77], v[138:141], v[196:199], v[74:77]
	v_mfma_f32_16x16x32_bf16 v[126:129], v[134:137], v[166:169], v[126:129]
	v_mfma_f32_16x16x32_bf16 v[122:125], v[142:145], v[166:169], v[122:125]
	v_mfma_f32_16x16x32_bf16 v[110:113], v[134:137], v[174:177], v[110:113]
	v_mfma_f32_16x16x32_bf16 v[106:109], v[142:145], v[174:177], v[106:109]
	v_mfma_f32_16x16x32_bf16 v[94:97], v[134:137], v[182:185], v[94:97]
	v_mfma_f32_16x16x32_bf16 v[90:93], v[142:145], v[182:185], v[90:93]
	v_mfma_f32_16x16x32_bf16 v[78:81], v[134:137], v[206:209], v[78:81]
	v_mfma_f32_16x16x32_bf16 v[74:77], v[142:145], v[206:209], v[74:77]
	v_mfma_f32_16x16x32_bf16 v[118:121], v[146:149], v[162:165], v[118:121]
	v_mfma_f32_16x16x32_bf16 v[114:117], v[154:157], v[162:165], v[114:117]
	v_mfma_f32_16x16x32_bf16 v[102:105], v[146:149], v[170:173], v[102:105]
	v_mfma_f32_16x16x32_bf16 v[98:101], v[154:157], v[170:173], v[98:101]
	v_mfma_f32_16x16x32_bf16 v[86:89], v[146:149], v[178:181], v[86:89]
	v_mfma_f32_16x16x32_bf16 v[82:85], v[154:157], v[178:181], v[82:85]
	v_mfma_f32_16x16x32_bf16 v[70:73], v[146:149], v[196:199], v[70:73]
	v_mfma_f32_16x16x32_bf16 v[66:69], v[154:157], v[196:199], v[66:69]
	v_mfma_f32_16x16x32_bf16 v[118:121], v[150:153], v[166:169], v[118:121]
	v_mfma_f32_16x16x32_bf16 v[114:117], v[158:161], v[166:169], v[114:117]
	v_mfma_f32_16x16x32_bf16 v[102:105], v[150:153], v[174:177], v[102:105]
	v_mfma_f32_16x16x32_bf16 v[98:101], v[158:161], v[174:177], v[98:101]
	v_mfma_f32_16x16x32_bf16 v[86:89], v[150:153], v[182:185], v[86:89]
	v_mfma_f32_16x16x32_bf16 v[82:85], v[158:161], v[182:185], v[82:85]
	v_mfma_f32_16x16x32_bf16 v[70:73], v[150:153], v[206:209], v[70:73]
	v_mfma_f32_16x16x32_bf16 v[66:69], v[158:161], v[206:209], v[66:69]
	s_setprio 0
	s_barrier
	s_add_i32 s52, s90, s47
	v_lshl_add_u64 v[210:211], v[210:211], 0, s[58:59]
	s_mov_b32 m0, s52
	ds_read_b128 v[162:165], v222 offset:49152
	ds_read_b128 v[166:169], v222 offset:50176
	ds_read_b128 v[170:173], v222 offset:51200
	ds_read_b128 v[174:177], v222 offset:52224
	ds_read_b128 v[178:181], v222 offset:53248
	ds_read_b128 v[182:185], v222 offset:54272
	ds_read_b128 v[196:199], v222 offset:55296
	ds_read_b128 v[206:209], v222 offset:56320
	global_load_lds_dwordx4 v[210:211], off
	s_add_i32 m0, s52, 0x2000
	s_add_u32 s34, s34, 0x80080
	v_lshl_add_u64 v[210:211], v[212:213], 0, s[58:59]
	s_addc_u32 s35, s35, 0
	s_add_i32 s52, s91, s47
	global_load_lds_dwordx4 v[210:211], off
	s_mov_b32 m0, s52
	v_lshl_add_u64 v[210:211], s[34:35], 0, v[190:191]
	global_load_lds_dwordx4 v[210:211], off
	s_add_i32 m0, s52, 0x2000
	v_lshl_add_u64 v[210:211], s[34:35], 0, v[200:201]
	global_load_lds_dwordx4 v[210:211], off
	s_mov_b32 m0, s61
	v_lshl_add_u64 v[210:211], v[214:215], 0, s[58:59]
	global_load_lds_dwordx4 v[210:211], off
	s_mov_b32 m0, s69
	v_lshl_add_u64 v[210:211], v[216:217], 0, s[58:59]
	global_load_lds_dwordx4 v[210:211], off
	s_waitcnt vmcnt(8) lgkmcnt(0)
	s_setprio 1
	s_barrier
	v_mfma_f32_16x16x32_bf16 v[62:65], v[130:133], v[162:165], v[62:65]
	v_mfma_f32_16x16x32_bf16 v[58:61], v[138:141], v[162:165], v[58:61]
	v_mfma_f32_16x16x32_bf16 v[46:49], v[130:133], v[170:173], v[46:49]
	v_mfma_f32_16x16x32_bf16 v[42:45], v[138:141], v[170:173], v[42:45]
	v_mfma_f32_16x16x32_bf16 v[30:33], v[130:133], v[178:181], v[30:33]
	v_mfma_f32_16x16x32_bf16 v[26:29], v[138:141], v[178:181], v[26:29]
	v_mfma_f32_16x16x32_bf16 v[14:17], v[130:133], v[196:199], v[14:17]
	v_mfma_f32_16x16x32_bf16 v[10:13], v[138:141], v[196:199], v[10:13]
	v_mfma_f32_16x16x32_bf16 v[62:65], v[134:137], v[166:169], v[62:65]
	v_mfma_f32_16x16x32_bf16 v[58:61], v[142:145], v[166:169], v[58:61]
	v_mfma_f32_16x16x32_bf16 v[46:49], v[134:137], v[174:177], v[46:49]
	v_mfma_f32_16x16x32_bf16 v[42:45], v[142:145], v[174:177], v[42:45]
	v_mfma_f32_16x16x32_bf16 v[30:33], v[134:137], v[182:185], v[30:33]
	v_mfma_f32_16x16x32_bf16 v[26:29], v[142:145], v[182:185], v[26:29]
	v_mfma_f32_16x16x32_bf16 v[14:17], v[134:137], v[206:209], v[14:17]
	v_mfma_f32_16x16x32_bf16 v[10:13], v[142:145], v[206:209], v[10:13]
	v_mfma_f32_16x16x32_bf16 v[54:57], v[146:149], v[162:165], v[54:57]
	v_mfma_f32_16x16x32_bf16 v[50:53], v[154:157], v[162:165], v[50:53]
	v_mfma_f32_16x16x32_bf16 v[38:41], v[146:149], v[170:173], v[38:41]
	v_mfma_f32_16x16x32_bf16 v[34:37], v[154:157], v[170:173], v[34:37]
	v_mfma_f32_16x16x32_bf16 v[22:25], v[146:149], v[178:181], v[22:25]
	v_mfma_f32_16x16x32_bf16 v[18:21], v[154:157], v[178:181], v[18:21]
	v_mfma_f32_16x16x32_bf16 v[6:9], v[146:149], v[196:199], v[6:9]
	v_mfma_f32_16x16x32_bf16 v[2:5], v[154:157], v[196:199], v[2:5]
	v_mfma_f32_16x16x32_bf16 v[54:57], v[150:153], v[166:169], v[54:57]
	v_mfma_f32_16x16x32_bf16 v[50:53], v[158:161], v[166:169], v[50:53]
	v_mfma_f32_16x16x32_bf16 v[38:41], v[150:153], v[174:177], v[38:41]
	v_mfma_f32_16x16x32_bf16 v[34:37], v[158:161], v[174:177], v[34:37]
	v_mfma_f32_16x16x32_bf16 v[22:25], v[150:153], v[182:185], v[22:25]
	v_mfma_f32_16x16x32_bf16 v[18:21], v[158:161], v[182:185], v[18:21]
	v_mfma_f32_16x16x32_bf16 v[6:9], v[150:153], v[206:209], v[6:9]
	v_mfma_f32_16x16x32_bf16 v[2:5], v[158:161], v[206:209], v[2:5]
	s_setprio 0
	s_barrier
	s_add_i32 s89, s89, 2
	s_add_u32 s30, s30, 0x100
	s_addc_u32 s31, s31, 0
	s_add_u32 s81, s81, 0x100
	s_addc_u32 s88, s88, 0
	s_cmp_gt_u32 s89, 29
	s_cbranch_scc0 .LBB0_823

.LBB0_937:
	s_ashr_i32 s23, s22, 31
	s_lshl_b64 s[4:5], s[22:23], 20
	s_add_u32 s4, s86, s4
	s_addc_u32 s5, s87, s5
	s_and_b64 s[26:27], s[24:25], exec
	s_cselect_b32 s11, s5, s29
	s_cselect_b32 s23, s4, s28
	s_ashr_i32 s21, s20, 31
	s_lshl_b64 s[26:27], s[20:21], 20
	v_readlane_b32 s0, v254, 38
	v_readlane_b32 s1, v254, 39
	s_add_u32 s26, s0, s26
	s_addc_u32 s27, s1, s27
	s_and_b64 s[34:35], s[24:25], exec
	s_cselect_b32 s21, s27, s31
	s_cselect_b32 s53, s26, s30
	s_add_u32 s28, s28, 0x80080
	s_addc_u32 s29, s29, 0
	s_add_u32 s55, s30, 0x100
	s_addc_u32 s56, s31, 0
	s_mov_b32 s57, -2
	v_readlane_b32 s60, v255, 49
	s_nop 3
	s_cmp_eq_u32 s60, 7
	v_writelane_b32 v255, 7, 49
	s_cbranch_scc0 .Ltrip0_strict_6
	s_add_u32 s30, s28, 0xfff80080
	s_addc_u32 s31, s29, -1
	s_add_i32 s60, 0, 0x10000
	s_cmp_eq_u32 s57, 28
	s_cselect_b32 s35, s11, s31
	s_cselect_b32 s34, s23, s30
	s_cselect_b32 s31, s21, s56
	s_cselect_b32 s30, s53, s55
	s_add_i32 s66, 0, 0x14000
	v_add_u32_e32 v154, s60, v139
	v_add_u32_e32 v170, s66, v139
	ds_read_b128 v[142:145], v154
	ds_read_b128 v[146:149], v154 offset:1024
	ds_read_b128 v[150:153], v154 offset:2048
	ds_read_b128 v[154:157], v154 offset:3072
	ds_read_b128 v[158:161], v170
	ds_read_b128 v[162:165], v170 offset:1024
	ds_read_b128 v[166:169], v170 offset:2048
	ds_read_b128 v[170:173], v170 offset:3072
	v_lshl_add_u64 v[186:187], s[28:29], 0, v[134:135]
	s_add_i32 m0, s13, 0xc000
	ds_read_b128 v[174:177], v141
	ds_read_b128 v[178:181], v141 offset:1024
	ds_read_b128 v[182:185], v141 offset:2048
	ds_read_b128 v[196:199], v141 offset:3072
	ds_read_b128 v[200:203], v141 offset:4096
	ds_read_b128 v[204:207], v141 offset:5120
	ds_read_b128 v[208:211], v141 offset:6144
	ds_read_b128 v[212:215], v141 offset:7168
	global_load_lds_dwordx4 v[186:187], off
	s_add_i32 m0, s13, 0xe000
	v_lshl_add_u64 v[186:187], s[28:29], 0, v[136:137]
	global_load_lds_dwordx4 v[186:187], off
	s_waitcnt vmcnt(24) lgkmcnt(0)
	s_setprio 1
	s_barrier
	v_mfma_f32_16x16x32_bf16 v[124:127], v[142:145], v[174:177], 0
	v_mfma_f32_16x16x32_bf16 v[120:123], v[150:153], v[174:177], 0
	v_mfma_f32_16x16x32_bf16 v[116:119], v[142:145], v[182:185], 0
	v_mfma_f32_16x16x32_bf16 v[112:115], v[150:153], v[182:185], 0
	v_mfma_f32_16x16x32_bf16 v[100:103], v[142:145], v[200:203], 0
	v_mfma_f32_16x16x32_bf16 v[96:99], v[150:153], v[200:203], 0
	v_mfma_f32_16x16x32_bf16 v[84:87], v[142:145], v[208:211], 0
	v_mfma_f32_16x16x32_bf16 v[80:83], v[150:153], v[208:211], 0
	v_mfma_f32_16x16x32_bf16 v[124:127], v[146:149], v[178:181], v[124:127]
	v_mfma_f32_16x16x32_bf16 v[120:123], v[154:157], v[178:181], v[120:123]
	v_mfma_f32_16x16x32_bf16 v[116:119], v[146:149], v[196:199], v[116:119]
	v_mfma_f32_16x16x32_bf16 v[112:115], v[154:157], v[196:199], v[112:115]
	v_mfma_f32_16x16x32_bf16 v[100:103], v[146:149], v[204:207], v[100:103]
	v_mfma_f32_16x16x32_bf16 v[96:99], v[154:157], v[204:207], v[96:99]
	v_mfma_f32_16x16x32_bf16 v[84:87], v[146:149], v[212:215], v[84:87]
	v_mfma_f32_16x16x32_bf16 v[80:83], v[154:157], v[212:215], v[80:83]
	v_mfma_f32_16x16x32_bf16 v[108:111], v[158:161], v[174:177], 0
	v_mfma_f32_16x16x32_bf16 v[104:107], v[166:169], v[174:177], 0
	v_mfma_f32_16x16x32_bf16 v[92:95], v[158:161], v[182:185], 0
	v_mfma_f32_16x16x32_bf16 v[88:91], v[166:169], v[182:185], 0
	v_mfma_f32_16x16x32_bf16 v[76:79], v[158:161], v[200:203], 0
	v_mfma_f32_16x16x32_bf16 v[72:75], v[166:169], v[200:203], 0
	v_mfma_f32_16x16x32_bf16 v[68:71], v[158:161], v[208:211], 0
	v_mfma_f32_16x16x32_bf16 v[64:67], v[166:169], v[208:211], 0
	v_mfma_f32_16x16x32_bf16 v[108:111], v[162:165], v[178:181], v[108:111]
	v_mfma_f32_16x16x32_bf16 v[104:107], v[170:173], v[178:181], v[104:107]
	v_mfma_f32_16x16x32_bf16 v[92:95], v[162:165], v[196:199], v[92:95]
	v_mfma_f32_16x16x32_bf16 v[88:91], v[170:173], v[196:199], v[88:91]
	v_mfma_f32_16x16x32_bf16 v[76:79], v[162:165], v[204:207], v[76:79]
	v_mfma_f32_16x16x32_bf16 v[72:75], v[170:173], v[204:207], v[72:75]
	v_mfma_f32_16x16x32_bf16 v[68:71], v[162:165], v[212:215], v[68:71]
	v_mfma_f32_16x16x32_bf16 v[64:67], v[170:173], v[212:215], v[64:67]
	s_barrier
	s_setprio 0
	s_add_i32 s60, s60, s38
	v_lshl_add_u64 v[186:187], s[30:31], 0, v[190:191]
	s_mov_b32 m0, s60
	ds_read_b128 v[174:177], v141 offset:16384
	ds_read_b128 v[178:181], v141 offset:17408
	ds_read_b128 v[182:185], v141 offset:18432
	ds_read_b128 v[196:199], v141 offset:19456
	ds_read_b128 v[200:203], v141 offset:20480
	ds_read_b128 v[204:207], v141 offset:21504
	ds_read_b128 v[208:211], v141 offset:22528
	ds_read_b128 v[212:215], v141 offset:23552
	global_load_lds_dwordx4 v[186:187], off
	s_add_i32 m0, s60, 0x2000
	s_add_u32 s60, s30, 0x80000
	v_lshl_add_u64 v[216:217], s[30:31], 0, v[132:133]
	s_addc_u32 s61, s31, 0
	s_add_i32 s66, s66, s38
	global_load_lds_dwordx4 v[216:217], off
	v_lshl_add_u64 v[218:219], s[60:61], 0, v[190:191]
	s_mov_b32 m0, s66
	v_lshl_add_u64 v[220:221], s[34:35], 0, v[130:131]
	global_load_lds_dwordx4 v[218:219], off
	s_add_i32 m0, s66, 0x2000
	v_lshl_add_u64 v[218:219], s[60:61], 0, v[132:133]
	global_load_lds_dwordx4 v[218:219], off
	s_mov_b32 m0, s13
	v_lshl_add_u64 v[218:219], s[34:35], 0, v[128:129]
	global_load_lds_dwordx4 v[218:219], off
	s_mov_b32 m0, s39
	s_nop 0
	global_load_lds_dwordx4 v[220:221], off
	s_waitcnt vmcnt(24) lgkmcnt(0)
	s_setprio 1
	s_barrier
	v_mfma_f32_16x16x32_bf16 v[60:63], v[142:145], v[174:177], 0
	v_mfma_f32_16x16x32_bf16 v[56:59], v[150:153], v[174:177], 0
	v_mfma_f32_16x16x32_bf16 v[52:55], v[142:145], v[182:185], 0
	v_mfma_f32_16x16x32_bf16 v[48:51], v[150:153], v[182:185], 0
	v_mfma_f32_16x16x32_bf16 v[36:39], v[142:145], v[200:203], 0
	v_mfma_f32_16x16x32_bf16 v[32:35], v[150:153], v[200:203], 0
	v_mfma_f32_16x16x32_bf16 v[20:23], v[142:145], v[208:211], 0
	v_mfma_f32_16x16x32_bf16 v[16:19], v[150:153], v[208:211], 0
	v_mfma_f32_16x16x32_bf16 v[60:63], v[146:149], v[178:181], v[60:63]
	v_mfma_f32_16x16x32_bf16 v[56:59], v[154:157], v[178:181], v[56:59]
	v_mfma_f32_16x16x32_bf16 v[52:55], v[146:149], v[196:199], v[52:55]
	v_mfma_f32_16x16x32_bf16 v[48:51], v[154:157], v[196:199], v[48:51]
	v_mfma_f32_16x16x32_bf16 v[36:39], v[146:149], v[204:207], v[36:39]
	v_mfma_f32_16x16x32_bf16 v[32:35], v[154:157], v[204:207], v[32:35]
	v_mfma_f32_16x16x32_bf16 v[20:23], v[146:149], v[212:215], v[20:23]
	v_mfma_f32_16x16x32_bf16 v[16:19], v[154:157], v[212:215], v[16:19]
	v_mfma_f32_16x16x32_bf16 v[44:47], v[158:161], v[174:177], 0
	v_mfma_f32_16x16x32_bf16 v[40:43], v[166:169], v[174:177], 0
	v_mfma_f32_16x16x32_bf16 v[28:31], v[158:161], v[182:185], 0
	v_mfma_f32_16x16x32_bf16 v[24:27], v[166:169], v[182:185], 0
	v_mfma_f32_16x16x32_bf16 v[12:15], v[158:161], v[200:203], 0
	v_mfma_f32_16x16x32_bf16 v[8:11], v[166:169], v[200:203], 0
	v_mfma_f32_16x16x32_bf16 v[4:7], v[158:161], v[208:211], 0
	v_mfma_f32_16x16x32_bf16 v[0:3], v[166:169], v[208:211], 0
	v_mfma_f32_16x16x32_bf16 v[44:47], v[162:165], v[178:181], v[44:47]
	v_mfma_f32_16x16x32_bf16 v[40:43], v[170:173], v[178:181], v[40:43]
	v_mfma_f32_16x16x32_bf16 v[28:31], v[162:165], v[196:199], v[28:31]
	v_mfma_f32_16x16x32_bf16 v[24:27], v[170:173], v[196:199], v[24:27]
	v_mfma_f32_16x16x32_bf16 v[12:15], v[162:165], v[204:207], v[12:15]
	v_mfma_f32_16x16x32_bf16 v[8:11], v[170:173], v[204:207], v[8:11]
	v_mfma_f32_16x16x32_bf16 v[4:7], v[162:165], v[212:215], v[4:7]
	v_mfma_f32_16x16x32_bf16 v[0:3], v[170:173], v[212:215], v[0:3]
	s_barrier
	s_setprio 0
	s_add_i32 s60, 0, 0x18000
	s_add_i32 s61, 0, 0x1c000
	v_add_u32_e32 v154, s60, v139
	v_add_u32_e32 v170, s61, v139
	ds_read_b128 v[142:145], v154
	ds_read_b128 v[146:149], v154 offset:1024
	ds_read_b128 v[150:153], v154 offset:2048
	ds_read_b128 v[154:157], v154 offset:3072
	ds_read_b128 v[158:161], v170
	ds_read_b128 v[162:165], v170 offset:1024
	ds_read_b128 v[166:169], v170 offset:2048
	ds_read_b128 v[170:173], v170 offset:3072
	s_add_u32 s34, s34, 0x80000
	s_addc_u32 s35, s35, 0
	s_mov_b32 m0, s41
	v_lshl_add_u64 v[222:223], s[34:35], 0, v[128:129]
	ds_read_b128 v[174:177], v141 offset:32768
	ds_read_b128 v[178:181], v141 offset:33792
	ds_read_b128 v[182:185], v141 offset:34816
	ds_read_b128 v[196:199], v141 offset:35840
	ds_read_b128 v[200:203], v141 offset:36864
	ds_read_b128 v[204:207], v141 offset:37888
	ds_read_b128 v[208:211], v141 offset:38912
	ds_read_b128 v[212:215], v141 offset:39936
	global_load_lds_dwordx4 v[222:223], off
	s_mov_b32 m0, s42
	v_lshl_add_u64 v[222:223], s[34:35], 0, v[130:131]
	global_load_lds_dwordx4 v[222:223], off
	s_waitcnt vmcnt(8) lgkmcnt(0)
	s_setprio 1
	s_barrier
	v_mfma_f32_16x16x32_bf16 v[124:127], v[142:145], v[174:177], v[124:127]
	v_mfma_f32_16x16x32_bf16 v[120:123], v[150:153], v[174:177], v[120:123]
	v_mfma_f32_16x16x32_bf16 v[116:119], v[142:145], v[182:185], v[116:119]
	v_mfma_f32_16x16x32_bf16 v[112:115], v[150:153], v[182:185], v[112:115]
	v_mfma_f32_16x16x32_bf16 v[100:103], v[142:145], v[200:203], v[100:103]
	v_mfma_f32_16x16x32_bf16 v[96:99], v[150:153], v[200:203], v[96:99]
	v_mfma_f32_16x16x32_bf16 v[84:87], v[142:145], v[208:211], v[84:87]
	v_mfma_f32_16x16x32_bf16 v[80:83], v[150:153], v[208:211], v[80:83]
	v_mfma_f32_16x16x32_bf16 v[124:127], v[146:149], v[178:181], v[124:127]
	v_mfma_f32_16x16x32_bf16 v[120:123], v[154:157], v[178:181], v[120:123]
	v_mfma_f32_16x16x32_bf16 v[116:119], v[146:149], v[196:199], v[116:119]
	v_mfma_f32_16x16x32_bf16 v[112:115], v[154:157], v[196:199], v[112:115]
	v_mfma_f32_16x16x32_bf16 v[100:103], v[146:149], v[204:207], v[100:103]
	v_mfma_f32_16x16x32_bf16 v[96:99], v[154:157], v[204:207], v[96:99]
	v_mfma_f32_16x16x32_bf16 v[84:87], v[146:149], v[212:215], v[84:87]
	v_mfma_f32_16x16x32_bf16 v[80:83], v[154:157], v[212:215], v[80:83]
	v_mfma_f32_16x16x32_bf16 v[108:111], v[158:161], v[174:177], v[108:111]
	v_mfma_f32_16x16x32_bf16 v[104:107], v[166:169], v[174:177], v[104:107]
	v_mfma_f32_16x16x32_bf16 v[92:95], v[158:161], v[182:185], v[92:95]
	v_mfma_f32_16x16x32_bf16 v[88:91], v[166:169], v[182:185], v[88:91]
	v_mfma_f32_16x16x32_bf16 v[76:79], v[158:161], v[200:203], v[76:79]
	v_mfma_f32_16x16x32_bf16 v[72:75], v[166:169], v[200:203], v[72:75]
	v_mfma_f32_16x16x32_bf16 v[68:71], v[158:161], v[208:211], v[68:71]
	v_mfma_f32_16x16x32_bf16 v[64:67], v[166:169], v[208:211], v[64:67]
	v_mfma_f32_16x16x32_bf16 v[108:111], v[162:165], v[178:181], v[108:111]
	v_mfma_f32_16x16x32_bf16 v[104:107], v[170:173], v[178:181], v[104:107]
	v_mfma_f32_16x16x32_bf16 v[92:95], v[162:165], v[196:199], v[92:95]
	v_mfma_f32_16x16x32_bf16 v[88:91], v[170:173], v[196:199], v[88:91]
	v_mfma_f32_16x16x32_bf16 v[76:79], v[162:165], v[204:207], v[76:79]
	v_mfma_f32_16x16x32_bf16 v[72:75], v[170:173], v[204:207], v[72:75]
	v_mfma_f32_16x16x32_bf16 v[68:71], v[162:165], v[212:215], v[68:71]
	v_mfma_f32_16x16x32_bf16 v[64:67], v[170:173], v[212:215], v[64:67]
	s_barrier
	s_setprio 0
	s_add_i32 s34, s60, s38
	v_lshl_add_u64 v[186:187], v[186:187], 0, s[58:59]
	s_mov_b32 m0, s34
	ds_read_b128 v[174:177], v141 offset:49152
	ds_read_b128 v[178:181], v141 offset:50176
	ds_read_b128 v[182:185], v141 offset:51200
	ds_read_b128 v[196:199], v141 offset:52224
	ds_read_b128 v[200:203], v141 offset:53248
	ds_read_b128 v[204:207], v141 offset:54272
	ds_read_b128 v[208:211], v141 offset:55296
	ds_read_b128 v[212:215], v141 offset:56320
	global_load_lds_dwordx4 v[186:187], off
	s_add_i32 m0, s34, 0x2000
	s_add_u32 s30, s30, 0x80080
	v_lshl_add_u64 v[186:187], v[216:217], 0, s[58:59]
	s_addc_u32 s31, s31, 0
	s_add_i32 s34, s61, s38
	global_load_lds_dwordx4 v[186:187], off
	s_mov_b32 m0, s34
	v_lshl_add_u64 v[186:187], s[30:31], 0, v[190:191]
	global_load_lds_dwordx4 v[186:187], off
	s_add_i32 m0, s34, 0x2000
	v_lshl_add_u64 v[186:187], s[30:31], 0, v[132:133]
	global_load_lds_dwordx4 v[186:187], off
	s_mov_b32 m0, s43
	v_lshl_add_u64 v[186:187], v[218:219], 0, s[58:59]
	global_load_lds_dwordx4 v[186:187], off
	s_mov_b32 m0, s47
	v_lshl_add_u64 v[186:187], v[220:221], 0, s[58:59]
	global_load_lds_dwordx4 v[186:187], off
	s_waitcnt vmcnt(8) lgkmcnt(0)
	s_setprio 1
	s_barrier
	v_mfma_f32_16x16x32_bf16 v[60:63], v[142:145], v[174:177], v[60:63]
	v_mfma_f32_16x16x32_bf16 v[56:59], v[150:153], v[174:177], v[56:59]
	v_mfma_f32_16x16x32_bf16 v[52:55], v[142:145], v[182:185], v[52:55]
	v_mfma_f32_16x16x32_bf16 v[48:51], v[150:153], v[182:185], v[48:51]
	v_mfma_f32_16x16x32_bf16 v[36:39], v[142:145], v[200:203], v[36:39]
	v_mfma_f32_16x16x32_bf16 v[32:35], v[150:153], v[200:203], v[32:35]
	v_mfma_f32_16x16x32_bf16 v[20:23], v[142:145], v[208:211], v[20:23]
	v_mfma_f32_16x16x32_bf16 v[16:19], v[150:153], v[208:211], v[16:19]
	v_mfma_f32_16x16x32_bf16 v[60:63], v[146:149], v[178:181], v[60:63]
	v_mfma_f32_16x16x32_bf16 v[56:59], v[154:157], v[178:181], v[56:59]
	v_mfma_f32_16x16x32_bf16 v[52:55], v[146:149], v[196:199], v[52:55]
	v_mfma_f32_16x16x32_bf16 v[48:51], v[154:157], v[196:199], v[48:51]
	v_mfma_f32_16x16x32_bf16 v[36:39], v[146:149], v[204:207], v[36:39]
	v_mfma_f32_16x16x32_bf16 v[32:35], v[154:157], v[204:207], v[32:35]
	v_mfma_f32_16x16x32_bf16 v[20:23], v[146:149], v[212:215], v[20:23]
	v_mfma_f32_16x16x32_bf16 v[16:19], v[154:157], v[212:215], v[16:19]
	v_mfma_f32_16x16x32_bf16 v[44:47], v[158:161], v[174:177], v[44:47]
	v_mfma_f32_16x16x32_bf16 v[40:43], v[166:169], v[174:177], v[40:43]
	v_mfma_f32_16x16x32_bf16 v[28:31], v[158:161], v[182:185], v[28:31]
	v_mfma_f32_16x16x32_bf16 v[24:27], v[166:169], v[182:185], v[24:27]
	v_mfma_f32_16x16x32_bf16 v[12:15], v[158:161], v[200:203], v[12:15]
	v_mfma_f32_16x16x32_bf16 v[8:11], v[166:169], v[200:203], v[8:11]
	v_mfma_f32_16x16x32_bf16 v[4:7], v[158:161], v[208:211], v[4:7]
	v_mfma_f32_16x16x32_bf16 v[0:3], v[166:169], v[208:211], v[0:3]
	v_mfma_f32_16x16x32_bf16 v[44:47], v[162:165], v[178:181], v[44:47]
	v_mfma_f32_16x16x32_bf16 v[40:43], v[170:173], v[178:181], v[40:43]
	v_mfma_f32_16x16x32_bf16 v[28:31], v[162:165], v[196:199], v[28:31]
	v_mfma_f32_16x16x32_bf16 v[24:27], v[170:173], v[196:199], v[24:27]
	v_mfma_f32_16x16x32_bf16 v[12:15], v[162:165], v[204:207], v[12:15]
	v_mfma_f32_16x16x32_bf16 v[8:11], v[170:173], v[204:207], v[8:11]
	v_mfma_f32_16x16x32_bf16 v[4:7], v[162:165], v[212:215], v[4:7]
	v_mfma_f32_16x16x32_bf16 v[0:3], v[170:173], v[212:215], v[0:3]
	s_barrier
	s_setprio 0
	s_add_i32 s57, s57, 2
	s_add_u32 s28, s28, 0x100
	s_addc_u32 s29, s29, 0
	s_add_u32 s55, s55, 0x100
	s_addc_u32 s56, s56, 0
	s_cmp_gt_u32 s57, 29
	s_cbranch_scc1 .Lpeel_done_6
	s_branch .LBB0_938
.Ltrip0_strict_6:
	s_add_u32 s30, s28, 0xfff80080
	s_addc_u32 s31, s29, -1
	s_add_i32 s60, 0, 0x10000
	s_cmp_eq_u32 s57, 28
	s_cselect_b32 s35, s11, s31
	s_cselect_b32 s34, s23, s30
	s_cselect_b32 s31, s21, s56
	s_cselect_b32 s30, s53, s55
	s_add_i32 s66, 0, 0x14000
	v_add_u32_e32 v154, s60, v139
	v_add_u32_e32 v170, s66, v139
	ds_read_b128 v[142:145], v154
	ds_read_b128 v[146:149], v154 offset:1024
	ds_read_b128 v[150:153], v154 offset:2048
	ds_read_b128 v[154:157], v154 offset:3072
	ds_read_b128 v[158:161], v170
	ds_read_b128 v[162:165], v170 offset:1024
	ds_read_b128 v[166:169], v170 offset:2048
	ds_read_b128 v[170:173], v170 offset:3072
	v_lshl_add_u64 v[186:187], s[28:29], 0, v[134:135]
	s_add_i32 m0, s13, 0xc000
	ds_read_b128 v[174:177], v141
	ds_read_b128 v[178:181], v141 offset:1024
	ds_read_b128 v[182:185], v141 offset:2048
	ds_read_b128 v[196:199], v141 offset:3072
	ds_read_b128 v[200:203], v141 offset:4096
	ds_read_b128 v[204:207], v141 offset:5120
	ds_read_b128 v[208:211], v141 offset:6144
	ds_read_b128 v[212:215], v141 offset:7168
	global_load_lds_dwordx4 v[186:187], off
	s_add_i32 m0, s13, 0xe000
	v_lshl_add_u64 v[186:187], s[28:29], 0, v[136:137]
	global_load_lds_dwordx4 v[186:187], off
	s_waitcnt vmcnt(8) lgkmcnt(0)
	s_setprio 1
	s_barrier
	v_mfma_f32_16x16x32_bf16 v[124:127], v[142:145], v[174:177], 0
	v_mfma_f32_16x16x32_bf16 v[120:123], v[150:153], v[174:177], 0
	v_mfma_f32_16x16x32_bf16 v[116:119], v[142:145], v[182:185], 0
	v_mfma_f32_16x16x32_bf16 v[112:115], v[150:153], v[182:185], 0
	v_mfma_f32_16x16x32_bf16 v[100:103], v[142:145], v[200:203], 0
	v_mfma_f32_16x16x32_bf16 v[96:99], v[150:153], v[200:203], 0
	v_mfma_f32_16x16x32_bf16 v[84:87], v[142:145], v[208:211], 0
	v_mfma_f32_16x16x32_bf16 v[80:83], v[150:153], v[208:211], 0
	v_mfma_f32_16x16x32_bf16 v[124:127], v[146:149], v[178:181], v[124:127]
	v_mfma_f32_16x16x32_bf16 v[120:123], v[154:157], v[178:181], v[120:123]
	v_mfma_f32_16x16x32_bf16 v[116:119], v[146:149], v[196:199], v[116:119]
	v_mfma_f32_16x16x32_bf16 v[112:115], v[154:157], v[196:199], v[112:115]
	v_mfma_f32_16x16x32_bf16 v[100:103], v[146:149], v[204:207], v[100:103]
	v_mfma_f32_16x16x32_bf16 v[96:99], v[154:157], v[204:207], v[96:99]
	v_mfma_f32_16x16x32_bf16 v[84:87], v[146:149], v[212:215], v[84:87]
	v_mfma_f32_16x16x32_bf16 v[80:83], v[154:157], v[212:215], v[80:83]
	v_mfma_f32_16x16x32_bf16 v[108:111], v[158:161], v[174:177], 0
	v_mfma_f32_16x16x32_bf16 v[104:107], v[166:169], v[174:177], 0
	v_mfma_f32_16x16x32_bf16 v[92:95], v[158:161], v[182:185], 0
	v_mfma_f32_16x16x32_bf16 v[88:91], v[166:169], v[182:185], 0
	v_mfma_f32_16x16x32_bf16 v[76:79], v[158:161], v[200:203], 0
	v_mfma_f32_16x16x32_bf16 v[72:75], v[166:169], v[200:203], 0
	v_mfma_f32_16x16x32_bf16 v[68:71], v[158:161], v[208:211], 0
	v_mfma_f32_16x16x32_bf16 v[64:67], v[166:169], v[208:211], 0
	v_mfma_f32_16x16x32_bf16 v[108:111], v[162:165], v[178:181], v[108:111]
	v_mfma_f32_16x16x32_bf16 v[104:107], v[170:173], v[178:181], v[104:107]
	v_mfma_f32_16x16x32_bf16 v[92:95], v[162:165], v[196:199], v[92:95]
	v_mfma_f32_16x16x32_bf16 v[88:91], v[170:173], v[196:199], v[88:91]
	v_mfma_f32_16x16x32_bf16 v[76:79], v[162:165], v[204:207], v[76:79]
	v_mfma_f32_16x16x32_bf16 v[72:75], v[170:173], v[204:207], v[72:75]
	v_mfma_f32_16x16x32_bf16 v[68:71], v[162:165], v[212:215], v[68:71]
	v_mfma_f32_16x16x32_bf16 v[64:67], v[170:173], v[212:215], v[64:67]
	s_barrier
	s_setprio 0
	s_add_i32 s60, s60, s38
	v_lshl_add_u64 v[186:187], s[30:31], 0, v[190:191]
	s_mov_b32 m0, s60
	ds_read_b128 v[174:177], v141 offset:16384
	ds_read_b128 v[178:181], v141 offset:17408
	ds_read_b128 v[182:185], v141 offset:18432
	ds_read_b128 v[196:199], v141 offset:19456
	ds_read_b128 v[200:203], v141 offset:20480
	ds_read_b128 v[204:207], v141 offset:21504
	ds_read_b128 v[208:211], v141 offset:22528
	ds_read_b128 v[212:215], v141 offset:23552
	global_load_lds_dwordx4 v[186:187], off
	s_add_i32 m0, s60, 0x2000
	s_add_u32 s60, s30, 0x80000
	v_lshl_add_u64 v[216:217], s[30:31], 0, v[132:133]
	s_addc_u32 s61, s31, 0
	s_add_i32 s66, s66, s38
	global_load_lds_dwordx4 v[216:217], off
	v_lshl_add_u64 v[218:219], s[60:61], 0, v[190:191]
	s_mov_b32 m0, s66
	v_lshl_add_u64 v[220:221], s[34:35], 0, v[130:131]
	global_load_lds_dwordx4 v[218:219], off
	s_add_i32 m0, s66, 0x2000
	v_lshl_add_u64 v[218:219], s[60:61], 0, v[132:133]
	global_load_lds_dwordx4 v[218:219], off
	s_mov_b32 m0, s13
	v_lshl_add_u64 v[218:219], s[34:35], 0, v[128:129]
	global_load_lds_dwordx4 v[218:219], off
	s_mov_b32 m0, s39
	s_nop 0
	global_load_lds_dwordx4 v[220:221], off
	s_waitcnt vmcnt(8) lgkmcnt(0)
	s_setprio 1
	s_barrier
	v_mfma_f32_16x16x32_bf16 v[60:63], v[142:145], v[174:177], 0
	v_mfma_f32_16x16x32_bf16 v[56:59], v[150:153], v[174:177], 0
	v_mfma_f32_16x16x32_bf16 v[52:55], v[142:145], v[182:185], 0
	v_mfma_f32_16x16x32_bf16 v[48:51], v[150:153], v[182:185], 0
	v_mfma_f32_16x16x32_bf16 v[36:39], v[142:145], v[200:203], 0
	v_mfma_f32_16x16x32_bf16 v[32:35], v[150:153], v[200:203], 0
	v_mfma_f32_16x16x32_bf16 v[20:23], v[142:145], v[208:211], 0
	v_mfma_f32_16x16x32_bf16 v[16:19], v[150:153], v[208:211], 0
	v_mfma_f32_16x16x32_bf16 v[60:63], v[146:149], v[178:181], v[60:63]
	v_mfma_f32_16x16x32_bf16 v[56:59], v[154:157], v[178:181], v[56:59]
	v_mfma_f32_16x16x32_bf16 v[52:55], v[146:149], v[196:199], v[52:55]
	v_mfma_f32_16x16x32_bf16 v[48:51], v[154:157], v[196:199], v[48:51]
	v_mfma_f32_16x16x32_bf16 v[36:39], v[146:149], v[204:207], v[36:39]
	v_mfma_f32_16x16x32_bf16 v[32:35], v[154:157], v[204:207], v[32:35]
	v_mfma_f32_16x16x32_bf16 v[20:23], v[146:149], v[212:215], v[20:23]
	v_mfma_f32_16x16x32_bf16 v[16:19], v[154:157], v[212:215], v[16:19]
	v_mfma_f32_16x16x32_bf16 v[44:47], v[158:161], v[174:177], 0
	v_mfma_f32_16x16x32_bf16 v[40:43], v[166:169], v[174:177], 0
	v_mfma_f32_16x16x32_bf16 v[28:31], v[158:161], v[182:185], 0
	v_mfma_f32_16x16x32_bf16 v[24:27], v[166:169], v[182:185], 0
	v_mfma_f32_16x16x32_bf16 v[12:15], v[158:161], v[200:203], 0
	v_mfma_f32_16x16x32_bf16 v[8:11], v[166:169], v[200:203], 0
	v_mfma_f32_16x16x32_bf16 v[4:7], v[158:161], v[208:211], 0
	v_mfma_f32_16x16x32_bf16 v[0:3], v[166:169], v[208:211], 0
	v_mfma_f32_16x16x32_bf16 v[44:47], v[162:165], v[178:181], v[44:47]
	v_mfma_f32_16x16x32_bf16 v[40:43], v[170:173], v[178:181], v[40:43]
	v_mfma_f32_16x16x32_bf16 v[28:31], v[162:165], v[196:199], v[28:31]
	v_mfma_f32_16x16x32_bf16 v[24:27], v[170:173], v[196:199], v[24:27]
	v_mfma_f32_16x16x32_bf16 v[12:15], v[162:165], v[204:207], v[12:15]
	v_mfma_f32_16x16x32_bf16 v[8:11], v[170:173], v[204:207], v[8:11]
	v_mfma_f32_16x16x32_bf16 v[4:7], v[162:165], v[212:215], v[4:7]
	v_mfma_f32_16x16x32_bf16 v[0:3], v[170:173], v[212:215], v[0:3]
	s_barrier
	s_setprio 0
	s_add_i32 s60, 0, 0x18000
	s_add_i32 s61, 0, 0x1c000
	v_add_u32_e32 v154, s60, v139
	v_add_u32_e32 v170, s61, v139
	ds_read_b128 v[142:145], v154
	ds_read_b128 v[146:149], v154 offset:1024
	ds_read_b128 v[150:153], v154 offset:2048
	ds_read_b128 v[154:157], v154 offset:3072
	ds_read_b128 v[158:161], v170
	ds_read_b128 v[162:165], v170 offset:1024
	ds_read_b128 v[166:169], v170 offset:2048
	ds_read_b128 v[170:173], v170 offset:3072
	s_add_u32 s34, s34, 0x80000
	s_addc_u32 s35, s35, 0
	s_mov_b32 m0, s41
	v_lshl_add_u64 v[222:223], s[34:35], 0, v[128:129]
	ds_read_b128 v[174:177], v141 offset:32768
	ds_read_b128 v[178:181], v141 offset:33792
	ds_read_b128 v[182:185], v141 offset:34816
	ds_read_b128 v[196:199], v141 offset:35840
	ds_read_b128 v[200:203], v141 offset:36864
	ds_read_b128 v[204:207], v141 offset:37888
	ds_read_b128 v[208:211], v141 offset:38912
	ds_read_b128 v[212:215], v141 offset:39936
	global_load_lds_dwordx4 v[222:223], off
	s_mov_b32 m0, s42
	v_lshl_add_u64 v[222:223], s[34:35], 0, v[130:131]
	global_load_lds_dwordx4 v[222:223], off
	s_waitcnt vmcnt(8) lgkmcnt(0)
	s_setprio 1
	s_barrier
	v_mfma_f32_16x16x32_bf16 v[124:127], v[142:145], v[174:177], v[124:127]
	v_mfma_f32_16x16x32_bf16 v[120:123], v[150:153], v[174:177], v[120:123]
	v_mfma_f32_16x16x32_bf16 v[116:119], v[142:145], v[182:185], v[116:119]
	v_mfma_f32_16x16x32_bf16 v[112:115], v[150:153], v[182:185], v[112:115]
	v_mfma_f32_16x16x32_bf16 v[100:103], v[142:145], v[200:203], v[100:103]
	v_mfma_f32_16x16x32_bf16 v[96:99], v[150:153], v[200:203], v[96:99]
	v_mfma_f32_16x16x32_bf16 v[84:87], v[142:145], v[208:211], v[84:87]
	v_mfma_f32_16x16x32_bf16 v[80:83], v[150:153], v[208:211], v[80:83]
	v_mfma_f32_16x16x32_bf16 v[124:127], v[146:149], v[178:181], v[124:127]
	v_mfma_f32_16x16x32_bf16 v[120:123], v[154:157], v[178:181], v[120:123]
	v_mfma_f32_16x16x32_bf16 v[116:119], v[146:149], v[196:199], v[116:119]
	v_mfma_f32_16x16x32_bf16 v[112:115], v[154:157], v[196:199], v[112:115]
	v_mfma_f32_16x16x32_bf16 v[100:103], v[146:149], v[204:207], v[100:103]
	v_mfma_f32_16x16x32_bf16 v[96:99], v[154:157], v[204:207], v[96:99]
	v_mfma_f32_16x16x32_bf16 v[84:87], v[146:149], v[212:215], v[84:87]
	v_mfma_f32_16x16x32_bf16 v[80:83], v[154:157], v[212:215], v[80:83]
	v_mfma_f32_16x16x32_bf16 v[108:111], v[158:161], v[174:177], v[108:111]
	v_mfma_f32_16x16x32_bf16 v[104:107], v[166:169], v[174:177], v[104:107]
	v_mfma_f32_16x16x32_bf16 v[92:95], v[158:161], v[182:185], v[92:95]
	v_mfma_f32_16x16x32_bf16 v[88:91], v[166:169], v[182:185], v[88:91]
	v_mfma_f32_16x16x32_bf16 v[76:79], v[158:161], v[200:203], v[76:79]
	v_mfma_f32_16x16x32_bf16 v[72:75], v[166:169], v[200:203], v[72:75]
	v_mfma_f32_16x16x32_bf16 v[68:71], v[158:161], v[208:211], v[68:71]
	v_mfma_f32_16x16x32_bf16 v[64:67], v[166:169], v[208:211], v[64:67]
	v_mfma_f32_16x16x32_bf16 v[108:111], v[162:165], v[178:181], v[108:111]
	v_mfma_f32_16x16x32_bf16 v[104:107], v[170:173], v[178:181], v[104:107]
	v_mfma_f32_16x16x32_bf16 v[92:95], v[162:165], v[196:199], v[92:95]
	v_mfma_f32_16x16x32_bf16 v[88:91], v[170:173], v[196:199], v[88:91]
	v_mfma_f32_16x16x32_bf16 v[76:79], v[162:165], v[204:207], v[76:79]
	v_mfma_f32_16x16x32_bf16 v[72:75], v[170:173], v[204:207], v[72:75]
	v_mfma_f32_16x16x32_bf16 v[68:71], v[162:165], v[212:215], v[68:71]
	v_mfma_f32_16x16x32_bf16 v[64:67], v[170:173], v[212:215], v[64:67]
	s_barrier
	s_setprio 0
	s_add_i32 s34, s60, s38
	v_lshl_add_u64 v[186:187], v[186:187], 0, s[58:59]
	s_mov_b32 m0, s34
	ds_read_b128 v[174:177], v141 offset:49152
	ds_read_b128 v[178:181], v141 offset:50176
	ds_read_b128 v[182:185], v141 offset:51200
	ds_read_b128 v[196:199], v141 offset:52224
	ds_read_b128 v[200:203], v141 offset:53248
	ds_read_b128 v[204:207], v141 offset:54272
	ds_read_b128 v[208:211], v141 offset:55296
	ds_read_b128 v[212:215], v141 offset:56320
	global_load_lds_dwordx4 v[186:187], off
	s_add_i32 m0, s34, 0x2000
	s_add_u32 s30, s30, 0x80080
	v_lshl_add_u64 v[186:187], v[216:217], 0, s[58:59]
	s_addc_u32 s31, s31, 0
	s_add_i32 s34, s61, s38
	global_load_lds_dwordx4 v[186:187], off
	s_mov_b32 m0, s34
	v_lshl_add_u64 v[186:187], s[30:31], 0, v[190:191]
	global_load_lds_dwordx4 v[186:187], off
	s_add_i32 m0, s34, 0x2000
	v_lshl_add_u64 v[186:187], s[30:31], 0, v[132:133]
	global_load_lds_dwordx4 v[186:187], off
	s_mov_b32 m0, s43
	v_lshl_add_u64 v[186:187], v[218:219], 0, s[58:59]
	global_load_lds_dwordx4 v[186:187], off
	s_mov_b32 m0, s47
	v_lshl_add_u64 v[186:187], v[220:221], 0, s[58:59]
	global_load_lds_dwordx4 v[186:187], off
	s_waitcnt vmcnt(8) lgkmcnt(0)
	s_setprio 1
	s_barrier
	v_mfma_f32_16x16x32_bf16 v[60:63], v[142:145], v[174:177], v[60:63]
	v_mfma_f32_16x16x32_bf16 v[56:59], v[150:153], v[174:177], v[56:59]
	v_mfma_f32_16x16x32_bf16 v[52:55], v[142:145], v[182:185], v[52:55]
	v_mfma_f32_16x16x32_bf16 v[48:51], v[150:153], v[182:185], v[48:51]
	v_mfma_f32_16x16x32_bf16 v[36:39], v[142:145], v[200:203], v[36:39]
	v_mfma_f32_16x16x32_bf16 v[32:35], v[150:153], v[200:203], v[32:35]
	v_mfma_f32_16x16x32_bf16 v[20:23], v[142:145], v[208:211], v[20:23]
	v_mfma_f32_16x16x32_bf16 v[16:19], v[150:153], v[208:211], v[16:19]
	v_mfma_f32_16x16x32_bf16 v[60:63], v[146:149], v[178:181], v[60:63]
	v_mfma_f32_16x16x32_bf16 v[56:59], v[154:157], v[178:181], v[56:59]
	v_mfma_f32_16x16x32_bf16 v[52:55], v[146:149], v[196:199], v[52:55]
	v_mfma_f32_16x16x32_bf16 v[48:51], v[154:157], v[196:199], v[48:51]
	v_mfma_f32_16x16x32_bf16 v[36:39], v[146:149], v[204:207], v[36:39]
	v_mfma_f32_16x16x32_bf16 v[32:35], v[154:157], v[204:207], v[32:35]
	v_mfma_f32_16x16x32_bf16 v[20:23], v[146:149], v[212:215], v[20:23]
	v_mfma_f32_16x16x32_bf16 v[16:19], v[154:157], v[212:215], v[16:19]
	v_mfma_f32_16x16x32_bf16 v[44:47], v[158:161], v[174:177], v[44:47]
	v_mfma_f32_16x16x32_bf16 v[40:43], v[166:169], v[174:177], v[40:43]
	v_mfma_f32_16x16x32_bf16 v[28:31], v[158:161], v[182:185], v[28:31]
	v_mfma_f32_16x16x32_bf16 v[24:27], v[166:169], v[182:185], v[24:27]
	v_mfma_f32_16x16x32_bf16 v[12:15], v[158:161], v[200:203], v[12:15]
	v_mfma_f32_16x16x32_bf16 v[8:11], v[166:169], v[200:203], v[8:11]
	v_mfma_f32_16x16x32_bf16 v[4:7], v[158:161], v[208:211], v[4:7]
	v_mfma_f32_16x16x32_bf16 v[0:3], v[166:169], v[208:211], v[0:3]
	v_mfma_f32_16x16x32_bf16 v[44:47], v[162:165], v[178:181], v[44:47]
	v_mfma_f32_16x16x32_bf16 v[40:43], v[170:173], v[178:181], v[40:43]
	v_mfma_f32_16x16x32_bf16 v[28:31], v[162:165], v[196:199], v[28:31]
	v_mfma_f32_16x16x32_bf16 v[24:27], v[170:173], v[196:199], v[24:27]
	v_mfma_f32_16x16x32_bf16 v[12:15], v[162:165], v[204:207], v[12:15]
	v_mfma_f32_16x16x32_bf16 v[8:11], v[170:173], v[204:207], v[8:11]
	v_mfma_f32_16x16x32_bf16 v[4:7], v[162:165], v[212:215], v[4:7]
	v_mfma_f32_16x16x32_bf16 v[0:3], v[170:173], v[212:215], v[0:3]
	s_barrier
	s_setprio 0
	s_add_i32 s57, s57, 2
	s_add_u32 s28, s28, 0x100
	s_addc_u32 s29, s29, 0
	s_add_u32 s55, s55, 0x100
	s_addc_u32 s56, s56, 0
	s_cmp_gt_u32 s57, 29
	s_cbranch_scc1 .Lpeel_done_6
.LBB0_938:
	s_add_u32 s30, s28, 0xfff80080
	s_addc_u32 s31, s29, -1
	s_add_i32 s60, 0, 0x10000
	s_cmp_eq_u32 s57, 28
	s_cselect_b32 s35, s11, s31
	s_cselect_b32 s34, s23, s30
	s_cselect_b32 s31, s21, s56
	s_cselect_b32 s30, s53, s55
	s_add_i32 s66, 0, 0x14000
	v_add_u32_e32 v154, s60, v139
	v_add_u32_e32 v170, s66, v139
	ds_read_b128 v[142:145], v154
	ds_read_b128 v[146:149], v154 offset:1024
	ds_read_b128 v[150:153], v154 offset:2048
	ds_read_b128 v[154:157], v154 offset:3072
	ds_read_b128 v[158:161], v170
	ds_read_b128 v[162:165], v170 offset:1024
	ds_read_b128 v[166:169], v170 offset:2048
	ds_read_b128 v[170:173], v170 offset:3072
	v_lshl_add_u64 v[186:187], s[28:29], 0, v[134:135]
	s_add_i32 m0, s13, 0xc000
	ds_read_b128 v[174:177], v141
	ds_read_b128 v[178:181], v141 offset:1024
	ds_read_b128 v[182:185], v141 offset:2048
	ds_read_b128 v[196:199], v141 offset:3072
	ds_read_b128 v[200:203], v141 offset:4096
	ds_read_b128 v[204:207], v141 offset:5120
	ds_read_b128 v[208:211], v141 offset:6144
	ds_read_b128 v[212:215], v141 offset:7168
	global_load_lds_dwordx4 v[186:187], off
	s_add_i32 m0, s13, 0xe000
	v_lshl_add_u64 v[186:187], s[28:29], 0, v[136:137]
	global_load_lds_dwordx4 v[186:187], off
	s_waitcnt vmcnt(8) lgkmcnt(0)
	s_setprio 1
	s_barrier
	v_mfma_f32_16x16x32_bf16 v[124:127], v[142:145], v[174:177], v[124:127]
	v_mfma_f32_16x16x32_bf16 v[120:123], v[150:153], v[174:177], v[120:123]
	v_mfma_f32_16x16x32_bf16 v[116:119], v[142:145], v[182:185], v[116:119]
	v_mfma_f32_16x16x32_bf16 v[112:115], v[150:153], v[182:185], v[112:115]
	v_mfma_f32_16x16x32_bf16 v[100:103], v[142:145], v[200:203], v[100:103]
	v_mfma_f32_16x16x32_bf16 v[96:99], v[150:153], v[200:203], v[96:99]
	v_mfma_f32_16x16x32_bf16 v[84:87], v[142:145], v[208:211], v[84:87]
	v_mfma_f32_16x16x32_bf16 v[80:83], v[150:153], v[208:211], v[80:83]
	v_mfma_f32_16x16x32_bf16 v[124:127], v[146:149], v[178:181], v[124:127]
	v_mfma_f32_16x16x32_bf16 v[120:123], v[154:157], v[178:181], v[120:123]
	v_mfma_f32_16x16x32_bf16 v[116:119], v[146:149], v[196:199], v[116:119]
	v_mfma_f32_16x16x32_bf16 v[112:115], v[154:157], v[196:199], v[112:115]
	v_mfma_f32_16x16x32_bf16 v[100:103], v[146:149], v[204:207], v[100:103]
	v_mfma_f32_16x16x32_bf16 v[96:99], v[154:157], v[204:207], v[96:99]
	v_mfma_f32_16x16x32_bf16 v[84:87], v[146:149], v[212:215], v[84:87]
	v_mfma_f32_16x16x32_bf16 v[80:83], v[154:157], v[212:215], v[80:83]
	v_mfma_f32_16x16x32_bf16 v[108:111], v[158:161], v[174:177], v[108:111]
	v_mfma_f32_16x16x32_bf16 v[104:107], v[166:169], v[174:177], v[104:107]
	v_mfma_f32_16x16x32_bf16 v[92:95], v[158:161], v[182:185], v[92:95]
	v_mfma_f32_16x16x32_bf16 v[88:91], v[166:169], v[182:185], v[88:91]
	v_mfma_f32_16x16x32_bf16 v[76:79], v[158:161], v[200:203], v[76:79]
	v_mfma_f32_16x16x32_bf16 v[72:75], v[166:169], v[200:203], v[72:75]
	v_mfma_f32_16x16x32_bf16 v[68:71], v[158:161], v[208:211], v[68:71]
	v_mfma_f32_16x16x32_bf16 v[64:67], v[166:169], v[208:211], v[64:67]
	v_mfma_f32_16x16x32_bf16 v[108:111], v[162:165], v[178:181], v[108:111]
	v_mfma_f32_16x16x32_bf16 v[104:107], v[170:173], v[178:181], v[104:107]
	v_mfma_f32_16x16x32_bf16 v[92:95], v[162:165], v[196:199], v[92:95]
	v_mfma_f32_16x16x32_bf16 v[88:91], v[170:173], v[196:199], v[88:91]
	v_mfma_f32_16x16x32_bf16 v[76:79], v[162:165], v[204:207], v[76:79]
	v_mfma_f32_16x16x32_bf16 v[72:75], v[170:173], v[204:207], v[72:75]
	v_mfma_f32_16x16x32_bf16 v[68:71], v[162:165], v[212:215], v[68:71]
	v_mfma_f32_16x16x32_bf16 v[64:67], v[170:173], v[212:215], v[64:67]
	s_setprio 0
	s_barrier
	s_add_i32 s60, s60, s38
	v_lshl_add_u64 v[186:187], s[30:31], 0, v[190:191]
	s_mov_b32 m0, s60
	ds_read_b128 v[174:177], v141 offset:16384
	ds_read_b128 v[178:181], v141 offset:17408
	ds_read_b128 v[182:185], v141 offset:18432
	ds_read_b128 v[196:199], v141 offset:19456
	ds_read_b128 v[200:203], v141 offset:20480
	ds_read_b128 v[204:207], v141 offset:21504
	ds_read_b128 v[208:211], v141 offset:22528
	ds_read_b128 v[212:215], v141 offset:23552
	global_load_lds_dwordx4 v[186:187], off
	s_add_i32 m0, s60, 0x2000
	s_add_u32 s60, s30, 0x80000
	v_lshl_add_u64 v[216:217], s[30:31], 0, v[132:133]
	s_addc_u32 s61, s31, 0
	s_add_i32 s66, s66, s38
	global_load_lds_dwordx4 v[216:217], off
	v_lshl_add_u64 v[218:219], s[60:61], 0, v[190:191]
	s_mov_b32 m0, s66
	v_lshl_add_u64 v[220:221], s[34:35], 0, v[130:131]
	global_load_lds_dwordx4 v[218:219], off
	s_add_i32 m0, s66, 0x2000
	v_lshl_add_u64 v[218:219], s[60:61], 0, v[132:133]
	global_load_lds_dwordx4 v[218:219], off
	s_mov_b32 m0, s13
	v_lshl_add_u64 v[218:219], s[34:35], 0, v[128:129]
	global_load_lds_dwordx4 v[218:219], off
	s_mov_b32 m0, s39
	s_nop 0
	global_load_lds_dwordx4 v[220:221], off
	s_waitcnt vmcnt(8) lgkmcnt(0)
	s_setprio 1
	s_barrier
	v_mfma_f32_16x16x32_bf16 v[60:63], v[142:145], v[174:177], v[60:63]
	v_mfma_f32_16x16x32_bf16 v[56:59], v[150:153], v[174:177], v[56:59]
	v_mfma_f32_16x16x32_bf16 v[52:55], v[142:145], v[182:185], v[52:55]
	v_mfma_f32_16x16x32_bf16 v[48:51], v[150:153], v[182:185], v[48:51]
	v_mfma_f32_16x16x32_bf16 v[36:39], v[142:145], v[200:203], v[36:39]
	v_mfma_f32_16x16x32_bf16 v[32:35], v[150:153], v[200:203], v[32:35]
	v_mfma_f32_16x16x32_bf16 v[20:23], v[142:145], v[208:211], v[20:23]
	v_mfma_f32_16x16x32_bf16 v[16:19], v[150:153], v[208:211], v[16:19]
	v_mfma_f32_16x16x32_bf16 v[60:63], v[146:149], v[178:181], v[60:63]
	v_mfma_f32_16x16x32_bf16 v[56:59], v[154:157], v[178:181], v[56:59]
	v_mfma_f32_16x16x32_bf16 v[52:55], v[146:149], v[196:199], v[52:55]
	v_mfma_f32_16x16x32_bf16 v[48:51], v[154:157], v[196:199], v[48:51]
	v_mfma_f32_16x16x32_bf16 v[36:39], v[146:149], v[204:207], v[36:39]
	v_mfma_f32_16x16x32_bf16 v[32:35], v[154:157], v[204:207], v[32:35]
	v_mfma_f32_16x16x32_bf16 v[20:23], v[146:149], v[212:215], v[20:23]
	v_mfma_f32_16x16x32_bf16 v[16:19], v[154:157], v[212:215], v[16:19]
	v_mfma_f32_16x16x32_bf16 v[44:47], v[158:161], v[174:177], v[44:47]
	v_mfma_f32_16x16x32_bf16 v[40:43], v[166:169], v[174:177], v[40:43]
	v_mfma_f32_16x16x32_bf16 v[28:31], v[158:161], v[182:185], v[28:31]
	v_mfma_f32_16x16x32_bf16 v[24:27], v[166:169], v[182:185], v[24:27]
	v_mfma_f32_16x16x32_bf16 v[12:15], v[158:161], v[200:203], v[12:15]
	v_mfma_f32_16x16x32_bf16 v[8:11], v[166:169], v[200:203], v[8:11]
	v_mfma_f32_16x16x32_bf16 v[4:7], v[158:161], v[208:211], v[4:7]
	v_mfma_f32_16x16x32_bf16 v[0:3], v[166:169], v[208:211], v[0:3]
	v_mfma_f32_16x16x32_bf16 v[44:47], v[162:165], v[178:181], v[44:47]
	v_mfma_f32_16x16x32_bf16 v[40:43], v[170:173], v[178:181], v[40:43]
	v_mfma_f32_16x16x32_bf16 v[28:31], v[162:165], v[196:199], v[28:31]
	v_mfma_f32_16x16x32_bf16 v[24:27], v[170:173], v[196:199], v[24:27]
	v_mfma_f32_16x16x32_bf16 v[12:15], v[162:165], v[204:207], v[12:15]
	v_mfma_f32_16x16x32_bf16 v[8:11], v[170:173], v[204:207], v[8:11]
	v_mfma_f32_16x16x32_bf16 v[4:7], v[162:165], v[212:215], v[4:7]
	v_mfma_f32_16x16x32_bf16 v[0:3], v[170:173], v[212:215], v[0:3]
	s_setprio 0
	s_barrier
	s_add_i32 s60, 0, 0x18000
	s_add_i32 s61, 0, 0x1c000
	v_add_u32_e32 v154, s60, v139
	v_add_u32_e32 v170, s61, v139
	ds_read_b128 v[142:145], v154
	ds_read_b128 v[146:149], v154 offset:1024
	ds_read_b128 v[150:153], v154 offset:2048
	ds_read_b128 v[154:157], v154 offset:3072
	ds_read_b128 v[158:161], v170
	ds_read_b128 v[162:165], v170 offset:1024
	ds_read_b128 v[166:169], v170 offset:2048
	ds_read_b128 v[170:173], v170 offset:3072
	s_add_u32 s34, s34, 0x80000
	s_addc_u32 s35, s35, 0
	s_mov_b32 m0, s41
	v_lshl_add_u64 v[222:223], s[34:35], 0, v[128:129]
	ds_read_b128 v[174:177], v141 offset:32768
	ds_read_b128 v[178:181], v141 offset:33792
	ds_read_b128 v[182:185], v141 offset:34816
	ds_read_b128 v[196:199], v141 offset:35840
	ds_read_b128 v[200:203], v141 offset:36864
	ds_read_b128 v[204:207], v141 offset:37888
	ds_read_b128 v[208:211], v141 offset:38912
	ds_read_b128 v[212:215], v141 offset:39936
	global_load_lds_dwordx4 v[222:223], off
	s_mov_b32 m0, s42
	v_lshl_add_u64 v[222:223], s[34:35], 0, v[130:131]
	global_load_lds_dwordx4 v[222:223], off
	s_waitcnt vmcnt(8) lgkmcnt(0)
	s_setprio 1
	s_barrier
	v_mfma_f32_16x16x32_bf16 v[124:127], v[142:145], v[174:177], v[124:127]
	v_mfma_f32_16x16x32_bf16 v[120:123], v[150:153], v[174:177], v[120:123]
	v_mfma_f32_16x16x32_bf16 v[116:119], v[142:145], v[182:185], v[116:119]
	v_mfma_f32_16x16x32_bf16 v[112:115], v[150:153], v[182:185], v[112:115]
	v_mfma_f32_16x16x32_bf16 v[100:103], v[142:145], v[200:203], v[100:103]
	v_mfma_f32_16x16x32_bf16 v[96:99], v[150:153], v[200:203], v[96:99]
	v_mfma_f32_16x16x32_bf16 v[84:87], v[142:145], v[208:211], v[84:87]
	v_mfma_f32_16x16x32_bf16 v[80:83], v[150:153], v[208:211], v[80:83]
	v_mfma_f32_16x16x32_bf16 v[124:127], v[146:149], v[178:181], v[124:127]
	v_mfma_f32_16x16x32_bf16 v[120:123], v[154:157], v[178:181], v[120:123]
	v_mfma_f32_16x16x32_bf16 v[116:119], v[146:149], v[196:199], v[116:119]
	v_mfma_f32_16x16x32_bf16 v[112:115], v[154:157], v[196:199], v[112:115]
	v_mfma_f32_16x16x32_bf16 v[100:103], v[146:149], v[204:207], v[100:103]
	v_mfma_f32_16x16x32_bf16 v[96:99], v[154:157], v[204:207], v[96:99]
	v_mfma_f32_16x16x32_bf16 v[84:87], v[146:149], v[212:215], v[84:87]
	v_mfma_f32_16x16x32_bf16 v[80:83], v[154:157], v[212:215], v[80:83]
	v_mfma_f32_16x16x32_bf16 v[108:111], v[158:161], v[174:177], v[108:111]
	v_mfma_f32_16x16x32_bf16 v[104:107], v[166:169], v[174:177], v[104:107]
	v_mfma_f32_16x16x32_bf16 v[92:95], v[158:161], v[182:185], v[92:95]
	v_mfma_f32_16x16x32_bf16 v[88:91], v[166:169], v[182:185], v[88:91]
	v_mfma_f32_16x16x32_bf16 v[76:79], v[158:161], v[200:203], v[76:79]
	v_mfma_f32_16x16x32_bf16 v[72:75], v[166:169], v[200:203], v[72:75]
	v_mfma_f32_16x16x32_bf16 v[68:71], v[158:161], v[208:211], v[68:71]
	v_mfma_f32_16x16x32_bf16 v[64:67], v[166:169], v[208:211], v[64:67]
	v_mfma_f32_16x16x32_bf16 v[108:111], v[162:165], v[178:181], v[108:111]
	v_mfma_f32_16x16x32_bf16 v[104:107], v[170:173], v[178:181], v[104:107]
	v_mfma_f32_16x16x32_bf16 v[92:95], v[162:165], v[196:199], v[92:95]
	v_mfma_f32_16x16x32_bf16 v[88:91], v[170:173], v[196:199], v[88:91]
	v_mfma_f32_16x16x32_bf16 v[76:79], v[162:165], v[204:207], v[76:79]
	v_mfma_f32_16x16x32_bf16 v[72:75], v[170:173], v[204:207], v[72:75]
	v_mfma_f32_16x16x32_bf16 v[68:71], v[162:165], v[212:215], v[68:71]
	v_mfma_f32_16x16x32_bf16 v[64:67], v[170:173], v[212:215], v[64:67]
	s_setprio 0
	s_barrier
	s_add_i32 s34, s60, s38
	v_lshl_add_u64 v[186:187], v[186:187], 0, s[58:59]
	s_mov_b32 m0, s34
	ds_read_b128 v[174:177], v141 offset:49152
	ds_read_b128 v[178:181], v141 offset:50176
	ds_read_b128 v[182:185], v141 offset:51200
	ds_read_b128 v[196:199], v141 offset:52224
	ds_read_b128 v[200:203], v141 offset:53248
	ds_read_b128 v[204:207], v141 offset:54272
	ds_read_b128 v[208:211], v141 offset:55296
	ds_read_b128 v[212:215], v141 offset:56320
	global_load_lds_dwordx4 v[186:187], off
	s_add_i32 m0, s34, 0x2000
	s_add_u32 s30, s30, 0x80080
	v_lshl_add_u64 v[186:187], v[216:217], 0, s[58:59]
	s_addc_u32 s31, s31, 0
	s_add_i32 s34, s61, s38
	global_load_lds_dwordx4 v[186:187], off
	s_mov_b32 m0, s34
	v_lshl_add_u64 v[186:187], s[30:31], 0, v[190:191]
	global_load_lds_dwordx4 v[186:187], off
	s_add_i32 m0, s34, 0x2000
	v_lshl_add_u64 v[186:187], s[30:31], 0, v[132:133]
	global_load_lds_dwordx4 v[186:187], off
	s_mov_b32 m0, s43
	v_lshl_add_u64 v[186:187], v[218:219], 0, s[58:59]
	global_load_lds_dwordx4 v[186:187], off
	s_mov_b32 m0, s47
	v_lshl_add_u64 v[186:187], v[220:221], 0, s[58:59]
	global_load_lds_dwordx4 v[186:187], off
	s_waitcnt vmcnt(8) lgkmcnt(0)
	s_setprio 1
	s_barrier
	v_mfma_f32_16x16x32_bf16 v[60:63], v[142:145], v[174:177], v[60:63]
	v_mfma_f32_16x16x32_bf16 v[56:59], v[150:153], v[174:177], v[56:59]
	v_mfma_f32_16x16x32_bf16 v[52:55], v[142:145], v[182:185], v[52:55]
	v_mfma_f32_16x16x32_bf16 v[48:51], v[150:153], v[182:185], v[48:51]
	v_mfma_f32_16x16x32_bf16 v[36:39], v[142:145], v[200:203], v[36:39]
	v_mfma_f32_16x16x32_bf16 v[32:35], v[150:153], v[200:203], v[32:35]
	v_mfma_f32_16x16x32_bf16 v[20:23], v[142:145], v[208:211], v[20:23]
	v_mfma_f32_16x16x32_bf16 v[16:19], v[150:153], v[208:211], v[16:19]
	v_mfma_f32_16x16x32_bf16 v[60:63], v[146:149], v[178:181], v[60:63]
	v_mfma_f32_16x16x32_bf16 v[56:59], v[154:157], v[178:181], v[56:59]
	v_mfma_f32_16x16x32_bf16 v[52:55], v[146:149], v[196:199], v[52:55]
	v_mfma_f32_16x16x32_bf16 v[48:51], v[154:157], v[196:199], v[48:51]
	v_mfma_f32_16x16x32_bf16 v[36:39], v[146:149], v[204:207], v[36:39]
	v_mfma_f32_16x16x32_bf16 v[32:35], v[154:157], v[204:207], v[32:35]
	v_mfma_f32_16x16x32_bf16 v[20:23], v[146:149], v[212:215], v[20:23]
	v_mfma_f32_16x16x32_bf16 v[16:19], v[154:157], v[212:215], v[16:19]
	v_mfma_f32_16x16x32_bf16 v[44:47], v[158:161], v[174:177], v[44:47]
	v_mfma_f32_16x16x32_bf16 v[40:43], v[166:169], v[174:177], v[40:43]
	v_mfma_f32_16x16x32_bf16 v[28:31], v[158:161], v[182:185], v[28:31]
	v_mfma_f32_16x16x32_bf16 v[24:27], v[166:169], v[182:185], v[24:27]
	v_mfma_f32_16x16x32_bf16 v[12:15], v[158:161], v[200:203], v[12:15]
	v_mfma_f32_16x16x32_bf16 v[8:11], v[166:169], v[200:203], v[8:11]
	v_mfma_f32_16x16x32_bf16 v[4:7], v[158:161], v[208:211], v[4:7]
	v_mfma_f32_16x16x32_bf16 v[0:3], v[166:169], v[208:211], v[0:3]
	v_mfma_f32_16x16x32_bf16 v[44:47], v[162:165], v[178:181], v[44:47]
	v_mfma_f32_16x16x32_bf16 v[40:43], v[170:173], v[178:181], v[40:43]
	v_mfma_f32_16x16x32_bf16 v[28:31], v[162:165], v[196:199], v[28:31]
	v_mfma_f32_16x16x32_bf16 v[24:27], v[170:173], v[196:199], v[24:27]
	v_mfma_f32_16x16x32_bf16 v[12:15], v[162:165], v[204:207], v[12:15]
	v_mfma_f32_16x16x32_bf16 v[8:11], v[170:173], v[204:207], v[8:11]
	v_mfma_f32_16x16x32_bf16 v[4:7], v[162:165], v[212:215], v[4:7]
	v_mfma_f32_16x16x32_bf16 v[0:3], v[170:173], v[212:215], v[0:3]
	s_setprio 0
	s_barrier
	s_add_i32 s57, s57, 2
	s_add_u32 s28, s28, 0x100
	s_addc_u32 s29, s29, 0
	s_add_u32 s55, s55, 0x100
	s_addc_u32 s56, s56, 0
	s_cmp_gt_u32 s57, 29
	s_cbranch_scc0 .LBB0_938

.LBB0_1104:
	s_ashr_i32 s61, s60, 31
	s_lshl_b64 s[52:53], s[60:61], 20
	v_readlane_b32 s0, v254, 17
	v_readlane_b32 s1, v254, 18
	s_add_u32 s88, s0, s52
	s_addc_u32 s89, s1, s53
	s_and_b64 s[52:53], s[8:9], exec
	s_cselect_b32 s13, s89, s11
	s_cselect_b32 s15, s88, s10
	s_ashr_i32 s57, s56, 31
	s_lshl_b64 s[52:53], s[56:57], 20
	v_readlane_b32 s0, v254, 36
	v_readlane_b32 s1, v254, 37
	s_add_u32 s90, s0, s52
	s_addc_u32 s91, s1, s53
	s_and_b64 s[52:53], s[8:9], exec
	s_cselect_b32 s57, s91, s17
	s_cselect_b32 s61, s90, s16
	s_add_u32 s66, s16, 0x100
	s_addc_u32 s67, s17, 0
	s_mov_b32 vcc_lo, -2
	v_readlane_b32 s0, v255, 49
	s_nop 3
	s_cmp_eq_u32 s0, 8
	v_writelane_b32 v255, 8, 49
	s_cbranch_scc0 .Ltrip0_strict_7
	s_add_u32 s16, s10, 0x100
	s_addc_u32 s17, s11, 0
	s_add_i32 vcc_hi, 0, 0x10000
	s_cmp_eq_u32 vcc_lo, 28
	s_cselect_b32 s69, s13, s17
	s_cselect_b32 s68, s15, s16
	s_cselect_b32 s53, s57, s67
	s_cselect_b32 s52, s61, s66
	s_add_i32 s0, 0, 0x14000
	v_add_u32_e32 v140, vcc_hi, v200
	v_add_u32_e32 v156, s0, v200
	ds_read_b128 v[128:131], v140
	ds_read_b128 v[132:135], v140 offset:1024
	ds_read_b128 v[136:139], v140 offset:2048
	ds_read_b128 v[140:143], v140 offset:3072
	ds_read_b128 v[144:147], v156
	ds_read_b128 v[148:151], v156 offset:1024
	ds_read_b128 v[152:155], v156 offset:2048
	ds_read_b128 v[156:159], v156 offset:3072
	v_lshl_add_u64 v[186:187], s[10:11], 0, v[182:183]
	s_add_i32 m0, s40, 0xc000
	ds_read_b128 v[160:163], v206
	ds_read_b128 v[164:167], v206 offset:1024
	ds_read_b128 v[168:171], v206 offset:2048
	ds_read_b128 v[172:175], v206 offset:3072
	ds_read_b128 v[196:199], v206 offset:4096
	ds_read_b128 v[208:211], v206 offset:5120
	ds_read_b128 v[212:215], v206 offset:6144
	ds_read_b128 v[216:219], v206 offset:7168
	global_load_lds_dwordx4 v[186:187], off
	s_add_i32 m0, s40, 0xe000
	v_lshl_add_u64 v[186:187], s[10:11], 0, v[184:185]
	global_load_lds_dwordx4 v[186:187], off
	s_waitcnt vmcnt(24) lgkmcnt(0)
	s_setprio 1
	s_barrier
	v_mfma_f32_16x16x32_bf16 v[120:123], v[128:131], v[160:163], 0
	v_mfma_f32_16x16x32_bf16 v[48:51], v[136:139], v[160:163], 0
	v_mfma_f32_16x16x32_bf16 v[124:127], v[128:131], v[168:171], 0
	v_mfma_f32_16x16x32_bf16 v[60:63], v[136:139], v[168:171], 0
	v_mfma_f32_16x16x32_bf16 v[112:115], v[128:131], v[196:199], 0
	v_mfma_f32_16x16x32_bf16 v[52:55], v[136:139], v[196:199], 0
	v_mfma_f32_16x16x32_bf16 v[108:111], v[128:131], v[212:215], 0
	v_mfma_f32_16x16x32_bf16 v[36:39], v[136:139], v[212:215], 0
	v_mfma_f32_16x16x32_bf16 v[120:123], v[132:135], v[164:167], v[120:123]
	v_mfma_f32_16x16x32_bf16 v[48:51], v[140:143], v[164:167], v[48:51]
	v_mfma_f32_16x16x32_bf16 v[124:127], v[132:135], v[172:175], v[124:127]
	v_mfma_f32_16x16x32_bf16 v[60:63], v[140:143], v[172:175], v[60:63]
	v_mfma_f32_16x16x32_bf16 v[112:115], v[132:135], v[208:211], v[112:115]
	v_mfma_f32_16x16x32_bf16 v[52:55], v[140:143], v[208:211], v[52:55]
	v_mfma_f32_16x16x32_bf16 v[108:111], v[132:135], v[216:219], v[108:111]
	v_mfma_f32_16x16x32_bf16 v[36:39], v[140:143], v[216:219], v[36:39]
	v_mfma_f32_16x16x32_bf16 v[100:103], v[144:147], v[160:163], 0
	v_mfma_f32_16x16x32_bf16 v[40:43], v[152:155], v[160:163], 0
	v_mfma_f32_16x16x32_bf16 v[116:119], v[144:147], v[168:171], 0
	v_mfma_f32_16x16x32_bf16 v[56:59], v[152:155], v[168:171], 0
	v_mfma_f32_16x16x32_bf16 v[104:107], v[144:147], v[196:199], 0
	v_mfma_f32_16x16x32_bf16 v[44:47], v[152:155], v[196:199], 0
	v_mfma_f32_16x16x32_bf16 v[96:99], v[144:147], v[212:215], 0
	v_mfma_f32_16x16x32_bf16 v[32:35], v[152:155], v[212:215], 0
	v_mfma_f32_16x16x32_bf16 v[100:103], v[148:151], v[164:167], v[100:103]
	v_mfma_f32_16x16x32_bf16 v[40:43], v[156:159], v[164:167], v[40:43]
	v_mfma_f32_16x16x32_bf16 v[116:119], v[148:151], v[172:175], v[116:119]
	v_mfma_f32_16x16x32_bf16 v[56:59], v[156:159], v[172:175], v[56:59]
	v_mfma_f32_16x16x32_bf16 v[104:107], v[148:151], v[208:211], v[104:107]
	v_mfma_f32_16x16x32_bf16 v[44:47], v[156:159], v[208:211], v[44:47]
	v_mfma_f32_16x16x32_bf16 v[96:99], v[148:151], v[216:219], v[96:99]
	v_mfma_f32_16x16x32_bf16 v[32:35], v[156:159], v[216:219], v[32:35]
	s_barrier
	s_setprio 0
	s_add_i32 s1, vcc_hi, s33
	v_lshl_add_u64 v[186:187], s[52:53], 0, v[190:191]
	s_mov_b32 m0, s1
	ds_read_b128 v[160:163], v206 offset:16384
	ds_read_b128 v[164:167], v206 offset:17408
	ds_read_b128 v[168:171], v206 offset:18432
	ds_read_b128 v[172:175], v206 offset:19456
	ds_read_b128 v[196:199], v206 offset:20480
	ds_read_b128 v[208:211], v206 offset:21504
	ds_read_b128 v[212:215], v206 offset:22528
	ds_read_b128 v[216:219], v206 offset:23552
	global_load_lds_dwordx4 v[186:187], off
	s_add_i32 m0, s1, 0x2000
	s_add_u32 s10, s52, 0x80000
	v_lshl_add_u64 v[220:221], s[52:53], 0, v[180:181]
	s_addc_u32 s11, s53, 0
	s_add_i32 s0, s0, s33
	global_load_lds_dwordx4 v[220:221], off
	v_lshl_add_u64 v[222:223], s[10:11], 0, v[190:191]
	s_mov_b32 m0, s0
	v_lshl_add_u64 v[224:225], s[68:69], 0, v[178:179]
	global_load_lds_dwordx4 v[222:223], off
	s_add_i32 m0, s0, 0x2000
	v_lshl_add_u64 v[222:223], s[10:11], 0, v[180:181]
	global_load_lds_dwordx4 v[222:223], off
	s_mov_b32 m0, s40
	v_lshl_add_u64 v[222:223], s[68:69], 0, v[176:177]
	global_load_lds_dwordx4 v[222:223], off
	s_mov_b32 m0, s41
	s_nop 0
	global_load_lds_dwordx4 v[224:225], off
	s_waitcnt vmcnt(24) lgkmcnt(0)
	s_setprio 1
	s_barrier
	v_mfma_f32_16x16x32_bf16 v[88:91], v[128:131], v[160:163], 0
	v_mfma_f32_16x16x32_bf16 v[20:23], v[136:139], v[160:163], 0
	v_mfma_f32_16x16x32_bf16 v[92:95], v[128:131], v[168:171], 0
	v_mfma_f32_16x16x32_bf16 v[28:31], v[136:139], v[168:171], 0
	v_mfma_f32_16x16x32_bf16 v[80:83], v[128:131], v[196:199], 0
	v_mfma_f32_16x16x32_bf16 v[16:19], v[136:139], v[196:199], 0
	v_mfma_f32_16x16x32_bf16 v[76:79], v[128:131], v[212:215], 0
	v_mfma_f32_16x16x32_bf16 v[12:15], v[136:139], v[212:215], 0
	v_mfma_f32_16x16x32_bf16 v[88:91], v[132:135], v[164:167], v[88:91]
	v_mfma_f32_16x16x32_bf16 v[20:23], v[140:143], v[164:167], v[20:23]
	v_mfma_f32_16x16x32_bf16 v[92:95], v[132:135], v[172:175], v[92:95]
	v_mfma_f32_16x16x32_bf16 v[28:31], v[140:143], v[172:175], v[28:31]
	v_mfma_f32_16x16x32_bf16 v[80:83], v[132:135], v[208:211], v[80:83]
	v_mfma_f32_16x16x32_bf16 v[16:19], v[140:143], v[208:211], v[16:19]
	v_mfma_f32_16x16x32_bf16 v[76:79], v[132:135], v[216:219], v[76:79]
	v_mfma_f32_16x16x32_bf16 v[12:15], v[140:143], v[216:219], v[12:15]
	v_mfma_f32_16x16x32_bf16 v[68:71], v[144:147], v[160:163], 0
	v_mfma_f32_16x16x32_bf16 v[4:7], v[152:155], v[160:163], 0
	v_mfma_f32_16x16x32_bf16 v[84:87], v[144:147], v[168:171], 0
	v_mfma_f32_16x16x32_bf16 v[24:27], v[152:155], v[168:171], 0
	v_mfma_f32_16x16x32_bf16 v[72:75], v[144:147], v[196:199], 0
	v_mfma_f32_16x16x32_bf16 v[8:11], v[152:155], v[196:199], 0
	v_mfma_f32_16x16x32_bf16 v[64:67], v[144:147], v[212:215], 0
	v_mfma_f32_16x16x32_bf16 v[0:3], v[152:155], v[212:215], 0
	v_mfma_f32_16x16x32_bf16 v[68:71], v[148:151], v[164:167], v[68:71]
	v_mfma_f32_16x16x32_bf16 v[4:7], v[156:159], v[164:167], v[4:7]
	v_mfma_f32_16x16x32_bf16 v[84:87], v[148:151], v[172:175], v[84:87]
	v_mfma_f32_16x16x32_bf16 v[24:27], v[156:159], v[172:175], v[24:27]
	v_mfma_f32_16x16x32_bf16 v[72:75], v[148:151], v[208:211], v[72:75]
	v_mfma_f32_16x16x32_bf16 v[8:11], v[156:159], v[208:211], v[8:11]
	v_mfma_f32_16x16x32_bf16 v[64:67], v[148:151], v[216:219], v[64:67]
	v_mfma_f32_16x16x32_bf16 v[0:3], v[156:159], v[216:219], v[0:3]
	s_barrier
	s_setprio 0
	s_add_i32 s0, 0, 0x18000
	s_add_i32 s1, 0, 0x1c000
	v_add_u32_e32 v140, s0, v200
	v_add_u32_e32 v156, s1, v200
	ds_read_b128 v[128:131], v140
	ds_read_b128 v[132:135], v140 offset:1024
	ds_read_b128 v[136:139], v140 offset:2048
	ds_read_b128 v[140:143], v140 offset:3072
	ds_read_b128 v[144:147], v156
	ds_read_b128 v[148:151], v156 offset:1024
	ds_read_b128 v[152:155], v156 offset:2048
	ds_read_b128 v[156:159], v156 offset:3072
	s_add_u32 s10, s68, 0x80000
	s_addc_u32 s11, s69, 0
	s_mov_b32 m0, s42
	v_lshl_add_u64 v[226:227], s[10:11], 0, v[176:177]
	ds_read_b128 v[160:163], v206 offset:32768
	ds_read_b128 v[164:167], v206 offset:33792
	ds_read_b128 v[168:171], v206 offset:34816
	ds_read_b128 v[172:175], v206 offset:35840
	ds_read_b128 v[196:199], v206 offset:36864
	ds_read_b128 v[208:211], v206 offset:37888
	ds_read_b128 v[212:215], v206 offset:38912
	ds_read_b128 v[216:219], v206 offset:39936
	global_load_lds_dwordx4 v[226:227], off
	s_mov_b32 m0, s43
	v_lshl_add_u64 v[226:227], s[10:11], 0, v[178:179]
	global_load_lds_dwordx4 v[226:227], off
	s_waitcnt vmcnt(8) lgkmcnt(0)
	s_setprio 1
	s_barrier
	v_mfma_f32_16x16x32_bf16 v[120:123], v[128:131], v[160:163], v[120:123]
	v_mfma_f32_16x16x32_bf16 v[48:51], v[136:139], v[160:163], v[48:51]
	v_mfma_f32_16x16x32_bf16 v[124:127], v[128:131], v[168:171], v[124:127]
	v_mfma_f32_16x16x32_bf16 v[60:63], v[136:139], v[168:171], v[60:63]
	v_mfma_f32_16x16x32_bf16 v[112:115], v[128:131], v[196:199], v[112:115]
	v_mfma_f32_16x16x32_bf16 v[52:55], v[136:139], v[196:199], v[52:55]
	v_mfma_f32_16x16x32_bf16 v[108:111], v[128:131], v[212:215], v[108:111]
	v_mfma_f32_16x16x32_bf16 v[36:39], v[136:139], v[212:215], v[36:39]
	v_mfma_f32_16x16x32_bf16 v[120:123], v[132:135], v[164:167], v[120:123]
	v_mfma_f32_16x16x32_bf16 v[48:51], v[140:143], v[164:167], v[48:51]
	v_mfma_f32_16x16x32_bf16 v[124:127], v[132:135], v[172:175], v[124:127]
	v_mfma_f32_16x16x32_bf16 v[60:63], v[140:143], v[172:175], v[60:63]
	v_mfma_f32_16x16x32_bf16 v[112:115], v[132:135], v[208:211], v[112:115]
	v_mfma_f32_16x16x32_bf16 v[52:55], v[140:143], v[208:211], v[52:55]
	v_mfma_f32_16x16x32_bf16 v[108:111], v[132:135], v[216:219], v[108:111]
	v_mfma_f32_16x16x32_bf16 v[36:39], v[140:143], v[216:219], v[36:39]
	v_mfma_f32_16x16x32_bf16 v[100:103], v[144:147], v[160:163], v[100:103]
	v_mfma_f32_16x16x32_bf16 v[40:43], v[152:155], v[160:163], v[40:43]
	v_mfma_f32_16x16x32_bf16 v[116:119], v[144:147], v[168:171], v[116:119]
	v_mfma_f32_16x16x32_bf16 v[56:59], v[152:155], v[168:171], v[56:59]
	v_mfma_f32_16x16x32_bf16 v[104:107], v[144:147], v[196:199], v[104:107]
	v_mfma_f32_16x16x32_bf16 v[44:47], v[152:155], v[196:199], v[44:47]
	v_mfma_f32_16x16x32_bf16 v[96:99], v[144:147], v[212:215], v[96:99]
	v_mfma_f32_16x16x32_bf16 v[32:35], v[152:155], v[212:215], v[32:35]
	v_mfma_f32_16x16x32_bf16 v[100:103], v[148:151], v[164:167], v[100:103]
	v_mfma_f32_16x16x32_bf16 v[40:43], v[156:159], v[164:167], v[40:43]
	v_mfma_f32_16x16x32_bf16 v[116:119], v[148:151], v[172:175], v[116:119]
	v_mfma_f32_16x16x32_bf16 v[56:59], v[156:159], v[172:175], v[56:59]
	v_mfma_f32_16x16x32_bf16 v[104:107], v[148:151], v[208:211], v[104:107]
	v_mfma_f32_16x16x32_bf16 v[44:47], v[156:159], v[208:211], v[44:47]
	v_mfma_f32_16x16x32_bf16 v[96:99], v[148:151], v[216:219], v[96:99]
	v_mfma_f32_16x16x32_bf16 v[32:35], v[156:159], v[216:219], v[32:35]
	s_barrier
	s_setprio 0
	s_add_i32 s0, s0, s33
	v_lshl_add_u64 v[186:187], v[186:187], 0, s[58:59]
	s_mov_b32 m0, s0
	ds_read_b128 v[160:163], v206 offset:49152
	ds_read_b128 v[164:167], v206 offset:50176
	ds_read_b128 v[168:171], v206 offset:51200
	ds_read_b128 v[172:175], v206 offset:52224
	ds_read_b128 v[196:199], v206 offset:53248
	ds_read_b128 v[208:211], v206 offset:54272
	ds_read_b128 v[212:215], v206 offset:55296
	ds_read_b128 v[216:219], v206 offset:56320
	global_load_lds_dwordx4 v[186:187], off
	s_add_i32 m0, s0, 0x2000
	s_add_u32 s10, s52, 0x80080
	v_lshl_add_u64 v[186:187], v[220:221], 0, s[58:59]
	s_addc_u32 s11, s53, 0
	s_add_i32 s0, s1, s33
	global_load_lds_dwordx4 v[186:187], off
	s_mov_b32 m0, s0
	v_lshl_add_u64 v[186:187], s[10:11], 0, v[190:191]
	global_load_lds_dwordx4 v[186:187], off
	s_add_i32 m0, s0, 0x2000
	v_lshl_add_u64 v[186:187], s[10:11], 0, v[180:181]
	global_load_lds_dwordx4 v[186:187], off
	s_mov_b32 m0, s55
	v_lshl_add_u64 v[186:187], v[222:223], 0, s[58:59]
	global_load_lds_dwordx4 v[186:187], off
	s_mov_b32 m0, s77
	v_lshl_add_u64 v[186:187], v[224:225], 0, s[58:59]
	global_load_lds_dwordx4 v[186:187], off
	s_waitcnt vmcnt(8) lgkmcnt(0)
	s_setprio 1
	s_barrier
	v_mfma_f32_16x16x32_bf16 v[88:91], v[128:131], v[160:163], v[88:91]
	v_mfma_f32_16x16x32_bf16 v[20:23], v[136:139], v[160:163], v[20:23]
	v_mfma_f32_16x16x32_bf16 v[92:95], v[128:131], v[168:171], v[92:95]
	v_mfma_f32_16x16x32_bf16 v[28:31], v[136:139], v[168:171], v[28:31]
	v_mfma_f32_16x16x32_bf16 v[80:83], v[128:131], v[196:199], v[80:83]
	v_mfma_f32_16x16x32_bf16 v[16:19], v[136:139], v[196:199], v[16:19]
	v_mfma_f32_16x16x32_bf16 v[76:79], v[128:131], v[212:215], v[76:79]
	v_mfma_f32_16x16x32_bf16 v[12:15], v[136:139], v[212:215], v[12:15]
	v_mfma_f32_16x16x32_bf16 v[88:91], v[132:135], v[164:167], v[88:91]
	v_mfma_f32_16x16x32_bf16 v[20:23], v[140:143], v[164:167], v[20:23]
	v_mfma_f32_16x16x32_bf16 v[92:95], v[132:135], v[172:175], v[92:95]
	v_mfma_f32_16x16x32_bf16 v[28:31], v[140:143], v[172:175], v[28:31]
	v_mfma_f32_16x16x32_bf16 v[80:83], v[132:135], v[208:211], v[80:83]
	v_mfma_f32_16x16x32_bf16 v[16:19], v[140:143], v[208:211], v[16:19]
	v_mfma_f32_16x16x32_bf16 v[76:79], v[132:135], v[216:219], v[76:79]
	v_mfma_f32_16x16x32_bf16 v[12:15], v[140:143], v[216:219], v[12:15]
	v_mfma_f32_16x16x32_bf16 v[68:71], v[144:147], v[160:163], v[68:71]
	v_mfma_f32_16x16x32_bf16 v[4:7], v[152:155], v[160:163], v[4:7]
	v_mfma_f32_16x16x32_bf16 v[84:87], v[144:147], v[168:171], v[84:87]
	v_mfma_f32_16x16x32_bf16 v[24:27], v[152:155], v[168:171], v[24:27]
	v_mfma_f32_16x16x32_bf16 v[72:75], v[144:147], v[196:199], v[72:75]
	v_mfma_f32_16x16x32_bf16 v[8:11], v[152:155], v[196:199], v[8:11]
	v_mfma_f32_16x16x32_bf16 v[64:67], v[144:147], v[212:215], v[64:67]
	v_mfma_f32_16x16x32_bf16 v[0:3], v[152:155], v[212:215], v[0:3]
	v_mfma_f32_16x16x32_bf16 v[68:71], v[148:151], v[164:167], v[68:71]
	v_mfma_f32_16x16x32_bf16 v[4:7], v[156:159], v[164:167], v[4:7]
	v_mfma_f32_16x16x32_bf16 v[84:87], v[148:151], v[172:175], v[84:87]
	v_mfma_f32_16x16x32_bf16 v[24:27], v[156:159], v[172:175], v[24:27]
	v_mfma_f32_16x16x32_bf16 v[72:75], v[148:151], v[208:211], v[72:75]
	v_mfma_f32_16x16x32_bf16 v[8:11], v[156:159], v[208:211], v[8:11]
	v_mfma_f32_16x16x32_bf16 v[64:67], v[148:151], v[216:219], v[64:67]
	v_mfma_f32_16x16x32_bf16 v[0:3], v[156:159], v[216:219], v[0:3]
	s_barrier
	s_setprio 0
	s_add_i32 vcc_lo, vcc_lo, 2
	s_add_u32 s66, s66, 0x100
	s_addc_u32 s67, s67, 0
	s_cmp_gt_u32 vcc_lo, 29
	s_mov_b64 s[10:11], s[16:17]
	s_cbranch_scc1 .Lpeel_done_7
	s_branch .LBB0_1105
.Ltrip0_strict_7:
	s_add_u32 s16, s10, 0x100
	s_addc_u32 s17, s11, 0
	s_add_i32 vcc_hi, 0, 0x10000
	s_cmp_eq_u32 vcc_lo, 28
	s_cselect_b32 s69, s13, s17
	s_cselect_b32 s68, s15, s16
	s_cselect_b32 s53, s57, s67
	s_cselect_b32 s52, s61, s66
	s_add_i32 s0, 0, 0x14000
	v_add_u32_e32 v140, vcc_hi, v200
	v_add_u32_e32 v156, s0, v200
	ds_read_b128 v[128:131], v140
	ds_read_b128 v[132:135], v140 offset:1024
	ds_read_b128 v[136:139], v140 offset:2048
	ds_read_b128 v[140:143], v140 offset:3072
	ds_read_b128 v[144:147], v156
	ds_read_b128 v[148:151], v156 offset:1024
	ds_read_b128 v[152:155], v156 offset:2048
	ds_read_b128 v[156:159], v156 offset:3072
	v_lshl_add_u64 v[186:187], s[10:11], 0, v[182:183]
	s_add_i32 m0, s40, 0xc000
	ds_read_b128 v[160:163], v206
	ds_read_b128 v[164:167], v206 offset:1024
	ds_read_b128 v[168:171], v206 offset:2048
	ds_read_b128 v[172:175], v206 offset:3072
	ds_read_b128 v[196:199], v206 offset:4096
	ds_read_b128 v[208:211], v206 offset:5120
	ds_read_b128 v[212:215], v206 offset:6144
	ds_read_b128 v[216:219], v206 offset:7168
	global_load_lds_dwordx4 v[186:187], off
	s_add_i32 m0, s40, 0xe000
	v_lshl_add_u64 v[186:187], s[10:11], 0, v[184:185]
	global_load_lds_dwordx4 v[186:187], off
	s_waitcnt vmcnt(8) lgkmcnt(0)
	s_setprio 1
	s_barrier
	v_mfma_f32_16x16x32_bf16 v[120:123], v[128:131], v[160:163], 0
	v_mfma_f32_16x16x32_bf16 v[48:51], v[136:139], v[160:163], 0
	v_mfma_f32_16x16x32_bf16 v[124:127], v[128:131], v[168:171], 0
	v_mfma_f32_16x16x32_bf16 v[60:63], v[136:139], v[168:171], 0
	v_mfma_f32_16x16x32_bf16 v[112:115], v[128:131], v[196:199], 0
	v_mfma_f32_16x16x32_bf16 v[52:55], v[136:139], v[196:199], 0
	v_mfma_f32_16x16x32_bf16 v[108:111], v[128:131], v[212:215], 0
	v_mfma_f32_16x16x32_bf16 v[36:39], v[136:139], v[212:215], 0
	v_mfma_f32_16x16x32_bf16 v[120:123], v[132:135], v[164:167], v[120:123]
	v_mfma_f32_16x16x32_bf16 v[48:51], v[140:143], v[164:167], v[48:51]
	v_mfma_f32_16x16x32_bf16 v[124:127], v[132:135], v[172:175], v[124:127]
	v_mfma_f32_16x16x32_bf16 v[60:63], v[140:143], v[172:175], v[60:63]
	v_mfma_f32_16x16x32_bf16 v[112:115], v[132:135], v[208:211], v[112:115]
	v_mfma_f32_16x16x32_bf16 v[52:55], v[140:143], v[208:211], v[52:55]
	v_mfma_f32_16x16x32_bf16 v[108:111], v[132:135], v[216:219], v[108:111]
	v_mfma_f32_16x16x32_bf16 v[36:39], v[140:143], v[216:219], v[36:39]
	v_mfma_f32_16x16x32_bf16 v[100:103], v[144:147], v[160:163], 0
	v_mfma_f32_16x16x32_bf16 v[40:43], v[152:155], v[160:163], 0
	v_mfma_f32_16x16x32_bf16 v[116:119], v[144:147], v[168:171], 0
	v_mfma_f32_16x16x32_bf16 v[56:59], v[152:155], v[168:171], 0
	v_mfma_f32_16x16x32_bf16 v[104:107], v[144:147], v[196:199], 0
	v_mfma_f32_16x16x32_bf16 v[44:47], v[152:155], v[196:199], 0
	v_mfma_f32_16x16x32_bf16 v[96:99], v[144:147], v[212:215], 0
	v_mfma_f32_16x16x32_bf16 v[32:35], v[152:155], v[212:215], 0
	v_mfma_f32_16x16x32_bf16 v[100:103], v[148:151], v[164:167], v[100:103]
	v_mfma_f32_16x16x32_bf16 v[40:43], v[156:159], v[164:167], v[40:43]
	v_mfma_f32_16x16x32_bf16 v[116:119], v[148:151], v[172:175], v[116:119]
	v_mfma_f32_16x16x32_bf16 v[56:59], v[156:159], v[172:175], v[56:59]
	v_mfma_f32_16x16x32_bf16 v[104:107], v[148:151], v[208:211], v[104:107]
	v_mfma_f32_16x16x32_bf16 v[44:47], v[156:159], v[208:211], v[44:47]
	v_mfma_f32_16x16x32_bf16 v[96:99], v[148:151], v[216:219], v[96:99]
	v_mfma_f32_16x16x32_bf16 v[32:35], v[156:159], v[216:219], v[32:35]
	s_barrier
	s_setprio 0
	s_add_i32 s1, vcc_hi, s33
	v_lshl_add_u64 v[186:187], s[52:53], 0, v[190:191]
	s_mov_b32 m0, s1
	ds_read_b128 v[160:163], v206 offset:16384
	ds_read_b128 v[164:167], v206 offset:17408
	ds_read_b128 v[168:171], v206 offset:18432
	ds_read_b128 v[172:175], v206 offset:19456
	ds_read_b128 v[196:199], v206 offset:20480
	ds_read_b128 v[208:211], v206 offset:21504
	ds_read_b128 v[212:215], v206 offset:22528
	ds_read_b128 v[216:219], v206 offset:23552
	global_load_lds_dwordx4 v[186:187], off
	s_add_i32 m0, s1, 0x2000
	s_add_u32 s10, s52, 0x80000
	v_lshl_add_u64 v[220:221], s[52:53], 0, v[180:181]
	s_addc_u32 s11, s53, 0
	s_add_i32 s0, s0, s33
	global_load_lds_dwordx4 v[220:221], off
	v_lshl_add_u64 v[222:223], s[10:11], 0, v[190:191]
	s_mov_b32 m0, s0
	v_lshl_add_u64 v[224:225], s[68:69], 0, v[178:179]
	global_load_lds_dwordx4 v[222:223], off
	s_add_i32 m0, s0, 0x2000
	v_lshl_add_u64 v[222:223], s[10:11], 0, v[180:181]
	global_load_lds_dwordx4 v[222:223], off
	s_mov_b32 m0, s40
	v_lshl_add_u64 v[222:223], s[68:69], 0, v[176:177]
	global_load_lds_dwordx4 v[222:223], off
	s_mov_b32 m0, s41
	s_nop 0
	global_load_lds_dwordx4 v[224:225], off
	s_waitcnt vmcnt(8) lgkmcnt(0)
	s_setprio 1
	s_barrier
	v_mfma_f32_16x16x32_bf16 v[88:91], v[128:131], v[160:163], 0
	v_mfma_f32_16x16x32_bf16 v[20:23], v[136:139], v[160:163], 0
	v_mfma_f32_16x16x32_bf16 v[92:95], v[128:131], v[168:171], 0
	v_mfma_f32_16x16x32_bf16 v[28:31], v[136:139], v[168:171], 0
	v_mfma_f32_16x16x32_bf16 v[80:83], v[128:131], v[196:199], 0
	v_mfma_f32_16x16x32_bf16 v[16:19], v[136:139], v[196:199], 0
	v_mfma_f32_16x16x32_bf16 v[76:79], v[128:131], v[212:215], 0
	v_mfma_f32_16x16x32_bf16 v[12:15], v[136:139], v[212:215], 0
	v_mfma_f32_16x16x32_bf16 v[88:91], v[132:135], v[164:167], v[88:91]
	v_mfma_f32_16x16x32_bf16 v[20:23], v[140:143], v[164:167], v[20:23]
	v_mfma_f32_16x16x32_bf16 v[92:95], v[132:135], v[172:175], v[92:95]
	v_mfma_f32_16x16x32_bf16 v[28:31], v[140:143], v[172:175], v[28:31]
	v_mfma_f32_16x16x32_bf16 v[80:83], v[132:135], v[208:211], v[80:83]
	v_mfma_f32_16x16x32_bf16 v[16:19], v[140:143], v[208:211], v[16:19]
	v_mfma_f32_16x16x32_bf16 v[76:79], v[132:135], v[216:219], v[76:79]
	v_mfma_f32_16x16x32_bf16 v[12:15], v[140:143], v[216:219], v[12:15]
	v_mfma_f32_16x16x32_bf16 v[68:71], v[144:147], v[160:163], 0
	v_mfma_f32_16x16x32_bf16 v[4:7], v[152:155], v[160:163], 0
	v_mfma_f32_16x16x32_bf16 v[84:87], v[144:147], v[168:171], 0
	v_mfma_f32_16x16x32_bf16 v[24:27], v[152:155], v[168:171], 0
	v_mfma_f32_16x16x32_bf16 v[72:75], v[144:147], v[196:199], 0
	v_mfma_f32_16x16x32_bf16 v[8:11], v[152:155], v[196:199], 0
	v_mfma_f32_16x16x32_bf16 v[64:67], v[144:147], v[212:215], 0
	v_mfma_f32_16x16x32_bf16 v[0:3], v[152:155], v[212:215], 0
	v_mfma_f32_16x16x32_bf16 v[68:71], v[148:151], v[164:167], v[68:71]
	v_mfma_f32_16x16x32_bf16 v[4:7], v[156:159], v[164:167], v[4:7]
	v_mfma_f32_16x16x32_bf16 v[84:87], v[148:151], v[172:175], v[84:87]
	v_mfma_f32_16x16x32_bf16 v[24:27], v[156:159], v[172:175], v[24:27]
	v_mfma_f32_16x16x32_bf16 v[72:75], v[148:151], v[208:211], v[72:75]
	v_mfma_f32_16x16x32_bf16 v[8:11], v[156:159], v[208:211], v[8:11]
	v_mfma_f32_16x16x32_bf16 v[64:67], v[148:151], v[216:219], v[64:67]
	v_mfma_f32_16x16x32_bf16 v[0:3], v[156:159], v[216:219], v[0:3]
	s_barrier
	s_setprio 0
	s_add_i32 s0, 0, 0x18000
	s_add_i32 s1, 0, 0x1c000
	v_add_u32_e32 v140, s0, v200
	v_add_u32_e32 v156, s1, v200
	ds_read_b128 v[128:131], v140
	ds_read_b128 v[132:135], v140 offset:1024
	ds_read_b128 v[136:139], v140 offset:2048
	ds_read_b128 v[140:143], v140 offset:3072
	ds_read_b128 v[144:147], v156
	ds_read_b128 v[148:151], v156 offset:1024
	ds_read_b128 v[152:155], v156 offset:2048
	ds_read_b128 v[156:159], v156 offset:3072
	s_add_u32 s10, s68, 0x80000
	s_addc_u32 s11, s69, 0
	s_mov_b32 m0, s42
	v_lshl_add_u64 v[226:227], s[10:11], 0, v[176:177]
	ds_read_b128 v[160:163], v206 offset:32768
	ds_read_b128 v[164:167], v206 offset:33792
	ds_read_b128 v[168:171], v206 offset:34816
	ds_read_b128 v[172:175], v206 offset:35840
	ds_read_b128 v[196:199], v206 offset:36864
	ds_read_b128 v[208:211], v206 offset:37888
	ds_read_b128 v[212:215], v206 offset:38912
	ds_read_b128 v[216:219], v206 offset:39936
	global_load_lds_dwordx4 v[226:227], off
	s_mov_b32 m0, s43
	v_lshl_add_u64 v[226:227], s[10:11], 0, v[178:179]
	global_load_lds_dwordx4 v[226:227], off
	s_waitcnt vmcnt(8) lgkmcnt(0)
	s_setprio 1
	s_barrier
	v_mfma_f32_16x16x32_bf16 v[120:123], v[128:131], v[160:163], v[120:123]
	v_mfma_f32_16x16x32_bf16 v[48:51], v[136:139], v[160:163], v[48:51]
	v_mfma_f32_16x16x32_bf16 v[124:127], v[128:131], v[168:171], v[124:127]
	v_mfma_f32_16x16x32_bf16 v[60:63], v[136:139], v[168:171], v[60:63]
	v_mfma_f32_16x16x32_bf16 v[112:115], v[128:131], v[196:199], v[112:115]
	v_mfma_f32_16x16x32_bf16 v[52:55], v[136:139], v[196:199], v[52:55]
	v_mfma_f32_16x16x32_bf16 v[108:111], v[128:131], v[212:215], v[108:111]
	v_mfma_f32_16x16x32_bf16 v[36:39], v[136:139], v[212:215], v[36:39]
	v_mfma_f32_16x16x32_bf16 v[120:123], v[132:135], v[164:167], v[120:123]
	v_mfma_f32_16x16x32_bf16 v[48:51], v[140:143], v[164:167], v[48:51]
	v_mfma_f32_16x16x32_bf16 v[124:127], v[132:135], v[172:175], v[124:127]
	v_mfma_f32_16x16x32_bf16 v[60:63], v[140:143], v[172:175], v[60:63]
	v_mfma_f32_16x16x32_bf16 v[112:115], v[132:135], v[208:211], v[112:115]
	v_mfma_f32_16x16x32_bf16 v[52:55], v[140:143], v[208:211], v[52:55]
	v_mfma_f32_16x16x32_bf16 v[108:111], v[132:135], v[216:219], v[108:111]
	v_mfma_f32_16x16x32_bf16 v[36:39], v[140:143], v[216:219], v[36:39]
	v_mfma_f32_16x16x32_bf16 v[100:103], v[144:147], v[160:163], v[100:103]
	v_mfma_f32_16x16x32_bf16 v[40:43], v[152:155], v[160:163], v[40:43]
	v_mfma_f32_16x16x32_bf16 v[116:119], v[144:147], v[168:171], v[116:119]
	v_mfma_f32_16x16x32_bf16 v[56:59], v[152:155], v[168:171], v[56:59]
	v_mfma_f32_16x16x32_bf16 v[104:107], v[144:147], v[196:199], v[104:107]
	v_mfma_f32_16x16x32_bf16 v[44:47], v[152:155], v[196:199], v[44:47]
	v_mfma_f32_16x16x32_bf16 v[96:99], v[144:147], v[212:215], v[96:99]
	v_mfma_f32_16x16x32_bf16 v[32:35], v[152:155], v[212:215], v[32:35]
	v_mfma_f32_16x16x32_bf16 v[100:103], v[148:151], v[164:167], v[100:103]
	v_mfma_f32_16x16x32_bf16 v[40:43], v[156:159], v[164:167], v[40:43]
	v_mfma_f32_16x16x32_bf16 v[116:119], v[148:151], v[172:175], v[116:119]
	v_mfma_f32_16x16x32_bf16 v[56:59], v[156:159], v[172:175], v[56:59]
	v_mfma_f32_16x16x32_bf16 v[104:107], v[148:151], v[208:211], v[104:107]
	v_mfma_f32_16x16x32_bf16 v[44:47], v[156:159], v[208:211], v[44:47]
	v_mfma_f32_16x16x32_bf16 v[96:99], v[148:151], v[216:219], v[96:99]
	v_mfma_f32_16x16x32_bf16 v[32:35], v[156:159], v[216:219], v[32:35]
	s_barrier
	s_setprio 0
	s_add_i32 s0, s0, s33
	v_lshl_add_u64 v[186:187], v[186:187], 0, s[58:59]
	s_mov_b32 m0, s0
	ds_read_b128 v[160:163], v206 offset:49152
	ds_read_b128 v[164:167], v206 offset:50176
	ds_read_b128 v[168:171], v206 offset:51200
	ds_read_b128 v[172:175], v206 offset:52224
	ds_read_b128 v[196:199], v206 offset:53248
	ds_read_b128 v[208:211], v206 offset:54272
	ds_read_b128 v[212:215], v206 offset:55296
	ds_read_b128 v[216:219], v206 offset:56320
	global_load_lds_dwordx4 v[186:187], off
	s_add_i32 m0, s0, 0x2000
	s_add_u32 s10, s52, 0x80080
	v_lshl_add_u64 v[186:187], v[220:221], 0, s[58:59]
	s_addc_u32 s11, s53, 0
	s_add_i32 s0, s1, s33
	global_load_lds_dwordx4 v[186:187], off
	s_mov_b32 m0, s0
	v_lshl_add_u64 v[186:187], s[10:11], 0, v[190:191]
	global_load_lds_dwordx4 v[186:187], off
	s_add_i32 m0, s0, 0x2000
	v_lshl_add_u64 v[186:187], s[10:11], 0, v[180:181]
	global_load_lds_dwordx4 v[186:187], off
	s_mov_b32 m0, s55
	v_lshl_add_u64 v[186:187], v[222:223], 0, s[58:59]
	global_load_lds_dwordx4 v[186:187], off
	s_mov_b32 m0, s77
	v_lshl_add_u64 v[186:187], v[224:225], 0, s[58:59]
	global_load_lds_dwordx4 v[186:187], off
	s_waitcnt vmcnt(8) lgkmcnt(0)
	s_setprio 1
	s_barrier
	v_mfma_f32_16x16x32_bf16 v[88:91], v[128:131], v[160:163], v[88:91]
	v_mfma_f32_16x16x32_bf16 v[20:23], v[136:139], v[160:163], v[20:23]
	v_mfma_f32_16x16x32_bf16 v[92:95], v[128:131], v[168:171], v[92:95]
	v_mfma_f32_16x16x32_bf16 v[28:31], v[136:139], v[168:171], v[28:31]
	v_mfma_f32_16x16x32_bf16 v[80:83], v[128:131], v[196:199], v[80:83]
	v_mfma_f32_16x16x32_bf16 v[16:19], v[136:139], v[196:199], v[16:19]
	v_mfma_f32_16x16x32_bf16 v[76:79], v[128:131], v[212:215], v[76:79]
	v_mfma_f32_16x16x32_bf16 v[12:15], v[136:139], v[212:215], v[12:15]
	v_mfma_f32_16x16x32_bf16 v[88:91], v[132:135], v[164:167], v[88:91]
	v_mfma_f32_16x16x32_bf16 v[20:23], v[140:143], v[164:167], v[20:23]
	v_mfma_f32_16x16x32_bf16 v[92:95], v[132:135], v[172:175], v[92:95]
	v_mfma_f32_16x16x32_bf16 v[28:31], v[140:143], v[172:175], v[28:31]
	v_mfma_f32_16x16x32_bf16 v[80:83], v[132:135], v[208:211], v[80:83]
	v_mfma_f32_16x16x32_bf16 v[16:19], v[140:143], v[208:211], v[16:19]
	v_mfma_f32_16x16x32_bf16 v[76:79], v[132:135], v[216:219], v[76:79]
	v_mfma_f32_16x16x32_bf16 v[12:15], v[140:143], v[216:219], v[12:15]
	v_mfma_f32_16x16x32_bf16 v[68:71], v[144:147], v[160:163], v[68:71]
	v_mfma_f32_16x16x32_bf16 v[4:7], v[152:155], v[160:163], v[4:7]
	v_mfma_f32_16x16x32_bf16 v[84:87], v[144:147], v[168:171], v[84:87]
	v_mfma_f32_16x16x32_bf16 v[24:27], v[152:155], v[168:171], v[24:27]
	v_mfma_f32_16x16x32_bf16 v[72:75], v[144:147], v[196:199], v[72:75]
	v_mfma_f32_16x16x32_bf16 v[8:11], v[152:155], v[196:199], v[8:11]
	v_mfma_f32_16x16x32_bf16 v[64:67], v[144:147], v[212:215], v[64:67]
	v_mfma_f32_16x16x32_bf16 v[0:3], v[152:155], v[212:215], v[0:3]
	v_mfma_f32_16x16x32_bf16 v[68:71], v[148:151], v[164:167], v[68:71]
	v_mfma_f32_16x16x32_bf16 v[4:7], v[156:159], v[164:167], v[4:7]
	v_mfma_f32_16x16x32_bf16 v[84:87], v[148:151], v[172:175], v[84:87]
	v_mfma_f32_16x16x32_bf16 v[24:27], v[156:159], v[172:175], v[24:27]
	v_mfma_f32_16x16x32_bf16 v[72:75], v[148:151], v[208:211], v[72:75]
	v_mfma_f32_16x16x32_bf16 v[8:11], v[156:159], v[208:211], v[8:11]
	v_mfma_f32_16x16x32_bf16 v[64:67], v[148:151], v[216:219], v[64:67]
	v_mfma_f32_16x16x32_bf16 v[0:3], v[156:159], v[216:219], v[0:3]
	s_barrier
	s_setprio 0
	s_add_i32 vcc_lo, vcc_lo, 2
	s_add_u32 s66, s66, 0x100
	s_addc_u32 s67, s67, 0
	s_cmp_gt_u32 vcc_lo, 29
	s_mov_b64 s[10:11], s[16:17]
	s_cbranch_scc1 .Lpeel_done_7
.LBB0_1105:
	s_add_u32 s16, s10, 0x100
	s_addc_u32 s17, s11, 0
	s_add_i32 vcc_hi, 0, 0x10000
	s_cmp_eq_u32 vcc_lo, 28
	s_cselect_b32 s69, s13, s17
	s_cselect_b32 s68, s15, s16
	s_cselect_b32 s53, s57, s67
	s_cselect_b32 s52, s61, s66
	s_add_i32 s0, 0, 0x14000
	v_add_u32_e32 v140, vcc_hi, v200
	v_add_u32_e32 v156, s0, v200
	ds_read_b128 v[128:131], v140
	ds_read_b128 v[132:135], v140 offset:1024
	ds_read_b128 v[136:139], v140 offset:2048
	ds_read_b128 v[140:143], v140 offset:3072
	ds_read_b128 v[144:147], v156
	ds_read_b128 v[148:151], v156 offset:1024
	ds_read_b128 v[152:155], v156 offset:2048
	ds_read_b128 v[156:159], v156 offset:3072
	v_lshl_add_u64 v[186:187], s[10:11], 0, v[182:183]
	s_add_i32 m0, s40, 0xc000
	ds_read_b128 v[160:163], v206
	ds_read_b128 v[164:167], v206 offset:1024
	ds_read_b128 v[168:171], v206 offset:2048
	ds_read_b128 v[172:175], v206 offset:3072
	ds_read_b128 v[196:199], v206 offset:4096
	ds_read_b128 v[208:211], v206 offset:5120
	ds_read_b128 v[212:215], v206 offset:6144
	ds_read_b128 v[216:219], v206 offset:7168
	global_load_lds_dwordx4 v[186:187], off
	s_add_i32 m0, s40, 0xe000
	v_lshl_add_u64 v[186:187], s[10:11], 0, v[184:185]
	global_load_lds_dwordx4 v[186:187], off
	s_waitcnt vmcnt(8) lgkmcnt(0)
	s_setprio 1
	s_barrier
	v_mfma_f32_16x16x32_bf16 v[120:123], v[128:131], v[160:163], v[120:123]
	v_mfma_f32_16x16x32_bf16 v[48:51], v[136:139], v[160:163], v[48:51]
	v_mfma_f32_16x16x32_bf16 v[124:127], v[128:131], v[168:171], v[124:127]
	v_mfma_f32_16x16x32_bf16 v[60:63], v[136:139], v[168:171], v[60:63]
	v_mfma_f32_16x16x32_bf16 v[112:115], v[128:131], v[196:199], v[112:115]
	v_mfma_f32_16x16x32_bf16 v[52:55], v[136:139], v[196:199], v[52:55]
	v_mfma_f32_16x16x32_bf16 v[108:111], v[128:131], v[212:215], v[108:111]
	v_mfma_f32_16x16x32_bf16 v[36:39], v[136:139], v[212:215], v[36:39]
	v_mfma_f32_16x16x32_bf16 v[120:123], v[132:135], v[164:167], v[120:123]
	v_mfma_f32_16x16x32_bf16 v[48:51], v[140:143], v[164:167], v[48:51]
	v_mfma_f32_16x16x32_bf16 v[124:127], v[132:135], v[172:175], v[124:127]
	v_mfma_f32_16x16x32_bf16 v[60:63], v[140:143], v[172:175], v[60:63]
	v_mfma_f32_16x16x32_bf16 v[112:115], v[132:135], v[208:211], v[112:115]
	v_mfma_f32_16x16x32_bf16 v[52:55], v[140:143], v[208:211], v[52:55]
	v_mfma_f32_16x16x32_bf16 v[108:111], v[132:135], v[216:219], v[108:111]
	v_mfma_f32_16x16x32_bf16 v[36:39], v[140:143], v[216:219], v[36:39]
	v_mfma_f32_16x16x32_bf16 v[100:103], v[144:147], v[160:163], v[100:103]
	v_mfma_f32_16x16x32_bf16 v[40:43], v[152:155], v[160:163], v[40:43]
	v_mfma_f32_16x16x32_bf16 v[116:119], v[144:147], v[168:171], v[116:119]
	v_mfma_f32_16x16x32_bf16 v[56:59], v[152:155], v[168:171], v[56:59]
	v_mfma_f32_16x16x32_bf16 v[104:107], v[144:147], v[196:199], v[104:107]
	v_mfma_f32_16x16x32_bf16 v[44:47], v[152:155], v[196:199], v[44:47]
	v_mfma_f32_16x16x32_bf16 v[96:99], v[144:147], v[212:215], v[96:99]
	v_mfma_f32_16x16x32_bf16 v[32:35], v[152:155], v[212:215], v[32:35]
	v_mfma_f32_16x16x32_bf16 v[100:103], v[148:151], v[164:167], v[100:103]
	v_mfma_f32_16x16x32_bf16 v[40:43], v[156:159], v[164:167], v[40:43]
	v_mfma_f32_16x16x32_bf16 v[116:119], v[148:151], v[172:175], v[116:119]
	v_mfma_f32_16x16x32_bf16 v[56:59], v[156:159], v[172:175], v[56:59]
	v_mfma_f32_16x16x32_bf16 v[104:107], v[148:151], v[208:211], v[104:107]
	v_mfma_f32_16x16x32_bf16 v[44:47], v[156:159], v[208:211], v[44:47]
	v_mfma_f32_16x16x32_bf16 v[96:99], v[148:151], v[216:219], v[96:99]
	v_mfma_f32_16x16x32_bf16 v[32:35], v[156:159], v[216:219], v[32:35]
	s_setprio 0
	s_barrier
	s_add_i32 s1, vcc_hi, s33
	v_lshl_add_u64 v[186:187], s[52:53], 0, v[190:191]
	s_mov_b32 m0, s1
	ds_read_b128 v[160:163], v206 offset:16384
	ds_read_b128 v[164:167], v206 offset:17408
	ds_read_b128 v[168:171], v206 offset:18432
	ds_read_b128 v[172:175], v206 offset:19456
	ds_read_b128 v[196:199], v206 offset:20480
	ds_read_b128 v[208:211], v206 offset:21504
	ds_read_b128 v[212:215], v206 offset:22528
	ds_read_b128 v[216:219], v206 offset:23552
	global_load_lds_dwordx4 v[186:187], off
	s_add_i32 m0, s1, 0x2000
	s_add_u32 s10, s52, 0x80000
	v_lshl_add_u64 v[220:221], s[52:53], 0, v[180:181]
	s_addc_u32 s11, s53, 0
	s_add_i32 s0, s0, s33
	global_load_lds_dwordx4 v[220:221], off
	v_lshl_add_u64 v[222:223], s[10:11], 0, v[190:191]
	s_mov_b32 m0, s0
	v_lshl_add_u64 v[224:225], s[68:69], 0, v[178:179]
	global_load_lds_dwordx4 v[222:223], off
	s_add_i32 m0, s0, 0x2000
	v_lshl_add_u64 v[222:223], s[10:11], 0, v[180:181]
	global_load_lds_dwordx4 v[222:223], off
	s_mov_b32 m0, s40
	v_lshl_add_u64 v[222:223], s[68:69], 0, v[176:177]
	global_load_lds_dwordx4 v[222:223], off
	s_mov_b32 m0, s41
	s_nop 0
	global_load_lds_dwordx4 v[224:225], off
	s_waitcnt vmcnt(8) lgkmcnt(0)
	s_setprio 1
	s_barrier
	v_mfma_f32_16x16x32_bf16 v[88:91], v[128:131], v[160:163], v[88:91]
	v_mfma_f32_16x16x32_bf16 v[20:23], v[136:139], v[160:163], v[20:23]
	v_mfma_f32_16x16x32_bf16 v[92:95], v[128:131], v[168:171], v[92:95]
	v_mfma_f32_16x16x32_bf16 v[28:31], v[136:139], v[168:171], v[28:31]
	v_mfma_f32_16x16x32_bf16 v[80:83], v[128:131], v[196:199], v[80:83]
	v_mfma_f32_16x16x32_bf16 v[16:19], v[136:139], v[196:199], v[16:19]
	v_mfma_f32_16x16x32_bf16 v[76:79], v[128:131], v[212:215], v[76:79]
	v_mfma_f32_16x16x32_bf16 v[12:15], v[136:139], v[212:215], v[12:15]
	v_mfma_f32_16x16x32_bf16 v[88:91], v[132:135], v[164:167], v[88:91]
	v_mfma_f32_16x16x32_bf16 v[20:23], v[140:143], v[164:167], v[20:23]
	v_mfma_f32_16x16x32_bf16 v[92:95], v[132:135], v[172:175], v[92:95]
	v_mfma_f32_16x16x32_bf16 v[28:31], v[140:143], v[172:175], v[28:31]
	v_mfma_f32_16x16x32_bf16 v[80:83], v[132:135], v[208:211], v[80:83]
	v_mfma_f32_16x16x32_bf16 v[16:19], v[140:143], v[208:211], v[16:19]
	v_mfma_f32_16x16x32_bf16 v[76:79], v[132:135], v[216:219], v[76:79]
	v_mfma_f32_16x16x32_bf16 v[12:15], v[140:143], v[216:219], v[12:15]
	v_mfma_f32_16x16x32_bf16 v[68:71], v[144:147], v[160:163], v[68:71]
	v_mfma_f32_16x16x32_bf16 v[4:7], v[152:155], v[160:163], v[4:7]
	v_mfma_f32_16x16x32_bf16 v[84:87], v[144:147], v[168:171], v[84:87]
	v_mfma_f32_16x16x32_bf16 v[24:27], v[152:155], v[168:171], v[24:27]
	v_mfma_f32_16x16x32_bf16 v[72:75], v[144:147], v[196:199], v[72:75]
	v_mfma_f32_16x16x32_bf16 v[8:11], v[152:155], v[196:199], v[8:11]
	v_mfma_f32_16x16x32_bf16 v[64:67], v[144:147], v[212:215], v[64:67]
	v_mfma_f32_16x16x32_bf16 v[0:3], v[152:155], v[212:215], v[0:3]
	v_mfma_f32_16x16x32_bf16 v[68:71], v[148:151], v[164:167], v[68:71]
	v_mfma_f32_16x16x32_bf16 v[4:7], v[156:159], v[164:167], v[4:7]
	v_mfma_f32_16x16x32_bf16 v[84:87], v[148:151], v[172:175], v[84:87]
	v_mfma_f32_16x16x32_bf16 v[24:27], v[156:159], v[172:175], v[24:27]
	v_mfma_f32_16x16x32_bf16 v[72:75], v[148:151], v[208:211], v[72:75]
	v_mfma_f32_16x16x32_bf16 v[8:11], v[156:159], v[208:211], v[8:11]
	v_mfma_f32_16x16x32_bf16 v[64:67], v[148:151], v[216:219], v[64:67]
	v_mfma_f32_16x16x32_bf16 v[0:3], v[156:159], v[216:219], v[0:3]
	s_setprio 0
	s_barrier
	s_add_i32 s0, 0, 0x18000
	s_add_i32 s1, 0, 0x1c000
	v_add_u32_e32 v140, s0, v200
	v_add_u32_e32 v156, s1, v200
	ds_read_b128 v[128:131], v140
	ds_read_b128 v[132:135], v140 offset:1024
	ds_read_b128 v[136:139], v140 offset:2048
	ds_read_b128 v[140:143], v140 offset:3072
	ds_read_b128 v[144:147], v156
	ds_read_b128 v[148:151], v156 offset:1024
	ds_read_b128 v[152:155], v156 offset:2048
	ds_read_b128 v[156:159], v156 offset:3072
	s_add_u32 s10, s68, 0x80000
	s_addc_u32 s11, s69, 0
	s_mov_b32 m0, s42
	v_lshl_add_u64 v[226:227], s[10:11], 0, v[176:177]
	ds_read_b128 v[160:163], v206 offset:32768
	ds_read_b128 v[164:167], v206 offset:33792
	ds_read_b128 v[168:171], v206 offset:34816
	ds_read_b128 v[172:175], v206 offset:35840
	ds_read_b128 v[196:199], v206 offset:36864
	ds_read_b128 v[208:211], v206 offset:37888
	ds_read_b128 v[212:215], v206 offset:38912
	ds_read_b128 v[216:219], v206 offset:39936
	global_load_lds_dwordx4 v[226:227], off
	s_mov_b32 m0, s43
	v_lshl_add_u64 v[226:227], s[10:11], 0, v[178:179]
	global_load_lds_dwordx4 v[226:227], off
	s_waitcnt vmcnt(8) lgkmcnt(0)
	s_setprio 1
	s_barrier
	v_mfma_f32_16x16x32_bf16 v[120:123], v[128:131], v[160:163], v[120:123]
	v_mfma_f32_16x16x32_bf16 v[48:51], v[136:139], v[160:163], v[48:51]
	v_mfma_f32_16x16x32_bf16 v[124:127], v[128:131], v[168:171], v[124:127]
	v_mfma_f32_16x16x32_bf16 v[60:63], v[136:139], v[168:171], v[60:63]
	v_mfma_f32_16x16x32_bf16 v[112:115], v[128:131], v[196:199], v[112:115]
	v_mfma_f32_16x16x32_bf16 v[52:55], v[136:139], v[196:199], v[52:55]
	v_mfma_f32_16x16x32_bf16 v[108:111], v[128:131], v[212:215], v[108:111]
	v_mfma_f32_16x16x32_bf16 v[36:39], v[136:139], v[212:215], v[36:39]
	v_mfma_f32_16x16x32_bf16 v[120:123], v[132:135], v[164:167], v[120:123]
	v_mfma_f32_16x16x32_bf16 v[48:51], v[140:143], v[164:167], v[48:51]
	v_mfma_f32_16x16x32_bf16 v[124:127], v[132:135], v[172:175], v[124:127]
	v_mfma_f32_16x16x32_bf16 v[60:63], v[140:143], v[172:175], v[60:63]
	v_mfma_f32_16x16x32_bf16 v[112:115], v[132:135], v[208:211], v[112:115]
	v_mfma_f32_16x16x32_bf16 v[52:55], v[140:143], v[208:211], v[52:55]
	v_mfma_f32_16x16x32_bf16 v[108:111], v[132:135], v[216:219], v[108:111]
	v_mfma_f32_16x16x32_bf16 v[36:39], v[140:143], v[216:219], v[36:39]
	v_mfma_f32_16x16x32_bf16 v[100:103], v[144:147], v[160:163], v[100:103]
	v_mfma_f32_16x16x32_bf16 v[40:43], v[152:155], v[160:163], v[40:43]
	v_mfma_f32_16x16x32_bf16 v[116:119], v[144:147], v[168:171], v[116:119]
	v_mfma_f32_16x16x32_bf16 v[56:59], v[152:155], v[168:171], v[56:59]
	v_mfma_f32_16x16x32_bf16 v[104:107], v[144:147], v[196:199], v[104:107]
	v_mfma_f32_16x16x32_bf16 v[44:47], v[152:155], v[196:199], v[44:47]
	v_mfma_f32_16x16x32_bf16 v[96:99], v[144:147], v[212:215], v[96:99]
	v_mfma_f32_16x16x32_bf16 v[32:35], v[152:155], v[212:215], v[32:35]
	v_mfma_f32_16x16x32_bf16 v[100:103], v[148:151], v[164:167], v[100:103]
	v_mfma_f32_16x16x32_bf16 v[40:43], v[156:159], v[164:167], v[40:43]
	v_mfma_f32_16x16x32_bf16 v[116:119], v[148:151], v[172:175], v[116:119]
	v_mfma_f32_16x16x32_bf16 v[56:59], v[156:159], v[172:175], v[56:59]
	v_mfma_f32_16x16x32_bf16 v[104:107], v[148:151], v[208:211], v[104:107]
	v_mfma_f32_16x16x32_bf16 v[44:47], v[156:159], v[208:211], v[44:47]
	v_mfma_f32_16x16x32_bf16 v[96:99], v[148:151], v[216:219], v[96:99]
	v_mfma_f32_16x16x32_bf16 v[32:35], v[156:159], v[216:219], v[32:35]
	s_setprio 0
	s_barrier
	s_add_i32 s0, s0, s33
	v_lshl_add_u64 v[186:187], v[186:187], 0, s[58:59]
	s_mov_b32 m0, s0
	ds_read_b128 v[160:163], v206 offset:49152
	ds_read_b128 v[164:167], v206 offset:50176
	ds_read_b128 v[168:171], v206 offset:51200
	ds_read_b128 v[172:175], v206 offset:52224
	ds_read_b128 v[196:199], v206 offset:53248
	ds_read_b128 v[208:211], v206 offset:54272
	ds_read_b128 v[212:215], v206 offset:55296
	ds_read_b128 v[216:219], v206 offset:56320
	global_load_lds_dwordx4 v[186:187], off
	s_add_i32 m0, s0, 0x2000
	s_add_u32 s10, s52, 0x80080
	v_lshl_add_u64 v[186:187], v[220:221], 0, s[58:59]
	s_addc_u32 s11, s53, 0
	s_add_i32 s0, s1, s33
	global_load_lds_dwordx4 v[186:187], off
	s_mov_b32 m0, s0
	v_lshl_add_u64 v[186:187], s[10:11], 0, v[190:191]
	global_load_lds_dwordx4 v[186:187], off
	s_add_i32 m0, s0, 0x2000
	v_lshl_add_u64 v[186:187], s[10:11], 0, v[180:181]
	global_load_lds_dwordx4 v[186:187], off
	s_mov_b32 m0, s55
	v_lshl_add_u64 v[186:187], v[222:223], 0, s[58:59]
	global_load_lds_dwordx4 v[186:187], off
	s_mov_b32 m0, s77
	v_lshl_add_u64 v[186:187], v[224:225], 0, s[58:59]
	global_load_lds_dwordx4 v[186:187], off
	s_waitcnt vmcnt(8) lgkmcnt(0)
	s_setprio 1
	s_barrier
	v_mfma_f32_16x16x32_bf16 v[88:91], v[128:131], v[160:163], v[88:91]
	v_mfma_f32_16x16x32_bf16 v[20:23], v[136:139], v[160:163], v[20:23]
	v_mfma_f32_16x16x32_bf16 v[92:95], v[128:131], v[168:171], v[92:95]
	v_mfma_f32_16x16x32_bf16 v[28:31], v[136:139], v[168:171], v[28:31]
	v_mfma_f32_16x16x32_bf16 v[80:83], v[128:131], v[196:199], v[80:83]
	v_mfma_f32_16x16x32_bf16 v[16:19], v[136:139], v[196:199], v[16:19]
	v_mfma_f32_16x16x32_bf16 v[76:79], v[128:131], v[212:215], v[76:79]
	v_mfma_f32_16x16x32_bf16 v[12:15], v[136:139], v[212:215], v[12:15]
	v_mfma_f32_16x16x32_bf16 v[88:91], v[132:135], v[164:167], v[88:91]
	v_mfma_f32_16x16x32_bf16 v[20:23], v[140:143], v[164:167], v[20:23]
	v_mfma_f32_16x16x32_bf16 v[92:95], v[132:135], v[172:175], v[92:95]
	v_mfma_f32_16x16x32_bf16 v[28:31], v[140:143], v[172:175], v[28:31]
	v_mfma_f32_16x16x32_bf16 v[80:83], v[132:135], v[208:211], v[80:83]
	v_mfma_f32_16x16x32_bf16 v[16:19], v[140:143], v[208:211], v[16:19]
	v_mfma_f32_16x16x32_bf16 v[76:79], v[132:135], v[216:219], v[76:79]
	v_mfma_f32_16x16x32_bf16 v[12:15], v[140:143], v[216:219], v[12:15]
	v_mfma_f32_16x16x32_bf16 v[68:71], v[144:147], v[160:163], v[68:71]
	v_mfma_f32_16x16x32_bf16 v[4:7], v[152:155], v[160:163], v[4:7]
	v_mfma_f32_16x16x32_bf16 v[84:87], v[144:147], v[168:171], v[84:87]
	v_mfma_f32_16x16x32_bf16 v[24:27], v[152:155], v[168:171], v[24:27]
	v_mfma_f32_16x16x32_bf16 v[72:75], v[144:147], v[196:199], v[72:75]
	v_mfma_f32_16x16x32_bf16 v[8:11], v[152:155], v[196:199], v[8:11]
	v_mfma_f32_16x16x32_bf16 v[64:67], v[144:147], v[212:215], v[64:67]
	v_mfma_f32_16x16x32_bf16 v[0:3], v[152:155], v[212:215], v[0:3]
	v_mfma_f32_16x16x32_bf16 v[68:71], v[148:151], v[164:167], v[68:71]
	v_mfma_f32_16x16x32_bf16 v[4:7], v[156:159], v[164:167], v[4:7]
	v_mfma_f32_16x16x32_bf16 v[84:87], v[148:151], v[172:175], v[84:87]
	v_mfma_f32_16x16x32_bf16 v[24:27], v[156:159], v[172:175], v[24:27]
	v_mfma_f32_16x16x32_bf16 v[72:75], v[148:151], v[208:211], v[72:75]
	v_mfma_f32_16x16x32_bf16 v[8:11], v[156:159], v[208:211], v[8:11]
	v_mfma_f32_16x16x32_bf16 v[64:67], v[148:151], v[216:219], v[64:67]
	v_mfma_f32_16x16x32_bf16 v[0:3], v[156:159], v[216:219], v[0:3]
	s_setprio 0
	s_barrier
	s_add_i32 vcc_lo, vcc_lo, 2
	s_add_u32 s66, s66, 0x100
	s_addc_u32 s67, s67, 0
	s_cmp_gt_u32 vcc_lo, 29
	s_mov_b64 s[10:11], s[16:17]
	s_cbranch_scc0 .LBB0_1105

.LBB0_1349:
	s_add_u32 s47, s20, 0x100
	s_addc_u32 s52, s21, 0
	s_mov_b32 s53, -2
	v_readlane_b32 s0, v255, 49
	s_nop 3
	s_cmp_eq_u32 s0, 9
	v_writelane_b32 v255, 9, 49
	s_cbranch_scc0 .Ltrip0_strict_8
	s_add_u32 s20, s16, 0x100
	s_addc_u32 s21, s17, 0
	s_add_i32 s0, 0, 0x10000
	s_cmpk_eq_i32 s53, 0x54
	s_cselect_b32 s25, s13, s21
	s_cselect_b32 s24, s12, s20
	s_cselect_b32 s23, s15, s52
	s_cselect_b32 s22, s14, s47
	s_add_i32 s1, 0, 0x14000
	v_add_u32_e32 v154, s0, v139
	v_add_u32_e32 v170, s1, v139
	ds_read_b128 v[142:145], v154
	ds_read_b128 v[146:149], v154 offset:1024
	ds_read_b128 v[150:153], v154 offset:2048
	ds_read_b128 v[154:157], v154 offset:3072
	ds_read_b128 v[158:161], v170
	ds_read_b128 v[162:165], v170 offset:1024
	ds_read_b128 v[166:169], v170 offset:2048
	ds_read_b128 v[170:173], v170 offset:3072
	v_lshl_add_u64 v[186:187], s[16:17], 0, v[134:135]
	s_add_i32 m0, s29, 0xc000
	ds_read_b128 v[174:177], v141
	ds_read_b128 v[178:181], v141 offset:1024
	ds_read_b128 v[182:185], v141 offset:2048
	ds_read_b128 v[196:199], v141 offset:3072
	ds_read_b128 v[200:203], v141 offset:4096
	ds_read_b128 v[204:207], v141 offset:5120
	ds_read_b128 v[208:211], v141 offset:6144
	ds_read_b128 v[212:215], v141 offset:7168
	global_load_lds_dwordx4 v[186:187], off
	s_add_i32 m0, s29, 0xe000
	v_lshl_add_u64 v[186:187], s[16:17], 0, v[136:137]
	global_load_lds_dwordx4 v[186:187], off
	s_waitcnt vmcnt(24) lgkmcnt(0)
	s_setprio 1
	s_barrier
	v_mfma_f32_16x16x32_bf16 v[124:127], v[142:145], v[174:177], 0
	v_mfma_f32_16x16x32_bf16 v[120:123], v[150:153], v[174:177], 0
	v_mfma_f32_16x16x32_bf16 v[116:119], v[142:145], v[182:185], 0
	v_mfma_f32_16x16x32_bf16 v[112:115], v[150:153], v[182:185], 0
	v_mfma_f32_16x16x32_bf16 v[100:103], v[142:145], v[200:203], 0
	v_mfma_f32_16x16x32_bf16 v[96:99], v[150:153], v[200:203], 0
	v_mfma_f32_16x16x32_bf16 v[84:87], v[142:145], v[208:211], 0
	v_mfma_f32_16x16x32_bf16 v[80:83], v[150:153], v[208:211], 0
	v_mfma_f32_16x16x32_bf16 v[124:127], v[146:149], v[178:181], v[124:127]
	v_mfma_f32_16x16x32_bf16 v[120:123], v[154:157], v[178:181], v[120:123]
	v_mfma_f32_16x16x32_bf16 v[116:119], v[146:149], v[196:199], v[116:119]
	v_mfma_f32_16x16x32_bf16 v[112:115], v[154:157], v[196:199], v[112:115]
	v_mfma_f32_16x16x32_bf16 v[100:103], v[146:149], v[204:207], v[100:103]
	v_mfma_f32_16x16x32_bf16 v[96:99], v[154:157], v[204:207], v[96:99]
	v_mfma_f32_16x16x32_bf16 v[84:87], v[146:149], v[212:215], v[84:87]
	v_mfma_f32_16x16x32_bf16 v[80:83], v[154:157], v[212:215], v[80:83]
	v_mfma_f32_16x16x32_bf16 v[108:111], v[158:161], v[174:177], 0
	v_mfma_f32_16x16x32_bf16 v[104:107], v[166:169], v[174:177], 0
	v_mfma_f32_16x16x32_bf16 v[92:95], v[158:161], v[182:185], 0
	v_mfma_f32_16x16x32_bf16 v[88:91], v[166:169], v[182:185], 0
	v_mfma_f32_16x16x32_bf16 v[76:79], v[158:161], v[200:203], 0
	v_mfma_f32_16x16x32_bf16 v[72:75], v[166:169], v[200:203], 0
	v_mfma_f32_16x16x32_bf16 v[68:71], v[158:161], v[208:211], 0
	v_mfma_f32_16x16x32_bf16 v[64:67], v[166:169], v[208:211], 0
	v_mfma_f32_16x16x32_bf16 v[108:111], v[162:165], v[178:181], v[108:111]
	v_mfma_f32_16x16x32_bf16 v[104:107], v[170:173], v[178:181], v[104:107]
	v_mfma_f32_16x16x32_bf16 v[92:95], v[162:165], v[196:199], v[92:95]
	v_mfma_f32_16x16x32_bf16 v[88:91], v[170:173], v[196:199], v[88:91]
	v_mfma_f32_16x16x32_bf16 v[76:79], v[162:165], v[204:207], v[76:79]
	v_mfma_f32_16x16x32_bf16 v[72:75], v[170:173], v[204:207], v[72:75]
	v_mfma_f32_16x16x32_bf16 v[68:71], v[162:165], v[212:215], v[68:71]
	v_mfma_f32_16x16x32_bf16 v[64:67], v[170:173], v[212:215], v[64:67]
	s_barrier
	s_setprio 0
	s_add_i32 s0, s0, s28
	v_lshl_add_u64 v[186:187], s[22:23], 0, v[190:191]
	s_mov_b32 m0, s0
	ds_read_b128 v[174:177], v141 offset:16384
	ds_read_b128 v[178:181], v141 offset:17408
	ds_read_b128 v[182:185], v141 offset:18432
	ds_read_b128 v[196:199], v141 offset:19456
	ds_read_b128 v[200:203], v141 offset:20480
	ds_read_b128 v[204:207], v141 offset:21504
	ds_read_b128 v[208:211], v141 offset:22528
	ds_read_b128 v[212:215], v141 offset:23552
	global_load_lds_dwordx4 v[186:187], off
	s_add_i32 m0, s0, 0x2000
	s_add_u32 s16, s22, 0x160000
	v_lshl_add_u64 v[216:217], s[22:23], 0, v[132:133]
	s_addc_u32 s17, s23, 0
	s_add_i32 s0, s1, s28
	global_load_lds_dwordx4 v[216:217], off
	v_lshl_add_u64 v[218:219], s[16:17], 0, v[190:191]
	s_mov_b32 m0, s0
	v_lshl_add_u64 v[220:221], s[24:25], 0, v[130:131]
	global_load_lds_dwordx4 v[218:219], off
	s_add_i32 m0, s0, 0x2000
	v_lshl_add_u64 v[218:219], s[16:17], 0, v[132:133]
	global_load_lds_dwordx4 v[218:219], off
	s_mov_b32 m0, s29
	v_lshl_add_u64 v[218:219], s[24:25], 0, v[128:129]
	global_load_lds_dwordx4 v[218:219], off
	s_mov_b32 m0, s30
	s_nop 0
	global_load_lds_dwordx4 v[220:221], off
	s_waitcnt vmcnt(24) lgkmcnt(0)
	s_setprio 1
	s_barrier
	v_mfma_f32_16x16x32_bf16 v[60:63], v[142:145], v[174:177], 0
	v_mfma_f32_16x16x32_bf16 v[56:59], v[150:153], v[174:177], 0
	v_mfma_f32_16x16x32_bf16 v[52:55], v[142:145], v[182:185], 0
	v_mfma_f32_16x16x32_bf16 v[48:51], v[150:153], v[182:185], 0
	v_mfma_f32_16x16x32_bf16 v[36:39], v[142:145], v[200:203], 0
	v_mfma_f32_16x16x32_bf16 v[32:35], v[150:153], v[200:203], 0
	v_mfma_f32_16x16x32_bf16 v[20:23], v[142:145], v[208:211], 0
	v_mfma_f32_16x16x32_bf16 v[16:19], v[150:153], v[208:211], 0
	v_mfma_f32_16x16x32_bf16 v[60:63], v[146:149], v[178:181], v[60:63]
	v_mfma_f32_16x16x32_bf16 v[56:59], v[154:157], v[178:181], v[56:59]
	v_mfma_f32_16x16x32_bf16 v[52:55], v[146:149], v[196:199], v[52:55]
	v_mfma_f32_16x16x32_bf16 v[48:51], v[154:157], v[196:199], v[48:51]
	v_mfma_f32_16x16x32_bf16 v[36:39], v[146:149], v[204:207], v[36:39]
	v_mfma_f32_16x16x32_bf16 v[32:35], v[154:157], v[204:207], v[32:35]
	v_mfma_f32_16x16x32_bf16 v[20:23], v[146:149], v[212:215], v[20:23]
	v_mfma_f32_16x16x32_bf16 v[16:19], v[154:157], v[212:215], v[16:19]
	v_mfma_f32_16x16x32_bf16 v[44:47], v[158:161], v[174:177], 0
	v_mfma_f32_16x16x32_bf16 v[40:43], v[166:169], v[174:177], 0
	v_mfma_f32_16x16x32_bf16 v[28:31], v[158:161], v[182:185], 0
	v_mfma_f32_16x16x32_bf16 v[24:27], v[166:169], v[182:185], 0
	v_mfma_f32_16x16x32_bf16 v[12:15], v[158:161], v[200:203], 0
	v_mfma_f32_16x16x32_bf16 v[8:11], v[166:169], v[200:203], 0
	v_mfma_f32_16x16x32_bf16 v[4:7], v[158:161], v[208:211], 0
	v_mfma_f32_16x16x32_bf16 v[0:3], v[166:169], v[208:211], 0
	v_mfma_f32_16x16x32_bf16 v[44:47], v[162:165], v[178:181], v[44:47]
	v_mfma_f32_16x16x32_bf16 v[40:43], v[170:173], v[178:181], v[40:43]
	v_mfma_f32_16x16x32_bf16 v[28:31], v[162:165], v[196:199], v[28:31]
	v_mfma_f32_16x16x32_bf16 v[24:27], v[170:173], v[196:199], v[24:27]
	v_mfma_f32_16x16x32_bf16 v[12:15], v[162:165], v[204:207], v[12:15]
	v_mfma_f32_16x16x32_bf16 v[8:11], v[170:173], v[204:207], v[8:11]
	v_mfma_f32_16x16x32_bf16 v[4:7], v[162:165], v[212:215], v[4:7]
	v_mfma_f32_16x16x32_bf16 v[0:3], v[170:173], v[212:215], v[0:3]
	s_barrier
	s_setprio 0
	s_add_i32 s0, 0, 0x18000
	s_add_i32 s1, 0, 0x1c000
	v_add_u32_e32 v154, s0, v139
	v_add_u32_e32 v170, s1, v139
	ds_read_b128 v[142:145], v154
	ds_read_b128 v[146:149], v154 offset:1024
	ds_read_b128 v[150:153], v154 offset:2048
	ds_read_b128 v[154:157], v154 offset:3072
	ds_read_b128 v[158:161], v170
	ds_read_b128 v[162:165], v170 offset:1024
	ds_read_b128 v[166:169], v170 offset:2048
	ds_read_b128 v[170:173], v170 offset:3072
	s_add_u32 s16, s24, 0x160000
	s_addc_u32 s17, s25, 0
	s_mov_b32 m0, s31
	v_lshl_add_u64 v[222:223], s[16:17], 0, v[128:129]
	ds_read_b128 v[174:177], v141 offset:32768
	ds_read_b128 v[178:181], v141 offset:33792
	ds_read_b128 v[182:185], v141 offset:34816
	ds_read_b128 v[196:199], v141 offset:35840
	ds_read_b128 v[200:203], v141 offset:36864
	ds_read_b128 v[204:207], v141 offset:37888
	ds_read_b128 v[208:211], v141 offset:38912
	ds_read_b128 v[212:215], v141 offset:39936
	global_load_lds_dwordx4 v[222:223], off
	s_mov_b32 m0, s33
	v_lshl_add_u64 v[222:223], s[16:17], 0, v[130:131]
	global_load_lds_dwordx4 v[222:223], off
	s_waitcnt vmcnt(8) lgkmcnt(0)
	s_setprio 1
	s_barrier
	v_mfma_f32_16x16x32_bf16 v[124:127], v[142:145], v[174:177], v[124:127]
	v_mfma_f32_16x16x32_bf16 v[120:123], v[150:153], v[174:177], v[120:123]
	v_mfma_f32_16x16x32_bf16 v[116:119], v[142:145], v[182:185], v[116:119]
	v_mfma_f32_16x16x32_bf16 v[112:115], v[150:153], v[182:185], v[112:115]
	v_mfma_f32_16x16x32_bf16 v[100:103], v[142:145], v[200:203], v[100:103]
	v_mfma_f32_16x16x32_bf16 v[96:99], v[150:153], v[200:203], v[96:99]
	v_mfma_f32_16x16x32_bf16 v[84:87], v[142:145], v[208:211], v[84:87]
	v_mfma_f32_16x16x32_bf16 v[80:83], v[150:153], v[208:211], v[80:83]
	v_mfma_f32_16x16x32_bf16 v[124:127], v[146:149], v[178:181], v[124:127]
	v_mfma_f32_16x16x32_bf16 v[120:123], v[154:157], v[178:181], v[120:123]
	v_mfma_f32_16x16x32_bf16 v[116:119], v[146:149], v[196:199], v[116:119]
	v_mfma_f32_16x16x32_bf16 v[112:115], v[154:157], v[196:199], v[112:115]
	v_mfma_f32_16x16x32_bf16 v[100:103], v[146:149], v[204:207], v[100:103]
	v_mfma_f32_16x16x32_bf16 v[96:99], v[154:157], v[204:207], v[96:99]
	v_mfma_f32_16x16x32_bf16 v[84:87], v[146:149], v[212:215], v[84:87]
	v_mfma_f32_16x16x32_bf16 v[80:83], v[154:157], v[212:215], v[80:83]
	v_mfma_f32_16x16x32_bf16 v[108:111], v[158:161], v[174:177], v[108:111]
	v_mfma_f32_16x16x32_bf16 v[104:107], v[166:169], v[174:177], v[104:107]
	v_mfma_f32_16x16x32_bf16 v[92:95], v[158:161], v[182:185], v[92:95]
	v_mfma_f32_16x16x32_bf16 v[88:91], v[166:169], v[182:185], v[88:91]
	v_mfma_f32_16x16x32_bf16 v[76:79], v[158:161], v[200:203], v[76:79]
	v_mfma_f32_16x16x32_bf16 v[72:75], v[166:169], v[200:203], v[72:75]
	v_mfma_f32_16x16x32_bf16 v[68:71], v[158:161], v[208:211], v[68:71]
	v_mfma_f32_16x16x32_bf16 v[64:67], v[166:169], v[208:211], v[64:67]
	v_mfma_f32_16x16x32_bf16 v[108:111], v[162:165], v[178:181], v[108:111]
	v_mfma_f32_16x16x32_bf16 v[104:107], v[170:173], v[178:181], v[104:107]
	v_mfma_f32_16x16x32_bf16 v[92:95], v[162:165], v[196:199], v[92:95]
	v_mfma_f32_16x16x32_bf16 v[88:91], v[170:173], v[196:199], v[88:91]
	v_mfma_f32_16x16x32_bf16 v[76:79], v[162:165], v[204:207], v[76:79]
	v_mfma_f32_16x16x32_bf16 v[72:75], v[170:173], v[204:207], v[72:75]
	v_mfma_f32_16x16x32_bf16 v[68:71], v[162:165], v[212:215], v[68:71]
	v_mfma_f32_16x16x32_bf16 v[64:67], v[170:173], v[212:215], v[64:67]
	s_barrier
	s_setprio 0
	s_add_i32 s0, s0, s28
	v_lshl_add_u64 v[186:187], v[186:187], 0, s[58:59]
	s_mov_b32 m0, s0
	ds_read_b128 v[174:177], v141 offset:49152
	ds_read_b128 v[178:181], v141 offset:50176
	ds_read_b128 v[182:185], v141 offset:51200
	ds_read_b128 v[196:199], v141 offset:52224
	ds_read_b128 v[200:203], v141 offset:53248
	ds_read_b128 v[204:207], v141 offset:54272
	ds_read_b128 v[208:211], v141 offset:55296
	ds_read_b128 v[212:215], v141 offset:56320
	global_load_lds_dwordx4 v[186:187], off
	s_add_i32 m0, s0, 0x2000
	s_add_u32 s16, s22, 0x160080
	v_lshl_add_u64 v[186:187], v[216:217], 0, s[58:59]
	s_addc_u32 s17, s23, 0
	s_add_i32 s0, s1, s28
	global_load_lds_dwordx4 v[186:187], off
	s_mov_b32 m0, s0
	v_lshl_add_u64 v[186:187], s[16:17], 0, v[190:191]
	global_load_lds_dwordx4 v[186:187], off
	s_add_i32 m0, s0, 0x2000
	v_lshl_add_u64 v[186:187], s[16:17], 0, v[132:133]
	global_load_lds_dwordx4 v[186:187], off
	s_mov_b32 m0, s37
	v_lshl_add_u64 v[186:187], v[218:219], 0, s[58:59]
	global_load_lds_dwordx4 v[186:187], off
	s_mov_b32 m0, s38
	v_lshl_add_u64 v[186:187], v[220:221], 0, s[58:59]
	global_load_lds_dwordx4 v[186:187], off
	s_waitcnt vmcnt(8) lgkmcnt(0)
	s_setprio 1
	s_barrier
	v_mfma_f32_16x16x32_bf16 v[60:63], v[142:145], v[174:177], v[60:63]
	v_mfma_f32_16x16x32_bf16 v[56:59], v[150:153], v[174:177], v[56:59]
	v_mfma_f32_16x16x32_bf16 v[52:55], v[142:145], v[182:185], v[52:55]
	v_mfma_f32_16x16x32_bf16 v[48:51], v[150:153], v[182:185], v[48:51]
	v_mfma_f32_16x16x32_bf16 v[36:39], v[142:145], v[200:203], v[36:39]
	v_mfma_f32_16x16x32_bf16 v[32:35], v[150:153], v[200:203], v[32:35]
	v_mfma_f32_16x16x32_bf16 v[20:23], v[142:145], v[208:211], v[20:23]
	v_mfma_f32_16x16x32_bf16 v[16:19], v[150:153], v[208:211], v[16:19]
	v_mfma_f32_16x16x32_bf16 v[60:63], v[146:149], v[178:181], v[60:63]
	v_mfma_f32_16x16x32_bf16 v[56:59], v[154:157], v[178:181], v[56:59]
	v_mfma_f32_16x16x32_bf16 v[52:55], v[146:149], v[196:199], v[52:55]
	v_mfma_f32_16x16x32_bf16 v[48:51], v[154:157], v[196:199], v[48:51]
	v_mfma_f32_16x16x32_bf16 v[36:39], v[146:149], v[204:207], v[36:39]
	v_mfma_f32_16x16x32_bf16 v[32:35], v[154:157], v[204:207], v[32:35]
	v_mfma_f32_16x16x32_bf16 v[20:23], v[146:149], v[212:215], v[20:23]
	v_mfma_f32_16x16x32_bf16 v[16:19], v[154:157], v[212:215], v[16:19]
	v_mfma_f32_16x16x32_bf16 v[44:47], v[158:161], v[174:177], v[44:47]
	v_mfma_f32_16x16x32_bf16 v[40:43], v[166:169], v[174:177], v[40:43]
	v_mfma_f32_16x16x32_bf16 v[28:31], v[158:161], v[182:185], v[28:31]
	v_mfma_f32_16x16x32_bf16 v[24:27], v[166:169], v[182:185], v[24:27]
	v_mfma_f32_16x16x32_bf16 v[12:15], v[158:161], v[200:203], v[12:15]
	v_mfma_f32_16x16x32_bf16 v[8:11], v[166:169], v[200:203], v[8:11]
	v_mfma_f32_16x16x32_bf16 v[4:7], v[158:161], v[208:211], v[4:7]
	v_mfma_f32_16x16x32_bf16 v[0:3], v[166:169], v[208:211], v[0:3]
	v_mfma_f32_16x16x32_bf16 v[44:47], v[162:165], v[178:181], v[44:47]
	v_mfma_f32_16x16x32_bf16 v[40:43], v[170:173], v[178:181], v[40:43]
	v_mfma_f32_16x16x32_bf16 v[28:31], v[162:165], v[196:199], v[28:31]
	v_mfma_f32_16x16x32_bf16 v[24:27], v[170:173], v[196:199], v[24:27]
	v_mfma_f32_16x16x32_bf16 v[12:15], v[162:165], v[204:207], v[12:15]
	v_mfma_f32_16x16x32_bf16 v[8:11], v[170:173], v[204:207], v[8:11]
	v_mfma_f32_16x16x32_bf16 v[4:7], v[162:165], v[212:215], v[4:7]
	v_mfma_f32_16x16x32_bf16 v[0:3], v[170:173], v[212:215], v[0:3]
	s_barrier
	s_setprio 0
	s_add_i32 s53, s53, 2
	s_add_u32 s47, s47, 0x100
	s_addc_u32 s52, s52, 0
	s_cmpk_gt_u32 s53, 0x55
	s_mov_b64 s[16:17], s[20:21]
	s_cbranch_scc1 .Lpeel_done_8
	s_branch .LBB0_1350
.Ltrip0_strict_8:
	s_add_u32 s20, s16, 0x100
	s_addc_u32 s21, s17, 0
	s_add_i32 s0, 0, 0x10000
	s_cmpk_eq_i32 s53, 0x54
	s_cselect_b32 s25, s13, s21
	s_cselect_b32 s24, s12, s20
	s_cselect_b32 s23, s15, s52
	s_cselect_b32 s22, s14, s47
	s_add_i32 s1, 0, 0x14000
	v_add_u32_e32 v154, s0, v139
	v_add_u32_e32 v170, s1, v139
	ds_read_b128 v[142:145], v154
	ds_read_b128 v[146:149], v154 offset:1024
	ds_read_b128 v[150:153], v154 offset:2048
	ds_read_b128 v[154:157], v154 offset:3072
	ds_read_b128 v[158:161], v170
	ds_read_b128 v[162:165], v170 offset:1024
	ds_read_b128 v[166:169], v170 offset:2048
	ds_read_b128 v[170:173], v170 offset:3072
	v_lshl_add_u64 v[186:187], s[16:17], 0, v[134:135]
	s_add_i32 m0, s29, 0xc000
	ds_read_b128 v[174:177], v141
	ds_read_b128 v[178:181], v141 offset:1024
	ds_read_b128 v[182:185], v141 offset:2048
	ds_read_b128 v[196:199], v141 offset:3072
	ds_read_b128 v[200:203], v141 offset:4096
	ds_read_b128 v[204:207], v141 offset:5120
	ds_read_b128 v[208:211], v141 offset:6144
	ds_read_b128 v[212:215], v141 offset:7168
	global_load_lds_dwordx4 v[186:187], off
	s_add_i32 m0, s29, 0xe000
	v_lshl_add_u64 v[186:187], s[16:17], 0, v[136:137]
	global_load_lds_dwordx4 v[186:187], off
	s_waitcnt vmcnt(8) lgkmcnt(0)
	s_setprio 1
	s_barrier
	v_mfma_f32_16x16x32_bf16 v[124:127], v[142:145], v[174:177], 0
	v_mfma_f32_16x16x32_bf16 v[120:123], v[150:153], v[174:177], 0
	v_mfma_f32_16x16x32_bf16 v[116:119], v[142:145], v[182:185], 0
	v_mfma_f32_16x16x32_bf16 v[112:115], v[150:153], v[182:185], 0
	v_mfma_f32_16x16x32_bf16 v[100:103], v[142:145], v[200:203], 0
	v_mfma_f32_16x16x32_bf16 v[96:99], v[150:153], v[200:203], 0
	v_mfma_f32_16x16x32_bf16 v[84:87], v[142:145], v[208:211], 0
	v_mfma_f32_16x16x32_bf16 v[80:83], v[150:153], v[208:211], 0
	v_mfma_f32_16x16x32_bf16 v[124:127], v[146:149], v[178:181], v[124:127]
	v_mfma_f32_16x16x32_bf16 v[120:123], v[154:157], v[178:181], v[120:123]
	v_mfma_f32_16x16x32_bf16 v[116:119], v[146:149], v[196:199], v[116:119]
	v_mfma_f32_16x16x32_bf16 v[112:115], v[154:157], v[196:199], v[112:115]
	v_mfma_f32_16x16x32_bf16 v[100:103], v[146:149], v[204:207], v[100:103]
	v_mfma_f32_16x16x32_bf16 v[96:99], v[154:157], v[204:207], v[96:99]
	v_mfma_f32_16x16x32_bf16 v[84:87], v[146:149], v[212:215], v[84:87]
	v_mfma_f32_16x16x32_bf16 v[80:83], v[154:157], v[212:215], v[80:83]
	v_mfma_f32_16x16x32_bf16 v[108:111], v[158:161], v[174:177], 0
	v_mfma_f32_16x16x32_bf16 v[104:107], v[166:169], v[174:177], 0
	v_mfma_f32_16x16x32_bf16 v[92:95], v[158:161], v[182:185], 0
	v_mfma_f32_16x16x32_bf16 v[88:91], v[166:169], v[182:185], 0
	v_mfma_f32_16x16x32_bf16 v[76:79], v[158:161], v[200:203], 0
	v_mfma_f32_16x16x32_bf16 v[72:75], v[166:169], v[200:203], 0
	v_mfma_f32_16x16x32_bf16 v[68:71], v[158:161], v[208:211], 0
	v_mfma_f32_16x16x32_bf16 v[64:67], v[166:169], v[208:211], 0
	v_mfma_f32_16x16x32_bf16 v[108:111], v[162:165], v[178:181], v[108:111]
	v_mfma_f32_16x16x32_bf16 v[104:107], v[170:173], v[178:181], v[104:107]
	v_mfma_f32_16x16x32_bf16 v[92:95], v[162:165], v[196:199], v[92:95]
	v_mfma_f32_16x16x32_bf16 v[88:91], v[170:173], v[196:199], v[88:91]
	v_mfma_f32_16x16x32_bf16 v[76:79], v[162:165], v[204:207], v[76:79]
	v_mfma_f32_16x16x32_bf16 v[72:75], v[170:173], v[204:207], v[72:75]
	v_mfma_f32_16x16x32_bf16 v[68:71], v[162:165], v[212:215], v[68:71]
	v_mfma_f32_16x16x32_bf16 v[64:67], v[170:173], v[212:215], v[64:67]
	s_barrier
	s_setprio 0
	s_add_i32 s0, s0, s28
	v_lshl_add_u64 v[186:187], s[22:23], 0, v[190:191]
	s_mov_b32 m0, s0
	ds_read_b128 v[174:177], v141 offset:16384
	ds_read_b128 v[178:181], v141 offset:17408
	ds_read_b128 v[182:185], v141 offset:18432
	ds_read_b128 v[196:199], v141 offset:19456
	ds_read_b128 v[200:203], v141 offset:20480
	ds_read_b128 v[204:207], v141 offset:21504
	ds_read_b128 v[208:211], v141 offset:22528
	ds_read_b128 v[212:215], v141 offset:23552
	global_load_lds_dwordx4 v[186:187], off
	s_add_i32 m0, s0, 0x2000
	s_add_u32 s16, s22, 0x160000
	v_lshl_add_u64 v[216:217], s[22:23], 0, v[132:133]
	s_addc_u32 s17, s23, 0
	s_add_i32 s0, s1, s28
	global_load_lds_dwordx4 v[216:217], off
	v_lshl_add_u64 v[218:219], s[16:17], 0, v[190:191]
	s_mov_b32 m0, s0
	v_lshl_add_u64 v[220:221], s[24:25], 0, v[130:131]
	global_load_lds_dwordx4 v[218:219], off
	s_add_i32 m0, s0, 0x2000
	v_lshl_add_u64 v[218:219], s[16:17], 0, v[132:133]
	global_load_lds_dwordx4 v[218:219], off
	s_mov_b32 m0, s29
	v_lshl_add_u64 v[218:219], s[24:25], 0, v[128:129]
	global_load_lds_dwordx4 v[218:219], off
	s_mov_b32 m0, s30
	s_nop 0
	global_load_lds_dwordx4 v[220:221], off
	s_waitcnt vmcnt(8) lgkmcnt(0)
	s_setprio 1
	s_barrier
	v_mfma_f32_16x16x32_bf16 v[60:63], v[142:145], v[174:177], 0
	v_mfma_f32_16x16x32_bf16 v[56:59], v[150:153], v[174:177], 0
	v_mfma_f32_16x16x32_bf16 v[52:55], v[142:145], v[182:185], 0
	v_mfma_f32_16x16x32_bf16 v[48:51], v[150:153], v[182:185], 0
	v_mfma_f32_16x16x32_bf16 v[36:39], v[142:145], v[200:203], 0
	v_mfma_f32_16x16x32_bf16 v[32:35], v[150:153], v[200:203], 0
	v_mfma_f32_16x16x32_bf16 v[20:23], v[142:145], v[208:211], 0
	v_mfma_f32_16x16x32_bf16 v[16:19], v[150:153], v[208:211], 0
	v_mfma_f32_16x16x32_bf16 v[60:63], v[146:149], v[178:181], v[60:63]
	v_mfma_f32_16x16x32_bf16 v[56:59], v[154:157], v[178:181], v[56:59]
	v_mfma_f32_16x16x32_bf16 v[52:55], v[146:149], v[196:199], v[52:55]
	v_mfma_f32_16x16x32_bf16 v[48:51], v[154:157], v[196:199], v[48:51]
	v_mfma_f32_16x16x32_bf16 v[36:39], v[146:149], v[204:207], v[36:39]
	v_mfma_f32_16x16x32_bf16 v[32:35], v[154:157], v[204:207], v[32:35]
	v_mfma_f32_16x16x32_bf16 v[20:23], v[146:149], v[212:215], v[20:23]
	v_mfma_f32_16x16x32_bf16 v[16:19], v[154:157], v[212:215], v[16:19]
	v_mfma_f32_16x16x32_bf16 v[44:47], v[158:161], v[174:177], 0
	v_mfma_f32_16x16x32_bf16 v[40:43], v[166:169], v[174:177], 0
	v_mfma_f32_16x16x32_bf16 v[28:31], v[158:161], v[182:185], 0
	v_mfma_f32_16x16x32_bf16 v[24:27], v[166:169], v[182:185], 0
	v_mfma_f32_16x16x32_bf16 v[12:15], v[158:161], v[200:203], 0
	v_mfma_f32_16x16x32_bf16 v[8:11], v[166:169], v[200:203], 0
	v_mfma_f32_16x16x32_bf16 v[4:7], v[158:161], v[208:211], 0
	v_mfma_f32_16x16x32_bf16 v[0:3], v[166:169], v[208:211], 0
	v_mfma_f32_16x16x32_bf16 v[44:47], v[162:165], v[178:181], v[44:47]
	v_mfma_f32_16x16x32_bf16 v[40:43], v[170:173], v[178:181], v[40:43]
	v_mfma_f32_16x16x32_bf16 v[28:31], v[162:165], v[196:199], v[28:31]
	v_mfma_f32_16x16x32_bf16 v[24:27], v[170:173], v[196:199], v[24:27]
	v_mfma_f32_16x16x32_bf16 v[12:15], v[162:165], v[204:207], v[12:15]
	v_mfma_f32_16x16x32_bf16 v[8:11], v[170:173], v[204:207], v[8:11]
	v_mfma_f32_16x16x32_bf16 v[4:7], v[162:165], v[212:215], v[4:7]
	v_mfma_f32_16x16x32_bf16 v[0:3], v[170:173], v[212:215], v[0:3]
	s_barrier
	s_setprio 0
	s_add_i32 s0, 0, 0x18000
	s_add_i32 s1, 0, 0x1c000
	v_add_u32_e32 v154, s0, v139
	v_add_u32_e32 v170, s1, v139
	ds_read_b128 v[142:145], v154
	ds_read_b128 v[146:149], v154 offset:1024
	ds_read_b128 v[150:153], v154 offset:2048
	ds_read_b128 v[154:157], v154 offset:3072
	ds_read_b128 v[158:161], v170
	ds_read_b128 v[162:165], v170 offset:1024
	ds_read_b128 v[166:169], v170 offset:2048
	ds_read_b128 v[170:173], v170 offset:3072
	s_add_u32 s16, s24, 0x160000
	s_addc_u32 s17, s25, 0
	s_mov_b32 m0, s31
	v_lshl_add_u64 v[222:223], s[16:17], 0, v[128:129]
	ds_read_b128 v[174:177], v141 offset:32768
	ds_read_b128 v[178:181], v141 offset:33792
	ds_read_b128 v[182:185], v141 offset:34816
	ds_read_b128 v[196:199], v141 offset:35840
	ds_read_b128 v[200:203], v141 offset:36864
	ds_read_b128 v[204:207], v141 offset:37888
	ds_read_b128 v[208:211], v141 offset:38912
	ds_read_b128 v[212:215], v141 offset:39936
	global_load_lds_dwordx4 v[222:223], off
	s_mov_b32 m0, s33
	v_lshl_add_u64 v[222:223], s[16:17], 0, v[130:131]
	global_load_lds_dwordx4 v[222:223], off
	s_waitcnt vmcnt(8) lgkmcnt(0)
	s_setprio 1
	s_barrier
	v_mfma_f32_16x16x32_bf16 v[124:127], v[142:145], v[174:177], v[124:127]
	v_mfma_f32_16x16x32_bf16 v[120:123], v[150:153], v[174:177], v[120:123]
	v_mfma_f32_16x16x32_bf16 v[116:119], v[142:145], v[182:185], v[116:119]
	v_mfma_f32_16x16x32_bf16 v[112:115], v[150:153], v[182:185], v[112:115]
	v_mfma_f32_16x16x32_bf16 v[100:103], v[142:145], v[200:203], v[100:103]
	v_mfma_f32_16x16x32_bf16 v[96:99], v[150:153], v[200:203], v[96:99]
	v_mfma_f32_16x16x32_bf16 v[84:87], v[142:145], v[208:211], v[84:87]
	v_mfma_f32_16x16x32_bf16 v[80:83], v[150:153], v[208:211], v[80:83]
	v_mfma_f32_16x16x32_bf16 v[124:127], v[146:149], v[178:181], v[124:127]
	v_mfma_f32_16x16x32_bf16 v[120:123], v[154:157], v[178:181], v[120:123]
	v_mfma_f32_16x16x32_bf16 v[116:119], v[146:149], v[196:199], v[116:119]
	v_mfma_f32_16x16x32_bf16 v[112:115], v[154:157], v[196:199], v[112:115]
	v_mfma_f32_16x16x32_bf16 v[100:103], v[146:149], v[204:207], v[100:103]
	v_mfma_f32_16x16x32_bf16 v[96:99], v[154:157], v[204:207], v[96:99]
	v_mfma_f32_16x16x32_bf16 v[84:87], v[146:149], v[212:215], v[84:87]
	v_mfma_f32_16x16x32_bf16 v[80:83], v[154:157], v[212:215], v[80:83]
	v_mfma_f32_16x16x32_bf16 v[108:111], v[158:161], v[174:177], v[108:111]
	v_mfma_f32_16x16x32_bf16 v[104:107], v[166:169], v[174:177], v[104:107]
	v_mfma_f32_16x16x32_bf16 v[92:95], v[158:161], v[182:185], v[92:95]
	v_mfma_f32_16x16x32_bf16 v[88:91], v[166:169], v[182:185], v[88:91]
	v_mfma_f32_16x16x32_bf16 v[76:79], v[158:161], v[200:203], v[76:79]
	v_mfma_f32_16x16x32_bf16 v[72:75], v[166:169], v[200:203], v[72:75]
	v_mfma_f32_16x16x32_bf16 v[68:71], v[158:161], v[208:211], v[68:71]
	v_mfma_f32_16x16x32_bf16 v[64:67], v[166:169], v[208:211], v[64:67]
	v_mfma_f32_16x16x32_bf16 v[108:111], v[162:165], v[178:181], v[108:111]
	v_mfma_f32_16x16x32_bf16 v[104:107], v[170:173], v[178:181], v[104:107]
	v_mfma_f32_16x16x32_bf16 v[92:95], v[162:165], v[196:199], v[92:95]
	v_mfma_f32_16x16x32_bf16 v[88:91], v[170:173], v[196:199], v[88:91]
	v_mfma_f32_16x16x32_bf16 v[76:79], v[162:165], v[204:207], v[76:79]
	v_mfma_f32_16x16x32_bf16 v[72:75], v[170:173], v[204:207], v[72:75]
	v_mfma_f32_16x16x32_bf16 v[68:71], v[162:165], v[212:215], v[68:71]
	v_mfma_f32_16x16x32_bf16 v[64:67], v[170:173], v[212:215], v[64:67]
	s_barrier
	s_setprio 0
	s_add_i32 s0, s0, s28
	v_lshl_add_u64 v[186:187], v[186:187], 0, s[58:59]
	s_mov_b32 m0, s0
	ds_read_b128 v[174:177], v141 offset:49152
	ds_read_b128 v[178:181], v141 offset:50176
	ds_read_b128 v[182:185], v141 offset:51200
	ds_read_b128 v[196:199], v141 offset:52224
	ds_read_b128 v[200:203], v141 offset:53248
	ds_read_b128 v[204:207], v141 offset:54272
	ds_read_b128 v[208:211], v141 offset:55296
	ds_read_b128 v[212:215], v141 offset:56320
	global_load_lds_dwordx4 v[186:187], off
	s_add_i32 m0, s0, 0x2000
	s_add_u32 s16, s22, 0x160080
	v_lshl_add_u64 v[186:187], v[216:217], 0, s[58:59]
	s_addc_u32 s17, s23, 0
	s_add_i32 s0, s1, s28
	global_load_lds_dwordx4 v[186:187], off
	s_mov_b32 m0, s0
	v_lshl_add_u64 v[186:187], s[16:17], 0, v[190:191]
	global_load_lds_dwordx4 v[186:187], off
	s_add_i32 m0, s0, 0x2000
	v_lshl_add_u64 v[186:187], s[16:17], 0, v[132:133]
	global_load_lds_dwordx4 v[186:187], off
	s_mov_b32 m0, s37
	v_lshl_add_u64 v[186:187], v[218:219], 0, s[58:59]
	global_load_lds_dwordx4 v[186:187], off
	s_mov_b32 m0, s38
	v_lshl_add_u64 v[186:187], v[220:221], 0, s[58:59]
	global_load_lds_dwordx4 v[186:187], off
	s_waitcnt vmcnt(8) lgkmcnt(0)
	s_setprio 1
	s_barrier
	v_mfma_f32_16x16x32_bf16 v[60:63], v[142:145], v[174:177], v[60:63]
	v_mfma_f32_16x16x32_bf16 v[56:59], v[150:153], v[174:177], v[56:59]
	v_mfma_f32_16x16x32_bf16 v[52:55], v[142:145], v[182:185], v[52:55]
	v_mfma_f32_16x16x32_bf16 v[48:51], v[150:153], v[182:185], v[48:51]
	v_mfma_f32_16x16x32_bf16 v[36:39], v[142:145], v[200:203], v[36:39]
	v_mfma_f32_16x16x32_bf16 v[32:35], v[150:153], v[200:203], v[32:35]
	v_mfma_f32_16x16x32_bf16 v[20:23], v[142:145], v[208:211], v[20:23]
	v_mfma_f32_16x16x32_bf16 v[16:19], v[150:153], v[208:211], v[16:19]
	v_mfma_f32_16x16x32_bf16 v[60:63], v[146:149], v[178:181], v[60:63]
	v_mfma_f32_16x16x32_bf16 v[56:59], v[154:157], v[178:181], v[56:59]
	v_mfma_f32_16x16x32_bf16 v[52:55], v[146:149], v[196:199], v[52:55]
	v_mfma_f32_16x16x32_bf16 v[48:51], v[154:157], v[196:199], v[48:51]
	v_mfma_f32_16x16x32_bf16 v[36:39], v[146:149], v[204:207], v[36:39]
	v_mfma_f32_16x16x32_bf16 v[32:35], v[154:157], v[204:207], v[32:35]
	v_mfma_f32_16x16x32_bf16 v[20:23], v[146:149], v[212:215], v[20:23]
	v_mfma_f32_16x16x32_bf16 v[16:19], v[154:157], v[212:215], v[16:19]
	v_mfma_f32_16x16x32_bf16 v[44:47], v[158:161], v[174:177], v[44:47]
	v_mfma_f32_16x16x32_bf16 v[40:43], v[166:169], v[174:177], v[40:43]
	v_mfma_f32_16x16x32_bf16 v[28:31], v[158:161], v[182:185], v[28:31]
	v_mfma_f32_16x16x32_bf16 v[24:27], v[166:169], v[182:185], v[24:27]
	v_mfma_f32_16x16x32_bf16 v[12:15], v[158:161], v[200:203], v[12:15]
	v_mfma_f32_16x16x32_bf16 v[8:11], v[166:169], v[200:203], v[8:11]
	v_mfma_f32_16x16x32_bf16 v[4:7], v[158:161], v[208:211], v[4:7]
	v_mfma_f32_16x16x32_bf16 v[0:3], v[166:169], v[208:211], v[0:3]
	v_mfma_f32_16x16x32_bf16 v[44:47], v[162:165], v[178:181], v[44:47]
	v_mfma_f32_16x16x32_bf16 v[40:43], v[170:173], v[178:181], v[40:43]
	v_mfma_f32_16x16x32_bf16 v[28:31], v[162:165], v[196:199], v[28:31]
	v_mfma_f32_16x16x32_bf16 v[24:27], v[170:173], v[196:199], v[24:27]
	v_mfma_f32_16x16x32_bf16 v[12:15], v[162:165], v[204:207], v[12:15]
	v_mfma_f32_16x16x32_bf16 v[8:11], v[170:173], v[204:207], v[8:11]
	v_mfma_f32_16x16x32_bf16 v[4:7], v[162:165], v[212:215], v[4:7]
	v_mfma_f32_16x16x32_bf16 v[0:3], v[170:173], v[212:215], v[0:3]
	s_barrier
	s_setprio 0
	s_add_i32 s53, s53, 2
	s_add_u32 s47, s47, 0x100
	s_addc_u32 s52, s52, 0
	s_cmpk_gt_u32 s53, 0x55
	s_mov_b64 s[16:17], s[20:21]
	s_cbranch_scc1 .Lpeel_done_8
.LBB0_1350:
	s_add_u32 s20, s16, 0x100
	s_addc_u32 s21, s17, 0
	s_add_i32 s0, 0, 0x10000
	s_cmpk_eq_i32 s53, 0x54
	s_cselect_b32 s25, s13, s21
	s_cselect_b32 s24, s12, s20
	s_cselect_b32 s23, s15, s52
	s_cselect_b32 s22, s14, s47
	s_add_i32 s1, 0, 0x14000
	v_add_u32_e32 v154, s0, v139
	v_add_u32_e32 v170, s1, v139
	ds_read_b128 v[142:145], v154
	ds_read_b128 v[146:149], v154 offset:1024
	ds_read_b128 v[150:153], v154 offset:2048
	ds_read_b128 v[154:157], v154 offset:3072
	ds_read_b128 v[158:161], v170
	ds_read_b128 v[162:165], v170 offset:1024
	ds_read_b128 v[166:169], v170 offset:2048
	ds_read_b128 v[170:173], v170 offset:3072
	v_lshl_add_u64 v[186:187], s[16:17], 0, v[134:135]
	s_add_i32 m0, s29, 0xc000
	ds_read_b128 v[174:177], v141
	ds_read_b128 v[178:181], v141 offset:1024
	ds_read_b128 v[182:185], v141 offset:2048
	ds_read_b128 v[196:199], v141 offset:3072
	ds_read_b128 v[200:203], v141 offset:4096
	ds_read_b128 v[204:207], v141 offset:5120
	ds_read_b128 v[208:211], v141 offset:6144
	ds_read_b128 v[212:215], v141 offset:7168
	global_load_lds_dwordx4 v[186:187], off
	s_add_i32 m0, s29, 0xe000
	v_lshl_add_u64 v[186:187], s[16:17], 0, v[136:137]
	global_load_lds_dwordx4 v[186:187], off
	s_waitcnt vmcnt(8) lgkmcnt(0)
	s_setprio 1
	s_barrier
	v_mfma_f32_16x16x32_bf16 v[124:127], v[142:145], v[174:177], v[124:127]
	v_mfma_f32_16x16x32_bf16 v[120:123], v[150:153], v[174:177], v[120:123]
	v_mfma_f32_16x16x32_bf16 v[116:119], v[142:145], v[182:185], v[116:119]
	v_mfma_f32_16x16x32_bf16 v[112:115], v[150:153], v[182:185], v[112:115]
	v_mfma_f32_16x16x32_bf16 v[100:103], v[142:145], v[200:203], v[100:103]
	v_mfma_f32_16x16x32_bf16 v[96:99], v[150:153], v[200:203], v[96:99]
	v_mfma_f32_16x16x32_bf16 v[84:87], v[142:145], v[208:211], v[84:87]
	v_mfma_f32_16x16x32_bf16 v[80:83], v[150:153], v[208:211], v[80:83]
	v_mfma_f32_16x16x32_bf16 v[124:127], v[146:149], v[178:181], v[124:127]
	v_mfma_f32_16x16x32_bf16 v[120:123], v[154:157], v[178:181], v[120:123]
	v_mfma_f32_16x16x32_bf16 v[116:119], v[146:149], v[196:199], v[116:119]
	v_mfma_f32_16x16x32_bf16 v[112:115], v[154:157], v[196:199], v[112:115]
	v_mfma_f32_16x16x32_bf16 v[100:103], v[146:149], v[204:207], v[100:103]
	v_mfma_f32_16x16x32_bf16 v[96:99], v[154:157], v[204:207], v[96:99]
	v_mfma_f32_16x16x32_bf16 v[84:87], v[146:149], v[212:215], v[84:87]
	v_mfma_f32_16x16x32_bf16 v[80:83], v[154:157], v[212:215], v[80:83]
	v_mfma_f32_16x16x32_bf16 v[108:111], v[158:161], v[174:177], v[108:111]
	v_mfma_f32_16x16x32_bf16 v[104:107], v[166:169], v[174:177], v[104:107]
	v_mfma_f32_16x16x32_bf16 v[92:95], v[158:161], v[182:185], v[92:95]
	v_mfma_f32_16x16x32_bf16 v[88:91], v[166:169], v[182:185], v[88:91]
	v_mfma_f32_16x16x32_bf16 v[76:79], v[158:161], v[200:203], v[76:79]
	v_mfma_f32_16x16x32_bf16 v[72:75], v[166:169], v[200:203], v[72:75]
	v_mfma_f32_16x16x32_bf16 v[68:71], v[158:161], v[208:211], v[68:71]
	v_mfma_f32_16x16x32_bf16 v[64:67], v[166:169], v[208:211], v[64:67]
	v_mfma_f32_16x16x32_bf16 v[108:111], v[162:165], v[178:181], v[108:111]
	v_mfma_f32_16x16x32_bf16 v[104:107], v[170:173], v[178:181], v[104:107]
	v_mfma_f32_16x16x32_bf16 v[92:95], v[162:165], v[196:199], v[92:95]
	v_mfma_f32_16x16x32_bf16 v[88:91], v[170:173], v[196:199], v[88:91]
	v_mfma_f32_16x16x32_bf16 v[76:79], v[162:165], v[204:207], v[76:79]
	v_mfma_f32_16x16x32_bf16 v[72:75], v[170:173], v[204:207], v[72:75]
	v_mfma_f32_16x16x32_bf16 v[68:71], v[162:165], v[212:215], v[68:71]
	v_mfma_f32_16x16x32_bf16 v[64:67], v[170:173], v[212:215], v[64:67]
	s_setprio 0
	s_barrier
	s_add_i32 s0, s0, s28
	v_lshl_add_u64 v[186:187], s[22:23], 0, v[190:191]
	s_mov_b32 m0, s0
	ds_read_b128 v[174:177], v141 offset:16384
	ds_read_b128 v[178:181], v141 offset:17408
	ds_read_b128 v[182:185], v141 offset:18432
	ds_read_b128 v[196:199], v141 offset:19456
	ds_read_b128 v[200:203], v141 offset:20480
	ds_read_b128 v[204:207], v141 offset:21504
	ds_read_b128 v[208:211], v141 offset:22528
	ds_read_b128 v[212:215], v141 offset:23552
	global_load_lds_dwordx4 v[186:187], off
	s_add_i32 m0, s0, 0x2000
	s_add_u32 s16, s22, 0x160000
	v_lshl_add_u64 v[216:217], s[22:23], 0, v[132:133]
	s_addc_u32 s17, s23, 0
	s_add_i32 s0, s1, s28
	global_load_lds_dwordx4 v[216:217], off
	v_lshl_add_u64 v[218:219], s[16:17], 0, v[190:191]
	s_mov_b32 m0, s0
	v_lshl_add_u64 v[220:221], s[24:25], 0, v[130:131]
	global_load_lds_dwordx4 v[218:219], off
	s_add_i32 m0, s0, 0x2000
	v_lshl_add_u64 v[218:219], s[16:17], 0, v[132:133]
	global_load_lds_dwordx4 v[218:219], off
	s_mov_b32 m0, s29
	v_lshl_add_u64 v[218:219], s[24:25], 0, v[128:129]
	global_load_lds_dwordx4 v[218:219], off
	s_mov_b32 m0, s30
	s_nop 0
	global_load_lds_dwordx4 v[220:221], off
	s_waitcnt vmcnt(8) lgkmcnt(0)
	s_setprio 1
	s_barrier
	v_mfma_f32_16x16x32_bf16 v[60:63], v[142:145], v[174:177], v[60:63]
	v_mfma_f32_16x16x32_bf16 v[56:59], v[150:153], v[174:177], v[56:59]
	v_mfma_f32_16x16x32_bf16 v[52:55], v[142:145], v[182:185], v[52:55]
	v_mfma_f32_16x16x32_bf16 v[48:51], v[150:153], v[182:185], v[48:51]
	v_mfma_f32_16x16x32_bf16 v[36:39], v[142:145], v[200:203], v[36:39]
	v_mfma_f32_16x16x32_bf16 v[32:35], v[150:153], v[200:203], v[32:35]
	v_mfma_f32_16x16x32_bf16 v[20:23], v[142:145], v[208:211], v[20:23]
	v_mfma_f32_16x16x32_bf16 v[16:19], v[150:153], v[208:211], v[16:19]
	v_mfma_f32_16x16x32_bf16 v[60:63], v[146:149], v[178:181], v[60:63]
	v_mfma_f32_16x16x32_bf16 v[56:59], v[154:157], v[178:181], v[56:59]
	v_mfma_f32_16x16x32_bf16 v[52:55], v[146:149], v[196:199], v[52:55]
	v_mfma_f32_16x16x32_bf16 v[48:51], v[154:157], v[196:199], v[48:51]
	v_mfma_f32_16x16x32_bf16 v[36:39], v[146:149], v[204:207], v[36:39]
	v_mfma_f32_16x16x32_bf16 v[32:35], v[154:157], v[204:207], v[32:35]
	v_mfma_f32_16x16x32_bf16 v[20:23], v[146:149], v[212:215], v[20:23]
	v_mfma_f32_16x16x32_bf16 v[16:19], v[154:157], v[212:215], v[16:19]
	v_mfma_f32_16x16x32_bf16 v[44:47], v[158:161], v[174:177], v[44:47]
	v_mfma_f32_16x16x32_bf16 v[40:43], v[166:169], v[174:177], v[40:43]
	v_mfma_f32_16x16x32_bf16 v[28:31], v[158:161], v[182:185], v[28:31]
	v_mfma_f32_16x16x32_bf16 v[24:27], v[166:169], v[182:185], v[24:27]
	v_mfma_f32_16x16x32_bf16 v[12:15], v[158:161], v[200:203], v[12:15]
	v_mfma_f32_16x16x32_bf16 v[8:11], v[166:169], v[200:203], v[8:11]
	v_mfma_f32_16x16x32_bf16 v[4:7], v[158:161], v[208:211], v[4:7]
	v_mfma_f32_16x16x32_bf16 v[0:3], v[166:169], v[208:211], v[0:3]
	v_mfma_f32_16x16x32_bf16 v[44:47], v[162:165], v[178:181], v[44:47]
	v_mfma_f32_16x16x32_bf16 v[40:43], v[170:173], v[178:181], v[40:43]
	v_mfma_f32_16x16x32_bf16 v[28:31], v[162:165], v[196:199], v[28:31]
	v_mfma_f32_16x16x32_bf16 v[24:27], v[170:173], v[196:199], v[24:27]
	v_mfma_f32_16x16x32_bf16 v[12:15], v[162:165], v[204:207], v[12:15]
	v_mfma_f32_16x16x32_bf16 v[8:11], v[170:173], v[204:207], v[8:11]
	v_mfma_f32_16x16x32_bf16 v[4:7], v[162:165], v[212:215], v[4:7]
	v_mfma_f32_16x16x32_bf16 v[0:3], v[170:173], v[212:215], v[0:3]
	s_setprio 0
	s_barrier
	s_add_i32 s0, 0, 0x18000
	s_add_i32 s1, 0, 0x1c000
	v_add_u32_e32 v154, s0, v139
	v_add_u32_e32 v170, s1, v139
	ds_read_b128 v[142:145], v154
	ds_read_b128 v[146:149], v154 offset:1024
	ds_read_b128 v[150:153], v154 offset:2048
	ds_read_b128 v[154:157], v154 offset:3072
	ds_read_b128 v[158:161], v170
	ds_read_b128 v[162:165], v170 offset:1024
	ds_read_b128 v[166:169], v170 offset:2048
	ds_read_b128 v[170:173], v170 offset:3072
	s_add_u32 s16, s24, 0x160000
	s_addc_u32 s17, s25, 0
	s_mov_b32 m0, s31
	v_lshl_add_u64 v[222:223], s[16:17], 0, v[128:129]
	ds_read_b128 v[174:177], v141 offset:32768
	ds_read_b128 v[178:181], v141 offset:33792
	ds_read_b128 v[182:185], v141 offset:34816
	ds_read_b128 v[196:199], v141 offset:35840
	ds_read_b128 v[200:203], v141 offset:36864
	ds_read_b128 v[204:207], v141 offset:37888
	ds_read_b128 v[208:211], v141 offset:38912
	ds_read_b128 v[212:215], v141 offset:39936
	global_load_lds_dwordx4 v[222:223], off
	s_mov_b32 m0, s33
	v_lshl_add_u64 v[222:223], s[16:17], 0, v[130:131]
	global_load_lds_dwordx4 v[222:223], off
	s_waitcnt vmcnt(8) lgkmcnt(0)
	s_setprio 1
	s_barrier
	v_mfma_f32_16x16x32_bf16 v[124:127], v[142:145], v[174:177], v[124:127]
	v_mfma_f32_16x16x32_bf16 v[120:123], v[150:153], v[174:177], v[120:123]
	v_mfma_f32_16x16x32_bf16 v[116:119], v[142:145], v[182:185], v[116:119]
	v_mfma_f32_16x16x32_bf16 v[112:115], v[150:153], v[182:185], v[112:115]
	v_mfma_f32_16x16x32_bf16 v[100:103], v[142:145], v[200:203], v[100:103]
	v_mfma_f32_16x16x32_bf16 v[96:99], v[150:153], v[200:203], v[96:99]
	v_mfma_f32_16x16x32_bf16 v[84:87], v[142:145], v[208:211], v[84:87]
	v_mfma_f32_16x16x32_bf16 v[80:83], v[150:153], v[208:211], v[80:83]
	v_mfma_f32_16x16x32_bf16 v[124:127], v[146:149], v[178:181], v[124:127]
	v_mfma_f32_16x16x32_bf16 v[120:123], v[154:157], v[178:181], v[120:123]
	v_mfma_f32_16x16x32_bf16 v[116:119], v[146:149], v[196:199], v[116:119]
	v_mfma_f32_16x16x32_bf16 v[112:115], v[154:157], v[196:199], v[112:115]
	v_mfma_f32_16x16x32_bf16 v[100:103], v[146:149], v[204:207], v[100:103]
	v_mfma_f32_16x16x32_bf16 v[96:99], v[154:157], v[204:207], v[96:99]
	v_mfma_f32_16x16x32_bf16 v[84:87], v[146:149], v[212:215], v[84:87]
	v_mfma_f32_16x16x32_bf16 v[80:83], v[154:157], v[212:215], v[80:83]
	v_mfma_f32_16x16x32_bf16 v[108:111], v[158:161], v[174:177], v[108:111]
	v_mfma_f32_16x16x32_bf16 v[104:107], v[166:169], v[174:177], v[104:107]
	v_mfma_f32_16x16x32_bf16 v[92:95], v[158:161], v[182:185], v[92:95]
	v_mfma_f32_16x16x32_bf16 v[88:91], v[166:169], v[182:185], v[88:91]
	v_mfma_f32_16x16x32_bf16 v[76:79], v[158:161], v[200:203], v[76:79]
	v_mfma_f32_16x16x32_bf16 v[72:75], v[166:169], v[200:203], v[72:75]
	v_mfma_f32_16x16x32_bf16 v[68:71], v[158:161], v[208:211], v[68:71]
	v_mfma_f32_16x16x32_bf16 v[64:67], v[166:169], v[208:211], v[64:67]
	v_mfma_f32_16x16x32_bf16 v[108:111], v[162:165], v[178:181], v[108:111]
	v_mfma_f32_16x16x32_bf16 v[104:107], v[170:173], v[178:181], v[104:107]
	v_mfma_f32_16x16x32_bf16 v[92:95], v[162:165], v[196:199], v[92:95]
	v_mfma_f32_16x16x32_bf16 v[88:91], v[170:173], v[196:199], v[88:91]
	v_mfma_f32_16x16x32_bf16 v[76:79], v[162:165], v[204:207], v[76:79]
	v_mfma_f32_16x16x32_bf16 v[72:75], v[170:173], v[204:207], v[72:75]
	v_mfma_f32_16x16x32_bf16 v[68:71], v[162:165], v[212:215], v[68:71]
	v_mfma_f32_16x16x32_bf16 v[64:67], v[170:173], v[212:215], v[64:67]
	s_setprio 0
	s_barrier
	s_add_i32 s0, s0, s28
	v_lshl_add_u64 v[186:187], v[186:187], 0, s[58:59]
	s_mov_b32 m0, s0
	ds_read_b128 v[174:177], v141 offset:49152
	ds_read_b128 v[178:181], v141 offset:50176
	ds_read_b128 v[182:185], v141 offset:51200
	ds_read_b128 v[196:199], v141 offset:52224
	ds_read_b128 v[200:203], v141 offset:53248
	ds_read_b128 v[204:207], v141 offset:54272
	ds_read_b128 v[208:211], v141 offset:55296
	ds_read_b128 v[212:215], v141 offset:56320
	global_load_lds_dwordx4 v[186:187], off
	s_add_i32 m0, s0, 0x2000
	s_add_u32 s16, s22, 0x160080
	v_lshl_add_u64 v[186:187], v[216:217], 0, s[58:59]
	s_addc_u32 s17, s23, 0
	s_add_i32 s0, s1, s28
	global_load_lds_dwordx4 v[186:187], off
	s_mov_b32 m0, s0
	v_lshl_add_u64 v[186:187], s[16:17], 0, v[190:191]
	global_load_lds_dwordx4 v[186:187], off
	s_add_i32 m0, s0, 0x2000
	v_lshl_add_u64 v[186:187], s[16:17], 0, v[132:133]
	global_load_lds_dwordx4 v[186:187], off
	s_mov_b32 m0, s37
	v_lshl_add_u64 v[186:187], v[218:219], 0, s[58:59]
	global_load_lds_dwordx4 v[186:187], off
	s_mov_b32 m0, s38
	v_lshl_add_u64 v[186:187], v[220:221], 0, s[58:59]
	global_load_lds_dwordx4 v[186:187], off
	s_waitcnt vmcnt(8) lgkmcnt(0)
	s_setprio 1
	s_barrier
	v_mfma_f32_16x16x32_bf16 v[60:63], v[142:145], v[174:177], v[60:63]
	v_mfma_f32_16x16x32_bf16 v[56:59], v[150:153], v[174:177], v[56:59]
	v_mfma_f32_16x16x32_bf16 v[52:55], v[142:145], v[182:185], v[52:55]
	v_mfma_f32_16x16x32_bf16 v[48:51], v[150:153], v[182:185], v[48:51]
	v_mfma_f32_16x16x32_bf16 v[36:39], v[142:145], v[200:203], v[36:39]
	v_mfma_f32_16x16x32_bf16 v[32:35], v[150:153], v[200:203], v[32:35]
	v_mfma_f32_16x16x32_bf16 v[20:23], v[142:145], v[208:211], v[20:23]
	v_mfma_f32_16x16x32_bf16 v[16:19], v[150:153], v[208:211], v[16:19]
	v_mfma_f32_16x16x32_bf16 v[60:63], v[146:149], v[178:181], v[60:63]
	v_mfma_f32_16x16x32_bf16 v[56:59], v[154:157], v[178:181], v[56:59]
	v_mfma_f32_16x16x32_bf16 v[52:55], v[146:149], v[196:199], v[52:55]
	v_mfma_f32_16x16x32_bf16 v[48:51], v[154:157], v[196:199], v[48:51]
	v_mfma_f32_16x16x32_bf16 v[36:39], v[146:149], v[204:207], v[36:39]
	v_mfma_f32_16x16x32_bf16 v[32:35], v[154:157], v[204:207], v[32:35]
	v_mfma_f32_16x16x32_bf16 v[20:23], v[146:149], v[212:215], v[20:23]
	v_mfma_f32_16x16x32_bf16 v[16:19], v[154:157], v[212:215], v[16:19]
	v_mfma_f32_16x16x32_bf16 v[44:47], v[158:161], v[174:177], v[44:47]
	v_mfma_f32_16x16x32_bf16 v[40:43], v[166:169], v[174:177], v[40:43]
	v_mfma_f32_16x16x32_bf16 v[28:31], v[158:161], v[182:185], v[28:31]
	v_mfma_f32_16x16x32_bf16 v[24:27], v[166:169], v[182:185], v[24:27]
	v_mfma_f32_16x16x32_bf16 v[12:15], v[158:161], v[200:203], v[12:15]
	v_mfma_f32_16x16x32_bf16 v[8:11], v[166:169], v[200:203], v[8:11]
	v_mfma_f32_16x16x32_bf16 v[4:7], v[158:161], v[208:211], v[4:7]
	v_mfma_f32_16x16x32_bf16 v[0:3], v[166:169], v[208:211], v[0:3]
	v_mfma_f32_16x16x32_bf16 v[44:47], v[162:165], v[178:181], v[44:47]
	v_mfma_f32_16x16x32_bf16 v[40:43], v[170:173], v[178:181], v[40:43]
	v_mfma_f32_16x16x32_bf16 v[28:31], v[162:165], v[196:199], v[28:31]
	v_mfma_f32_16x16x32_bf16 v[24:27], v[170:173], v[196:199], v[24:27]
	v_mfma_f32_16x16x32_bf16 v[12:15], v[162:165], v[204:207], v[12:15]
	v_mfma_f32_16x16x32_bf16 v[8:11], v[170:173], v[204:207], v[8:11]
	v_mfma_f32_16x16x32_bf16 v[4:7], v[162:165], v[212:215], v[4:7]
	v_mfma_f32_16x16x32_bf16 v[0:3], v[170:173], v[212:215], v[0:3]
	s_setprio 0
	s_barrier
	s_add_i32 s53, s53, 2
	s_add_u32 s47, s47, 0x100
	s_addc_u32 s52, s52, 0
	s_cmpk_gt_u32 s53, 0x55
	s_mov_b64 s[16:17], s[20:21]
	s_cbranch_scc0 .LBB0_1350
